# GEMM1 epilogue activation stores made write-through (sc1) on top of nt x loads
# baseline (speedup 1.0000x reference)
.LBB0_151:
	ds_read_b128 v[130:133], v169
	ds_read_b128 v[134:137], v169 offset:1024
	ds_read_b128 v[138:141], v169 offset:2048
	ds_read_b128 v[142:145], v169 offset:3072
	s_add_u32 s57, s58, 0xfffc0080
	s_addc_u32 s60, s59, -1
	s_cmp_eq_u32 s55, 12
	s_cselect_b32 s63, s11, s60
	s_cselect_b32 s62, s10, s57
	s_cselect_b32 s61, s9, s3
	s_cselect_b32 s60, s8, s2
	v_lshl_add_u64 v[200:201], s[58:59], 0, v[160:161]
	s_add_i32 m0, s70, 0xc000
	ds_read_b128 v[164:167], v170
	ds_read_b128 v[172:175], v170 offset:1024
	ds_read_b128 v[176:179], v170 offset:2048
	ds_read_b128 v[180:183], v170 offset:3072
	ds_read_b128 v[184:187], v170 offset:4096
	ds_read_b128 v[188:191], v170 offset:5120
	ds_read_b128 v[192:195], v170 offset:6144
	ds_read_b128 v[196:199], v170 offset:7168
	global_load_lds_dwordx4 v[200:201], off
	v_lshl_add_u64 v[200:201], s[58:59], 0, v[162:163]
	s_add_i32 m0, s70, 0xe000
	s_nop 0
	global_load_lds_dwordx4 v[200:201], off
	s_waitcnt lgkmcnt(8)
	s_barrier
	s_waitcnt lgkmcnt(0)
	s_setprio 1
	s_waitcnt lgkmcnt(0)
	v_mfma_f32_16x16x32_bf16 v[126:129], v[130:133], v[164:167], v[126:129]
	v_mfma_f32_16x16x32_bf16 v[122:125], v[138:141], v[164:167], v[122:125]
	v_mfma_f32_16x16x32_bf16 v[114:117], v[130:133], v[176:179], v[114:117]
	v_mfma_f32_16x16x32_bf16 v[106:109], v[138:141], v[176:179], v[106:109]
	v_mfma_f32_16x16x32_bf16 v[98:101], v[130:133], v[184:187], v[98:101]
	v_mfma_f32_16x16x32_bf16 v[90:93], v[138:141], v[184:187], v[90:93]
	v_mfma_f32_16x16x32_bf16 v[82:85], v[130:133], v[192:195], v[82:85]
	v_mfma_f32_16x16x32_bf16 v[74:77], v[138:141], v[192:195], v[74:77]
	v_mfma_f32_16x16x32_bf16 v[126:129], v[134:137], v[172:175], v[126:129]
	v_mfma_f32_16x16x32_bf16 v[122:125], v[142:145], v[172:175], v[122:125]
	v_mfma_f32_16x16x32_bf16 v[114:117], v[134:137], v[180:183], v[114:117]
	v_mfma_f32_16x16x32_bf16 v[106:109], v[142:145], v[180:183], v[106:109]
	v_mfma_f32_16x16x32_bf16 v[98:101], v[134:137], v[188:191], v[98:101]
	v_mfma_f32_16x16x32_bf16 v[90:93], v[142:145], v[188:191], v[90:93]
	v_mfma_f32_16x16x32_bf16 v[82:85], v[134:137], v[196:199], v[82:85]
	v_mfma_f32_16x16x32_bf16 v[74:77], v[142:145], v[196:199], v[74:77]
	s_setprio 0
	s_barrier
	s_add_i32 s57, s96, s69
	v_lshl_add_u64 v[216:217], s[60:61], 0, v[152:153]
	s_mov_b32 m0, s57
	ds_read_b128 v[200:203], v171
	ds_read_b128 v[204:207], v171 offset:1024
	ds_read_b128 v[208:211], v171 offset:2048
	ds_read_b128 v[212:215], v171 offset:3072
	global_load_lds_dwordx4 v[216:217], off
	v_lshl_add_u64 v[218:219], s[60:61], 0, v[156:157]
	s_add_i32 m0, s57, 0x2000
	s_nop 0
	global_load_lds_dwordx4 v[218:219], off
	s_barrier
	s_waitcnt lgkmcnt(0)
	s_setprio 1
	s_waitcnt lgkmcnt(0)
	v_mfma_f32_16x16x32_bf16 v[118:121], v[200:203], v[164:167], v[118:121]
	v_mfma_f32_16x16x32_bf16 v[110:113], v[208:211], v[164:167], v[110:113]
	v_mfma_f32_16x16x32_bf16 v[102:105], v[200:203], v[176:179], v[102:105]
	v_mfma_f32_16x16x32_bf16 v[94:97], v[208:211], v[176:179], v[94:97]
	v_mfma_f32_16x16x32_bf16 v[86:89], v[200:203], v[184:187], v[86:89]
	v_mfma_f32_16x16x32_bf16 v[78:81], v[208:211], v[184:187], v[78:81]
	v_mfma_f32_16x16x32_bf16 v[70:73], v[200:203], v[192:195], v[70:73]
	v_mfma_f32_16x16x32_bf16 v[66:69], v[208:211], v[192:195], v[66:69]
	v_mfma_f32_16x16x32_bf16 v[118:121], v[204:207], v[172:175], v[118:121]
	v_mfma_f32_16x16x32_bf16 v[110:113], v[212:215], v[172:175], v[110:113]
	v_mfma_f32_16x16x32_bf16 v[102:105], v[204:207], v[180:183], v[102:105]
	v_mfma_f32_16x16x32_bf16 v[94:97], v[212:215], v[180:183], v[94:97]
	v_mfma_f32_16x16x32_bf16 v[86:89], v[204:207], v[188:191], v[86:89]
	v_mfma_f32_16x16x32_bf16 v[78:81], v[212:215], v[188:191], v[78:81]
	v_mfma_f32_16x16x32_bf16 v[70:73], v[204:207], v[196:199], v[70:73]
	v_mfma_f32_16x16x32_bf16 v[66:69], v[212:215], v[196:199], v[66:69]
	s_setprio 0
	s_mov_b32 m0, s70
	v_lshl_add_u64 v[220:221], s[62:63], 0, v[150:151]
	s_barrier
	ds_read_b128 v[164:167], v170 offset:16384
	ds_read_b128 v[172:175], v170 offset:17408
	ds_read_b128 v[176:179], v170 offset:18432
	ds_read_b128 v[180:183], v170 offset:19456
	ds_read_b128 v[184:187], v170 offset:20480
	ds_read_b128 v[188:191], v170 offset:21504
	ds_read_b128 v[192:195], v170 offset:22528
	ds_read_b128 v[196:199], v170 offset:23552
	global_load_lds_dwordx4 v[220:221], off
	v_lshl_add_u64 v[222:223], s[62:63], 0, v[154:155]
	s_mov_b32 m0, s71
	s_nop 0
	global_load_lds_dwordx4 v[222:223], off
	s_barrier
	s_waitcnt lgkmcnt(0)
	s_setprio 1
	s_waitcnt lgkmcnt(0)
	v_mfma_f32_16x16x32_bf16 v[62:65], v[130:133], v[164:167], v[62:65]
	v_mfma_f32_16x16x32_bf16 v[58:61], v[138:141], v[164:167], v[58:61]
	v_mfma_f32_16x16x32_bf16 v[50:53], v[130:133], v[176:179], v[50:53]
	v_mfma_f32_16x16x32_bf16 v[42:45], v[138:141], v[176:179], v[42:45]
	v_mfma_f32_16x16x32_bf16 v[34:37], v[130:133], v[184:187], v[34:37]
	v_mfma_f32_16x16x32_bf16 v[26:29], v[138:141], v[184:187], v[26:29]
	v_mfma_f32_16x16x32_bf16 v[18:21], v[130:133], v[192:195], v[18:21]
	v_mfma_f32_16x16x32_bf16 v[10:13], v[138:141], v[192:195], v[10:13]
	v_mfma_f32_16x16x32_bf16 v[62:65], v[134:137], v[172:175], v[62:65]
	v_mfma_f32_16x16x32_bf16 v[58:61], v[142:145], v[172:175], v[58:61]
	v_mfma_f32_16x16x32_bf16 v[50:53], v[134:137], v[180:183], v[50:53]
	v_mfma_f32_16x16x32_bf16 v[42:45], v[142:145], v[180:183], v[42:45]
	v_mfma_f32_16x16x32_bf16 v[34:37], v[134:137], v[188:191], v[34:37]
	v_mfma_f32_16x16x32_bf16 v[26:29], v[142:145], v[188:191], v[26:29]
	v_mfma_f32_16x16x32_bf16 v[18:21], v[134:137], v[196:199], v[18:21]
	v_mfma_f32_16x16x32_bf16 v[10:13], v[142:145], v[196:199], v[10:13]
	s_setprio 0
	s_barrier
	s_add_u32 s64, s60, 0x40000
	s_addc_u32 s65, s61, 0
	s_add_i32 s57, s33, s69
	v_lshl_add_u64 v[130:131], s[64:65], 0, v[152:153]
	s_mov_b32 m0, s57
	s_nop 0
	global_load_lds_dwordx4 v[130:131], off
	v_lshl_add_u64 v[130:131], s[64:65], 0, v[156:157]
	s_add_i32 m0, s57, 0x2000
	s_nop 0
	global_load_lds_dwordx4 v[130:131], off
	s_waitcnt vmcnt(6)
	s_barrier
	s_setprio 1
	v_mfma_f32_16x16x32_bf16 v[54:57], v[200:203], v[164:167], v[54:57]
	v_mfma_f32_16x16x32_bf16 v[46:49], v[208:211], v[164:167], v[46:49]
	v_mfma_f32_16x16x32_bf16 v[38:41], v[200:203], v[176:179], v[38:41]
	v_mfma_f32_16x16x32_bf16 v[30:33], v[208:211], v[176:179], v[30:33]
	v_mfma_f32_16x16x32_bf16 v[22:25], v[200:203], v[184:187], v[22:25]
	v_mfma_f32_16x16x32_bf16 v[14:17], v[208:211], v[184:187], v[14:17]
	v_mfma_f32_16x16x32_bf16 v[6:9], v[200:203], v[192:195], v[6:9]
	v_mfma_f32_16x16x32_bf16 v[2:5], v[208:211], v[192:195], v[2:5]
	v_mfma_f32_16x16x32_bf16 v[54:57], v[204:207], v[172:175], v[54:57]
	v_mfma_f32_16x16x32_bf16 v[46:49], v[212:215], v[172:175], v[46:49]
	v_mfma_f32_16x16x32_bf16 v[38:41], v[204:207], v[180:183], v[38:41]
	v_mfma_f32_16x16x32_bf16 v[30:33], v[212:215], v[180:183], v[30:33]
	v_mfma_f32_16x16x32_bf16 v[22:25], v[204:207], v[188:191], v[22:25]
	v_mfma_f32_16x16x32_bf16 v[14:17], v[212:215], v[188:191], v[14:17]
	v_mfma_f32_16x16x32_bf16 v[6:9], v[204:207], v[196:199], v[6:9]
	v_mfma_f32_16x16x32_bf16 v[2:5], v[212:215], v[196:199], v[2:5]
	s_setprio 0
	s_add_i32 s57, 0, 0x18000
	v_add_u32_e32 v142, s57, v149
	s_barrier
	ds_read_b128 v[130:133], v142
	ds_read_b128 v[134:137], v142 offset:1024
	ds_read_b128 v[138:141], v142 offset:2048
	ds_read_b128 v[142:145], v142 offset:3072
	s_add_u32 s62, s62, 0x40000
	s_addc_u32 s63, s63, 0
	s_mov_b32 m0, s72
	v_lshl_add_u64 v[200:201], s[62:63], 0, v[150:151]
	ds_read_b128 v[164:167], v170 offset:32768
	ds_read_b128 v[172:175], v170 offset:33792
	ds_read_b128 v[176:179], v170 offset:34816
	ds_read_b128 v[180:183], v170 offset:35840
	ds_read_b128 v[184:187], v170 offset:36864
	ds_read_b128 v[188:191], v170 offset:37888
	ds_read_b128 v[192:195], v170 offset:38912
	ds_read_b128 v[196:199], v170 offset:39936
	global_load_lds_dwordx4 v[200:201], off
	v_lshl_add_u64 v[200:201], s[62:63], 0, v[154:155]
	s_mov_b32 m0, s73
	s_nop 0
	global_load_lds_dwordx4 v[200:201], off
	s_waitcnt lgkmcnt(8)
	s_barrier
	s_waitcnt lgkmcnt(0)
	s_setprio 1
	s_waitcnt lgkmcnt(0)
	v_mfma_f32_16x16x32_bf16 v[126:129], v[130:133], v[164:167], v[126:129]
	v_mfma_f32_16x16x32_bf16 v[122:125], v[138:141], v[164:167], v[122:125]
	v_mfma_f32_16x16x32_bf16 v[114:117], v[130:133], v[176:179], v[114:117]
	v_mfma_f32_16x16x32_bf16 v[106:109], v[138:141], v[176:179], v[106:109]
	v_mfma_f32_16x16x32_bf16 v[98:101], v[130:133], v[184:187], v[98:101]
	v_mfma_f32_16x16x32_bf16 v[90:93], v[138:141], v[184:187], v[90:93]
	v_mfma_f32_16x16x32_bf16 v[82:85], v[130:133], v[192:195], v[82:85]
	v_mfma_f32_16x16x32_bf16 v[74:77], v[138:141], v[192:195], v[74:77]
	v_mfma_f32_16x16x32_bf16 v[126:129], v[134:137], v[172:175], v[126:129]
	v_mfma_f32_16x16x32_bf16 v[122:125], v[142:145], v[172:175], v[122:125]
	v_mfma_f32_16x16x32_bf16 v[114:117], v[134:137], v[180:183], v[114:117]
	v_mfma_f32_16x16x32_bf16 v[106:109], v[142:145], v[180:183], v[106:109]
	v_mfma_f32_16x16x32_bf16 v[98:101], v[134:137], v[188:191], v[98:101]
	v_mfma_f32_16x16x32_bf16 v[90:93], v[142:145], v[188:191], v[90:93]
	v_mfma_f32_16x16x32_bf16 v[82:85], v[134:137], v[196:199], v[82:85]
	v_mfma_f32_16x16x32_bf16 v[74:77], v[142:145], v[196:199], v[74:77]
	s_setprio 0
	s_barrier
	s_add_i32 s62, 0, 0x1c000
	s_add_i32 s57, s57, s69
	v_add_u32_e32 v158, s62, v149
	v_lshl_add_u64 v[216:217], v[216:217], 0, s[0:1]
	s_mov_b32 m0, s57
	ds_read_b128 v[200:203], v158
	ds_read_b128 v[204:207], v158 offset:1024
	ds_read_b128 v[208:211], v158 offset:2048
	ds_read_b128 v[212:215], v158 offset:3072
	global_load_lds_dwordx4 v[216:217], off
	v_lshl_add_u64 v[216:217], v[218:219], 0, s[0:1]
	s_add_i32 m0, s57, 0x2000
	s_nop 0
	global_load_lds_dwordx4 v[216:217], off
	s_barrier
	s_waitcnt lgkmcnt(0)
	s_setprio 1
	s_waitcnt lgkmcnt(0)
	v_mfma_f32_16x16x32_bf16 v[118:121], v[200:203], v[164:167], v[118:121]
	v_mfma_f32_16x16x32_bf16 v[110:113], v[208:211], v[164:167], v[110:113]
	v_mfma_f32_16x16x32_bf16 v[102:105], v[200:203], v[176:179], v[102:105]
	v_mfma_f32_16x16x32_bf16 v[94:97], v[208:211], v[176:179], v[94:97]
	v_mfma_f32_16x16x32_bf16 v[86:89], v[200:203], v[184:187], v[86:89]
	v_mfma_f32_16x16x32_bf16 v[78:81], v[208:211], v[184:187], v[78:81]
	v_mfma_f32_16x16x32_bf16 v[70:73], v[200:203], v[192:195], v[70:73]
	v_mfma_f32_16x16x32_bf16 v[66:69], v[208:211], v[192:195], v[66:69]
	v_mfma_f32_16x16x32_bf16 v[118:121], v[204:207], v[172:175], v[118:121]
	v_mfma_f32_16x16x32_bf16 v[110:113], v[212:215], v[172:175], v[110:113]
	v_mfma_f32_16x16x32_bf16 v[102:105], v[204:207], v[180:183], v[102:105]
	v_mfma_f32_16x16x32_bf16 v[94:97], v[212:215], v[180:183], v[94:97]
	v_mfma_f32_16x16x32_bf16 v[86:89], v[204:207], v[188:191], v[86:89]
	v_mfma_f32_16x16x32_bf16 v[78:81], v[212:215], v[188:191], v[78:81]
	v_mfma_f32_16x16x32_bf16 v[70:73], v[204:207], v[196:199], v[70:73]
	v_mfma_f32_16x16x32_bf16 v[66:69], v[212:215], v[196:199], v[66:69]
	s_setprio 0
	s_mov_b32 m0, s90
	v_lshl_add_u64 v[216:217], v[220:221], 0, s[0:1]
	s_barrier
	ds_read_b128 v[164:167], v170 offset:49152
	ds_read_b128 v[172:175], v170 offset:50176
	ds_read_b128 v[176:179], v170 offset:51200
	ds_read_b128 v[180:183], v170 offset:52224
	ds_read_b128 v[184:187], v170 offset:53248
	ds_read_b128 v[188:191], v170 offset:54272
	ds_read_b128 v[192:195], v170 offset:55296
	ds_read_b128 v[196:199], v170 offset:56320
	global_load_lds_dwordx4 v[216:217], off
	v_lshl_add_u64 v[216:217], v[222:223], 0, s[0:1]
	s_mov_b32 m0, s91
	s_nop 0
	global_load_lds_dwordx4 v[216:217], off
	s_barrier
	s_waitcnt lgkmcnt(0)
	s_setprio 1
	s_waitcnt lgkmcnt(0)
	v_mfma_f32_16x16x32_bf16 v[62:65], v[130:133], v[164:167], v[62:65]
	v_mfma_f32_16x16x32_bf16 v[58:61], v[138:141], v[164:167], v[58:61]
	v_mfma_f32_16x16x32_bf16 v[50:53], v[130:133], v[176:179], v[50:53]
	v_mfma_f32_16x16x32_bf16 v[42:45], v[138:141], v[176:179], v[42:45]
	v_mfma_f32_16x16x32_bf16 v[34:37], v[130:133], v[184:187], v[34:37]
	v_mfma_f32_16x16x32_bf16 v[26:29], v[138:141], v[184:187], v[26:29]
	v_mfma_f32_16x16x32_bf16 v[18:21], v[130:133], v[192:195], v[18:21]
	v_mfma_f32_16x16x32_bf16 v[10:13], v[138:141], v[192:195], v[10:13]
	v_mfma_f32_16x16x32_bf16 v[62:65], v[134:137], v[172:175], v[62:65]
	v_mfma_f32_16x16x32_bf16 v[58:61], v[142:145], v[172:175], v[58:61]
	v_mfma_f32_16x16x32_bf16 v[50:53], v[134:137], v[180:183], v[50:53]
	v_mfma_f32_16x16x32_bf16 v[42:45], v[142:145], v[180:183], v[42:45]
	v_mfma_f32_16x16x32_bf16 v[34:37], v[134:137], v[188:191], v[34:37]
	v_mfma_f32_16x16x32_bf16 v[26:29], v[142:145], v[188:191], v[26:29]
	v_mfma_f32_16x16x32_bf16 v[18:21], v[134:137], v[196:199], v[18:21]
	v_mfma_f32_16x16x32_bf16 v[10:13], v[142:145], v[196:199], v[10:13]
	s_setprio 0
	s_barrier
	s_add_u32 s60, s60, 0x40080
	s_addc_u32 s61, s61, 0
	s_add_i32 s57, s62, s69
	v_lshl_add_u64 v[130:131], s[60:61], 0, v[152:153]
	s_mov_b32 m0, s57
	s_nop 0
	global_load_lds_dwordx4 v[130:131], off
	v_lshl_add_u64 v[130:131], s[60:61], 0, v[156:157]
	s_add_i32 m0, s57, 0x2000
	s_nop 0
	global_load_lds_dwordx4 v[130:131], off
	s_waitcnt vmcnt(6)
	s_barrier
	s_setprio 1
	v_mfma_f32_16x16x32_bf16 v[54:57], v[200:203], v[164:167], v[54:57]
	v_mfma_f32_16x16x32_bf16 v[46:49], v[208:211], v[164:167], v[46:49]
	v_mfma_f32_16x16x32_bf16 v[38:41], v[200:203], v[176:179], v[38:41]
	v_mfma_f32_16x16x32_bf16 v[30:33], v[208:211], v[176:179], v[30:33]
	v_mfma_f32_16x16x32_bf16 v[22:25], v[200:203], v[184:187], v[22:25]
	v_mfma_f32_16x16x32_bf16 v[14:17], v[208:211], v[184:187], v[14:17]
	v_mfma_f32_16x16x32_bf16 v[6:9], v[200:203], v[192:195], v[6:9]
	v_mfma_f32_16x16x32_bf16 v[2:5], v[208:211], v[192:195], v[2:5]
	v_mfma_f32_16x16x32_bf16 v[54:57], v[204:207], v[172:175], v[54:57]
	v_mfma_f32_16x16x32_bf16 v[46:49], v[212:215], v[172:175], v[46:49]
	v_mfma_f32_16x16x32_bf16 v[38:41], v[204:207], v[180:183], v[38:41]
	v_mfma_f32_16x16x32_bf16 v[30:33], v[212:215], v[180:183], v[30:33]
	v_mfma_f32_16x16x32_bf16 v[22:25], v[204:207], v[188:191], v[22:25]
	v_mfma_f32_16x16x32_bf16 v[14:17], v[212:215], v[188:191], v[14:17]
	v_mfma_f32_16x16x32_bf16 v[6:9], v[204:207], v[196:199], v[6:9]
	v_mfma_f32_16x16x32_bf16 v[2:5], v[212:215], v[196:199], v[2:5]
	s_setprio 0
	s_add_i32 s55, s55, 2
	s_add_u32 s58, s58, 0x100
	s_addc_u32 s59, s59, 0
	s_add_u32 s2, s2, 0x100
	s_addc_u32 s3, s3, 0
	s_cmp_gt_u32 s55, 13
	s_barrier
	s_cbranch_scc0 .LBB0_151
	v_mov_b32_e32 v130, v147
	v_mov_b32_e32 v173, v1
	s_ashr_i32 s55, s19, 1
	s_mov_b64 s[62:63], -1
	v_lshlrev_b32_e32 v174, 3, v130
	s_mov_b64 s[60:61], 0
	s_cmp_lt_i32 s55, 4
	s_mov_b64 s[58:59], 0
	s_cbranch_scc1 .LBB0_167
	s_cmp_gt_i32 s55, 5
	s_cbranch_scc0 .LBB0_161
	s_cmp_gt_i32 s55, 6
	s_cbranch_scc0 .LBB0_158
	s_cmp_eq_u32 s55, 7
	s_mov_b64 s[58:59], -1
	s_cbranch_scc0 .LBB0_157
	s_lshl_b32 s2, s18, 8
	s_or_b32 s2, s2, s85
	v_add_u32_e32 v140, s2, v174
	s_lshl_b32 s2, s19, 8
	v_ashrrev_i32_e32 v130, 3, v140
	s_and_b32 s2, s2, 0x100
	v_and_b32_e32 v130, 0xfffffe00, v130
	s_add_i32 s2, s2, s84
	v_add3_u32 v134, s2, v173, v130
	v_ashrrev_i32_e32 v135, 31, v134
	v_lshlrev_b64 v[136:137], 13, v[134:135]
	v_and_b32_e32 v135, 0xff8, v140
	v_lshl_add_u64 v[136:137], s[14:15], 0, v[136:137]
	v_lshlrev_b32_e32 v158, 1, v135
	v_cvt_pk_bf16_f32 v130, v126, v127
	v_cvt_pk_bf16_f32 v131, v128, v129
	v_cvt_pk_bf16_f32 v132, v122, v123
	v_cvt_pk_bf16_f32 v133, v124, v125
	v_lshl_add_u64 v[138:139], v[136:137], 0, v[158:159]
	global_store_dwordx4 v[138:139], v[130:133], off sc1
	v_mov_b32_e32 v139, v159
	s_mov_b64 s[58:59], 0
	v_add_u32_e32 v130, 0x80, v140
	v_and_b32_e32 v135, 0xff8, v130
	v_lshlrev_b32_e32 v138, 1, v135
	v_cvt_pk_bf16_f32 v130, v118, v119
	v_cvt_pk_bf16_f32 v131, v120, v121
	v_cvt_pk_bf16_f32 v132, v110, v111
	v_cvt_pk_bf16_f32 v133, v112, v113
	v_lshl_add_u64 v[136:137], v[136:137], 0, v[138:139]
	global_store_dwordx4 v[136:137], v[130:133], off sc1
	s_nop 1
	v_add_u32_e32 v130, 16, v134
	v_ashrrev_i32_e32 v131, 31, v130
	v_lshlrev_b64 v[136:137], 13, v[130:131]
	v_lshl_add_u64 v[136:137], s[14:15], 0, v[136:137]
	v_cvt_pk_bf16_f32 v130, v114, v115
	v_cvt_pk_bf16_f32 v131, v116, v117
	v_cvt_pk_bf16_f32 v132, v106, v107
	v_cvt_pk_bf16_f32 v133, v108, v109
	v_lshl_add_u64 v[140:141], v[136:137], 0, v[158:159]
	global_store_dwordx4 v[140:141], v[130:133], off sc1
	v_lshl_add_u64 v[136:137], v[136:137], 0, v[138:139]
	s_nop 0
	v_cvt_pk_bf16_f32 v130, v102, v103
	v_cvt_pk_bf16_f32 v131, v104, v105
	v_cvt_pk_bf16_f32 v132, v94, v95
	v_cvt_pk_bf16_f32 v133, v96, v97
	global_store_dwordx4 v[136:137], v[130:133], off sc1
	s_nop 1
	v_add_u32_e32 v130, 32, v134
	v_ashrrev_i32_e32 v131, 31, v130
	v_lshlrev_b64 v[136:137], 13, v[130:131]
	v_lshl_add_u64 v[136:137], s[14:15], 0, v[136:137]
	v_cvt_pk_bf16_f32 v130, v98, v99
	v_cvt_pk_bf16_f32 v131, v100, v101
	v_cvt_pk_bf16_f32 v132, v90, v91
	v_cvt_pk_bf16_f32 v133, v92, v93
	v_lshl_add_u64 v[140:141], v[136:137], 0, v[158:159]
	global_store_dwordx4 v[140:141], v[130:133], off sc1
	v_lshl_add_u64 v[136:137], v[136:137], 0, v[138:139]
	s_nop 0
	v_cvt_pk_bf16_f32 v130, v86, v87
	v_cvt_pk_bf16_f32 v131, v88, v89
	v_cvt_pk_bf16_f32 v132, v78, v79
	v_cvt_pk_bf16_f32 v133, v80, v81
	global_store_dwordx4 v[136:137], v[130:133], off sc1
	s_nop 1
	v_add_u32_e32 v130, 48, v134
	v_ashrrev_i32_e32 v131, 31, v130
	v_lshlrev_b64 v[136:137], 13, v[130:131]
	v_lshl_add_u64 v[136:137], s[14:15], 0, v[136:137]
	v_cvt_pk_bf16_f32 v130, v82, v83
	v_cvt_pk_bf16_f32 v131, v84, v85
	v_cvt_pk_bf16_f32 v132, v74, v75
	v_cvt_pk_bf16_f32 v133, v76, v77
	v_lshl_add_u64 v[140:141], v[136:137], 0, v[158:159]
	global_store_dwordx4 v[140:141], v[130:133], off sc1
	v_lshl_add_u64 v[136:137], v[136:137], 0, v[138:139]
	s_nop 0
	v_cvt_pk_bf16_f32 v130, v70, v71
	v_cvt_pk_bf16_f32 v131, v72, v73
	v_cvt_pk_bf16_f32 v132, v66, v67
	v_cvt_pk_bf16_f32 v133, v68, v69
	global_store_dwordx4 v[136:137], v[130:133], off sc1
	s_nop 1
	v_add_u32_e32 v130, 0x80, v134
	v_ashrrev_i32_e32 v131, 31, v130
	v_lshlrev_b64 v[136:137], 13, v[130:131]
	v_lshl_add_u64 v[136:137], s[14:15], 0, v[136:137]
	v_cvt_pk_bf16_f32 v130, v62, v63
	v_cvt_pk_bf16_f32 v131, v64, v65
	v_cvt_pk_bf16_f32 v132, v58, v59
	v_cvt_pk_bf16_f32 v133, v60, v61
	v_lshl_add_u64 v[140:141], v[136:137], 0, v[158:159]
	global_store_dwordx4 v[140:141], v[130:133], off sc1
	v_lshl_add_u64 v[136:137], v[136:137], 0, v[138:139]
	s_nop 0
	v_cvt_pk_bf16_f32 v130, v54, v55
	v_cvt_pk_bf16_f32 v131, v56, v57
	v_cvt_pk_bf16_f32 v132, v46, v47
	v_cvt_pk_bf16_f32 v133, v48, v49
	global_store_dwordx4 v[136:137], v[130:133], off sc1
	s_nop 1
	v_add_u32_e32 v130, 0x90, v134
	v_ashrrev_i32_e32 v131, 31, v130
	v_lshlrev_b64 v[136:137], 13, v[130:131]
	v_lshl_add_u64 v[136:137], s[14:15], 0, v[136:137]
	v_cvt_pk_bf16_f32 v130, v50, v51
	v_cvt_pk_bf16_f32 v131, v52, v53
	v_cvt_pk_bf16_f32 v132, v42, v43
	v_cvt_pk_bf16_f32 v133, v44, v45
	v_lshl_add_u64 v[140:141], v[136:137], 0, v[158:159]
	global_store_dwordx4 v[140:141], v[130:133], off sc1
	v_lshl_add_u64 v[136:137], v[136:137], 0, v[138:139]
	s_nop 0
	v_cvt_pk_bf16_f32 v130, v38, v39
	v_cvt_pk_bf16_f32 v131, v40, v41
	v_cvt_pk_bf16_f32 v132, v30, v31
	v_cvt_pk_bf16_f32 v133, v32, v33
	global_store_dwordx4 v[136:137], v[130:133], off sc1
	s_nop 1
	v_add_u32_e32 v130, 0xa0, v134
	v_ashrrev_i32_e32 v131, 31, v130
	v_lshlrev_b64 v[136:137], 13, v[130:131]
	v_lshl_add_u64 v[136:137], s[14:15], 0, v[136:137]
	v_cvt_pk_bf16_f32 v130, v34, v35
	v_cvt_pk_bf16_f32 v131, v36, v37
	v_cvt_pk_bf16_f32 v132, v26, v27
	v_cvt_pk_bf16_f32 v133, v28, v29
	v_lshl_add_u64 v[140:141], v[136:137], 0, v[158:159]
	global_store_dwordx4 v[140:141], v[130:133], off sc1
	v_lshl_add_u64 v[136:137], v[136:137], 0, v[138:139]
	s_nop 0
	v_cvt_pk_bf16_f32 v130, v22, v23
	v_cvt_pk_bf16_f32 v131, v24, v25
	v_cvt_pk_bf16_f32 v132, v14, v15
	v_cvt_pk_bf16_f32 v133, v16, v17
	global_store_dwordx4 v[136:137], v[130:133], off sc1
	s_nop 1
	v_add_u32_e32 v130, 0xb0, v134
	v_ashrrev_i32_e32 v131, 31, v130
	v_lshlrev_b64 v[134:135], 13, v[130:131]
	v_lshl_add_u64 v[134:135], s[14:15], 0, v[134:135]
	v_cvt_pk_bf16_f32 v130, v18, v19
	v_cvt_pk_bf16_f32 v131, v20, v21
	v_cvt_pk_bf16_f32 v132, v10, v11
	v_cvt_pk_bf16_f32 v133, v12, v13
	v_lshl_add_u64 v[136:137], v[134:135], 0, v[158:159]
	global_store_dwordx4 v[136:137], v[130:133], off sc1
	v_lshl_add_u64 v[134:135], v[134:135], 0, v[138:139]
	s_nop 0
	v_cvt_pk_bf16_f32 v130, v6, v7
	v_cvt_pk_bf16_f32 v131, v8, v9
	v_cvt_pk_bf16_f32 v132, v2, v3
	v_cvt_pk_bf16_f32 v133, v4, v5
	global_store_dwordx4 v[134:135], v[130:133], off sc1

.LBB0_158:
	s_and_b64 vcc, exec, s[62:63]
	s_cbranch_vccz .LBB0_160
	s_lshl_b32 s2, s19, 8
	s_and_b32 s2, s2, 0x100
	s_or_b32 s2, s2, s85
	v_add_u32_e32 v164, s2, v174
	v_ashrrev_i32_e32 v165, 31, v164
	v_lshl_add_u64 v[138:139], v[164:165], 2, s[88:89]
	global_load_dwordx4 v[130:133], v[138:139], off offset:512
	global_load_dwordx4 v[142:145], v[138:139], off
	global_load_dwordx4 v[134:137], v[138:139], off offset:16
	v_mul_f32_e32 v140, 0xbfb8aa3b, v126
	v_mul_f32_e32 v141, 0xbfb8aa3b, v127
	v_exp_f32_e32 v179, v140
	v_exp_f32_e32 v180, v141
	global_load_dwordx4 v[138:141], v[138:139], off offset:528
	v_mul_f32_e32 v158, 0xbfb8aa3b, v128
	v_mul_f32_e32 v166, 0xbfb8aa3b, v129
	v_mul_f32_e32 v167, 0xbfb8aa3b, v122
	v_mul_f32_e32 v168, 0xbfb8aa3b, v123
	v_exp_f32_e32 v158, v158
	v_exp_f32_e32 v181, v166
	v_exp_f32_e32 v182, v167
	v_exp_f32_e32 v168, v168
	s_lshl_b32 s2, s18, 8
	v_mul_f32_e32 v172, 0xbfb8aa3b, v124
	v_mul_f32_e32 v175, 0xbfb8aa3b, v125
	v_mul_f32_e32 v176, 0xbfb8aa3b, v118
	v_mul_f32_e32 v177, 0xbfb8aa3b, v119
	v_mul_f32_e32 v178, 0xbfb8aa3b, v120
	s_add_i32 s2, s2, s84
	v_exp_f32_e32 v172, v172
	v_exp_f32_e32 v175, v175
	v_exp_f32_e32 v176, v176
	v_exp_f32_e32 v177, v177
	v_exp_f32_e32 v190, v178
	v_add_u32_e32 v166, s2, v173
	v_add_f32_e32 v178, 1.0, v179
	v_add_f32_e32 v179, 1.0, v180
	v_add_f32_e32 v158, 1.0, v158
	v_add_f32_e32 v180, 1.0, v181
	v_add_f32_e32 v181, 1.0, v182
	v_add_f32_e32 v168, 1.0, v168
	v_ashrrev_i32_e32 v167, 31, v166
	v_rcp_f32_e32 v186, v178
	v_rcp_f32_e32 v187, v179
	v_rcp_f32_e32 v188, v158
	v_rcp_f32_e32 v189, v180
	v_rcp_f32_e32 v191, v181
	v_rcp_f32_e32 v168, v168
	v_lshlrev_b64 v[166:167], 10, v[166:167]
	v_add_f32_e32 v172, 1.0, v172
	v_add_f32_e32 v175, 1.0, v175
	v_lshl_add_u64 v[166:167], s[20:21], 0, v[166:167]
	v_add_f32_e32 v176, 1.0, v176
	v_add_f32_e32 v177, 1.0, v177
	v_rcp_f32_e32 v172, v172
	v_rcp_f32_e32 v175, v175
	v_lshl_add_u64 v[164:165], v[164:165], 1, v[166:167]
	v_rcp_f32_e32 v167, v176
	v_rcp_f32_e32 v176, v177
	s_waitcnt vmcnt(0)
	v_sub_f32_e32 v158, 1.0, v130
	v_sub_f32_e32 v185, 1.0, v142
	v_sub_f32_e32 v184, 1.0, v143
	v_sub_f32_e32 v183, 1.0, v144
	v_sub_f32_e32 v182, 1.0, v145
	v_sub_f32_e32 v181, 1.0, v134
	v_sub_f32_e32 v180, 1.0, v135
	v_fma_f32 v177, v186, v185, v142
	v_fma_f32 v186, v187, v184, v143
	v_fma_f32 v187, v188, v183, v144
	v_fma_f32 v188, v189, v182, v145
	v_fma_f32 v189, v191, v181, v134
	v_fma_f32 v168, v168, v180, v135
	v_log_f32_e32 v187, v187
	v_log_f32_e32 v188, v188
	v_log_f32_e32 v189, v189
	v_log_f32_e32 v168, v168
	v_sub_f32_e32 v179, 1.0, v136
	v_sub_f32_e32 v178, 1.0, v137
	v_fma_f32 v172, v172, v179, v136
	v_fma_f32 v175, v175, v178, v137
	v_fma_f32 v167, v167, v158, v130
	v_log_f32_e32 v172, v172
	v_log_f32_e32 v175, v175
	v_log_f32_e32 v191, v167
	v_mul_f32_e32 v167, 0xbfb8aa3b, v121
	v_cvt_pk_bf16_f32 v187, v187, v188
	v_cvt_pk_bf16_f32 v188, v189, v168
	v_exp_f32_e32 v168, v167
	v_add_f32_e32 v167, 1.0, v190
	v_log_f32_e32 v177, v177
	v_log_f32_e32 v186, v186
	v_cvt_pk_bf16_f32 v189, v172, v175
	v_rcp_f32_e32 v172, v167
	v_add_f32_e32 v168, 1.0, v168
	v_rcp_f32_e32 v168, v168
	v_sub_f32_e32 v167, 1.0, v132
	v_cvt_pk_bf16_f32 v186, v177, v186
	v_fma_f32 v172, v172, v167, v132
	global_store_dwordx4 v[164:165], v[186:189], off sc1
	v_mul_f32_e32 v175, 0xbfb8aa3b, v110
	v_exp_f32_e32 v175, v175
	v_log_f32_e32 v187, v172
	v_sub_f32_e32 v172, 1.0, v133
	v_fma_f32 v168, v168, v172, v133
	v_log_f32_e32 v188, v168
	v_mul_f32_e32 v168, 0xbfb8aa3b, v111
	v_exp_f32_e32 v168, v168
	v_sub_f32_e32 v166, 1.0, v131
	v_fma_f32 v176, v176, v166, v131
	v_add_f32_e32 v175, 1.0, v175
	v_log_f32_e32 v192, v176
	v_rcp_f32_e32 v176, v175
	v_add_f32_e32 v168, 1.0, v168
	v_rcp_f32_e32 v177, v168
	v_sub_f32_e32 v175, 1.0, v138
	v_fma_f32 v168, v176, v175, v138
	v_log_f32_e32 v189, v168
	v_sub_f32_e32 v168, 1.0, v139
	v_fma_f32 v176, v177, v168, v139
	v_mul_f32_e32 v177, 0xbfb8aa3b, v112
	v_exp_f32_e32 v177, v177
	v_log_f32_e32 v190, v176
	v_mul_f32_e32 v176, 0xbfb8aa3b, v113
	v_exp_f32_e32 v186, v176
	v_add_f32_e32 v176, 1.0, v177
	v_rcp_f32_e32 v177, v176
	v_sub_f32_e32 v176, 1.0, v140
	v_add_f32_e32 v186, 1.0, v186
	v_rcp_f32_e32 v186, v186
	v_fma_f32 v177, v177, v176, v140
	v_log_f32_e32 v193, v177
	v_sub_f32_e32 v177, 1.0, v141
	v_cvt_pk_bf16_f32 v187, v187, v188
	v_cvt_pk_bf16_f32 v188, v189, v190
	v_mul_f32_e32 v189, 0xbfb8aa3b, v114
	v_fma_f32 v186, v186, v177, v141
	v_exp_f32_e32 v190, v189
	v_mul_f32_e32 v189, 0xbfb8aa3b, v115
	v_log_f32_e32 v194, v186
	v_cvt_pk_bf16_f32 v186, v191, v192
	v_exp_f32_e32 v191, v189
	v_add_f32_e32 v190, 1.0, v190
	v_cvt_pk_bf16_f32 v189, v193, v194
	v_rcp_f32_e32 v190, v190
	v_add_f32_e32 v191, 1.0, v191
	v_rcp_f32_e32 v191, v191
	global_store_dwordx4 v[164:165], v[186:189], off offset:256 sc1
	v_mul_f32_e32 v192, 0xbfb8aa3b, v108
	v_mul_f32_e32 v193, 0xbfb8aa3b, v109
	v_mul_f32_e32 v188, 0xbfb8aa3b, v116
	v_mul_f32_e32 v189, 0xbfb8aa3b, v117
	v_exp_f32_e32 v188, v188
	v_exp_f32_e32 v189, v189
	v_exp_f32_e32 v192, v192
	v_exp_f32_e32 v193, v193
	v_fma_f32 v186, v190, v185, v142
	v_fma_f32 v187, v191, v184, v143
	v_mul_f32_e32 v190, 0xbfb8aa3b, v106
	v_mul_f32_e32 v191, 0xbfb8aa3b, v107
	v_exp_f32_e32 v190, v190
	v_exp_f32_e32 v191, v191
	v_add_f32_e32 v188, 1.0, v188
	v_add_f32_e32 v189, 1.0, v189
	v_add_f32_e32 v192, 1.0, v192
	v_add_f32_e32 v193, 1.0, v193
	v_rcp_f32_e32 v188, v188
	v_rcp_f32_e32 v189, v189
	v_rcp_f32_e32 v192, v192
	v_rcp_f32_e32 v193, v193
	v_add_f32_e32 v190, 1.0, v190
	v_add_f32_e32 v191, 1.0, v191
	v_rcp_f32_e32 v190, v190
	v_rcp_f32_e32 v191, v191
	v_fma_f32 v188, v188, v183, v144
	v_fma_f32 v189, v189, v182, v145
	v_fma_f32 v192, v192, v179, v136
	v_fma_f32 v193, v193, v178, v137
	v_log_f32_e32 v186, v186
	v_log_f32_e32 v187, v187
	v_log_f32_e32 v188, v188
	v_log_f32_e32 v189, v189
	v_log_f32_e32 v192, v192
	v_log_f32_e32 v193, v193
	v_fma_f32 v190, v190, v181, v134
	v_fma_f32 v191, v191, v180, v135
	v_log_f32_e32 v190, v190
	v_log_f32_e32 v191, v191
	v_cvt_pk_bf16_f32 v186, v186, v187
	v_cvt_pk_bf16_f32 v187, v188, v189
	v_cvt_pk_bf16_f32 v189, v192, v193
	v_mul_f32_e32 v192, 0xbfb8aa3b, v102
	v_exp_f32_e32 v194, v192
	v_mul_f32_e32 v192, 0xbfb8aa3b, v103
	v_exp_f32_e32 v195, v192
	v_add_co_u32_e32 v192, vcc, s75, v164
	v_cvt_pk_bf16_f32 v188, v190, v191
	s_nop 0
	v_addc_co_u32_e32 v193, vcc, 0, v165, vcc
	global_store_dwordx4 v[192:193], v[186:189], off sc1
	v_mul_f32_e32 v192, 0xbfb8aa3b, v94
	v_mul_f32_e32 v193, 0xbfb8aa3b, v95
	v_mul_f32_e32 v188, 0xbfb8aa3b, v104
	v_mul_f32_e32 v189, 0xbfb8aa3b, v105
	v_exp_f32_e32 v188, v188
	v_exp_f32_e32 v189, v189
	v_exp_f32_e32 v192, v192
	v_exp_f32_e32 v193, v193
	v_add_f32_e32 v194, 1.0, v194
	v_add_f32_e32 v195, 1.0, v195
	v_add_f32_e32 v188, 1.0, v188
	v_add_f32_e32 v189, 1.0, v189
	v_rcp_f32_e32 v194, v194
	v_rcp_f32_e32 v195, v195
	v_rcp_f32_e32 v188, v188
	v_rcp_f32_e32 v189, v189
	v_add_f32_e32 v192, 1.0, v192
	v_add_f32_e32 v193, 1.0, v193
	v_rcp_f32_e32 v192, v192
	v_rcp_f32_e32 v193, v193
	v_fma_f32 v186, v194, v158, v130
	v_fma_f32 v187, v195, v166, v131
	v_fma_f32 v188, v188, v167, v132
	v_fma_f32 v189, v189, v172, v133
	v_mul_f32_e32 v194, 0xbfb8aa3b, v96
	v_mul_f32_e32 v195, 0xbfb8aa3b, v97
	v_log_f32_e32 v186, v186
	v_log_f32_e32 v187, v187
	v_log_f32_e32 v188, v188
	v_log_f32_e32 v189, v189
	v_fma_f32 v192, v192, v175, v138
	v_exp_f32_e32 v194, v194
	v_exp_f32_e32 v195, v195
	v_fma_f32 v193, v193, v168, v139
	v_log_f32_e32 v192, v192
	v_log_f32_e32 v193, v193
	v_add_f32_e32 v194, 1.0, v194
	v_add_f32_e32 v195, 1.0, v195
	v_cvt_pk_bf16_f32 v186, v186, v187
	v_cvt_pk_bf16_f32 v187, v188, v189
	v_mul_f32_e32 v189, 0xbfb8aa3b, v98
	v_rcp_f32_e32 v194, v194
	v_rcp_f32_e32 v195, v195
	v_cvt_pk_bf16_f32 v188, v192, v193
	v_exp_f32_e32 v192, v189
	v_mul_f32_e32 v189, 0xbfb8aa3b, v99
	v_exp_f32_e32 v193, v189
	v_fma_f32 v194, v194, v176, v140
	v_fma_f32 v195, v195, v177, v141
	v_log_f32_e32 v194, v194
	v_log_f32_e32 v195, v195
	v_add_f32_e32 v192, 1.0, v192
	v_add_f32_e32 v193, 1.0, v193
	v_rcp_f32_e32 v192, v192
	v_rcp_f32_e32 v193, v193
	v_lshl_add_u64 v[190:191], v[164:165], 0, s[38:39]
	v_cvt_pk_bf16_f32 v189, v194, v195
	global_store_dwordx4 v[190:191], v[186:189], off offset:256 sc1
	v_mul_f32_e32 v190, 0xbfb8aa3b, v90
	v_mul_f32_e32 v191, 0xbfb8aa3b, v91
	v_fma_f32 v186, v192, v185, v142
	v_fma_f32 v187, v193, v184, v143
	v_mul_f32_e32 v188, 0xbfb8aa3b, v100
	v_mul_f32_e32 v189, 0xbfb8aa3b, v101
	v_mul_f32_e32 v192, 0xbfb8aa3b, v92
	v_mul_f32_e32 v193, 0xbfb8aa3b, v93
	v_exp_f32_e32 v188, v188
	v_exp_f32_e32 v189, v189
	v_exp_f32_e32 v192, v192
	v_exp_f32_e32 v193, v193
	v_exp_f32_e32 v190, v190
	v_exp_f32_e32 v191, v191
	v_add_f32_e32 v188, 1.0, v188
	v_add_f32_e32 v189, 1.0, v189
	v_add_f32_e32 v192, 1.0, v192
	v_add_f32_e32 v193, 1.0, v193
	v_rcp_f32_e32 v188, v188
	v_rcp_f32_e32 v189, v189
	v_rcp_f32_e32 v192, v192
	v_rcp_f32_e32 v193, v193
	v_add_f32_e32 v190, 1.0, v190
	v_add_f32_e32 v191, 1.0, v191
	v_rcp_f32_e32 v190, v190
	v_rcp_f32_e32 v191, v191
	v_fma_f32 v188, v188, v183, v144
	v_fma_f32 v189, v189, v182, v145
	v_fma_f32 v192, v192, v179, v136
	v_fma_f32 v193, v193, v178, v137
	v_log_f32_e32 v186, v186
	v_log_f32_e32 v187, v187
	v_log_f32_e32 v188, v188
	v_log_f32_e32 v189, v189
	v_log_f32_e32 v192, v192
	v_log_f32_e32 v193, v193
	v_fma_f32 v190, v190, v181, v134
	v_fma_f32 v191, v191, v180, v135
	v_log_f32_e32 v190, v190
	v_log_f32_e32 v191, v191
	v_cvt_pk_bf16_f32 v186, v186, v187
	v_cvt_pk_bf16_f32 v187, v188, v189
	v_cvt_pk_bf16_f32 v189, v192, v193
	v_mul_f32_e32 v192, 0xbfb8aa3b, v86
	v_exp_f32_e32 v194, v192
	v_mul_f32_e32 v192, 0xbfb8aa3b, v87
	v_exp_f32_e32 v195, v192
	v_add_co_u32_e32 v192, vcc, s92, v164
	v_cvt_pk_bf16_f32 v188, v190, v191
	s_nop 0
	v_addc_co_u32_e32 v193, vcc, 0, v165, vcc
	global_store_dwordx4 v[192:193], v[186:189], off sc1
	v_mul_f32_e32 v192, 0xbfb8aa3b, v78
	v_mul_f32_e32 v193, 0xbfb8aa3b, v79
	v_mul_f32_e32 v188, 0xbfb8aa3b, v88
	v_mul_f32_e32 v189, 0xbfb8aa3b, v89
	v_exp_f32_e32 v188, v188
	v_exp_f32_e32 v189, v189
	v_exp_f32_e32 v192, v192
	v_exp_f32_e32 v193, v193
	v_add_f32_e32 v194, 1.0, v194
	v_add_f32_e32 v195, 1.0, v195
	v_add_f32_e32 v188, 1.0, v188
	v_add_f32_e32 v189, 1.0, v189
	v_rcp_f32_e32 v194, v194
	v_rcp_f32_e32 v195, v195
	v_rcp_f32_e32 v188, v188
	v_rcp_f32_e32 v189, v189
	v_add_f32_e32 v192, 1.0, v192
	v_add_f32_e32 v193, 1.0, v193
	v_rcp_f32_e32 v192, v192
	v_rcp_f32_e32 v193, v193
	v_fma_f32 v186, v194, v158, v130
	v_fma_f32 v187, v195, v166, v131
	v_fma_f32 v188, v188, v167, v132
	v_fma_f32 v189, v189, v172, v133
	v_mul_f32_e32 v194, 0xbfb8aa3b, v80
	v_mul_f32_e32 v195, 0xbfb8aa3b, v81
	v_log_f32_e32 v186, v186
	v_log_f32_e32 v187, v187
	v_log_f32_e32 v188, v188
	v_log_f32_e32 v189, v189
	v_fma_f32 v192, v192, v175, v138
	v_exp_f32_e32 v194, v194
	v_exp_f32_e32 v195, v195
	v_fma_f32 v193, v193, v168, v139
	v_log_f32_e32 v192, v192
	v_log_f32_e32 v193, v193
	v_add_f32_e32 v194, 1.0, v194
	v_add_f32_e32 v195, 1.0, v195
	v_cvt_pk_bf16_f32 v186, v186, v187
	v_cvt_pk_bf16_f32 v187, v188, v189
	v_mul_f32_e32 v189, 0xbfb8aa3b, v82
	v_rcp_f32_e32 v194, v194
	v_rcp_f32_e32 v195, v195
	v_cvt_pk_bf16_f32 v188, v192, v193
	v_exp_f32_e32 v192, v189
	v_mul_f32_e32 v189, 0xbfb8aa3b, v83
	v_exp_f32_e32 v193, v189
	v_fma_f32 v194, v194, v176, v140
	v_fma_f32 v195, v195, v177, v141
	v_log_f32_e32 v194, v194
	v_log_f32_e32 v195, v195
	v_add_f32_e32 v192, 1.0, v192
	v_add_f32_e32 v193, 1.0, v193
	v_rcp_f32_e32 v192, v192
	v_rcp_f32_e32 v193, v193
	v_lshl_add_u64 v[190:191], v[164:165], 0, s[40:41]
	v_cvt_pk_bf16_f32 v189, v194, v195
	global_store_dwordx4 v[190:191], v[186:189], off offset:256 sc1
	v_mul_f32_e32 v190, 0xbfb8aa3b, v74
	v_mul_f32_e32 v191, 0xbfb8aa3b, v75
	v_fma_f32 v186, v192, v185, v142
	v_fma_f32 v187, v193, v184, v143
	v_mul_f32_e32 v188, 0xbfb8aa3b, v84
	v_mul_f32_e32 v189, 0xbfb8aa3b, v85
	v_mul_f32_e32 v192, 0xbfb8aa3b, v76
	v_mul_f32_e32 v193, 0xbfb8aa3b, v77
	v_exp_f32_e32 v188, v188
	v_exp_f32_e32 v189, v189
	v_exp_f32_e32 v192, v192
	v_exp_f32_e32 v193, v193
	v_exp_f32_e32 v190, v190
	v_exp_f32_e32 v191, v191
	v_add_f32_e32 v188, 1.0, v188
	v_add_f32_e32 v189, 1.0, v189
	v_add_f32_e32 v192, 1.0, v192
	v_add_f32_e32 v193, 1.0, v193
	v_rcp_f32_e32 v188, v188
	v_rcp_f32_e32 v189, v189
	v_rcp_f32_e32 v192, v192
	v_rcp_f32_e32 v193, v193
	v_add_f32_e32 v190, 1.0, v190
	v_add_f32_e32 v191, 1.0, v191
	v_rcp_f32_e32 v190, v190
	v_rcp_f32_e32 v191, v191
	v_fma_f32 v188, v188, v183, v144
	v_fma_f32 v189, v189, v182, v145
	v_fma_f32 v192, v192, v179, v136
	v_fma_f32 v193, v193, v178, v137
	v_log_f32_e32 v186, v186
	v_log_f32_e32 v187, v187
	v_log_f32_e32 v188, v188
	v_log_f32_e32 v189, v189
	v_log_f32_e32 v192, v192
	v_log_f32_e32 v193, v193
	v_fma_f32 v190, v190, v181, v134
	v_fma_f32 v191, v191, v180, v135
	v_log_f32_e32 v190, v190
	v_log_f32_e32 v191, v191
	v_cvt_pk_bf16_f32 v186, v186, v187
	v_cvt_pk_bf16_f32 v187, v188, v189
	v_cvt_pk_bf16_f32 v189, v192, v193
	v_mul_f32_e32 v192, 0xbfb8aa3b, v70
	v_exp_f32_e32 v194, v192
	v_mul_f32_e32 v192, 0xbfb8aa3b, v71
	v_exp_f32_e32 v195, v192
	v_add_co_u32_e32 v192, vcc, s97, v164
	v_cvt_pk_bf16_f32 v188, v190, v191
	s_nop 0
	v_addc_co_u32_e32 v193, vcc, 0, v165, vcc
	global_store_dwordx4 v[192:193], v[186:189], off sc1
	v_mul_f32_e32 v192, 0xbfb8aa3b, v66
	v_mul_f32_e32 v193, 0xbfb8aa3b, v67
	v_mul_f32_e32 v188, 0xbfb8aa3b, v72
	v_mul_f32_e32 v189, 0xbfb8aa3b, v73
	v_exp_f32_e32 v188, v188
	v_exp_f32_e32 v189, v189
	v_exp_f32_e32 v192, v192
	v_exp_f32_e32 v193, v193
	v_add_f32_e32 v194, 1.0, v194
	v_add_f32_e32 v195, 1.0, v195
	v_add_f32_e32 v188, 1.0, v188
	v_add_f32_e32 v189, 1.0, v189
	v_rcp_f32_e32 v194, v194
	v_rcp_f32_e32 v195, v195
	v_rcp_f32_e32 v188, v188
	v_rcp_f32_e32 v189, v189
	v_add_f32_e32 v192, 1.0, v192
	v_add_f32_e32 v193, 1.0, v193
	v_rcp_f32_e32 v192, v192
	v_rcp_f32_e32 v193, v193
	v_fma_f32 v186, v194, v158, v130
	v_fma_f32 v187, v195, v166, v131
	v_fma_f32 v188, v188, v167, v132
	v_fma_f32 v189, v189, v172, v133
	v_mul_f32_e32 v194, 0xbfb8aa3b, v68
	v_mul_f32_e32 v195, 0xbfb8aa3b, v69
	v_log_f32_e32 v186, v186
	v_log_f32_e32 v187, v187
	v_log_f32_e32 v188, v188
	v_log_f32_e32 v189, v189
	v_fma_f32 v192, v192, v175, v138
	v_exp_f32_e32 v194, v194
	v_exp_f32_e32 v195, v195
	v_fma_f32 v193, v193, v168, v139
	v_log_f32_e32 v192, v192
	v_log_f32_e32 v193, v193
	v_add_f32_e32 v194, 1.0, v194
	v_add_f32_e32 v195, 1.0, v195
	v_cvt_pk_bf16_f32 v186, v186, v187
	v_cvt_pk_bf16_f32 v187, v188, v189
	v_mul_f32_e32 v189, 0xbfb8aa3b, v62
	v_rcp_f32_e32 v194, v194
	v_rcp_f32_e32 v195, v195
	v_cvt_pk_bf16_f32 v188, v192, v193
	v_exp_f32_e32 v192, v189
	v_mul_f32_e32 v189, 0xbfb8aa3b, v63
	v_exp_f32_e32 v193, v189
	v_fma_f32 v194, v194, v176, v140
	v_fma_f32 v195, v195, v177, v141
	v_log_f32_e32 v194, v194
	v_log_f32_e32 v195, v195
	v_add_f32_e32 v192, 1.0, v192
	v_add_f32_e32 v193, 1.0, v193
	v_rcp_f32_e32 v192, v192
	v_rcp_f32_e32 v193, v193
	v_lshl_add_u64 v[190:191], v[164:165], 0, s[42:43]
	v_cvt_pk_bf16_f32 v189, v194, v195
	global_store_dwordx4 v[190:191], v[186:189], off offset:256 sc1
	v_mul_f32_e32 v190, 0xbfb8aa3b, v58
	v_mul_f32_e32 v191, 0xbfb8aa3b, v59
	v_fma_f32 v186, v192, v185, v142
	v_fma_f32 v187, v193, v184, v143
	v_mul_f32_e32 v188, 0xbfb8aa3b, v64
	v_mul_f32_e32 v189, 0xbfb8aa3b, v65
	v_mul_f32_e32 v192, 0xbfb8aa3b, v60
	v_mul_f32_e32 v193, 0xbfb8aa3b, v61
	v_exp_f32_e32 v188, v188
	v_exp_f32_e32 v189, v189
	v_exp_f32_e32 v192, v192
	v_exp_f32_e32 v193, v193
	v_exp_f32_e32 v190, v190
	v_exp_f32_e32 v191, v191
	v_add_f32_e32 v188, 1.0, v188
	v_add_f32_e32 v189, 1.0, v189
	v_add_f32_e32 v192, 1.0, v192
	v_add_f32_e32 v193, 1.0, v193
	v_rcp_f32_e32 v188, v188
	v_rcp_f32_e32 v189, v189
	v_rcp_f32_e32 v192, v192
	v_rcp_f32_e32 v193, v193
	v_add_f32_e32 v190, 1.0, v190
	v_add_f32_e32 v191, 1.0, v191
	v_rcp_f32_e32 v190, v190
	v_rcp_f32_e32 v191, v191
	v_fma_f32 v188, v188, v183, v144
	v_fma_f32 v189, v189, v182, v145
	v_fma_f32 v192, v192, v179, v136
	v_fma_f32 v193, v193, v178, v137
	v_log_f32_e32 v186, v186
	v_log_f32_e32 v187, v187
	v_log_f32_e32 v188, v188
	v_log_f32_e32 v189, v189
	v_log_f32_e32 v192, v192
	v_log_f32_e32 v193, v193
	v_fma_f32 v190, v190, v181, v134
	v_fma_f32 v191, v191, v180, v135
	v_log_f32_e32 v190, v190
	v_log_f32_e32 v191, v191
	v_cvt_pk_bf16_f32 v186, v186, v187
	v_cvt_pk_bf16_f32 v187, v188, v189
	v_cvt_pk_bf16_f32 v189, v192, v193
	v_mul_f32_e32 v192, 0xbfb8aa3b, v54
	v_exp_f32_e32 v194, v192
	v_mul_f32_e32 v192, 0xbfb8aa3b, v55
	v_exp_f32_e32 v195, v192
	v_add_co_u32_e32 v192, vcc, s66, v164
	v_cvt_pk_bf16_f32 v188, v190, v191
	s_nop 0
	v_addc_co_u32_e32 v193, vcc, 0, v165, vcc
	global_store_dwordx4 v[192:193], v[186:189], off sc1
	v_mul_f32_e32 v192, 0xbfb8aa3b, v46
	v_mul_f32_e32 v193, 0xbfb8aa3b, v47
	v_mul_f32_e32 v188, 0xbfb8aa3b, v56
	v_mul_f32_e32 v189, 0xbfb8aa3b, v57
	v_exp_f32_e32 v188, v188
	v_exp_f32_e32 v189, v189
	v_exp_f32_e32 v192, v192
	v_exp_f32_e32 v193, v193
	v_add_f32_e32 v194, 1.0, v194
	v_add_f32_e32 v195, 1.0, v195
	v_add_f32_e32 v188, 1.0, v188
	v_add_f32_e32 v189, 1.0, v189
	v_rcp_f32_e32 v194, v194
	v_rcp_f32_e32 v195, v195
	v_rcp_f32_e32 v188, v188
	v_rcp_f32_e32 v189, v189
	v_add_f32_e32 v192, 1.0, v192
	v_add_f32_e32 v193, 1.0, v193
	v_rcp_f32_e32 v192, v192
	v_rcp_f32_e32 v193, v193
	v_fma_f32 v186, v194, v158, v130
	v_fma_f32 v187, v195, v166, v131
	v_fma_f32 v188, v188, v167, v132
	v_fma_f32 v189, v189, v172, v133
	v_mul_f32_e32 v194, 0xbfb8aa3b, v48
	v_mul_f32_e32 v195, 0xbfb8aa3b, v49
	v_log_f32_e32 v186, v186
	v_log_f32_e32 v187, v187
	v_log_f32_e32 v188, v188
	v_log_f32_e32 v189, v189
	v_fma_f32 v192, v192, v175, v138
	v_exp_f32_e32 v194, v194
	v_exp_f32_e32 v195, v195
	v_fma_f32 v193, v193, v168, v139
	v_log_f32_e32 v192, v192
	v_log_f32_e32 v193, v193
	v_add_f32_e32 v194, 1.0, v194
	v_add_f32_e32 v195, 1.0, v195
	v_cvt_pk_bf16_f32 v186, v186, v187
	v_cvt_pk_bf16_f32 v187, v188, v189
	v_mul_f32_e32 v189, 0xbfb8aa3b, v50
	v_rcp_f32_e32 v194, v194
	v_rcp_f32_e32 v195, v195
	v_cvt_pk_bf16_f32 v188, v192, v193
	v_exp_f32_e32 v192, v189
	v_mul_f32_e32 v189, 0xbfb8aa3b, v51
	v_exp_f32_e32 v193, v189
	v_fma_f32 v194, v194, v176, v140
	v_fma_f32 v195, v195, v177, v141
	v_log_f32_e32 v194, v194
	v_log_f32_e32 v195, v195
	v_add_f32_e32 v192, 1.0, v192
	v_add_f32_e32 v193, 1.0, v193
	v_rcp_f32_e32 v192, v192
	v_rcp_f32_e32 v193, v193
	v_lshl_add_u64 v[190:191], v[164:165], 0, s[44:45]
	v_cvt_pk_bf16_f32 v189, v194, v195
	global_store_dwordx4 v[190:191], v[186:189], off offset:256 sc1
	v_mul_f32_e32 v190, 0xbfb8aa3b, v42
	v_mul_f32_e32 v191, 0xbfb8aa3b, v43
	v_fma_f32 v186, v192, v185, v142
	v_fma_f32 v187, v193, v184, v143
	v_mul_f32_e32 v188, 0xbfb8aa3b, v52
	v_mul_f32_e32 v189, 0xbfb8aa3b, v53
	v_mul_f32_e32 v192, 0xbfb8aa3b, v44
	v_mul_f32_e32 v193, 0xbfb8aa3b, v45
	v_exp_f32_e32 v188, v188
	v_exp_f32_e32 v189, v189
	v_exp_f32_e32 v192, v192
	v_exp_f32_e32 v193, v193
	v_exp_f32_e32 v190, v190
	v_exp_f32_e32 v191, v191
	v_add_f32_e32 v188, 1.0, v188
	v_add_f32_e32 v189, 1.0, v189
	v_add_f32_e32 v192, 1.0, v192
	v_add_f32_e32 v193, 1.0, v193
	v_rcp_f32_e32 v188, v188
	v_rcp_f32_e32 v189, v189
	v_rcp_f32_e32 v192, v192
	v_rcp_f32_e32 v193, v193
	v_add_f32_e32 v190, 1.0, v190
	v_add_f32_e32 v191, 1.0, v191
	v_rcp_f32_e32 v190, v190
	v_rcp_f32_e32 v191, v191
	v_fma_f32 v188, v188, v183, v144
	v_fma_f32 v189, v189, v182, v145
	v_fma_f32 v192, v192, v179, v136
	v_fma_f32 v193, v193, v178, v137
	v_log_f32_e32 v186, v186
	v_log_f32_e32 v187, v187
	v_log_f32_e32 v188, v188
	v_log_f32_e32 v189, v189
	v_log_f32_e32 v192, v192
	v_log_f32_e32 v193, v193
	v_fma_f32 v190, v190, v181, v134
	v_fma_f32 v191, v191, v180, v135
	v_log_f32_e32 v190, v190
	v_log_f32_e32 v191, v191
	v_cvt_pk_bf16_f32 v186, v186, v187
	v_cvt_pk_bf16_f32 v187, v188, v189
	v_cvt_pk_bf16_f32 v189, v192, v193
	v_mul_f32_e32 v192, 0xbfb8aa3b, v38
	v_exp_f32_e32 v194, v192
	v_mul_f32_e32 v192, 0xbfb8aa3b, v39
	v_exp_f32_e32 v195, v192
	v_add_co_u32_e32 v192, vcc, s53, v164
	v_cvt_pk_bf16_f32 v188, v190, v191
	s_nop 0
	v_addc_co_u32_e32 v193, vcc, 0, v165, vcc
	global_store_dwordx4 v[192:193], v[186:189], off sc1
	v_mul_f32_e32 v192, 0xbfb8aa3b, v30
	v_mul_f32_e32 v193, 0xbfb8aa3b, v31
	v_mul_f32_e32 v188, 0xbfb8aa3b, v40
	v_mul_f32_e32 v189, 0xbfb8aa3b, v41
	v_exp_f32_e32 v188, v188
	v_exp_f32_e32 v189, v189
	v_exp_f32_e32 v192, v192
	v_exp_f32_e32 v193, v193
	v_add_f32_e32 v194, 1.0, v194
	v_add_f32_e32 v195, 1.0, v195
	v_add_f32_e32 v188, 1.0, v188
	v_add_f32_e32 v189, 1.0, v189
	v_rcp_f32_e32 v194, v194
	v_rcp_f32_e32 v195, v195
	v_rcp_f32_e32 v188, v188
	v_rcp_f32_e32 v189, v189
	v_add_f32_e32 v192, 1.0, v192
	v_add_f32_e32 v193, 1.0, v193
	v_rcp_f32_e32 v192, v192
	v_rcp_f32_e32 v193, v193
	v_fma_f32 v186, v194, v158, v130
	v_fma_f32 v187, v195, v166, v131
	v_fma_f32 v188, v188, v167, v132
	v_fma_f32 v189, v189, v172, v133
	v_mul_f32_e32 v194, 0xbfb8aa3b, v32
	v_mul_f32_e32 v195, 0xbfb8aa3b, v33
	v_log_f32_e32 v186, v186
	v_log_f32_e32 v187, v187
	v_log_f32_e32 v188, v188
	v_log_f32_e32 v189, v189
	v_fma_f32 v192, v192, v175, v138
	v_exp_f32_e32 v194, v194
	v_exp_f32_e32 v195, v195
	v_fma_f32 v193, v193, v168, v139
	v_log_f32_e32 v192, v192
	v_log_f32_e32 v193, v193
	v_add_f32_e32 v194, 1.0, v194
	v_add_f32_e32 v195, 1.0, v195
	v_cvt_pk_bf16_f32 v186, v186, v187
	v_cvt_pk_bf16_f32 v187, v188, v189
	v_mul_f32_e32 v189, 0xbfb8aa3b, v34
	v_rcp_f32_e32 v194, v194
	v_rcp_f32_e32 v195, v195
	v_cvt_pk_bf16_f32 v188, v192, v193
	v_exp_f32_e32 v192, v189
	v_mul_f32_e32 v189, 0xbfb8aa3b, v35
	v_exp_f32_e32 v193, v189
	v_fma_f32 v194, v194, v176, v140
	v_fma_f32 v195, v195, v177, v141
	v_log_f32_e32 v194, v194
	v_log_f32_e32 v195, v195
	v_add_f32_e32 v192, 1.0, v192
	v_add_f32_e32 v193, 1.0, v193
	v_rcp_f32_e32 v192, v192
	v_rcp_f32_e32 v193, v193
	v_lshl_add_u64 v[190:191], v[164:165], 0, s[46:47]
	v_cvt_pk_bf16_f32 v189, v194, v195
	global_store_dwordx4 v[190:191], v[186:189], off offset:256 sc1
	v_mul_f32_e32 v190, 0xbfb8aa3b, v26
	v_mul_f32_e32 v191, 0xbfb8aa3b, v27
	v_fma_f32 v186, v192, v185, v142
	v_fma_f32 v187, v193, v184, v143
	v_mul_f32_e32 v188, 0xbfb8aa3b, v36
	v_mul_f32_e32 v189, 0xbfb8aa3b, v37
	v_mul_f32_e32 v192, 0xbfb8aa3b, v28
	v_mul_f32_e32 v193, 0xbfb8aa3b, v29
	v_exp_f32_e32 v188, v188
	v_exp_f32_e32 v189, v189
	v_exp_f32_e32 v192, v192
	v_exp_f32_e32 v193, v193
	v_exp_f32_e32 v190, v190
	v_exp_f32_e32 v191, v191
	v_add_f32_e32 v188, 1.0, v188
	v_add_f32_e32 v189, 1.0, v189
	v_add_f32_e32 v192, 1.0, v192
	v_add_f32_e32 v193, 1.0, v193
	v_rcp_f32_e32 v188, v188
	v_rcp_f32_e32 v189, v189
	v_rcp_f32_e32 v192, v192
	v_rcp_f32_e32 v193, v193
	v_add_f32_e32 v190, 1.0, v190
	v_add_f32_e32 v191, 1.0, v191
	v_rcp_f32_e32 v190, v190
	v_rcp_f32_e32 v191, v191
	v_fma_f32 v188, v188, v183, v144
	v_fma_f32 v189, v189, v182, v145
	v_fma_f32 v192, v192, v179, v136
	v_fma_f32 v193, v193, v178, v137
	v_log_f32_e32 v186, v186
	v_log_f32_e32 v187, v187
	v_log_f32_e32 v188, v188
	v_log_f32_e32 v189, v189
	v_log_f32_e32 v192, v192
	v_log_f32_e32 v193, v193
	v_fma_f32 v190, v190, v181, v134
	v_fma_f32 v191, v191, v180, v135
	v_log_f32_e32 v190, v190
	v_log_f32_e32 v191, v191
	v_cvt_pk_bf16_f32 v186, v186, v187
	v_cvt_pk_bf16_f32 v187, v188, v189
	v_cvt_pk_bf16_f32 v189, v192, v193
	v_mul_f32_e32 v192, 0xbfb8aa3b, v22
	v_exp_f32_e32 v194, v192
	v_mul_f32_e32 v192, 0xbfb8aa3b, v23
	v_exp_f32_e32 v195, v192
	v_add_co_u32_e32 v192, vcc, s68, v164
	v_cvt_pk_bf16_f32 v188, v190, v191
	s_nop 0
	v_addc_co_u32_e32 v193, vcc, 0, v165, vcc
	global_store_dwordx4 v[192:193], v[186:189], off sc1
	v_mul_f32_e32 v192, 0xbfb8aa3b, v14
	v_mul_f32_e32 v193, 0xbfb8aa3b, v15
	v_mul_f32_e32 v188, 0xbfb8aa3b, v24
	v_mul_f32_e32 v189, 0xbfb8aa3b, v25
	v_exp_f32_e32 v188, v188
	v_exp_f32_e32 v189, v189
	v_exp_f32_e32 v192, v192
	v_exp_f32_e32 v193, v193
	v_add_f32_e32 v194, 1.0, v194
	v_add_f32_e32 v195, 1.0, v195
	v_add_f32_e32 v188, 1.0, v188
	v_add_f32_e32 v189, 1.0, v189
	v_rcp_f32_e32 v194, v194
	v_rcp_f32_e32 v195, v195
	v_rcp_f32_e32 v188, v188
	v_rcp_f32_e32 v189, v189
	v_add_f32_e32 v192, 1.0, v192
	v_add_f32_e32 v193, 1.0, v193
	v_rcp_f32_e32 v192, v192
	v_rcp_f32_e32 v193, v193
	v_fma_f32 v186, v194, v158, v130
	v_fma_f32 v187, v195, v166, v131
	v_fma_f32 v188, v188, v167, v132
	v_fma_f32 v189, v189, v172, v133
	v_log_f32_e32 v186, v186
	v_log_f32_e32 v187, v187
	v_log_f32_e32 v188, v188
	v_log_f32_e32 v189, v189
	v_fma_f32 v192, v192, v175, v138
	v_fma_f32 v193, v193, v168, v139
	v_log_f32_e32 v192, v192
	v_log_f32_e32 v193, v193
	v_mul_f32_e32 v194, 0xbfb8aa3b, v16
	v_mul_f32_e32 v195, 0xbfb8aa3b, v17
	v_exp_f32_e32 v194, v194
	v_exp_f32_e32 v195, v195
	v_cvt_pk_bf16_f32 v186, v186, v187
	v_cvt_pk_bf16_f32 v187, v188, v189
	v_mul_f32_e32 v189, 0xbfb8aa3b, v18
	v_cvt_pk_bf16_f32 v188, v192, v193
	v_exp_f32_e32 v192, v189
	v_mul_f32_e32 v189, 0xbfb8aa3b, v19
	v_exp_f32_e32 v193, v189
	v_add_f32_e32 v194, 1.0, v194
	v_add_f32_e32 v195, 1.0, v195
	v_rcp_f32_e32 v194, v194
	v_rcp_f32_e32 v195, v195
	v_add_f32_e32 v192, 1.0, v192
	v_rcp_f32_e32 v192, v192
	v_add_f32_e32 v193, 1.0, v193
	v_rcp_f32_e32 v193, v193
	v_fma_f32 v194, v194, v176, v140
	v_fma_f32 v195, v195, v177, v141
	v_log_f32_e32 v194, v194
	v_log_f32_e32 v195, v195
	v_fma_f32 v142, v192, v185, v142
	v_mul_f32_e32 v185, 0xbfb8aa3b, v21
	v_fma_f32 v143, v193, v184, v143
	v_mul_f32_e32 v184, 0xbfb8aa3b, v20
	v_exp_f32_e32 v185, v185
	v_exp_f32_e32 v184, v184
	v_lshl_add_u64 v[190:191], v[164:165], 0, s[48:49]
	v_cvt_pk_bf16_f32 v189, v194, v195
	global_store_dwordx4 v[190:191], v[186:189], off offset:256 sc1
	v_add_f32_e32 v185, 1.0, v185
	v_add_f32_e32 v184, 1.0, v184
	v_mul_f32_e32 v186, 0xbfb8aa3b, v10
	v_rcp_f32_e32 v185, v185
	v_exp_f32_e32 v186, v186
	v_rcp_f32_e32 v184, v184
	v_log_f32_e32 v142, v142
	v_fmac_f32_e32 v145, v185, v182
	v_add_f32_e32 v182, 1.0, v186
	v_fma_f32 v144, v184, v183, v144
	v_rcp_f32_e32 v182, v182
	v_mul_f32_e32 v183, 0xbfb8aa3b, v11
	v_exp_f32_e32 v183, v183
	v_log_f32_e32 v144, v144
	v_fma_f32 v134, v182, v181, v134
	v_log_f32_e32 v181, v134
	v_add_f32_e32 v134, 1.0, v183
	v_mul_f32_e32 v182, 0xbfb8aa3b, v12
	v_mul_f32_e32 v183, 0xbfb8aa3b, v13
	v_rcp_f32_e32 v134, v134
	v_exp_f32_e32 v182, v182
	v_exp_f32_e32 v183, v183
	v_log_f32_e32 v145, v145
	v_fma_f32 v134, v134, v180, v135
	v_add_f32_e32 v135, 1.0, v182
	v_add_f32_e32 v180, 1.0, v183
	v_rcp_f32_e32 v135, v135
	v_rcp_f32_e32 v180, v180
	v_log_f32_e32 v182, v134
	v_log_f32_e32 v143, v143
	v_fma_f32 v134, v135, v179, v136
	v_fmac_f32_e32 v137, v180, v178
	v_log_f32_e32 v179, v134
	v_log_f32_e32 v137, v137
	v_cvt_pk_bf16_f32 v135, v144, v145
	v_mul_f32_e32 v144, 0xbfb8aa3b, v6
	v_exp_f32_e32 v178, v144
	v_mul_f32_e32 v144, 0xbfb8aa3b, v7
	v_cvt_pk_bf16_f32 v137, v179, v137
	v_exp_f32_e32 v179, v144
	v_add_co_u32_e32 v144, vcc, s4, v164
	v_cvt_pk_bf16_f32 v134, v142, v143
	v_cvt_pk_bf16_f32 v136, v181, v182
	v_addc_co_u32_e32 v145, vcc, 0, v165, vcc
	global_store_dwordx4 v[144:145], v[134:137], off sc1
	v_lshl_add_u64 v[142:143], v[164:165], 0, s[50:51]
	v_add_f32_e32 v164, 1.0, v178
	v_mul_f32_e32 v134, 0xbfb8aa3b, v8
	v_mul_f32_e32 v135, 0xbfb8aa3b, v9
	v_exp_f32_e32 v134, v134
	v_exp_f32_e32 v135, v135
	v_mul_f32_e32 v136, 0xbfb8aa3b, v2
	v_exp_f32_e32 v136, v136
	v_add_f32_e32 v134, 1.0, v134
	v_add_f32_e32 v135, 1.0, v135
	v_rcp_f32_e32 v134, v134
	v_rcp_f32_e32 v135, v135
	v_mul_f32_e32 v137, 0xbfb8aa3b, v5
	v_exp_f32_e32 v137, v137
	v_fma_f32 v132, v134, v167, v132
	v_fmac_f32_e32 v133, v135, v172
	v_add_f32_e32 v134, 1.0, v136
	v_mul_f32_e32 v135, 0xbfb8aa3b, v3
	v_mul_f32_e32 v136, 0xbfb8aa3b, v4
	v_exp_f32_e32 v135, v135
	v_exp_f32_e32 v136, v136
	v_add_f32_e32 v165, 1.0, v179
	v_add_f32_e32 v137, 1.0, v137
	v_add_f32_e32 v135, 1.0, v135
	v_add_f32_e32 v136, 1.0, v136
	v_rcp_f32_e32 v164, v164
	v_rcp_f32_e32 v165, v165
	v_rcp_f32_e32 v134, v134
	v_rcp_f32_e32 v135, v135
	v_rcp_f32_e32 v136, v136
	v_rcp_f32_e32 v137, v137
	v_fma_f32 v130, v164, v158, v130
	v_fma_f32 v131, v165, v166, v131
	v_fma_f32 v134, v134, v175, v138
	v_fma_f32 v135, v135, v168, v139
	v_fma_f32 v136, v136, v176, v140
	v_fmac_f32_e32 v141, v137, v177
	v_log_f32_e32 v130, v130
	v_log_f32_e32 v131, v131
	v_log_f32_e32 v132, v132
	v_log_f32_e32 v133, v133
	v_log_f32_e32 v134, v134
	v_log_f32_e32 v135, v135
	v_log_f32_e32 v136, v136
	v_log_f32_e32 v137, v141
	v_cvt_pk_bf16_f32 v130, v130, v131
	v_cvt_pk_bf16_f32 v131, v132, v133
	v_cvt_pk_bf16_f32 v132, v134, v135
	v_cvt_pk_bf16_f32 v133, v136, v137
	global_store_dwordx4 v[142:143], v[130:133], off offset:256 sc1

.LBB0_161:
	s_and_b64 vcc, exec, s[62:63]
	s_cbranch_vccz .LBB0_166
	v_mul_f32_e32 v130, 0xbfb8aa3b, v126
	v_mul_f32_e32 v131, 0xbfb8aa3b, v127
	v_mul_f32_e32 v132, 0xbfb8aa3b, v128
	v_mul_f32_e32 v133, 0xbfb8aa3b, v129
	v_mul_f32_e32 v134, 0xbfb8aa3b, v122
	v_mul_f32_e32 v135, 0xbfb8aa3b, v123
	v_mul_f32_e32 v136, 0xbfb8aa3b, v124
	v_mul_f32_e32 v137, 0xbfb8aa3b, v125
	v_mul_f32_e32 v138, 0xbfb8aa3b, v118
	v_mul_f32_e32 v139, 0xbfb8aa3b, v119
	v_mul_f32_e32 v140, 0xbfb8aa3b, v120
	v_mul_f32_e32 v141, 0xbfb8aa3b, v121
	v_mul_f32_e32 v142, 0xbfb8aa3b, v110
	v_mul_f32_e32 v143, 0xbfb8aa3b, v111
	v_mul_f32_e32 v144, 0xbfb8aa3b, v112
	v_mul_f32_e32 v145, 0xbfb8aa3b, v113
	v_mul_f32_e32 v158, 0xbfb8aa3b, v114
	v_mul_f32_e32 v164, 0xbfb8aa3b, v115
	v_mul_f32_e32 v165, 0xbfb8aa3b, v116
	v_mul_f32_e32 v166, 0xbfb8aa3b, v117
	v_mul_f32_e32 v167, 0xbfb8aa3b, v106
	v_mul_f32_e32 v168, 0xbfb8aa3b, v107
	v_mul_f32_e32 v172, 0xbfb8aa3b, v108
	v_mul_f32_e32 v175, 0xbfb8aa3b, v109
	v_mul_f32_e32 v176, 0xbfb8aa3b, v102
	v_mul_f32_e32 v177, 0xbfb8aa3b, v103
	v_mul_f32_e32 v178, 0xbfb8aa3b, v104
	v_mul_f32_e32 v179, 0xbfb8aa3b, v105
	v_mul_f32_e32 v180, 0xbfb8aa3b, v94
	v_mul_f32_e32 v181, 0xbfb8aa3b, v95
	v_mul_f32_e32 v182, 0xbfb8aa3b, v96
	v_mul_f32_e32 v183, 0xbfb8aa3b, v97
	v_mul_f32_e32 v184, 0xbfb8aa3b, v98
	v_mul_f32_e32 v185, 0xbfb8aa3b, v99
	v_mul_f32_e32 v186, 0xbfb8aa3b, v100
	v_mul_f32_e32 v187, 0xbfb8aa3b, v101
	v_mul_f32_e32 v188, 0xbfb8aa3b, v90
	v_mul_f32_e32 v189, 0xbfb8aa3b, v91
	v_mul_f32_e32 v190, 0xbfb8aa3b, v92
	v_mul_f32_e32 v191, 0xbfb8aa3b, v93
	v_mul_f32_e32 v192, 0xbfb8aa3b, v86
	v_mul_f32_e32 v193, 0xbfb8aa3b, v87
	v_mul_f32_e32 v194, 0xbfb8aa3b, v88
	v_mul_f32_e32 v195, 0xbfb8aa3b, v89
	v_mul_f32_e32 v196, 0xbfb8aa3b, v78
	v_mul_f32_e32 v197, 0xbfb8aa3b, v79
	v_mul_f32_e32 v198, 0xbfb8aa3b, v80
	v_mul_f32_e32 v199, 0xbfb8aa3b, v81
	v_mul_f32_e32 v200, 0xbfb8aa3b, v82
	v_mul_f32_e32 v249, 0xbfb8aa3b, v83
	v_mul_f32_e32 v250, 0xbfb8aa3b, v84
	v_mul_f32_e32 v251, 0xbfb8aa3b, v85
	v_mul_f32_e32 v252, 0xbfb8aa3b, v74
	v_exp_f32_e32 v248, v130
	v_exp_f32_e32 v247, v131
	v_exp_f32_e32 v246, v132
	v_exp_f32_e32 v245, v133
	v_exp_f32_e32 v244, v134
	v_exp_f32_e32 v243, v135
	v_exp_f32_e32 v242, v136
	v_exp_f32_e32 v241, v137
	v_exp_f32_e32 v240, v138
	v_exp_f32_e32 v239, v139
	v_exp_f32_e32 v238, v140
	v_exp_f32_e32 v237, v141
	v_exp_f32_e32 v236, v142
	v_exp_f32_e32 v235, v143
	v_exp_f32_e32 v234, v144
	v_exp_f32_e32 v233, v145
	v_exp_f32_e32 v232, v158
	v_exp_f32_e32 v231, v164
	v_exp_f32_e32 v230, v165
	v_exp_f32_e32 v229, v166
	v_exp_f32_e32 v228, v167
	v_exp_f32_e32 v227, v168
	v_exp_f32_e32 v226, v172
	v_exp_f32_e32 v225, v175
	v_exp_f32_e32 v224, v176
	v_exp_f32_e32 v223, v177
	v_exp_f32_e32 v222, v178
	v_exp_f32_e32 v221, v179
	v_exp_f32_e32 v220, v180
	v_exp_f32_e32 v219, v181
	v_exp_f32_e32 v218, v182
	v_exp_f32_e32 v217, v183
	v_exp_f32_e32 v216, v184
	v_exp_f32_e32 v215, v185
	v_exp_f32_e32 v214, v186
	v_exp_f32_e32 v213, v187
	v_exp_f32_e32 v212, v188
	v_exp_f32_e32 v211, v189
	v_exp_f32_e32 v210, v190
	v_exp_f32_e32 v209, v191
	v_exp_f32_e32 v208, v192
	v_exp_f32_e32 v207, v193
	v_exp_f32_e32 v206, v194
	v_exp_f32_e32 v205, v195
	v_exp_f32_e32 v204, v196
	v_exp_f32_e32 v203, v197
	v_exp_f32_e32 v202, v198
	v_exp_f32_e32 v201, v199
	v_exp_f32_e32 v200, v200
	v_exp_f32_e32 v199, v249
	v_exp_f32_e32 v198, v250
	v_exp_f32_e32 v197, v251
	v_exp_f32_e32 v195, v252
	s_mov_b64 s[62:63], -1
	s_cmp_gt_i32 s55, 4
	v_mul_f32_e32 v196, 0xbfb8aa3b, v75
	v_mul_f32_e32 v194, 0xbfb8aa3b, v76
	v_mul_f32_e32 v193, 0xbfb8aa3b, v77
	v_mul_f32_e32 v192, 0xbfb8aa3b, v70
	v_mul_f32_e32 v191, 0xbfb8aa3b, v71
	v_mul_f32_e32 v190, 0xbfb8aa3b, v72
	s_cbranch_scc0 .LBB0_164
	s_lshl_b32 s2, s19, 8
	s_and_b32 s2, s2, 0x100
	s_or_b32 s2, s2, s85
	v_add_u32_e32 v164, s2, v174
	v_ashrrev_i32_e32 v165, 31, v164
	v_lshl_add_u64 v[134:135], v[164:165], 2, s[12:13]
	global_load_dwordx4 v[138:141], v[134:135], off offset:16
	global_load_dwordx4 v[142:145], v[134:135], off
	global_load_dwordx4 v[130:133], v[134:135], off offset:528
	s_nop 0
	global_load_dwordx4 v[134:137], v[134:135], off offset:512
	v_add_f32_e32 v158, 1.0, v248
	v_rcp_f32_e32 v158, v158
	v_add_f32_e32 v172, 1.0, v243
	v_rcp_f32_e32 v172, v172
	v_add_f32_e32 v187, 1.0, v241
	v_rcp_f32_e32 v187, v187
	s_lshl_b32 s2, s18, 8
	s_add_i32 s2, s2, s84
	v_add_u32_e32 v166, s2, v173
	v_ashrrev_i32_e32 v167, 31, v166
	v_lshlrev_b64 v[166:167], 10, v[166:167]
	v_lshl_add_u64 v[166:167], s[22:23], 0, v[166:167]
	v_lshl_add_u64 v[164:165], v[164:165], 1, v[166:167]
	v_add_f32_e32 v166, 1.0, v240
	v_add_f32_e32 v167, 1.0, v239
	v_rcp_f32_e32 v166, v166
	v_rcp_f32_e32 v167, v167
	v_add_f32_e32 v189, 1.0, v217
	v_rcp_f32_e32 v189, v189
	s_mov_b64 s[62:63], 0
	s_waitcnt vmcnt(0)
	v_sub_f32_e32 v175, 1.0, v138
	v_sub_f32_e32 v179, 1.0, v142
	v_fma_f32 v158, v158, v179, v142
	v_log_f32_e32 v168, v158
	v_add_f32_e32 v158, 1.0, v247
	v_rcp_f32_e32 v158, v158
	v_sub_f32_e32 v180, 1.0, v143
	v_sub_f32_e32 v181, 1.0, v144
	v_sub_f32_e32 v178, 1.0, v145
	v_fma_f32 v158, v158, v180, v143
	v_log_f32_e32 v176, v158
	v_add_f32_e32 v158, 1.0, v246
	v_rcp_f32_e32 v158, v158
	v_sub_f32_e32 v177, 1.0, v140
	v_cvt_pk_bf16_f32 v250, v168, v176
	v_add_f32_e32 v176, 1.0, v238
	v_fma_f32 v158, v158, v181, v144
	v_log_f32_e32 v182, v158
	v_add_f32_e32 v158, 1.0, v245
	v_rcp_f32_e32 v158, v158
	v_rcp_f32_e32 v176, v176
	v_sub_f32_e32 v168, 1.0, v136
	v_sub_f32_e32 v249, 1.0, v134
	v_fma_f32 v158, v158, v178, v145
	v_log_f32_e32 v183, v158
	v_add_f32_e32 v158, 1.0, v244
	v_rcp_f32_e32 v158, v158
	v_fma_f32 v176, v176, v168, v136
	v_cvt_pk_bf16_f32 v251, v182, v183
	v_log_f32_e32 v183, v176
	v_fma_f32 v158, v158, v175, v138
	v_log_f32_e32 v184, v158
	v_sub_f32_e32 v158, 1.0, v139
	v_fma_f32 v172, v172, v158, v139
	v_log_f32_e32 v185, v172
	v_add_f32_e32 v172, 1.0, v242
	v_rcp_f32_e32 v172, v172
	v_add_f32_e32 v176, 1.0, v237
	v_rcp_f32_e32 v176, v176
	v_cvt_pk_bf16_f32 v252, v184, v185
	v_fma_f32 v172, v172, v177, v140
	v_log_f32_e32 v186, v172
	v_sub_f32_e32 v172, 1.0, v141
	v_fma_f32 v187, v187, v172, v141
	v_log_f32_e32 v187, v187
	v_add_f32_e32 v182, 1.0, v233
	v_rcp_f32_e32 v182, v182
	v_sub_f32_e32 v254, 1.0, v135
	v_cvt_pk_bf16_f32 v253, v186, v187
	global_store_dwordx4 v[164:165], v[250:253], off sc1
	v_fma_f32 v166, v166, v249, v134
	v_fma_f32 v167, v167, v254, v135
	v_sub_f32_e32 v253, 1.0, v137
	v_fma_f32 v176, v176, v253, v137
	v_log_f32_e32 v184, v176
	v_add_f32_e32 v176, 1.0, v236
	v_rcp_f32_e32 v176, v176
	v_sub_f32_e32 v251, 1.0, v130
	v_sub_f32_e32 v250, 1.0, v131
	v_sub_f32_e32 v252, 1.0, v132
	v_fma_f32 v176, v176, v251, v130
	v_log_f32_e32 v185, v176
	v_add_f32_e32 v176, 1.0, v235
	v_rcp_f32_e32 v176, v176
	v_log_f32_e32 v166, v166
	v_log_f32_e32 v167, v167
	v_cvt_pk_bf16_f32 v183, v183, v184
	v_fma_f32 v176, v176, v250, v131
	v_log_f32_e32 v186, v176
	v_add_f32_e32 v176, 1.0, v234
	v_rcp_f32_e32 v176, v176
	v_cvt_pk_bf16_f32 v184, v185, v186
	v_fma_f32 v176, v176, v252, v132
	v_log_f32_e32 v187, v176
	v_sub_f32_e32 v176, 1.0, v133
	v_fma_f32 v182, v182, v176, v133
	v_log_f32_e32 v188, v182
	v_cvt_pk_bf16_f32 v182, v166, v167
	v_add_f32_e32 v166, 1.0, v232
	v_add_f32_e32 v167, 1.0, v231
	v_cvt_pk_bf16_f32 v185, v187, v188
	global_store_dwordx4 v[164:165], v[182:185], off offset:256 sc1
	v_rcp_f32_e32 v166, v166
	v_rcp_f32_e32 v167, v167
	v_add_f32_e32 v182, 1.0, v230
	v_rcp_f32_e32 v182, v182
	v_fma_f32 v166, v166, v179, v142
	v_fma_f32 v167, v167, v180, v143
	v_log_f32_e32 v166, v166
	v_fma_f32 v182, v182, v181, v144
	v_log_f32_e32 v183, v182
	v_add_f32_e32 v182, 1.0, v229
	v_rcp_f32_e32 v182, v182
	v_log_f32_e32 v167, v167
	v_fma_f32 v189, v189, v176, v133
	v_log_f32_e32 v189, v189
	v_fma_f32 v182, v182, v178, v145
	v_log_f32_e32 v184, v182
	v_add_f32_e32 v182, 1.0, v228
	v_rcp_f32_e32 v182, v182
	v_cvt_pk_bf16_f32 v183, v183, v184
	v_fma_f32 v182, v182, v175, v138
	v_log_f32_e32 v185, v182
	v_add_f32_e32 v182, 1.0, v227
	v_rcp_f32_e32 v182, v182
	s_nop 0
	v_fma_f32 v182, v182, v158, v139
	v_log_f32_e32 v186, v182
	v_add_f32_e32 v182, 1.0, v226
	v_rcp_f32_e32 v182, v182
	v_cvt_pk_bf16_f32 v184, v185, v186
	v_add_co_u32_e32 v186, vcc, s75, v164
	v_fma_f32 v182, v182, v177, v140
	v_log_f32_e32 v187, v182
	v_add_f32_e32 v182, 1.0, v225
	v_rcp_f32_e32 v182, v182
	s_nop 0
	v_fma_f32 v182, v182, v172, v141
	v_log_f32_e32 v188, v182
	v_cvt_pk_bf16_f32 v182, v166, v167
	v_lshl_add_u64 v[166:167], v[164:165], 0, s[38:39]
	v_cvt_pk_bf16_f32 v185, v187, v188
	v_addc_co_u32_e32 v187, vcc, 0, v165, vcc
	global_store_dwordx4 v[186:187], v[182:185], off sc1
	v_add_f32_e32 v186, 1.0, v220
	v_add_f32_e32 v187, 1.0, v219
	v_add_f32_e32 v182, 1.0, v224
	v_add_f32_e32 v183, 1.0, v223
	v_add_f32_e32 v184, 1.0, v222
	v_add_f32_e32 v185, 1.0, v221
	v_add_f32_e32 v188, 1.0, v218
	v_rcp_f32_e32 v182, v182
	v_rcp_f32_e32 v183, v183
	v_rcp_f32_e32 v184, v184
	v_rcp_f32_e32 v185, v185
	v_rcp_f32_e32 v186, v186
	v_rcp_f32_e32 v187, v187
	v_rcp_f32_e32 v188, v188
	v_fma_f32 v182, v182, v249, v134
	v_fma_f32 v183, v183, v254, v135
	v_fma_f32 v184, v184, v168, v136
	v_fma_f32 v185, v185, v253, v137
	v_fma_f32 v186, v186, v251, v130
	v_fma_f32 v187, v187, v250, v131
	v_fma_f32 v188, v188, v252, v132
	v_log_f32_e32 v182, v182
	v_log_f32_e32 v183, v183
	v_log_f32_e32 v184, v184
	v_log_f32_e32 v185, v185
	v_log_f32_e32 v186, v186
	v_log_f32_e32 v187, v187
	v_log_f32_e32 v188, v188
	v_cvt_pk_bf16_f32 v182, v182, v183
	v_cvt_pk_bf16_f32 v183, v184, v185
	v_cvt_pk_bf16_f32 v184, v186, v187
	v_cvt_pk_bf16_f32 v185, v188, v189
	global_store_dwordx4 v[166:167], v[182:185], off offset:256 sc1
	v_add_f32_e32 v166, 1.0, v216
	v_add_f32_e32 v167, 1.0, v215
	v_add_f32_e32 v182, 1.0, v214
	v_rcp_f32_e32 v182, v182
	v_rcp_f32_e32 v166, v166
	v_rcp_f32_e32 v167, v167
	v_add_f32_e32 v189, 1.0, v201
	v_fma_f32 v182, v182, v181, v144
	v_log_f32_e32 v183, v182
	v_add_f32_e32 v182, 1.0, v213
	v_rcp_f32_e32 v182, v182
	v_fma_f32 v166, v166, v179, v142
	v_fma_f32 v167, v167, v180, v143
	v_log_f32_e32 v166, v166
	v_fma_f32 v182, v182, v178, v145
	v_log_f32_e32 v184, v182
	v_add_f32_e32 v182, 1.0, v212
	v_rcp_f32_e32 v182, v182
	v_log_f32_e32 v167, v167
	v_cvt_pk_bf16_f32 v183, v183, v184
	v_rcp_f32_e32 v189, v189
	v_fma_f32 v182, v182, v175, v138
	v_log_f32_e32 v185, v182
	v_add_f32_e32 v182, 1.0, v211
	v_rcp_f32_e32 v182, v182
	v_fma_f32 v189, v189, v176, v133
	v_log_f32_e32 v189, v189
	v_fma_f32 v182, v182, v158, v139
	v_log_f32_e32 v186, v182
	v_add_f32_e32 v182, 1.0, v210
	v_rcp_f32_e32 v182, v182
	v_cvt_pk_bf16_f32 v184, v185, v186
	v_add_co_u32_e32 v186, vcc, s92, v164
	v_fma_f32 v182, v182, v177, v140
	v_log_f32_e32 v187, v182
	v_add_f32_e32 v182, 1.0, v209
	v_rcp_f32_e32 v182, v182
	s_nop 0
	v_fma_f32 v182, v182, v172, v141
	v_log_f32_e32 v188, v182
	v_cvt_pk_bf16_f32 v182, v166, v167
	v_lshl_add_u64 v[166:167], v[164:165], 0, s[40:41]
	v_cvt_pk_bf16_f32 v185, v187, v188
	v_addc_co_u32_e32 v187, vcc, 0, v165, vcc
	global_store_dwordx4 v[186:187], v[182:185], off sc1
	v_add_f32_e32 v186, 1.0, v204
	v_add_f32_e32 v187, 1.0, v203
	v_add_f32_e32 v182, 1.0, v208
	v_add_f32_e32 v183, 1.0, v207
	v_add_f32_e32 v184, 1.0, v206
	v_add_f32_e32 v185, 1.0, v205
	v_add_f32_e32 v188, 1.0, v202
	v_rcp_f32_e32 v182, v182
	v_rcp_f32_e32 v183, v183
	v_rcp_f32_e32 v184, v184
	v_rcp_f32_e32 v185, v185
	v_rcp_f32_e32 v186, v186
	v_rcp_f32_e32 v187, v187
	v_rcp_f32_e32 v188, v188
	v_fma_f32 v182, v182, v249, v134
	v_fma_f32 v183, v183, v254, v135
	v_fma_f32 v184, v184, v168, v136
	v_fma_f32 v185, v185, v253, v137
	v_fma_f32 v186, v186, v251, v130
	v_fma_f32 v187, v187, v250, v131
	v_fma_f32 v188, v188, v252, v132
	v_log_f32_e32 v182, v182
	v_log_f32_e32 v183, v183
	v_log_f32_e32 v184, v184
	v_log_f32_e32 v185, v185
	v_log_f32_e32 v186, v186
	v_log_f32_e32 v187, v187
	v_log_f32_e32 v188, v188
	v_cvt_pk_bf16_f32 v182, v182, v183
	v_cvt_pk_bf16_f32 v183, v184, v185
	v_cvt_pk_bf16_f32 v184, v186, v187
	v_cvt_pk_bf16_f32 v185, v188, v189
	global_store_dwordx4 v[166:167], v[182:185], off offset:256 sc1
	v_add_f32_e32 v166, 1.0, v200
	v_add_f32_e32 v167, 1.0, v199
	v_add_f32_e32 v182, 1.0, v198
	v_rcp_f32_e32 v182, v182
	v_rcp_f32_e32 v166, v166
	v_rcp_f32_e32 v167, v167
	v_mul_f32_e32 v189, 0xbfb8aa3b, v69
	v_fma_f32 v182, v182, v181, v144
	v_log_f32_e32 v183, v182
	v_add_f32_e32 v182, 1.0, v197
	v_rcp_f32_e32 v182, v182
	v_fma_f32 v166, v166, v179, v142
	v_fma_f32 v167, v167, v180, v143
	v_log_f32_e32 v166, v166
	v_fma_f32 v182, v182, v178, v145
	v_log_f32_e32 v184, v182
	v_add_f32_e32 v182, 1.0, v195
	v_rcp_f32_e32 v182, v182
	v_log_f32_e32 v167, v167
	v_cvt_pk_bf16_f32 v183, v183, v184
	v_exp_f32_e32 v189, v189
	v_fma_f32 v182, v182, v175, v138
	v_log_f32_e32 v185, v182
	v_exp_f32_e32 v182, v196
	v_add_f32_e32 v189, 1.0, v189
	v_rcp_f32_e32 v189, v189
	v_add_f32_e32 v182, 1.0, v182
	v_rcp_f32_e32 v182, v182
	v_fma_f32 v189, v189, v176, v133
	v_log_f32_e32 v189, v189
	v_fma_f32 v182, v182, v158, v139
	v_log_f32_e32 v186, v182
	v_exp_f32_e32 v182, v194
	v_cvt_pk_bf16_f32 v184, v185, v186
	v_add_f32_e32 v182, 1.0, v182
	v_rcp_f32_e32 v182, v182
	v_add_co_u32_e32 v186, vcc, s97, v164
	v_fma_f32 v182, v182, v177, v140
	v_log_f32_e32 v187, v182
	v_exp_f32_e32 v182, v193
	s_nop 0
	v_add_f32_e32 v182, 1.0, v182
	v_rcp_f32_e32 v182, v182
	s_nop 0
	v_fma_f32 v182, v182, v172, v141
	v_log_f32_e32 v188, v182
	v_cvt_pk_bf16_f32 v182, v166, v167
	v_lshl_add_u64 v[166:167], v[164:165], 0, s[42:43]
	v_cvt_pk_bf16_f32 v185, v187, v188
	v_addc_co_u32_e32 v187, vcc, 0, v165, vcc
	global_store_dwordx4 v[186:187], v[182:185], off sc1
	v_mul_f32_e32 v186, 0xbfb8aa3b, v66
	v_mul_f32_e32 v187, 0xbfb8aa3b, v67
	v_mul_f32_e32 v185, 0xbfb8aa3b, v73
	v_mul_f32_e32 v188, 0xbfb8aa3b, v68
	v_exp_f32_e32 v182, v192
	v_exp_f32_e32 v183, v191
	v_exp_f32_e32 v184, v190
	v_exp_f32_e32 v185, v185
	v_exp_f32_e32 v186, v186
	v_exp_f32_e32 v187, v187
	v_exp_f32_e32 v188, v188
	v_add_f32_e32 v182, 1.0, v182
	v_add_f32_e32 v183, 1.0, v183
	v_add_f32_e32 v184, 1.0, v184
	v_add_f32_e32 v185, 1.0, v185
	v_add_f32_e32 v186, 1.0, v186
	v_add_f32_e32 v187, 1.0, v187
	v_add_f32_e32 v188, 1.0, v188
	v_rcp_f32_e32 v182, v182
	v_rcp_f32_e32 v183, v183
	v_rcp_f32_e32 v184, v184
	v_rcp_f32_e32 v185, v185
	v_rcp_f32_e32 v186, v186
	v_rcp_f32_e32 v187, v187
	v_rcp_f32_e32 v188, v188
	v_fma_f32 v182, v182, v249, v134
	v_fma_f32 v183, v183, v254, v135
	v_fma_f32 v184, v184, v168, v136
	v_fma_f32 v185, v185, v253, v137
	v_fma_f32 v186, v186, v251, v130
	v_fma_f32 v187, v187, v250, v131
	v_fma_f32 v188, v188, v252, v132
	v_log_f32_e32 v182, v182
	v_log_f32_e32 v183, v183
	v_log_f32_e32 v184, v184
	v_log_f32_e32 v185, v185
	v_log_f32_e32 v186, v186
	v_log_f32_e32 v187, v187
	v_log_f32_e32 v188, v188
	v_cvt_pk_bf16_f32 v182, v182, v183
	v_cvt_pk_bf16_f32 v183, v184, v185
	v_cvt_pk_bf16_f32 v184, v186, v187
	v_cvt_pk_bf16_f32 v185, v188, v189
	global_store_dwordx4 v[166:167], v[182:185], off offset:256 sc1
	v_mul_f32_e32 v166, 0xbfb8aa3b, v62
	v_mul_f32_e32 v167, 0xbfb8aa3b, v63
	v_mul_f32_e32 v182, 0xbfb8aa3b, v64
	v_exp_f32_e32 v182, v182
	v_exp_f32_e32 v166, v166
	v_exp_f32_e32 v167, v167
	v_mul_f32_e32 v189, 0xbfb8aa3b, v49
	v_add_f32_e32 v182, 1.0, v182
	v_rcp_f32_e32 v182, v182
	v_add_f32_e32 v166, 1.0, v166
	v_add_f32_e32 v167, 1.0, v167
	v_rcp_f32_e32 v166, v166
	v_fma_f32 v182, v182, v181, v144
	v_log_f32_e32 v183, v182
	v_mul_f32_e32 v182, 0xbfb8aa3b, v65
	v_exp_f32_e32 v182, v182
	v_rcp_f32_e32 v167, v167
	v_fma_f32 v166, v166, v179, v142
	v_log_f32_e32 v166, v166
	v_add_f32_e32 v182, 1.0, v182
	v_rcp_f32_e32 v182, v182
	v_fma_f32 v167, v167, v180, v143
	v_log_f32_e32 v167, v167
	v_exp_f32_e32 v189, v189
	v_fma_f32 v182, v182, v178, v145
	v_log_f32_e32 v184, v182
	v_mul_f32_e32 v182, 0xbfb8aa3b, v58
	v_exp_f32_e32 v182, v182
	v_add_f32_e32 v189, 1.0, v189
	v_cvt_pk_bf16_f32 v183, v183, v184
	v_rcp_f32_e32 v189, v189
	v_add_f32_e32 v182, 1.0, v182
	v_rcp_f32_e32 v182, v182
	v_fma_f32 v189, v189, v176, v133
	v_log_f32_e32 v189, v189
	v_fma_f32 v182, v182, v175, v138
	v_log_f32_e32 v185, v182
	v_mul_f32_e32 v182, 0xbfb8aa3b, v59
	v_exp_f32_e32 v182, v182
	s_nop 0
	v_add_f32_e32 v182, 1.0, v182
	v_rcp_f32_e32 v182, v182
	s_nop 0
	v_fma_f32 v182, v182, v158, v139
	v_log_f32_e32 v186, v182
	v_mul_f32_e32 v182, 0xbfb8aa3b, v60
	v_exp_f32_e32 v182, v182
	v_cvt_pk_bf16_f32 v184, v185, v186
	v_add_co_u32_e32 v186, vcc, s66, v164
	v_add_f32_e32 v182, 1.0, v182
	v_rcp_f32_e32 v182, v182
	s_nop 0
	v_fma_f32 v182, v182, v177, v140
	v_log_f32_e32 v187, v182
	v_mul_f32_e32 v182, 0xbfb8aa3b, v61
	v_exp_f32_e32 v182, v182
	s_nop 0
	v_add_f32_e32 v182, 1.0, v182
	v_rcp_f32_e32 v182, v182
	s_nop 0
	v_fma_f32 v182, v182, v172, v141
	v_log_f32_e32 v188, v182
	v_cvt_pk_bf16_f32 v182, v166, v167
	v_lshl_add_u64 v[166:167], v[164:165], 0, s[44:45]
	v_cvt_pk_bf16_f32 v185, v187, v188
	v_addc_co_u32_e32 v187, vcc, 0, v165, vcc
	global_store_dwordx4 v[186:187], v[182:185], off sc1
	v_mul_f32_e32 v186, 0xbfb8aa3b, v46
	v_mul_f32_e32 v187, 0xbfb8aa3b, v47
	v_mul_f32_e32 v182, 0xbfb8aa3b, v54
	v_mul_f32_e32 v183, 0xbfb8aa3b, v55
	v_mul_f32_e32 v184, 0xbfb8aa3b, v56
	v_mul_f32_e32 v185, 0xbfb8aa3b, v57
	v_mul_f32_e32 v188, 0xbfb8aa3b, v48
	v_exp_f32_e32 v182, v182
	v_exp_f32_e32 v183, v183
	v_exp_f32_e32 v184, v184
	v_exp_f32_e32 v185, v185
	v_exp_f32_e32 v186, v186
	v_exp_f32_e32 v187, v187
	v_exp_f32_e32 v188, v188
	v_add_f32_e32 v182, 1.0, v182
	v_add_f32_e32 v183, 1.0, v183
	v_add_f32_e32 v184, 1.0, v184
	v_add_f32_e32 v185, 1.0, v185
	v_add_f32_e32 v186, 1.0, v186
	v_add_f32_e32 v187, 1.0, v187
	v_add_f32_e32 v188, 1.0, v188
	v_rcp_f32_e32 v182, v182
	v_rcp_f32_e32 v183, v183
	v_rcp_f32_e32 v184, v184
	v_rcp_f32_e32 v185, v185
	v_rcp_f32_e32 v186, v186
	v_rcp_f32_e32 v187, v187
	v_rcp_f32_e32 v188, v188
	v_fma_f32 v182, v182, v249, v134
	v_fma_f32 v183, v183, v254, v135
	v_fma_f32 v184, v184, v168, v136
	v_fma_f32 v185, v185, v253, v137
	v_fma_f32 v186, v186, v251, v130
	v_fma_f32 v187, v187, v250, v131
	v_fma_f32 v188, v188, v252, v132
	v_log_f32_e32 v182, v182
	v_log_f32_e32 v183, v183
	v_log_f32_e32 v184, v184
	v_log_f32_e32 v185, v185
	v_log_f32_e32 v186, v186
	v_log_f32_e32 v187, v187
	v_log_f32_e32 v188, v188
	v_cvt_pk_bf16_f32 v182, v182, v183
	v_cvt_pk_bf16_f32 v183, v184, v185
	v_cvt_pk_bf16_f32 v184, v186, v187
	v_cvt_pk_bf16_f32 v185, v188, v189
	global_store_dwordx4 v[166:167], v[182:185], off offset:256 sc1
	v_mul_f32_e32 v166, 0xbfb8aa3b, v50
	v_mul_f32_e32 v167, 0xbfb8aa3b, v51
	v_mul_f32_e32 v182, 0xbfb8aa3b, v52
	v_exp_f32_e32 v182, v182
	v_exp_f32_e32 v166, v166
	v_exp_f32_e32 v167, v167
	v_mul_f32_e32 v189, 0xbfb8aa3b, v33
	v_add_f32_e32 v182, 1.0, v182
	v_rcp_f32_e32 v182, v182
	v_add_f32_e32 v166, 1.0, v166
	v_add_f32_e32 v167, 1.0, v167
	v_rcp_f32_e32 v166, v166
	v_fma_f32 v182, v182, v181, v144
	v_log_f32_e32 v183, v182
	v_mul_f32_e32 v182, 0xbfb8aa3b, v53
	v_exp_f32_e32 v182, v182
	v_rcp_f32_e32 v167, v167
	v_fma_f32 v166, v166, v179, v142
	v_log_f32_e32 v166, v166
	v_add_f32_e32 v182, 1.0, v182
	v_rcp_f32_e32 v182, v182
	v_fma_f32 v167, v167, v180, v143
	v_log_f32_e32 v167, v167
	v_exp_f32_e32 v189, v189
	v_fma_f32 v182, v182, v178, v145
	v_log_f32_e32 v184, v182
	v_mul_f32_e32 v182, 0xbfb8aa3b, v42
	v_exp_f32_e32 v182, v182
	v_add_f32_e32 v189, 1.0, v189
	v_cvt_pk_bf16_f32 v183, v183, v184
	v_rcp_f32_e32 v189, v189
	v_add_f32_e32 v182, 1.0, v182
	v_rcp_f32_e32 v182, v182
	v_fma_f32 v189, v189, v176, v133
	v_log_f32_e32 v189, v189
	v_fma_f32 v182, v182, v175, v138
	v_log_f32_e32 v185, v182
	v_mul_f32_e32 v182, 0xbfb8aa3b, v43
	v_exp_f32_e32 v182, v182
	s_nop 0
	v_add_f32_e32 v182, 1.0, v182
	v_rcp_f32_e32 v182, v182
	s_nop 0
	v_fma_f32 v182, v182, v158, v139
	v_log_f32_e32 v186, v182
	v_mul_f32_e32 v182, 0xbfb8aa3b, v44
	v_exp_f32_e32 v182, v182
	v_cvt_pk_bf16_f32 v184, v185, v186
	v_add_co_u32_e32 v186, vcc, s53, v164
	v_add_f32_e32 v182, 1.0, v182
	v_rcp_f32_e32 v182, v182
	s_nop 0
	v_fma_f32 v182, v182, v177, v140
	v_log_f32_e32 v187, v182
	v_mul_f32_e32 v182, 0xbfb8aa3b, v45
	v_exp_f32_e32 v182, v182
	s_nop 0
	v_add_f32_e32 v182, 1.0, v182
	v_rcp_f32_e32 v182, v182
	s_nop 0
	v_fma_f32 v182, v182, v172, v141
	v_log_f32_e32 v188, v182
	v_cvt_pk_bf16_f32 v182, v166, v167
	v_lshl_add_u64 v[166:167], v[164:165], 0, s[46:47]
	v_cvt_pk_bf16_f32 v185, v187, v188
	v_addc_co_u32_e32 v187, vcc, 0, v165, vcc
	global_store_dwordx4 v[186:187], v[182:185], off sc1
	v_mul_f32_e32 v186, 0xbfb8aa3b, v30
	v_mul_f32_e32 v187, 0xbfb8aa3b, v31
	v_mul_f32_e32 v182, 0xbfb8aa3b, v38
	v_mul_f32_e32 v183, 0xbfb8aa3b, v39
	v_mul_f32_e32 v184, 0xbfb8aa3b, v40
	v_mul_f32_e32 v185, 0xbfb8aa3b, v41
	v_mul_f32_e32 v188, 0xbfb8aa3b, v32
	v_exp_f32_e32 v182, v182
	v_exp_f32_e32 v183, v183
	v_exp_f32_e32 v184, v184
	v_exp_f32_e32 v185, v185
	v_exp_f32_e32 v186, v186
	v_exp_f32_e32 v187, v187
	v_exp_f32_e32 v188, v188
	v_add_f32_e32 v182, 1.0, v182
	v_add_f32_e32 v183, 1.0, v183
	v_add_f32_e32 v184, 1.0, v184
	v_add_f32_e32 v185, 1.0, v185
	v_add_f32_e32 v186, 1.0, v186
	v_add_f32_e32 v187, 1.0, v187
	v_add_f32_e32 v188, 1.0, v188
	v_rcp_f32_e32 v182, v182
	v_rcp_f32_e32 v183, v183
	v_rcp_f32_e32 v184, v184
	v_rcp_f32_e32 v185, v185
	v_rcp_f32_e32 v186, v186
	v_rcp_f32_e32 v187, v187
	v_rcp_f32_e32 v188, v188
	v_fma_f32 v182, v182, v249, v134
	v_fma_f32 v183, v183, v254, v135
	v_fma_f32 v184, v184, v168, v136
	v_fma_f32 v185, v185, v253, v137
	v_fma_f32 v186, v186, v251, v130
	v_fma_f32 v187, v187, v250, v131
	v_fma_f32 v188, v188, v252, v132
	v_log_f32_e32 v182, v182
	v_log_f32_e32 v183, v183
	v_log_f32_e32 v184, v184
	v_log_f32_e32 v185, v185
	v_log_f32_e32 v186, v186
	v_log_f32_e32 v187, v187
	v_log_f32_e32 v188, v188
	v_cvt_pk_bf16_f32 v182, v182, v183
	v_cvt_pk_bf16_f32 v183, v184, v185
	v_cvt_pk_bf16_f32 v184, v186, v187
	v_cvt_pk_bf16_f32 v185, v188, v189
	global_store_dwordx4 v[166:167], v[182:185], off offset:256 sc1
	v_mul_f32_e32 v166, 0xbfb8aa3b, v34
	v_mul_f32_e32 v167, 0xbfb8aa3b, v35
	v_mul_f32_e32 v182, 0xbfb8aa3b, v36
	v_exp_f32_e32 v182, v182
	v_exp_f32_e32 v166, v166
	v_exp_f32_e32 v167, v167
	v_mul_f32_e32 v189, 0xbfb8aa3b, v17
	v_add_f32_e32 v182, 1.0, v182
	v_rcp_f32_e32 v182, v182
	v_add_f32_e32 v166, 1.0, v166
	v_add_f32_e32 v167, 1.0, v167
	v_rcp_f32_e32 v166, v166
	v_fma_f32 v182, v182, v181, v144
	v_log_f32_e32 v183, v182
	v_mul_f32_e32 v182, 0xbfb8aa3b, v37
	v_exp_f32_e32 v182, v182
	v_rcp_f32_e32 v167, v167
	v_fma_f32 v166, v166, v179, v142
	v_log_f32_e32 v166, v166
	v_add_f32_e32 v182, 1.0, v182
	v_rcp_f32_e32 v182, v182
	v_fma_f32 v167, v167, v180, v143
	v_log_f32_e32 v167, v167
	v_exp_f32_e32 v189, v189
	v_fma_f32 v182, v182, v178, v145
	v_log_f32_e32 v184, v182
	v_mul_f32_e32 v182, 0xbfb8aa3b, v26
	v_exp_f32_e32 v182, v182
	v_add_f32_e32 v189, 1.0, v189
	v_cvt_pk_bf16_f32 v183, v183, v184
	v_rcp_f32_e32 v189, v189
	v_add_f32_e32 v182, 1.0, v182
	v_rcp_f32_e32 v182, v182
	v_fma_f32 v189, v189, v176, v133
	v_log_f32_e32 v189, v189
	v_fma_f32 v182, v182, v175, v138
	v_log_f32_e32 v185, v182
	v_mul_f32_e32 v182, 0xbfb8aa3b, v27
	v_exp_f32_e32 v182, v182
	s_nop 0
	v_add_f32_e32 v182, 1.0, v182
	v_rcp_f32_e32 v182, v182
	s_nop 0
	v_fma_f32 v182, v182, v158, v139
	v_log_f32_e32 v186, v182
	v_mul_f32_e32 v182, 0xbfb8aa3b, v28
	v_exp_f32_e32 v182, v182
	v_cvt_pk_bf16_f32 v184, v185, v186
	v_add_co_u32_e32 v186, vcc, s68, v164
	v_add_f32_e32 v182, 1.0, v182
	v_rcp_f32_e32 v182, v182
	s_nop 0
	v_fma_f32 v182, v182, v177, v140
	v_log_f32_e32 v187, v182
	v_mul_f32_e32 v182, 0xbfb8aa3b, v29
	v_exp_f32_e32 v182, v182
	s_nop 0
	v_add_f32_e32 v182, 1.0, v182
	v_rcp_f32_e32 v182, v182
	s_nop 0
	v_fma_f32 v182, v182, v172, v141
	v_log_f32_e32 v188, v182
	v_cvt_pk_bf16_f32 v182, v166, v167
	v_lshl_add_u64 v[166:167], v[164:165], 0, s[48:49]
	v_cvt_pk_bf16_f32 v185, v187, v188
	v_addc_co_u32_e32 v187, vcc, 0, v165, vcc
	global_store_dwordx4 v[186:187], v[182:185], off sc1
	v_mul_f32_e32 v186, 0xbfb8aa3b, v14
	v_mul_f32_e32 v187, 0xbfb8aa3b, v15
	v_mul_f32_e32 v182, 0xbfb8aa3b, v22
	v_mul_f32_e32 v183, 0xbfb8aa3b, v23
	v_mul_f32_e32 v184, 0xbfb8aa3b, v24
	v_mul_f32_e32 v185, 0xbfb8aa3b, v25
	v_mul_f32_e32 v188, 0xbfb8aa3b, v16
	v_exp_f32_e32 v182, v182
	v_exp_f32_e32 v183, v183
	v_exp_f32_e32 v184, v184
	v_exp_f32_e32 v185, v185
	v_exp_f32_e32 v186, v186
	v_exp_f32_e32 v187, v187
	v_exp_f32_e32 v188, v188
	v_add_f32_e32 v182, 1.0, v182
	v_add_f32_e32 v183, 1.0, v183
	v_add_f32_e32 v184, 1.0, v184
	v_add_f32_e32 v185, 1.0, v185
	v_add_f32_e32 v186, 1.0, v186
	v_add_f32_e32 v187, 1.0, v187
	v_add_f32_e32 v188, 1.0, v188
	v_rcp_f32_e32 v182, v182
	v_rcp_f32_e32 v183, v183
	v_rcp_f32_e32 v184, v184
	v_rcp_f32_e32 v185, v185
	v_rcp_f32_e32 v186, v186
	v_rcp_f32_e32 v187, v187
	v_rcp_f32_e32 v188, v188
	v_fma_f32 v182, v182, v249, v134
	v_fma_f32 v183, v183, v254, v135
	v_fma_f32 v184, v184, v168, v136
	v_fma_f32 v185, v185, v253, v137
	v_fma_f32 v186, v186, v251, v130
	v_fma_f32 v187, v187, v250, v131
	v_fma_f32 v188, v188, v252, v132
	v_log_f32_e32 v182, v182
	v_log_f32_e32 v183, v183
	v_log_f32_e32 v184, v184
	v_log_f32_e32 v185, v185
	v_log_f32_e32 v186, v186
	v_log_f32_e32 v187, v187
	v_log_f32_e32 v188, v188
	v_cvt_pk_bf16_f32 v182, v182, v183
	v_cvt_pk_bf16_f32 v183, v184, v185
	v_cvt_pk_bf16_f32 v184, v186, v187
	v_cvt_pk_bf16_f32 v185, v188, v189
	global_store_dwordx4 v[166:167], v[182:185], off offset:256 sc1
	v_mul_f32_e32 v166, 0xbfb8aa3b, v18
	v_exp_f32_e32 v166, v166
	s_nop 0
	v_add_f32_e32 v166, 1.0, v166
	v_rcp_f32_e32 v166, v166
	s_nop 0
	v_fma_f32 v142, v166, v179, v142
	v_mul_f32_e32 v166, 0xbfb8aa3b, v19
	v_exp_f32_e32 v166, v166
	v_log_f32_e32 v142, v142
	v_add_f32_e32 v166, 1.0, v166
	v_rcp_f32_e32 v166, v166
	s_nop 0
	v_fma_f32 v143, v166, v180, v143
	v_mul_f32_e32 v166, 0xbfb8aa3b, v20
	v_exp_f32_e32 v166, v166
	v_log_f32_e32 v143, v143
	v_add_f32_e32 v166, 1.0, v166
	v_rcp_f32_e32 v166, v166
	s_nop 0
	v_fma_f32 v144, v166, v181, v144
	v_mul_f32_e32 v166, 0xbfb8aa3b, v21
	v_exp_f32_e32 v166, v166
	v_log_f32_e32 v144, v144
	v_add_f32_e32 v166, 1.0, v166
	v_rcp_f32_e32 v166, v166
	s_nop 0
	v_fmac_f32_e32 v145, v166, v178
	v_mul_f32_e32 v166, 0xbfb8aa3b, v10
	v_exp_f32_e32 v166, v166
	v_log_f32_e32 v145, v145
	v_add_f32_e32 v166, 1.0, v166
	v_rcp_f32_e32 v166, v166
	s_nop 0
	v_fma_f32 v138, v166, v175, v138
	v_log_f32_e32 v166, v138
	v_mul_f32_e32 v138, 0xbfb8aa3b, v11
	v_exp_f32_e32 v138, v138
	s_nop 0
	v_add_f32_e32 v138, 1.0, v138
	v_rcp_f32_e32 v138, v138
	s_nop 0
	v_fma_f32 v138, v138, v158, v139
	v_log_f32_e32 v158, v138
	v_mul_f32_e32 v138, 0xbfb8aa3b, v12
	v_exp_f32_e32 v138, v138
	v_cvt_pk_bf16_f32 v139, v144, v145
	v_add_co_u32_e32 v144, vcc, s4, v164
	v_add_f32_e32 v138, 1.0, v138
	v_rcp_f32_e32 v138, v138
	v_addc_co_u32_e32 v145, vcc, 0, v165, vcc
	v_fma_f32 v138, v138, v177, v140
	v_log_f32_e32 v167, v138
	v_mul_f32_e32 v138, 0xbfb8aa3b, v13
	v_exp_f32_e32 v138, v138
	v_cvt_pk_bf16_f32 v140, v166, v158
	v_add_f32_e32 v138, 1.0, v138
	v_rcp_f32_e32 v138, v138
	s_nop 0
	v_fmac_f32_e32 v141, v138, v172
	v_log_f32_e32 v141, v141
	v_cvt_pk_bf16_f32 v138, v142, v143
	v_lshl_add_u64 v[142:143], v[164:165], 0, s[50:51]
	v_cvt_pk_bf16_f32 v141, v167, v141
	global_store_dwordx4 v[144:145], v[138:141], off sc1
	s_nop 1
	v_mul_f32_e32 v138, 0xbfb8aa3b, v6
	v_exp_f32_e32 v138, v138
	s_nop 0
	v_add_f32_e32 v138, 1.0, v138
	v_rcp_f32_e32 v138, v138
	s_nop 0
	v_fma_f32 v134, v138, v249, v134
	v_mul_f32_e32 v138, 0xbfb8aa3b, v7
	v_exp_f32_e32 v138, v138
	v_log_f32_e32 v134, v134
	v_add_f32_e32 v138, 1.0, v138
	v_rcp_f32_e32 v138, v138
	s_nop 0
	v_fma_f32 v135, v138, v254, v135
	v_mul_f32_e32 v138, 0xbfb8aa3b, v8
	v_exp_f32_e32 v138, v138
	v_log_f32_e32 v135, v135
	v_add_f32_e32 v138, 1.0, v138
	v_rcp_f32_e32 v138, v138
	s_nop 0
	v_fma_f32 v136, v138, v168, v136
	v_mul_f32_e32 v138, 0xbfb8aa3b, v9
	v_exp_f32_e32 v138, v138
	v_log_f32_e32 v136, v136
	v_add_f32_e32 v138, 1.0, v138
	v_rcp_f32_e32 v138, v138
	s_nop 0
	v_fmac_f32_e32 v137, v138, v253
	v_mul_f32_e32 v138, 0xbfb8aa3b, v2
	v_exp_f32_e32 v138, v138
	v_log_f32_e32 v137, v137
	v_add_f32_e32 v138, 1.0, v138
	v_rcp_f32_e32 v138, v138
	s_nop 0
	v_fma_f32 v130, v138, v251, v130
	v_log_f32_e32 v138, v130
	v_mul_f32_e32 v130, 0xbfb8aa3b, v3
	v_exp_f32_e32 v130, v130
	s_nop 0
	v_add_f32_e32 v130, 1.0, v130
	v_rcp_f32_e32 v130, v130
	s_nop 0
	v_fma_f32 v130, v130, v250, v131
	v_log_f32_e32 v139, v130
	v_mul_f32_e32 v130, 0xbfb8aa3b, v4
	v_exp_f32_e32 v130, v130
	v_cvt_pk_bf16_f32 v131, v136, v137
	v_add_f32_e32 v130, 1.0, v130
	v_rcp_f32_e32 v130, v130
	s_nop 0
	v_fma_f32 v130, v130, v252, v132
	v_log_f32_e32 v140, v130
	v_mul_f32_e32 v130, 0xbfb8aa3b, v5
	v_exp_f32_e32 v130, v130
	v_cvt_pk_bf16_f32 v132, v138, v139
	v_add_f32_e32 v130, 1.0, v130
	v_rcp_f32_e32 v130, v130
	s_nop 0
	v_fmac_f32_e32 v133, v130, v176
	v_log_f32_e32 v133, v133
	v_cvt_pk_bf16_f32 v130, v134, v135
	v_cvt_pk_bf16_f32 v133, v140, v133
	global_store_dwordx4 v[142:143], v[130:133], off offset:256 sc1
.LBB0_164:
	s_andn2_b64 vcc, exec, s[62:63]
	s_cbranch_vccnz .LBB0_166
	s_lshl_b32 s2, s19, 8
	s_and_b32 s2, s2, 0x100
	s_or_b32 s2, s2, s85
	v_add_u32_e32 v130, s2, v174
	s_lshl_b32 s2, s18, 8
	s_add_i32 s2, s2, s84
	v_add_u32_e32 v132, s2, v173
	v_ashrrev_i32_e32 v133, 31, v132
	v_add_f32_e32 v131, 1.0, v248
	v_lshlrev_b64 v[136:137], 10, v[132:133]
	v_rcp_f32_e32 v132, v131
	v_add_f32_e32 v131, 1.0, v247
	v_rcp_f32_e32 v133, v131
	v_add_f32_e32 v131, 1.0, v246
	v_rcp_f32_e32 v134, v131
	v_add_f32_e32 v131, 1.0, v245
	v_rcp_f32_e32 v135, v131
	v_add_f32_e32 v131, 1.0, v244
	v_rcp_f32_e32 v138, v131
	v_add_f32_e32 v131, 1.0, v243
	v_rcp_f32_e32 v139, v131
	v_add_f32_e32 v131, 1.0, v242
	v_rcp_f32_e32 v140, v131
	v_add_f32_e32 v131, 1.0, v241
	v_rcp_f32_e32 v141, v131
	v_pk_mul_f32 v[132:133], v[126:127], v[132:133]
	v_pk_mul_f32 v[134:135], v[128:129], v[134:135]
	v_pk_mul_f32 v[138:139], v[122:123], v[138:139]
	v_pk_mul_f32 v[140:141], v[124:125], v[140:141]
	v_lshl_add_u64 v[136:137], s[24:25], 0, v[136:137]
	v_ashrrev_i32_e32 v131, 31, v130
	v_cvt_pk_bf16_f32 v132, v132, v133
	v_cvt_pk_bf16_f32 v133, v134, v135
	v_cvt_pk_bf16_f32 v134, v138, v139
	v_cvt_pk_bf16_f32 v135, v140, v141
	v_lshl_add_u64 v[130:131], v[130:131], 1, v[136:137]
	global_store_dwordx4 v[130:131], v[132:135], off sc1
	v_add_f32_e32 v136, 1.0, v236
	v_add_f32_e32 v137, 1.0, v235
	v_add_f32_e32 v132, 1.0, v240
	v_add_f32_e32 v133, 1.0, v239
	v_add_f32_e32 v134, 1.0, v238
	v_add_f32_e32 v135, 1.0, v237
	v_add_f32_e32 v138, 1.0, v234
	v_add_f32_e32 v139, 1.0, v233
	v_rcp_f32_e32 v132, v132
	v_rcp_f32_e32 v133, v133
	v_rcp_f32_e32 v134, v134
	v_rcp_f32_e32 v135, v135
	v_rcp_f32_e32 v136, v136
	v_rcp_f32_e32 v137, v137
	v_rcp_f32_e32 v138, v138
	v_rcp_f32_e32 v139, v139
	v_pk_mul_f32 v[132:133], v[118:119], v[132:133]
	v_pk_mul_f32 v[134:135], v[120:121], v[134:135]
	v_pk_mul_f32 v[136:137], v[110:111], v[136:137]
	v_pk_mul_f32 v[138:139], v[112:113], v[138:139]
	v_cvt_pk_bf16_f32 v132, v132, v133
	v_cvt_pk_bf16_f32 v133, v134, v135
	v_cvt_pk_bf16_f32 v134, v136, v137
	v_cvt_pk_bf16_f32 v135, v138, v139
	global_store_dwordx4 v[130:131], v[132:135], off offset:256 sc1
	v_add_f32_e32 v138, 1.0, v226
	v_add_f32_e32 v139, 1.0, v225
	v_add_f32_e32 v132, 1.0, v232
	v_add_f32_e32 v133, 1.0, v231
	v_add_f32_e32 v134, 1.0, v230
	v_add_f32_e32 v135, 1.0, v229
	v_rcp_f32_e32 v132, v132
	v_rcp_f32_e32 v133, v133
	v_rcp_f32_e32 v134, v134
	v_rcp_f32_e32 v135, v135
	v_add_f32_e32 v136, 1.0, v228
	v_add_f32_e32 v137, 1.0, v227
	v_rcp_f32_e32 v138, v138
	v_rcp_f32_e32 v139, v139
	v_rcp_f32_e32 v136, v136
	v_rcp_f32_e32 v137, v137
	v_pk_mul_f32 v[132:133], v[114:115], v[132:133]
	v_pk_mul_f32 v[134:135], v[116:117], v[134:135]
	v_pk_mul_f32 v[138:139], v[108:109], v[138:139]
	v_pk_mul_f32 v[136:137], v[106:107], v[136:137]
	v_cvt_pk_bf16_f32 v132, v132, v133
	v_cvt_pk_bf16_f32 v133, v134, v135
	v_cvt_pk_bf16_f32 v135, v138, v139
	v_add_co_u32_e32 v138, vcc, s75, v130
	v_cvt_pk_bf16_f32 v134, v136, v137
	s_nop 0
	v_addc_co_u32_e32 v139, vcc, 0, v131, vcc
	global_store_dwordx4 v[138:139], v[132:135], off sc1
	v_add_f32_e32 v138, 1.0, v220
	v_add_f32_e32 v139, 1.0, v219
	v_add_f32_e32 v132, 1.0, v224
	v_add_f32_e32 v133, 1.0, v223
	v_add_f32_e32 v134, 1.0, v222
	v_add_f32_e32 v135, 1.0, v221
	v_add_f32_e32 v140, 1.0, v218
	v_add_f32_e32 v141, 1.0, v217
	v_rcp_f32_e32 v132, v132
	v_rcp_f32_e32 v133, v133
	v_rcp_f32_e32 v134, v134
	v_rcp_f32_e32 v135, v135
	v_rcp_f32_e32 v138, v138
	v_rcp_f32_e32 v139, v139
	v_rcp_f32_e32 v140, v140
	v_rcp_f32_e32 v141, v141
	v_pk_mul_f32 v[132:133], v[102:103], v[132:133]
	v_pk_mul_f32 v[134:135], v[104:105], v[134:135]
	v_pk_mul_f32 v[138:139], v[94:95], v[138:139]
	v_pk_mul_f32 v[140:141], v[96:97], v[140:141]
	v_lshl_add_u64 v[136:137], v[130:131], 0, s[38:39]
	v_cvt_pk_bf16_f32 v132, v132, v133
	v_cvt_pk_bf16_f32 v133, v134, v135
	v_cvt_pk_bf16_f32 v134, v138, v139
	v_cvt_pk_bf16_f32 v135, v140, v141
	global_store_dwordx4 v[136:137], v[132:135], off offset:256 sc1
	v_add_f32_e32 v138, 1.0, v210
	v_add_f32_e32 v139, 1.0, v209
	v_add_f32_e32 v132, 1.0, v216
	v_add_f32_e32 v133, 1.0, v215
	v_add_f32_e32 v134, 1.0, v214
	v_add_f32_e32 v135, 1.0, v213
	v_rcp_f32_e32 v132, v132
	v_rcp_f32_e32 v133, v133
	v_rcp_f32_e32 v134, v134
	v_rcp_f32_e32 v135, v135
	v_add_f32_e32 v136, 1.0, v212
	v_add_f32_e32 v137, 1.0, v211
	v_rcp_f32_e32 v138, v138
	v_rcp_f32_e32 v139, v139
	v_rcp_f32_e32 v136, v136
	v_rcp_f32_e32 v137, v137
	v_pk_mul_f32 v[132:133], v[98:99], v[132:133]
	v_pk_mul_f32 v[134:135], v[100:101], v[134:135]
	v_pk_mul_f32 v[138:139], v[92:93], v[138:139]
	v_pk_mul_f32 v[136:137], v[90:91], v[136:137]
	v_cvt_pk_bf16_f32 v132, v132, v133
	v_cvt_pk_bf16_f32 v133, v134, v135
	v_cvt_pk_bf16_f32 v135, v138, v139
	v_add_co_u32_e32 v138, vcc, s92, v130
	v_cvt_pk_bf16_f32 v134, v136, v137
	s_nop 0
	v_addc_co_u32_e32 v139, vcc, 0, v131, vcc
	global_store_dwordx4 v[138:139], v[132:135], off sc1
	v_add_f32_e32 v138, 1.0, v204
	v_add_f32_e32 v139, 1.0, v203
	v_add_f32_e32 v132, 1.0, v208
	v_add_f32_e32 v133, 1.0, v207
	v_add_f32_e32 v134, 1.0, v206
	v_add_f32_e32 v135, 1.0, v205
	v_add_f32_e32 v140, 1.0, v202
	v_add_f32_e32 v141, 1.0, v201
	v_rcp_f32_e32 v132, v132
	v_rcp_f32_e32 v133, v133
	v_rcp_f32_e32 v134, v134
	v_rcp_f32_e32 v135, v135
	v_rcp_f32_e32 v138, v138
	v_rcp_f32_e32 v139, v139
	v_rcp_f32_e32 v140, v140
	v_rcp_f32_e32 v141, v141
	v_pk_mul_f32 v[132:133], v[86:87], v[132:133]
	v_pk_mul_f32 v[134:135], v[88:89], v[134:135]
	v_pk_mul_f32 v[138:139], v[78:79], v[138:139]
	v_pk_mul_f32 v[140:141], v[80:81], v[140:141]
	v_lshl_add_u64 v[136:137], v[130:131], 0, s[40:41]
	v_cvt_pk_bf16_f32 v132, v132, v133
	v_cvt_pk_bf16_f32 v133, v134, v135
	v_cvt_pk_bf16_f32 v134, v138, v139
	v_cvt_pk_bf16_f32 v135, v140, v141
	v_exp_f32_e32 v138, v194
	v_exp_f32_e32 v139, v193
	global_store_dwordx4 v[136:137], v[132:135], off offset:256 sc1
	v_exp_f32_e32 v137, v196
	v_add_f32_e32 v138, 1.0, v138
	v_add_f32_e32 v132, 1.0, v200
	v_add_f32_e32 v133, 1.0, v199
	v_add_f32_e32 v134, 1.0, v198
	v_add_f32_e32 v135, 1.0, v197
	v_add_f32_e32 v139, 1.0, v139
	v_rcp_f32_e32 v132, v132
	v_rcp_f32_e32 v133, v133
	v_rcp_f32_e32 v134, v134
	v_rcp_f32_e32 v135, v135
	v_add_f32_e32 v136, 1.0, v195
	v_add_f32_e32 v137, 1.0, v137
	v_rcp_f32_e32 v138, v138
	v_rcp_f32_e32 v139, v139
	v_rcp_f32_e32 v136, v136
	v_rcp_f32_e32 v137, v137
	v_pk_mul_f32 v[132:133], v[82:83], v[132:133]
	v_pk_mul_f32 v[134:135], v[84:85], v[134:135]
	v_pk_mul_f32 v[138:139], v[76:77], v[138:139]
	v_pk_mul_f32 v[136:137], v[74:75], v[136:137]
	v_cvt_pk_bf16_f32 v132, v132, v133
	v_cvt_pk_bf16_f32 v133, v134, v135
	v_cvt_pk_bf16_f32 v135, v138, v139
	v_add_co_u32_e32 v138, vcc, s97, v130
	v_cvt_pk_bf16_f32 v134, v136, v137
	v_exp_f32_e32 v140, v192
	v_addc_co_u32_e32 v139, vcc, 0, v131, vcc
	global_store_dwordx4 v[138:139], v[132:135], off sc1
	v_mul_f32_e32 v138, 0xbfb8aa3b, v66
	v_mul_f32_e32 v139, 0xbfb8aa3b, v67
	v_mul_f32_e32 v135, 0xbfb8aa3b, v73
	v_exp_f32_e32 v133, v191
	v_exp_f32_e32 v134, v190
	v_exp_f32_e32 v135, v135
	v_exp_f32_e32 v138, v138
	v_exp_f32_e32 v139, v139
	v_add_f32_e32 v132, 1.0, v140
	v_mul_f32_e32 v140, 0xbfb8aa3b, v68
	v_mul_f32_e32 v141, 0xbfb8aa3b, v69
	v_exp_f32_e32 v140, v140
	v_exp_f32_e32 v141, v141
	v_add_f32_e32 v133, 1.0, v133
	v_add_f32_e32 v134, 1.0, v134
	v_add_f32_e32 v135, 1.0, v135
	v_rcp_f32_e32 v132, v132
	v_rcp_f32_e32 v133, v133
	v_rcp_f32_e32 v134, v134
	v_rcp_f32_e32 v135, v135
	v_add_f32_e32 v138, 1.0, v138
	v_add_f32_e32 v139, 1.0, v139
	v_rcp_f32_e32 v138, v138
	v_rcp_f32_e32 v139, v139
	v_add_f32_e32 v140, 1.0, v140
	v_add_f32_e32 v141, 1.0, v141
	v_rcp_f32_e32 v140, v140
	v_rcp_f32_e32 v141, v141
	v_pk_mul_f32 v[132:133], v[70:71], v[132:133]
	v_pk_mul_f32 v[134:135], v[72:73], v[134:135]
	v_pk_mul_f32 v[138:139], v[66:67], v[138:139]
	v_cvt_pk_bf16_f32 v132, v132, v133
	v_cvt_pk_bf16_f32 v133, v134, v135
	v_mul_f32_e32 v135, 0xbfb8aa3b, v62
	v_cvt_pk_bf16_f32 v134, v138, v139
	v_exp_f32_e32 v138, v135
	v_pk_mul_f32 v[140:141], v[68:69], v[140:141]
	v_lshl_add_u64 v[136:137], v[130:131], 0, s[42:43]
	v_cvt_pk_bf16_f32 v135, v140, v141
	global_store_dwordx4 v[136:137], v[132:135], off offset:256 sc1
	v_mul_f32_e32 v139, 0xbfb8aa3b, v61
	v_exp_f32_e32 v139, v139
	v_mul_f32_e32 v132, 0xbfb8aa3b, v63
	v_exp_f32_e32 v133, v132
	v_add_f32_e32 v132, 1.0, v138
	v_mul_f32_e32 v134, 0xbfb8aa3b, v64
	v_mul_f32_e32 v135, 0xbfb8aa3b, v65
	v_mul_f32_e32 v138, 0xbfb8aa3b, v60
	v_exp_f32_e32 v134, v134
	v_exp_f32_e32 v135, v135
	v_exp_f32_e32 v138, v138
	v_mul_f32_e32 v136, 0xbfb8aa3b, v58
	v_mul_f32_e32 v137, 0xbfb8aa3b, v59
	v_exp_f32_e32 v136, v136
	v_exp_f32_e32 v137, v137
	v_add_f32_e32 v133, 1.0, v133
	v_add_f32_e32 v134, 1.0, v134
	v_add_f32_e32 v135, 1.0, v135
	v_add_f32_e32 v138, 1.0, v138
	v_add_f32_e32 v139, 1.0, v139
	v_rcp_f32_e32 v132, v132
	v_rcp_f32_e32 v133, v133
	v_rcp_f32_e32 v134, v134
	v_rcp_f32_e32 v135, v135
	v_rcp_f32_e32 v138, v138
	v_rcp_f32_e32 v139, v139
	v_add_f32_e32 v136, 1.0, v136
	v_add_f32_e32 v137, 1.0, v137
	v_rcp_f32_e32 v136, v136
	v_rcp_f32_e32 v137, v137
	v_pk_mul_f32 v[132:133], v[62:63], v[132:133]
	v_pk_mul_f32 v[134:135], v[64:65], v[134:135]
	v_pk_mul_f32 v[138:139], v[60:61], v[138:139]
	v_cvt_pk_bf16_f32 v132, v132, v133
	v_cvt_pk_bf16_f32 v133, v134, v135
	v_cvt_pk_bf16_f32 v135, v138, v139
	v_mul_f32_e32 v138, 0xbfb8aa3b, v54
	v_pk_mul_f32 v[136:137], v[58:59], v[136:137]
	v_exp_f32_e32 v140, v138
	v_add_co_u32_e32 v138, vcc, s66, v130
	v_cvt_pk_bf16_f32 v134, v136, v137
	s_nop 0
	v_addc_co_u32_e32 v139, vcc, 0, v131, vcc
	v_mul_f32_e32 v141, 0xbfb8aa3b, v55
	v_exp_f32_e32 v141, v141
	global_store_dwordx4 v[138:139], v[132:135], off sc1
	v_mul_f32_e32 v138, 0xbfb8aa3b, v46
	v_mul_f32_e32 v139, 0xbfb8aa3b, v47
	v_mul_f32_e32 v134, 0xbfb8aa3b, v56
	v_mul_f32_e32 v135, 0xbfb8aa3b, v57
	v_exp_f32_e32 v134, v134
	v_exp_f32_e32 v135, v135
	v_exp_f32_e32 v138, v138
	v_exp_f32_e32 v139, v139
	v_add_f32_e32 v132, 1.0, v140
	v_add_f32_e32 v133, 1.0, v141
	v_mul_f32_e32 v140, 0xbfb8aa3b, v48
	v_mul_f32_e32 v141, 0xbfb8aa3b, v49
	v_add_f32_e32 v134, 1.0, v134
	v_add_f32_e32 v135, 1.0, v135
	v_add_f32_e32 v138, 1.0, v138
	v_add_f32_e32 v139, 1.0, v139
	v_exp_f32_e32 v140, v140
	v_exp_f32_e32 v141, v141
	v_rcp_f32_e32 v132, v132
	v_rcp_f32_e32 v133, v133
	v_rcp_f32_e32 v134, v134
	v_rcp_f32_e32 v135, v135
	v_rcp_f32_e32 v138, v138
	v_rcp_f32_e32 v139, v139
	v_add_f32_e32 v140, 1.0, v140
	v_add_f32_e32 v141, 1.0, v141
	v_rcp_f32_e32 v140, v140
	v_rcp_f32_e32 v141, v141
	v_pk_mul_f32 v[132:133], v[54:55], v[132:133]
	v_pk_mul_f32 v[134:135], v[56:57], v[134:135]
	v_pk_mul_f32 v[138:139], v[46:47], v[138:139]
	v_cvt_pk_bf16_f32 v132, v132, v133
	v_cvt_pk_bf16_f32 v133, v134, v135
	v_cvt_pk_bf16_f32 v134, v138, v139
	v_mul_f32_e32 v138, 0xbfb8aa3b, v50
	v_mul_f32_e32 v139, 0xbfb8aa3b, v51
	v_exp_f32_e32 v138, v138
	v_exp_f32_e32 v139, v139
	v_pk_mul_f32 v[140:141], v[48:49], v[140:141]
	v_lshl_add_u64 v[136:137], v[130:131], 0, s[44:45]
	v_cvt_pk_bf16_f32 v135, v140, v141
	global_store_dwordx4 v[136:137], v[132:135], off offset:256 sc1
	v_mul_f32_e32 v136, 0xbfb8aa3b, v42
	v_mul_f32_e32 v137, 0xbfb8aa3b, v43
	v_add_f32_e32 v132, 1.0, v138
	v_add_f32_e32 v133, 1.0, v139
	v_mul_f32_e32 v134, 0xbfb8aa3b, v52
	v_mul_f32_e32 v135, 0xbfb8aa3b, v53
	v_mul_f32_e32 v138, 0xbfb8aa3b, v44
	v_mul_f32_e32 v139, 0xbfb8aa3b, v45
	v_exp_f32_e32 v134, v134
	v_exp_f32_e32 v135, v135
	v_exp_f32_e32 v138, v138
	v_exp_f32_e32 v139, v139
	v_exp_f32_e32 v136, v136
	v_exp_f32_e32 v137, v137
	v_add_f32_e32 v134, 1.0, v134
	v_add_f32_e32 v135, 1.0, v135
	v_add_f32_e32 v138, 1.0, v138
	v_add_f32_e32 v139, 1.0, v139
	v_rcp_f32_e32 v132, v132
	v_rcp_f32_e32 v133, v133
	v_rcp_f32_e32 v134, v134
	v_rcp_f32_e32 v135, v135
	v_add_f32_e32 v136, 1.0, v136
	v_add_f32_e32 v137, 1.0, v137
	v_rcp_f32_e32 v138, v138
	v_rcp_f32_e32 v139, v139
	v_rcp_f32_e32 v136, v136
	v_rcp_f32_e32 v137, v137
	v_pk_mul_f32 v[132:133], v[50:51], v[132:133]
	v_pk_mul_f32 v[134:135], v[52:53], v[134:135]
	v_pk_mul_f32 v[138:139], v[44:45], v[138:139]
	v_pk_mul_f32 v[136:137], v[42:43], v[136:137]
	v_cvt_pk_bf16_f32 v132, v132, v133
	v_cvt_pk_bf16_f32 v133, v134, v135
	v_cvt_pk_bf16_f32 v135, v138, v139
	v_add_co_u32_e32 v138, vcc, s53, v130
	v_cvt_pk_bf16_f32 v134, v136, v137
	s_nop 0
	v_addc_co_u32_e32 v139, vcc, 0, v131, vcc
	v_mul_f32_e32 v140, 0xbfb8aa3b, v38
	v_mul_f32_e32 v141, 0xbfb8aa3b, v39
	v_exp_f32_e32 v140, v140
	v_exp_f32_e32 v141, v141
	global_store_dwordx4 v[138:139], v[132:135], off sc1
	v_mul_f32_e32 v138, 0xbfb8aa3b, v30
	v_mul_f32_e32 v139, 0xbfb8aa3b, v31
	v_mul_f32_e32 v134, 0xbfb8aa3b, v40
	v_mul_f32_e32 v135, 0xbfb8aa3b, v41
	v_exp_f32_e32 v134, v134
	v_exp_f32_e32 v135, v135
	v_exp_f32_e32 v138, v138
	v_exp_f32_e32 v139, v139
	v_add_f32_e32 v132, 1.0, v140
	v_add_f32_e32 v133, 1.0, v141
	v_mul_f32_e32 v140, 0xbfb8aa3b, v32
	v_mul_f32_e32 v141, 0xbfb8aa3b, v33
	v_add_f32_e32 v134, 1.0, v134
	v_add_f32_e32 v135, 1.0, v135
	v_add_f32_e32 v138, 1.0, v138
	v_add_f32_e32 v139, 1.0, v139
	v_exp_f32_e32 v140, v140
	v_exp_f32_e32 v141, v141
	v_rcp_f32_e32 v132, v132
	v_rcp_f32_e32 v133, v133
	v_rcp_f32_e32 v134, v134
	v_rcp_f32_e32 v135, v135
	v_rcp_f32_e32 v138, v138
	v_rcp_f32_e32 v139, v139
	v_add_f32_e32 v140, 1.0, v140
	v_add_f32_e32 v141, 1.0, v141
	v_rcp_f32_e32 v140, v140
	v_rcp_f32_e32 v141, v141
	v_pk_mul_f32 v[132:133], v[38:39], v[132:133]
	v_pk_mul_f32 v[134:135], v[40:41], v[134:135]
	v_pk_mul_f32 v[138:139], v[30:31], v[138:139]
	v_cvt_pk_bf16_f32 v132, v132, v133
	v_cvt_pk_bf16_f32 v133, v134, v135
	v_cvt_pk_bf16_f32 v134, v138, v139
	v_mul_f32_e32 v138, 0xbfb8aa3b, v34
	v_mul_f32_e32 v139, 0xbfb8aa3b, v35
	v_exp_f32_e32 v138, v138
	v_exp_f32_e32 v139, v139
	v_pk_mul_f32 v[140:141], v[32:33], v[140:141]
	v_lshl_add_u64 v[136:137], v[130:131], 0, s[46:47]
	v_cvt_pk_bf16_f32 v135, v140, v141
	global_store_dwordx4 v[136:137], v[132:135], off offset:256 sc1
	v_mul_f32_e32 v136, 0xbfb8aa3b, v26
	v_mul_f32_e32 v137, 0xbfb8aa3b, v27
	v_add_f32_e32 v132, 1.0, v138
	v_add_f32_e32 v133, 1.0, v139
	v_mul_f32_e32 v134, 0xbfb8aa3b, v36
	v_mul_f32_e32 v135, 0xbfb8aa3b, v37
	v_mul_f32_e32 v138, 0xbfb8aa3b, v28
	v_mul_f32_e32 v139, 0xbfb8aa3b, v29
	v_exp_f32_e32 v134, v134
	v_exp_f32_e32 v135, v135
	v_exp_f32_e32 v138, v138
	v_exp_f32_e32 v139, v139
	v_exp_f32_e32 v136, v136
	v_exp_f32_e32 v137, v137
	v_add_f32_e32 v134, 1.0, v134
	v_add_f32_e32 v135, 1.0, v135
	v_add_f32_e32 v138, 1.0, v138
	v_add_f32_e32 v139, 1.0, v139
	v_rcp_f32_e32 v132, v132
	v_rcp_f32_e32 v133, v133
	v_rcp_f32_e32 v134, v134
	v_rcp_f32_e32 v135, v135
	v_add_f32_e32 v136, 1.0, v136
	v_add_f32_e32 v137, 1.0, v137
	v_rcp_f32_e32 v138, v138
	v_rcp_f32_e32 v139, v139
	v_rcp_f32_e32 v136, v136
	v_rcp_f32_e32 v137, v137
	v_pk_mul_f32 v[132:133], v[34:35], v[132:133]
	v_pk_mul_f32 v[134:135], v[36:37], v[134:135]
	v_pk_mul_f32 v[138:139], v[28:29], v[138:139]
	v_pk_mul_f32 v[136:137], v[26:27], v[136:137]
	v_cvt_pk_bf16_f32 v132, v132, v133
	v_cvt_pk_bf16_f32 v133, v134, v135
	v_cvt_pk_bf16_f32 v135, v138, v139
	v_add_co_u32_e32 v138, vcc, s68, v130
	v_cvt_pk_bf16_f32 v134, v136, v137
	s_nop 0
	v_addc_co_u32_e32 v139, vcc, 0, v131, vcc
	v_mul_f32_e32 v140, 0xbfb8aa3b, v22
	v_mul_f32_e32 v141, 0xbfb8aa3b, v23
	v_exp_f32_e32 v140, v140
	v_exp_f32_e32 v141, v141
	global_store_dwordx4 v[138:139], v[132:135], off sc1
	v_mul_f32_e32 v138, 0xbfb8aa3b, v14
	v_mul_f32_e32 v139, 0xbfb8aa3b, v15
	v_mul_f32_e32 v134, 0xbfb8aa3b, v24
	v_mul_f32_e32 v135, 0xbfb8aa3b, v25
	v_exp_f32_e32 v134, v134
	v_exp_f32_e32 v135, v135
	v_exp_f32_e32 v138, v138
	v_exp_f32_e32 v139, v139
	v_add_f32_e32 v132, 1.0, v140
	v_add_f32_e32 v133, 1.0, v141
	v_mul_f32_e32 v140, 0xbfb8aa3b, v16
	v_mul_f32_e32 v141, 0xbfb8aa3b, v17
	v_add_f32_e32 v134, 1.0, v134
	v_add_f32_e32 v135, 1.0, v135
	v_add_f32_e32 v138, 1.0, v138
	v_add_f32_e32 v139, 1.0, v139
	v_exp_f32_e32 v140, v140
	v_exp_f32_e32 v141, v141
	v_rcp_f32_e32 v132, v132
	v_rcp_f32_e32 v133, v133
	v_rcp_f32_e32 v134, v134
	v_rcp_f32_e32 v135, v135
	v_rcp_f32_e32 v138, v138
	v_rcp_f32_e32 v139, v139
	v_add_f32_e32 v140, 1.0, v140
	v_add_f32_e32 v141, 1.0, v141
	v_rcp_f32_e32 v140, v140
	v_rcp_f32_e32 v141, v141
	v_pk_mul_f32 v[132:133], v[22:23], v[132:133]
	v_pk_mul_f32 v[134:135], v[24:25], v[134:135]
	v_pk_mul_f32 v[138:139], v[14:15], v[138:139]
	v_cvt_pk_bf16_f32 v132, v132, v133
	v_cvt_pk_bf16_f32 v133, v134, v135
	v_cvt_pk_bf16_f32 v134, v138, v139
	v_mul_f32_e32 v138, 0xbfb8aa3b, v18
	v_mul_f32_e32 v139, 0xbfb8aa3b, v19
	v_exp_f32_e32 v138, v138
	v_exp_f32_e32 v139, v139
	v_pk_mul_f32 v[140:141], v[16:17], v[140:141]
	v_lshl_add_u64 v[136:137], v[130:131], 0, s[48:49]
	v_cvt_pk_bf16_f32 v135, v140, v141
	global_store_dwordx4 v[136:137], v[132:135], off offset:256 sc1
	v_mul_f32_e32 v136, 0xbfb8aa3b, v10
	v_mul_f32_e32 v137, 0xbfb8aa3b, v11
	v_add_f32_e32 v132, 1.0, v138
	v_add_f32_e32 v133, 1.0, v139
	v_mul_f32_e32 v134, 0xbfb8aa3b, v20
	v_mul_f32_e32 v135, 0xbfb8aa3b, v21
	v_mul_f32_e32 v138, 0xbfb8aa3b, v12
	v_mul_f32_e32 v139, 0xbfb8aa3b, v13
	v_exp_f32_e32 v134, v134
	v_exp_f32_e32 v135, v135
	v_exp_f32_e32 v138, v138
	v_exp_f32_e32 v139, v139
	v_exp_f32_e32 v136, v136
	v_exp_f32_e32 v137, v137
	v_add_f32_e32 v134, 1.0, v134
	v_add_f32_e32 v135, 1.0, v135
	v_add_f32_e32 v138, 1.0, v138
	v_add_f32_e32 v139, 1.0, v139
	v_rcp_f32_e32 v132, v132
	v_rcp_f32_e32 v133, v133
	v_rcp_f32_e32 v134, v134
	v_rcp_f32_e32 v135, v135
	v_rcp_f32_e32 v138, v138
	v_rcp_f32_e32 v139, v139
	v_add_f32_e32 v136, 1.0, v136
	v_add_f32_e32 v137, 1.0, v137
	v_rcp_f32_e32 v136, v136
	v_rcp_f32_e32 v137, v137
	v_pk_mul_f32 v[132:133], v[18:19], v[132:133]
	v_pk_mul_f32 v[134:135], v[20:21], v[134:135]
	v_pk_mul_f32 v[138:139], v[12:13], v[138:139]
	v_cvt_pk_bf16_f32 v132, v132, v133
	v_cvt_pk_bf16_f32 v133, v134, v135
	v_cvt_pk_bf16_f32 v135, v138, v139
	v_mul_f32_e32 v138, 0xbfb8aa3b, v6
	v_mul_f32_e32 v139, 0xbfb8aa3b, v7
	v_exp_f32_e32 v138, v138
	v_exp_f32_e32 v139, v139
	v_pk_mul_f32 v[136:137], v[10:11], v[136:137]
	s_nop 0
	v_cvt_pk_bf16_f32 v134, v136, v137
	v_lshl_add_u64 v[136:137], v[130:131], 0, s[50:51]
	v_add_co_u32_e32 v130, vcc, s4, v130
	s_nop 1
	v_addc_co_u32_e32 v131, vcc, 0, v131, vcc
	global_store_dwordx4 v[130:131], v[132:135], off sc1
	v_add_f32_e32 v130, 1.0, v138
	v_add_f32_e32 v131, 1.0, v139
	v_mul_f32_e32 v132, 0xbfb8aa3b, v8
	v_mul_f32_e32 v133, 0xbfb8aa3b, v9
	v_mul_f32_e32 v134, 0xbfb8aa3b, v2
	v_mul_f32_e32 v135, 0xbfb8aa3b, v3
	v_mul_f32_e32 v138, 0xbfb8aa3b, v4
	v_mul_f32_e32 v139, 0xbfb8aa3b, v5
	v_exp_f32_e32 v132, v132
	v_exp_f32_e32 v133, v133
	v_exp_f32_e32 v134, v134
	v_exp_f32_e32 v135, v135
	v_exp_f32_e32 v138, v138
	v_exp_f32_e32 v139, v139
	v_add_f32_e32 v132, 1.0, v132
	v_add_f32_e32 v133, 1.0, v133
	v_add_f32_e32 v134, 1.0, v134
	v_add_f32_e32 v135, 1.0, v135
	v_add_f32_e32 v138, 1.0, v138
	v_add_f32_e32 v139, 1.0, v139
	v_rcp_f32_e32 v130, v130
	v_rcp_f32_e32 v131, v131
	v_rcp_f32_e32 v132, v132
	v_rcp_f32_e32 v133, v133
	v_rcp_f32_e32 v134, v134
	v_rcp_f32_e32 v135, v135
	v_rcp_f32_e32 v138, v138
	v_rcp_f32_e32 v139, v139
	v_pk_mul_f32 v[130:131], v[6:7], v[130:131]
	v_pk_mul_f32 v[132:133], v[8:9], v[132:133]
	v_pk_mul_f32 v[134:135], v[2:3], v[134:135]
	v_pk_mul_f32 v[138:139], v[4:5], v[138:139]
	v_cvt_pk_bf16_f32 v130, v130, v131
	v_cvt_pk_bf16_f32 v131, v132, v133
	v_cvt_pk_bf16_f32 v132, v134, v135
	v_cvt_pk_bf16_f32 v133, v138, v139
	global_store_dwordx4 v[136:137], v[130:133], off offset:256 sc1

.LBB0_167:
	s_and_b64 vcc, exec, s[62:63]
	s_cbranch_vccz .LBB0_179
	s_cmp_gt_i32 s55, 1
	s_mov_b64 s[60:61], -1
	s_cbranch_scc0 .LBB0_174
	s_cmp_gt_i32 s55, 2
	s_cbranch_scc0 .LBB0_171
	s_lshl_b32 s2, s19, 8
	s_and_b32 s2, s2, 0x100
	s_or_b32 s2, s2, s85
	v_add_u32_e32 v134, s2, v174
	s_lshl_b32 s2, s18, 8
	s_add_i32 s2, s2, s84
	v_add_u32_e32 v130, s2, v173
	v_ashrrev_i32_e32 v131, 31, v130
	v_lshlrev_b64 v[136:137], 10, v[130:131]
	v_lshl_add_u64 v[136:137], s[26:27], 0, v[136:137]
	v_ashrrev_i32_e32 v135, 31, v134
	v_cvt_pk_bf16_f32 v130, v126, v127
	v_cvt_pk_bf16_f32 v131, v128, v129
	v_cvt_pk_bf16_f32 v132, v122, v123
	v_cvt_pk_bf16_f32 v133, v124, v125
	v_lshl_add_u64 v[134:135], v[134:135], 1, v[136:137]
	global_store_dwordx4 v[134:135], v[130:133], off sc1
	v_add_co_u32_e32 v138, vcc, s75, v134
	s_nop 0
	v_cvt_pk_bf16_f32 v130, v118, v119
	v_cvt_pk_bf16_f32 v131, v120, v121
	v_cvt_pk_bf16_f32 v132, v110, v111
	v_cvt_pk_bf16_f32 v133, v112, v113
	global_store_dwordx4 v[134:135], v[130:133], off offset:256 sc1
	v_addc_co_u32_e32 v139, vcc, 0, v135, vcc
	s_nop 0
	v_cvt_pk_bf16_f32 v130, v114, v115
	v_cvt_pk_bf16_f32 v131, v116, v117
	v_cvt_pk_bf16_f32 v132, v106, v107
	v_cvt_pk_bf16_f32 v133, v108, v109
	v_lshl_add_u64 v[136:137], v[134:135], 0, s[38:39]
	global_store_dwordx4 v[138:139], v[130:133], off sc1
	v_add_co_u32_e32 v138, vcc, s92, v134
	s_nop 0
	v_cvt_pk_bf16_f32 v130, v102, v103
	v_cvt_pk_bf16_f32 v131, v104, v105
	v_cvt_pk_bf16_f32 v132, v94, v95
	v_cvt_pk_bf16_f32 v133, v96, v97
	global_store_dwordx4 v[136:137], v[130:133], off offset:256 sc1
	v_addc_co_u32_e32 v139, vcc, 0, v135, vcc
	s_nop 0
	v_cvt_pk_bf16_f32 v130, v98, v99
	v_cvt_pk_bf16_f32 v131, v100, v101
	v_cvt_pk_bf16_f32 v132, v90, v91
	v_cvt_pk_bf16_f32 v133, v92, v93
	v_lshl_add_u64 v[136:137], v[134:135], 0, s[40:41]
	global_store_dwordx4 v[138:139], v[130:133], off sc1
	v_add_co_u32_e32 v138, vcc, s97, v134
	s_nop 0
	v_cvt_pk_bf16_f32 v130, v86, v87
	v_cvt_pk_bf16_f32 v131, v88, v89
	v_cvt_pk_bf16_f32 v132, v78, v79
	v_cvt_pk_bf16_f32 v133, v80, v81
	global_store_dwordx4 v[136:137], v[130:133], off offset:256 sc1
	v_addc_co_u32_e32 v139, vcc, 0, v135, vcc
	s_nop 0
	v_cvt_pk_bf16_f32 v130, v82, v83
	v_cvt_pk_bf16_f32 v131, v84, v85
	v_cvt_pk_bf16_f32 v132, v74, v75
	v_cvt_pk_bf16_f32 v133, v76, v77
	v_lshl_add_u64 v[136:137], v[134:135], 0, s[42:43]
	global_store_dwordx4 v[138:139], v[130:133], off sc1
	v_add_co_u32_e32 v138, vcc, s66, v134
	s_nop 0
	v_cvt_pk_bf16_f32 v130, v70, v71
	v_cvt_pk_bf16_f32 v131, v72, v73
	v_cvt_pk_bf16_f32 v132, v66, v67
	v_cvt_pk_bf16_f32 v133, v68, v69
	global_store_dwordx4 v[136:137], v[130:133], off offset:256 sc1
	v_addc_co_u32_e32 v139, vcc, 0, v135, vcc
	s_nop 0
	v_cvt_pk_bf16_f32 v130, v62, v63
	v_cvt_pk_bf16_f32 v131, v64, v65
	v_cvt_pk_bf16_f32 v132, v58, v59
	v_cvt_pk_bf16_f32 v133, v60, v61
	v_lshl_add_u64 v[136:137], v[134:135], 0, s[44:45]
	global_store_dwordx4 v[138:139], v[130:133], off sc1
	v_add_co_u32_e32 v138, vcc, s53, v134
	s_nop 0
	v_cvt_pk_bf16_f32 v130, v54, v55
	v_cvt_pk_bf16_f32 v131, v56, v57
	v_cvt_pk_bf16_f32 v132, v46, v47
	v_cvt_pk_bf16_f32 v133, v48, v49
	global_store_dwordx4 v[136:137], v[130:133], off offset:256 sc1
	v_addc_co_u32_e32 v139, vcc, 0, v135, vcc
	s_nop 0
	v_cvt_pk_bf16_f32 v130, v50, v51
	v_cvt_pk_bf16_f32 v131, v52, v53
	v_cvt_pk_bf16_f32 v132, v42, v43
	v_cvt_pk_bf16_f32 v133, v44, v45
	v_lshl_add_u64 v[136:137], v[134:135], 0, s[46:47]
	global_store_dwordx4 v[138:139], v[130:133], off sc1
	v_add_co_u32_e32 v138, vcc, s68, v134
	s_nop 0
	v_cvt_pk_bf16_f32 v130, v38, v39
	v_cvt_pk_bf16_f32 v131, v40, v41
	v_cvt_pk_bf16_f32 v132, v30, v31
	v_cvt_pk_bf16_f32 v133, v32, v33
	global_store_dwordx4 v[136:137], v[130:133], off offset:256 sc1
	v_addc_co_u32_e32 v139, vcc, 0, v135, vcc
	s_nop 0
	v_cvt_pk_bf16_f32 v130, v34, v35
	v_cvt_pk_bf16_f32 v131, v36, v37
	v_cvt_pk_bf16_f32 v132, v26, v27
	v_cvt_pk_bf16_f32 v133, v28, v29
	v_lshl_add_u64 v[136:137], v[134:135], 0, s[48:49]
	global_store_dwordx4 v[138:139], v[130:133], off sc1
	s_mov_b64 s[60:61], 0
	s_nop 0
	v_cvt_pk_bf16_f32 v130, v22, v23
	v_cvt_pk_bf16_f32 v131, v24, v25
	v_cvt_pk_bf16_f32 v132, v14, v15
	v_cvt_pk_bf16_f32 v133, v16, v17
	global_store_dwordx4 v[136:137], v[130:133], off offset:256 sc1
	v_lshl_add_u64 v[136:137], v[134:135], 0, s[50:51]
	v_add_co_u32_e32 v134, vcc, s4, v134
	v_cvt_pk_bf16_f32 v130, v18, v19
	v_cvt_pk_bf16_f32 v131, v20, v21
	v_cvt_pk_bf16_f32 v132, v10, v11
	v_cvt_pk_bf16_f32 v133, v12, v13
	v_addc_co_u32_e32 v135, vcc, 0, v135, vcc
	global_store_dwordx4 v[134:135], v[130:133], off sc1
	s_nop 1
	v_cvt_pk_bf16_f32 v130, v6, v7
	v_cvt_pk_bf16_f32 v131, v8, v9
	v_cvt_pk_bf16_f32 v132, v2, v3
	v_cvt_pk_bf16_f32 v133, v4, v5
	global_store_dwordx4 v[136:137], v[130:133], off offset:256 sc1
.LBB0_171:
	s_andn2_b64 vcc, exec, s[60:61]
	s_cbranch_vccnz .LBB0_173
	v_add_u32_e32 v130, s85, v174
	v_lshl_add_u32 v138, s18, 8, v130
	v_ashrrev_i32_e32 v131, 3, v138
	s_lshl_b32 s2, s19, 8
	v_and_b32_e32 v131, 0xfffffe00, v131
	s_and_b32 s2, s2, 0x100
	v_add_u32_e32 v140, s84, v173
	v_or_b32_e32 v141, s2, v131
	v_add_u32_e32 v142, v141, v140
	v_lshrrev_b32_e32 v144, 6, v138
	v_and_b32_e32 v139, 56, v130
	v_bfi_b32 v130, s5, v142, v144
	v_ashrrev_i32_e32 v131, 31, v130
	v_lshlrev_b64 v[130:131], 13, v[130:131]
	v_lshlrev_b32_e32 v136, 7, v173
	v_lshl_add_u64 v[130:131], s[28:29], 0, v[130:131]
	v_and_b32_e32 v158, 0x1f80, v136
	v_lshl_add_u64 v[136:137], v[130:131], 0, v[158:159]
	v_lshlrev_b32_e32 v130, 1, v139
	v_mov_b32_e32 v131, v159
	v_cvt_pk_bf16_f32 v132, v126, v127
	v_cvt_pk_bf16_f32 v133, v128, v129
	v_cvt_pk_bf16_f32 v134, v122, v123
	v_cvt_pk_bf16_f32 v135, v124, v125
	v_lshl_add_u64 v[136:137], v[136:137], 0, v[130:131]
	global_store_dwordx4 v[136:137], v[132:135], off sc1
	v_add_u32_e32 v136, 0x80, v138
	v_lshrrev_b32_e32 v164, 6, v136
	v_bfe_u32 v165, v136, 6, 6
	v_bfi_b32 v136, s5, v142, v164
	v_ashrrev_i32_e32 v137, 31, v136
	v_lshlrev_b64 v[136:137], 13, v[136:137]
	v_lshl_add_u64 v[136:137], s[28:29], 0, v[136:137]
	v_bfe_u32 v145, v138, 6, 6
	v_lshl_add_u64 v[136:137], v[136:137], 0, v[158:159]
	v_add_u32_e32 v138, 16, v140
	v_and_b32_e32 v143, 0xffffffc0, v142
	v_cvt_pk_bf16_f32 v132, v118, v119
	v_cvt_pk_bf16_f32 v133, v120, v121
	v_cvt_pk_bf16_f32 v134, v110, v111
	v_cvt_pk_bf16_f32 v135, v112, v113
	v_lshl_add_u64 v[136:137], v[136:137], 0, v[130:131]
	v_add_u32_e32 v142, v141, v138
	global_store_dwordx4 v[136:137], v[132:135], off sc1
	v_bfi_b32 v136, s5, v142, v144
	v_ashrrev_i32_e32 v137, 31, v136
	v_lshlrev_b64 v[136:137], 13, v[136:137]
	v_lshlrev_b32_e32 v138, 7, v138
	v_lshl_add_u64 v[136:137], s[28:29], 0, v[136:137]
	v_and_b32_e32 v138, 0x1f80, v138
	v_mov_b32_e32 v139, v159
	v_lshl_add_u64 v[136:137], v[136:137], 0, v[138:139]
	v_cvt_pk_bf16_f32 v132, v114, v115
	v_cvt_pk_bf16_f32 v133, v116, v117
	v_cvt_pk_bf16_f32 v134, v106, v107
	v_cvt_pk_bf16_f32 v135, v108, v109
	v_lshl_add_u64 v[136:137], v[136:137], 0, v[130:131]
	global_store_dwordx4 v[136:137], v[132:135], off sc1
	v_bfi_b32 v136, s5, v142, v164
	v_ashrrev_i32_e32 v137, 31, v136
	v_lshlrev_b64 v[136:137], 13, v[136:137]
	v_lshl_add_u64 v[136:137], s[28:29], 0, v[136:137]
	v_lshl_add_u64 v[136:137], v[136:137], 0, v[138:139]
	v_add_u32_e32 v138, 32, v140
	v_cvt_pk_bf16_f32 v132, v102, v103
	v_cvt_pk_bf16_f32 v133, v104, v105
	v_cvt_pk_bf16_f32 v134, v94, v95
	v_cvt_pk_bf16_f32 v135, v96, v97
	v_lshl_add_u64 v[136:137], v[136:137], 0, v[130:131]
	v_add_u32_e32 v142, v141, v138
	global_store_dwordx4 v[136:137], v[132:135], off sc1
	v_bfi_b32 v136, s5, v142, v144
	v_ashrrev_i32_e32 v137, 31, v136
	v_lshlrev_b64 v[136:137], 13, v[136:137]
	v_lshlrev_b32_e32 v138, 7, v138
	v_lshl_add_u64 v[136:137], s[28:29], 0, v[136:137]
	v_and_b32_e32 v138, 0x1f80, v138
	v_lshl_add_u64 v[136:137], v[136:137], 0, v[138:139]
	v_cvt_pk_bf16_f32 v132, v98, v99
	v_cvt_pk_bf16_f32 v133, v100, v101
	v_cvt_pk_bf16_f32 v134, v90, v91
	v_cvt_pk_bf16_f32 v135, v92, v93
	v_lshl_add_u64 v[136:137], v[136:137], 0, v[130:131]
	global_store_dwordx4 v[136:137], v[132:135], off sc1
	v_bfi_b32 v136, s5, v142, v164
	v_ashrrev_i32_e32 v137, 31, v136
	v_lshlrev_b64 v[136:137], 13, v[136:137]
	v_lshl_add_u64 v[136:137], s[28:29], 0, v[136:137]
	v_lshl_add_u64 v[136:137], v[136:137], 0, v[138:139]
	v_add_u32_e32 v138, 48, v140
	v_cvt_pk_bf16_f32 v132, v86, v87
	v_cvt_pk_bf16_f32 v133, v88, v89
	v_cvt_pk_bf16_f32 v134, v78, v79
	v_cvt_pk_bf16_f32 v135, v80, v81
	v_lshl_add_u64 v[136:137], v[136:137], 0, v[130:131]
	v_add_u32_e32 v142, v141, v138
	global_store_dwordx4 v[136:137], v[132:135], off sc1
	v_bfi_b32 v136, s5, v142, v144
	v_ashrrev_i32_e32 v137, 31, v136
	v_lshlrev_b64 v[136:137], 13, v[136:137]
	v_lshlrev_b32_e32 v138, 7, v138
	v_lshl_add_u64 v[136:137], s[28:29], 0, v[136:137]
	v_and_b32_e32 v138, 0x1f80, v138
	v_lshl_add_u64 v[136:137], v[136:137], 0, v[138:139]
	v_cvt_pk_bf16_f32 v132, v82, v83
	v_cvt_pk_bf16_f32 v133, v84, v85
	v_cvt_pk_bf16_f32 v134, v74, v75
	v_cvt_pk_bf16_f32 v135, v76, v77
	v_lshl_add_u64 v[136:137], v[136:137], 0, v[130:131]
	global_store_dwordx4 v[136:137], v[132:135], off sc1
	v_bfi_b32 v136, s5, v142, v164
	v_ashrrev_i32_e32 v137, 31, v136
	v_lshlrev_b64 v[136:137], 13, v[136:137]
	v_lshl_add_u64 v[136:137], s[28:29], 0, v[136:137]
	v_lshl_add_u64 v[136:137], v[136:137], 0, v[138:139]
	v_cvt_pk_bf16_f32 v132, v70, v71
	v_cvt_pk_bf16_f32 v133, v72, v73
	v_cvt_pk_bf16_f32 v134, v66, v67
	v_cvt_pk_bf16_f32 v135, v68, v69
	v_lshl_add_u64 v[136:137], v[136:137], 0, v[130:131]
	v_add_u32_e32 v138, 0x80, v143
	global_store_dwordx4 v[136:137], v[132:135], off sc1
	v_or_b32_e32 v136, v145, v138
	v_ashrrev_i32_e32 v137, 31, v136
	v_lshlrev_b64 v[136:137], 13, v[136:137]
	v_lshl_add_u64 v[136:137], s[28:29], 0, v[136:137]
	v_lshl_add_u64 v[136:137], v[136:137], 0, v[158:159]
	v_cvt_pk_bf16_f32 v132, v62, v63
	v_cvt_pk_bf16_f32 v133, v64, v65
	v_cvt_pk_bf16_f32 v134, v58, v59
	v_cvt_pk_bf16_f32 v135, v60, v61
	v_lshl_add_u64 v[136:137], v[136:137], 0, v[130:131]
	global_store_dwordx4 v[136:137], v[132:135], off sc1
	v_or_b32_e32 v136, v165, v138
	v_ashrrev_i32_e32 v137, 31, v136
	v_lshlrev_b64 v[136:137], 13, v[136:137]
	v_lshl_add_u64 v[136:137], s[28:29], 0, v[136:137]
	v_lshl_add_u64 v[136:137], v[136:137], 0, v[158:159]
	v_add_u32_e32 v138, 0x90, v140
	v_cvt_pk_bf16_f32 v132, v54, v55
	v_cvt_pk_bf16_f32 v133, v56, v57
	v_cvt_pk_bf16_f32 v134, v46, v47
	v_cvt_pk_bf16_f32 v135, v48, v49
	v_lshl_add_u64 v[136:137], v[136:137], 0, v[130:131]
	v_add_u32_e32 v139, v141, v138
	global_store_dwordx4 v[136:137], v[132:135], off sc1
	v_bfi_b32 v136, s5, v139, v144
	v_ashrrev_i32_e32 v137, 31, v136
	v_lshlrev_b64 v[136:137], 13, v[136:137]
	v_lshlrev_b32_e32 v138, 7, v138
	v_lshl_add_u64 v[136:137], s[28:29], 0, v[136:137]
	v_and_b32_e32 v158, 0x1f80, v138
	v_lshl_add_u64 v[136:137], v[136:137], 0, v[158:159]
	v_cvt_pk_bf16_f32 v132, v50, v51
	v_cvt_pk_bf16_f32 v133, v52, v53
	v_cvt_pk_bf16_f32 v134, v42, v43
	v_cvt_pk_bf16_f32 v135, v44, v45
	v_lshl_add_u64 v[136:137], v[136:137], 0, v[130:131]
	global_store_dwordx4 v[136:137], v[132:135], off sc1
	v_bfi_b32 v136, s5, v139, v164
	v_ashrrev_i32_e32 v137, 31, v136
	v_lshlrev_b64 v[136:137], 13, v[136:137]
	v_lshl_add_u64 v[136:137], s[28:29], 0, v[136:137]
	v_lshl_add_u64 v[136:137], v[136:137], 0, v[158:159]
	v_add_u32_e32 v138, 0xa0, v140
	v_cvt_pk_bf16_f32 v132, v38, v39
	v_cvt_pk_bf16_f32 v133, v40, v41
	v_cvt_pk_bf16_f32 v134, v30, v31
	v_cvt_pk_bf16_f32 v135, v32, v33
	v_lshl_add_u64 v[136:137], v[136:137], 0, v[130:131]
	v_add_u32_e32 v139, v141, v138
	global_store_dwordx4 v[136:137], v[132:135], off sc1
	v_bfi_b32 v136, s5, v139, v144
	v_ashrrev_i32_e32 v137, 31, v136
	v_lshlrev_b64 v[136:137], 13, v[136:137]
	v_lshlrev_b32_e32 v138, 7, v138
	v_lshl_add_u64 v[136:137], s[28:29], 0, v[136:137]
	v_and_b32_e32 v158, 0x1f80, v138
	v_lshl_add_u64 v[136:137], v[136:137], 0, v[158:159]
	v_cvt_pk_bf16_f32 v132, v34, v35
	v_cvt_pk_bf16_f32 v133, v36, v37
	v_cvt_pk_bf16_f32 v134, v26, v27
	v_cvt_pk_bf16_f32 v135, v28, v29
	v_lshl_add_u64 v[136:137], v[136:137], 0, v[130:131]
	global_store_dwordx4 v[136:137], v[132:135], off sc1
	v_bfi_b32 v136, s5, v139, v164
	v_ashrrev_i32_e32 v137, 31, v136
	v_lshlrev_b64 v[136:137], 13, v[136:137]
	v_lshl_add_u64 v[136:137], s[28:29], 0, v[136:137]
	v_lshl_add_u64 v[136:137], v[136:137], 0, v[158:159]
	v_add_u32_e32 v138, 0xb0, v140
	v_cvt_pk_bf16_f32 v132, v22, v23
	v_cvt_pk_bf16_f32 v133, v24, v25
	v_cvt_pk_bf16_f32 v134, v14, v15
	v_cvt_pk_bf16_f32 v135, v16, v17
	v_lshl_add_u64 v[136:137], v[136:137], 0, v[130:131]
	v_add_u32_e32 v139, v141, v138
	global_store_dwordx4 v[136:137], v[132:135], off sc1
	v_bfi_b32 v136, s5, v139, v144
	v_ashrrev_i32_e32 v137, 31, v136
	v_lshlrev_b64 v[136:137], 13, v[136:137]
	v_lshlrev_b32_e32 v138, 7, v138
	v_lshl_add_u64 v[136:137], s[28:29], 0, v[136:137]
	v_and_b32_e32 v158, 0x1f80, v138
	v_lshl_add_u64 v[136:137], v[136:137], 0, v[158:159]
	v_cvt_pk_bf16_f32 v132, v18, v19
	v_cvt_pk_bf16_f32 v133, v20, v21
	v_cvt_pk_bf16_f32 v134, v10, v11
	v_cvt_pk_bf16_f32 v135, v12, v13
	v_lshl_add_u64 v[136:137], v[136:137], 0, v[130:131]
	global_store_dwordx4 v[136:137], v[132:135], off sc1
	v_bfi_b32 v136, s5, v139, v164
	v_ashrrev_i32_e32 v137, 31, v136
	v_lshlrev_b64 v[136:137], 13, v[136:137]
	v_lshl_add_u64 v[136:137], s[28:29], 0, v[136:137]
	v_lshl_add_u64 v[136:137], v[136:137], 0, v[158:159]
	v_cvt_pk_bf16_f32 v132, v6, v7
	v_cvt_pk_bf16_f32 v133, v8, v9
	v_cvt_pk_bf16_f32 v134, v2, v3
	v_cvt_pk_bf16_f32 v135, v4, v5
	v_lshl_add_u64 v[130:131], v[136:137], 0, v[130:131]
	global_store_dwordx4 v[130:131], v[132:135], off sc1

.LBB0_174:
	s_andn2_b64 vcc, exec, s[60:61]
	s_mov_b64 s[60:61], 0
	s_cbranch_vccnz .LBB0_179
	s_cmp_gt_i32 s55, 0
	s_mov_b64 s[60:61], -1
	s_cbranch_scc0 .LBB0_177
	s_lshl_b32 s2, s19, 8
	s_and_b32 s2, s2, 0x100
	s_or_b32 s2, s2, s85
	v_add_u32_e32 v138, s2, v174
	s_lshl_b32 s2, s18, 8
	s_add_i32 s2, s2, s84
	v_add_u32_e32 v139, s2, v173
	v_ashrrev_i32_e32 v130, 9, v139
	v_and_b32_e32 v141, -8, v130
	v_ashrrev_i32_e32 v142, 6, v138
	v_add_u32_e32 v130, v141, v142
	v_ashrrev_i32_e32 v131, 31, v130
	v_lshlrev_b64 v[130:131], 19, v[130:131]
	v_lshlrev_b32_e32 v136, 7, v139
	v_and_b32_e32 v140, 56, v138
	v_lshl_add_u64 v[130:131], s[30:31], 0, v[130:131]
	v_and_b32_e32 v158, 0x7ff80, v136
	v_lshl_add_u64 v[136:137], v[130:131], 0, v[158:159]
	v_lshlrev_b32_e32 v130, 1, v140
	v_mov_b32_e32 v131, v159
	v_cvt_pk_bf16_f32 v132, v126, v127
	v_cvt_pk_bf16_f32 v133, v128, v129
	v_cvt_pk_bf16_f32 v134, v122, v123
	v_cvt_pk_bf16_f32 v135, v124, v125
	v_lshl_add_u64 v[136:137], v[136:137], 0, v[130:131]
	global_store_dwordx4 v[136:137], v[132:135], off sc1
	v_add_u32_e32 v136, 0x80, v138
	v_ashrrev_i32_e32 v138, 6, v136
	v_add_u32_e32 v136, v138, v141
	v_ashrrev_i32_e32 v137, 31, v136
	v_lshlrev_b64 v[136:137], 19, v[136:137]
	v_lshl_add_u64 v[136:137], s[30:31], 0, v[136:137]
	v_lshl_add_u64 v[136:137], v[136:137], 0, v[158:159]
	v_cvt_pk_bf16_f32 v132, v118, v119
	v_cvt_pk_bf16_f32 v133, v120, v121
	v_cvt_pk_bf16_f32 v134, v110, v111
	v_cvt_pk_bf16_f32 v135, v112, v113
	v_lshl_add_u64 v[136:137], v[136:137], 0, v[130:131]
	v_add_u32_e32 v140, 16, v139
	global_store_dwordx4 v[136:137], v[132:135], off sc1
	s_mov_b64 s[60:61], 0
	s_nop 0
	v_ashrrev_i32_e32 v132, 9, v140
	v_and_b32_e32 v141, -8, v132
	v_add_u32_e32 v136, v141, v142
	v_ashrrev_i32_e32 v137, 31, v136
	v_lshlrev_b64 v[136:137], 19, v[136:137]
	v_lshlrev_b32_e32 v140, 7, v140
	v_lshl_add_u64 v[136:137], s[30:31], 0, v[136:137]
	v_and_b32_e32 v158, 0x7ff80, v140
	v_lshl_add_u64 v[136:137], v[136:137], 0, v[158:159]
	v_cvt_pk_bf16_f32 v132, v114, v115
	v_cvt_pk_bf16_f32 v133, v116, v117
	v_cvt_pk_bf16_f32 v134, v106, v107
	v_cvt_pk_bf16_f32 v135, v108, v109
	v_lshl_add_u64 v[136:137], v[136:137], 0, v[130:131]
	global_store_dwordx4 v[136:137], v[132:135], off sc1
	v_add_u32_e32 v136, v141, v138
	v_ashrrev_i32_e32 v137, 31, v136
	v_lshlrev_b64 v[136:137], 19, v[136:137]
	v_lshl_add_u64 v[136:137], s[30:31], 0, v[136:137]
	v_lshl_add_u64 v[136:137], v[136:137], 0, v[158:159]
	v_cvt_pk_bf16_f32 v132, v102, v103
	v_cvt_pk_bf16_f32 v133, v104, v105
	v_cvt_pk_bf16_f32 v134, v94, v95
	v_cvt_pk_bf16_f32 v135, v96, v97
	v_lshl_add_u64 v[136:137], v[136:137], 0, v[130:131]
	v_add_u32_e32 v140, 32, v139
	global_store_dwordx4 v[136:137], v[132:135], off sc1
	s_nop 1
	v_ashrrev_i32_e32 v132, 9, v140
	v_and_b32_e32 v141, -8, v132
	v_add_u32_e32 v136, v141, v142
	v_ashrrev_i32_e32 v137, 31, v136
	v_lshlrev_b64 v[136:137], 19, v[136:137]
	v_lshlrev_b32_e32 v140, 7, v140
	v_lshl_add_u64 v[136:137], s[30:31], 0, v[136:137]
	v_and_b32_e32 v158, 0x7ff80, v140
	v_lshl_add_u64 v[136:137], v[136:137], 0, v[158:159]
	v_cvt_pk_bf16_f32 v132, v98, v99
	v_cvt_pk_bf16_f32 v133, v100, v101
	v_cvt_pk_bf16_f32 v134, v90, v91
	v_cvt_pk_bf16_f32 v135, v92, v93
	v_lshl_add_u64 v[136:137], v[136:137], 0, v[130:131]
	global_store_dwordx4 v[136:137], v[132:135], off sc1
	v_add_u32_e32 v136, v141, v138
	v_ashrrev_i32_e32 v137, 31, v136
	v_lshlrev_b64 v[136:137], 19, v[136:137]
	v_lshl_add_u64 v[136:137], s[30:31], 0, v[136:137]
	v_lshl_add_u64 v[136:137], v[136:137], 0, v[158:159]
	v_cvt_pk_bf16_f32 v132, v86, v87
	v_cvt_pk_bf16_f32 v133, v88, v89
	v_cvt_pk_bf16_f32 v134, v78, v79
	v_cvt_pk_bf16_f32 v135, v80, v81
	v_lshl_add_u64 v[136:137], v[136:137], 0, v[130:131]
	v_add_u32_e32 v140, 48, v139
	global_store_dwordx4 v[136:137], v[132:135], off sc1
	s_nop 1
	v_ashrrev_i32_e32 v132, 9, v140
	v_and_b32_e32 v141, -8, v132
	v_add_u32_e32 v136, v141, v142
	v_ashrrev_i32_e32 v137, 31, v136
	v_lshlrev_b64 v[136:137], 19, v[136:137]
	v_lshlrev_b32_e32 v140, 7, v140
	v_lshl_add_u64 v[136:137], s[30:31], 0, v[136:137]
	v_and_b32_e32 v158, 0x7ff80, v140
	v_lshl_add_u64 v[136:137], v[136:137], 0, v[158:159]
	v_cvt_pk_bf16_f32 v132, v82, v83
	v_cvt_pk_bf16_f32 v133, v84, v85
	v_cvt_pk_bf16_f32 v134, v74, v75
	v_cvt_pk_bf16_f32 v135, v76, v77
	v_lshl_add_u64 v[136:137], v[136:137], 0, v[130:131]
	global_store_dwordx4 v[136:137], v[132:135], off sc1
	v_add_u32_e32 v136, v141, v138
	v_ashrrev_i32_e32 v137, 31, v136
	v_lshlrev_b64 v[136:137], 19, v[136:137]
	v_lshl_add_u64 v[136:137], s[30:31], 0, v[136:137]
	v_lshl_add_u64 v[136:137], v[136:137], 0, v[158:159]
	v_cvt_pk_bf16_f32 v132, v70, v71
	v_cvt_pk_bf16_f32 v133, v72, v73
	v_cvt_pk_bf16_f32 v134, v66, v67
	v_cvt_pk_bf16_f32 v135, v68, v69
	v_lshl_add_u64 v[136:137], v[136:137], 0, v[130:131]
	v_add_u32_e32 v140, 0x80, v139
	global_store_dwordx4 v[136:137], v[132:135], off sc1
	s_nop 1
	v_ashrrev_i32_e32 v132, 9, v140
	v_and_b32_e32 v141, -8, v132
	v_add_u32_e32 v136, v141, v142
	v_ashrrev_i32_e32 v137, 31, v136
	v_lshlrev_b64 v[136:137], 19, v[136:137]
	v_lshlrev_b32_e32 v140, 7, v140
	v_lshl_add_u64 v[136:137], s[30:31], 0, v[136:137]
	v_and_b32_e32 v158, 0x7ff80, v140
	v_lshl_add_u64 v[136:137], v[136:137], 0, v[158:159]
	v_cvt_pk_bf16_f32 v132, v62, v63
	v_cvt_pk_bf16_f32 v133, v64, v65
	v_cvt_pk_bf16_f32 v134, v58, v59
	v_cvt_pk_bf16_f32 v135, v60, v61
	v_lshl_add_u64 v[136:137], v[136:137], 0, v[130:131]
	global_store_dwordx4 v[136:137], v[132:135], off sc1
	v_add_u32_e32 v136, v141, v138
	v_ashrrev_i32_e32 v137, 31, v136
	v_lshlrev_b64 v[136:137], 19, v[136:137]
	v_lshl_add_u64 v[136:137], s[30:31], 0, v[136:137]
	v_lshl_add_u64 v[136:137], v[136:137], 0, v[158:159]
	v_cvt_pk_bf16_f32 v132, v54, v55
	v_cvt_pk_bf16_f32 v133, v56, v57
	v_cvt_pk_bf16_f32 v134, v46, v47
	v_cvt_pk_bf16_f32 v135, v48, v49
	v_lshl_add_u64 v[136:137], v[136:137], 0, v[130:131]
	v_add_u32_e32 v140, 0x90, v139
	global_store_dwordx4 v[136:137], v[132:135], off sc1
	s_nop 1
	v_ashrrev_i32_e32 v132, 9, v140
	v_and_b32_e32 v141, -8, v132
	v_add_u32_e32 v136, v141, v142
	v_ashrrev_i32_e32 v137, 31, v136
	v_lshlrev_b64 v[136:137], 19, v[136:137]
	v_lshlrev_b32_e32 v140, 7, v140
	v_lshl_add_u64 v[136:137], s[30:31], 0, v[136:137]
	v_and_b32_e32 v158, 0x7ff80, v140
	v_lshl_add_u64 v[136:137], v[136:137], 0, v[158:159]
	v_cvt_pk_bf16_f32 v132, v50, v51
	v_cvt_pk_bf16_f32 v133, v52, v53
	v_cvt_pk_bf16_f32 v134, v42, v43
	v_cvt_pk_bf16_f32 v135, v44, v45
	v_lshl_add_u64 v[136:137], v[136:137], 0, v[130:131]
	global_store_dwordx4 v[136:137], v[132:135], off sc1
	v_add_u32_e32 v136, v141, v138
	v_ashrrev_i32_e32 v137, 31, v136
	v_lshlrev_b64 v[136:137], 19, v[136:137]
	v_lshl_add_u64 v[136:137], s[30:31], 0, v[136:137]
	v_lshl_add_u64 v[136:137], v[136:137], 0, v[158:159]
	v_cvt_pk_bf16_f32 v132, v38, v39
	v_cvt_pk_bf16_f32 v133, v40, v41
	v_cvt_pk_bf16_f32 v134, v30, v31
	v_cvt_pk_bf16_f32 v135, v32, v33
	v_lshl_add_u64 v[136:137], v[136:137], 0, v[130:131]
	v_add_u32_e32 v140, 0xa0, v139
	global_store_dwordx4 v[136:137], v[132:135], off sc1
	v_add_u32_e32 v139, 0xb0, v139
	s_nop 0
	v_ashrrev_i32_e32 v132, 9, v140
	v_and_b32_e32 v141, -8, v132
	v_add_u32_e32 v136, v141, v142
	v_ashrrev_i32_e32 v137, 31, v136
	v_lshlrev_b64 v[136:137], 19, v[136:137]
	v_lshlrev_b32_e32 v140, 7, v140
	v_lshl_add_u64 v[136:137], s[30:31], 0, v[136:137]
	v_and_b32_e32 v158, 0x7ff80, v140
	v_lshl_add_u64 v[136:137], v[136:137], 0, v[158:159]
	v_cvt_pk_bf16_f32 v132, v34, v35
	v_cvt_pk_bf16_f32 v133, v36, v37
	v_cvt_pk_bf16_f32 v134, v26, v27
	v_cvt_pk_bf16_f32 v135, v28, v29
	v_lshl_add_u64 v[136:137], v[136:137], 0, v[130:131]
	global_store_dwordx4 v[136:137], v[132:135], off sc1
	v_add_u32_e32 v136, v141, v138
	v_ashrrev_i32_e32 v137, 31, v136
	v_lshlrev_b64 v[136:137], 19, v[136:137]
	v_lshl_add_u64 v[136:137], s[30:31], 0, v[136:137]
	v_lshl_add_u64 v[136:137], v[136:137], 0, v[158:159]
	v_cvt_pk_bf16_f32 v132, v22, v23
	v_cvt_pk_bf16_f32 v133, v24, v25
	v_cvt_pk_bf16_f32 v134, v14, v15
	v_cvt_pk_bf16_f32 v135, v16, v17
	v_lshl_add_u64 v[136:137], v[136:137], 0, v[130:131]
	global_store_dwordx4 v[136:137], v[132:135], off sc1
	s_nop 1
	v_ashrrev_i32_e32 v132, 9, v139
	v_and_b32_e32 v140, -8, v132
	v_add_u32_e32 v136, v140, v142
	v_ashrrev_i32_e32 v137, 31, v136
	v_lshlrev_b64 v[136:137], 19, v[136:137]
	v_lshlrev_b32_e32 v139, 7, v139
	v_lshl_add_u64 v[136:137], s[30:31], 0, v[136:137]
	v_and_b32_e32 v158, 0x7ff80, v139
	v_lshl_add_u64 v[136:137], v[136:137], 0, v[158:159]
	v_cvt_pk_bf16_f32 v132, v18, v19
	v_cvt_pk_bf16_f32 v133, v20, v21
	v_cvt_pk_bf16_f32 v134, v10, v11
	v_cvt_pk_bf16_f32 v135, v12, v13
	v_lshl_add_u64 v[136:137], v[136:137], 0, v[130:131]
	global_store_dwordx4 v[136:137], v[132:135], off sc1
	v_add_u32_e32 v136, v140, v138
	v_ashrrev_i32_e32 v137, 31, v136
	v_lshlrev_b64 v[136:137], 19, v[136:137]
	v_lshl_add_u64 v[136:137], s[30:31], 0, v[136:137]
	v_lshl_add_u64 v[136:137], v[136:137], 0, v[158:159]
	v_cvt_pk_bf16_f32 v132, v6, v7
	v_cvt_pk_bf16_f32 v133, v8, v9
	v_cvt_pk_bf16_f32 v134, v2, v3
	v_cvt_pk_bf16_f32 v135, v4, v5
	v_lshl_add_u64 v[130:131], v[136:137], 0, v[130:131]
	global_store_dwordx4 v[130:131], v[132:135], off sc1

.LBB0_179:
	s_and_b64 vcc, exec, s[58:59]
	s_cbranch_vccz .LBB0_181
	s_lshl_b32 s2, s19, 8
	s_and_b32 s2, s2, 0x100
	s_or_b32 s2, s2, s85
	v_add_u32_e32 v134, s2, v174
	s_lshl_b32 s2, s18, 8
	s_add_i32 s2, s2, s84
	v_add_u32_e32 v130, s2, v173
	v_ashrrev_i32_e32 v131, 31, v130
	v_lshlrev_b64 v[136:137], 10, v[130:131]
	v_lshl_add_u64 v[136:137], s[36:37], 0, v[136:137]
	v_ashrrev_i32_e32 v135, 31, v134
	v_cvt_pk_bf16_f32 v130, v126, v127
	v_cvt_pk_bf16_f32 v131, v128, v129
	v_cvt_pk_bf16_f32 v132, v122, v123
	v_cvt_pk_bf16_f32 v133, v124, v125
	v_lshl_add_u64 v[134:135], v[134:135], 1, v[136:137]
	global_store_dwordx4 v[134:135], v[130:133], off sc1
	v_add_co_u32_e32 v138, vcc, s75, v134
	s_nop 0
	v_cvt_pk_bf16_f32 v130, v118, v119
	v_cvt_pk_bf16_f32 v131, v120, v121
	v_cvt_pk_bf16_f32 v132, v110, v111
	v_cvt_pk_bf16_f32 v133, v112, v113
	global_store_dwordx4 v[134:135], v[130:133], off offset:256 sc1
	v_addc_co_u32_e32 v139, vcc, 0, v135, vcc
	s_nop 0
	v_cvt_pk_bf16_f32 v130, v114, v115
	v_cvt_pk_bf16_f32 v131, v116, v117
	v_cvt_pk_bf16_f32 v132, v106, v107
	v_cvt_pk_bf16_f32 v133, v108, v109
	v_lshl_add_u64 v[136:137], v[134:135], 0, s[38:39]
	global_store_dwordx4 v[138:139], v[130:133], off sc1
	v_add_co_u32_e32 v138, vcc, s92, v134
	s_nop 0
	v_cvt_pk_bf16_f32 v130, v102, v103
	v_cvt_pk_bf16_f32 v131, v104, v105
	v_cvt_pk_bf16_f32 v132, v94, v95
	v_cvt_pk_bf16_f32 v133, v96, v97
	global_store_dwordx4 v[136:137], v[130:133], off offset:256 sc1
	v_addc_co_u32_e32 v139, vcc, 0, v135, vcc
	s_nop 0
	v_cvt_pk_bf16_f32 v130, v98, v99
	v_cvt_pk_bf16_f32 v131, v100, v101
	v_cvt_pk_bf16_f32 v132, v90, v91
	v_cvt_pk_bf16_f32 v133, v92, v93
	v_lshl_add_u64 v[136:137], v[134:135], 0, s[40:41]
	global_store_dwordx4 v[138:139], v[130:133], off sc1
	v_add_co_u32_e32 v138, vcc, s97, v134
	s_nop 0
	v_cvt_pk_bf16_f32 v130, v86, v87
	v_cvt_pk_bf16_f32 v131, v88, v89
	v_cvt_pk_bf16_f32 v132, v78, v79
	v_cvt_pk_bf16_f32 v133, v80, v81
	global_store_dwordx4 v[136:137], v[130:133], off offset:256 sc1
	v_addc_co_u32_e32 v139, vcc, 0, v135, vcc
	s_nop 0
	v_cvt_pk_bf16_f32 v130, v82, v83
	v_cvt_pk_bf16_f32 v131, v84, v85
	v_cvt_pk_bf16_f32 v132, v74, v75
	v_cvt_pk_bf16_f32 v133, v76, v77
	v_lshl_add_u64 v[136:137], v[134:135], 0, s[42:43]
	global_store_dwordx4 v[138:139], v[130:133], off sc1
	v_add_co_u32_e32 v138, vcc, s66, v134
	s_nop 0
	v_cvt_pk_bf16_f32 v130, v70, v71
	v_cvt_pk_bf16_f32 v131, v72, v73
	v_cvt_pk_bf16_f32 v132, v66, v67
	v_cvt_pk_bf16_f32 v133, v68, v69
	global_store_dwordx4 v[136:137], v[130:133], off offset:256 sc1
	v_addc_co_u32_e32 v139, vcc, 0, v135, vcc
	s_nop 0
	v_cvt_pk_bf16_f32 v130, v62, v63
	v_cvt_pk_bf16_f32 v131, v64, v65
	v_cvt_pk_bf16_f32 v132, v58, v59
	v_cvt_pk_bf16_f32 v133, v60, v61
	v_lshl_add_u64 v[136:137], v[134:135], 0, s[44:45]
	global_store_dwordx4 v[138:139], v[130:133], off sc1
	v_add_co_u32_e32 v138, vcc, s53, v134
	s_nop 0
	v_cvt_pk_bf16_f32 v130, v54, v55
	v_cvt_pk_bf16_f32 v131, v56, v57
	v_cvt_pk_bf16_f32 v132, v46, v47
	v_cvt_pk_bf16_f32 v133, v48, v49
	global_store_dwordx4 v[136:137], v[130:133], off offset:256 sc1
	v_addc_co_u32_e32 v139, vcc, 0, v135, vcc
	s_nop 0
	v_cvt_pk_bf16_f32 v130, v50, v51
	v_cvt_pk_bf16_f32 v131, v52, v53
	v_cvt_pk_bf16_f32 v132, v42, v43
	v_cvt_pk_bf16_f32 v133, v44, v45
	v_lshl_add_u64 v[136:137], v[134:135], 0, s[46:47]
	global_store_dwordx4 v[138:139], v[130:133], off sc1
	v_add_co_u32_e32 v138, vcc, s68, v134
	s_nop 0
	v_cvt_pk_bf16_f32 v130, v38, v39
	v_cvt_pk_bf16_f32 v131, v40, v41
	v_cvt_pk_bf16_f32 v132, v30, v31
	v_cvt_pk_bf16_f32 v133, v32, v33
	global_store_dwordx4 v[136:137], v[130:133], off offset:256 sc1
	v_addc_co_u32_e32 v139, vcc, 0, v135, vcc
	s_nop 0
	v_cvt_pk_bf16_f32 v130, v34, v35
	v_cvt_pk_bf16_f32 v131, v36, v37
	v_cvt_pk_bf16_f32 v132, v26, v27
	v_cvt_pk_bf16_f32 v133, v28, v29
	v_lshl_add_u64 v[136:137], v[134:135], 0, s[48:49]
	global_store_dwordx4 v[138:139], v[130:133], off sc1
	s_mov_b64 s[60:61], 0
	s_nop 0
	v_cvt_pk_bf16_f32 v130, v22, v23
	v_cvt_pk_bf16_f32 v131, v24, v25
	v_cvt_pk_bf16_f32 v132, v14, v15
	v_cvt_pk_bf16_f32 v133, v16, v17
	global_store_dwordx4 v[136:137], v[130:133], off offset:256 sc1
	v_lshl_add_u64 v[136:137], v[134:135], 0, s[50:51]
	v_add_co_u32_e32 v134, vcc, s4, v134
	v_cvt_pk_bf16_f32 v130, v18, v19
	v_cvt_pk_bf16_f32 v131, v20, v21
	v_cvt_pk_bf16_f32 v132, v10, v11
	v_cvt_pk_bf16_f32 v133, v12, v13
	v_addc_co_u32_e32 v135, vcc, 0, v135, vcc
	global_store_dwordx4 v[134:135], v[130:133], off sc1
	s_nop 1
	v_cvt_pk_bf16_f32 v130, v6, v7
	v_cvt_pk_bf16_f32 v131, v8, v9
	v_cvt_pk_bf16_f32 v132, v2, v3
	v_cvt_pk_bf16_f32 v133, v4, v5
	global_store_dwordx4 v[136:137], v[130:133], off offset:256 sc1
.LBB0_181:
	s_andn2_b64 vcc, exec, s[60:61]
	s_cbranch_vccnz .LBB0_130
	s_lshl_b32 s2, s19, 8
	s_and_b32 s2, s2, 0x100
	s_or_b32 s2, s2, s85
	v_add_u32_e32 v132, s2, v174
	s_lshl_b32 s2, s18, 8
	s_add_i32 s2, s2, s84
	v_add_u32_e32 v133, s2, v173
	v_ashrrev_i32_e32 v130, 9, v133
	v_and_b32_e32 v135, -8, v130
	v_pk_mul_f32 v[126:127], v[126:127], s[52:53] op_sel_hi:[1,0]
	v_pk_mul_f32 v[130:131], v[124:125], s[52:53] op_sel_hi:[1,0]
	v_pk_mul_f32 v[122:123], v[122:123], s[52:53] op_sel_hi:[1,0]
	v_cvt_pk_bf16_f32 v124, v126, v127
	v_cvt_pk_bf16_f32 v127, v130, v131
	v_ashrrev_i32_e32 v130, 6, v132
	v_cvt_pk_bf16_f32 v126, v122, v123
	v_add_u32_e32 v122, v135, v130
	v_pk_mul_f32 v[128:129], v[128:129], s[52:53] op_sel_hi:[1,0]
	v_ashrrev_i32_e32 v123, 31, v122
	v_cvt_pk_bf16_f32 v125, v128, v129
	v_lshlrev_b64 v[122:123], 19, v[122:123]
	v_lshlrev_b32_e32 v128, 7, v133
	v_and_b32_e32 v134, 56, v132
	v_lshl_add_u64 v[122:123], s[34:35], 0, v[122:123]
	v_and_b32_e32 v158, 0x7ff80, v128
	v_lshl_add_u64 v[128:129], v[122:123], 0, v[158:159]
	v_lshlrev_b32_e32 v122, 1, v134
	v_mov_b32_e32 v123, v159
	v_lshl_add_u64 v[128:129], v[128:129], 0, v[122:123]
	global_store_dwordx4 v[128:129], v[124:127], off sc1
	v_pk_mul_f32 v[120:121], v[120:121], s[52:53] op_sel_hi:[1,0]
	v_add_u32_e32 v128, 0x80, v132
	v_pk_mul_f32 v[118:119], v[118:119], s[52:53] op_sel_hi:[1,0]
	v_pk_mul_f32 v[124:125], v[110:111], s[52:53] op_sel_hi:[1,0]
	v_cvt_pk_bf16_f32 v111, v120, v121
	v_ashrrev_i32_e32 v120, 6, v128
	v_cvt_pk_bf16_f32 v110, v118, v119
	v_add_u32_e32 v118, v120, v135
	v_ashrrev_i32_e32 v119, 31, v118
	v_lshlrev_b64 v[118:119], 19, v[118:119]
	v_lshl_add_u64 v[118:119], s[34:35], 0, v[118:119]
	v_pk_mul_f32 v[126:127], v[112:113], s[52:53] op_sel_hi:[1,0]
	v_lshl_add_u64 v[118:119], v[118:119], 0, v[158:159]
	v_cvt_pk_bf16_f32 v112, v124, v125
	v_cvt_pk_bf16_f32 v113, v126, v127
	v_lshl_add_u64 v[118:119], v[118:119], 0, v[122:123]
	global_store_dwordx4 v[118:119], v[110:113], off sc1
	v_add_u32_e32 v118, 16, v133
	v_pk_mul_f32 v[102:103], v[102:103], s[52:53] op_sel_hi:[1,0]
	v_ashrrev_i32_e32 v110, 9, v118
	v_and_b32_e32 v119, -8, v110
	v_pk_mul_f32 v[110:111], v[114:115], s[52:53] op_sel_hi:[1,0]
	v_pk_mul_f32 v[114:115], v[106:107], s[52:53] op_sel_hi:[1,0]
	v_cvt_pk_bf16_f32 v106, v110, v111
	v_add_u32_e32 v110, v119, v130
	v_pk_mul_f32 v[112:113], v[116:117], s[52:53] op_sel_hi:[1,0]
	v_ashrrev_i32_e32 v111, 31, v110
	v_cvt_pk_bf16_f32 v107, v112, v113
	v_lshlrev_b64 v[110:111], 19, v[110:111]
	v_lshlrev_b32_e32 v112, 7, v118
	v_lshl_add_u64 v[110:111], s[34:35], 0, v[110:111]
	v_and_b32_e32 v158, 0x7ff80, v112
	v_pk_mul_f32 v[116:117], v[108:109], s[52:53] op_sel_hi:[1,0]
	v_lshl_add_u64 v[110:111], v[110:111], 0, v[158:159]
	v_cvt_pk_bf16_f32 v108, v114, v115
	v_cvt_pk_bf16_f32 v109, v116, v117
	v_lshl_add_u64 v[110:111], v[110:111], 0, v[122:123]
	global_store_dwordx4 v[110:111], v[106:109], off sc1
	v_pk_mul_f32 v[104:105], v[104:105], s[52:53] op_sel_hi:[1,0]
	v_pk_mul_f32 v[86:87], v[86:87], s[52:53] op_sel_hi:[1,0]
	v_pk_mul_f32 v[106:107], v[94:95], s[52:53] op_sel_hi:[1,0]
	v_cvt_pk_bf16_f32 v94, v102, v103
	v_add_u32_e32 v102, v119, v120
	v_ashrrev_i32_e32 v103, 31, v102
	v_lshlrev_b64 v[102:103], 19, v[102:103]
	v_lshl_add_u64 v[102:103], s[34:35], 0, v[102:103]
	v_pk_mul_f32 v[108:109], v[96:97], s[52:53] op_sel_hi:[1,0]
	v_lshl_add_u64 v[102:103], v[102:103], 0, v[158:159]
	v_cvt_pk_bf16_f32 v95, v104, v105
	v_cvt_pk_bf16_f32 v96, v106, v107
	v_cvt_pk_bf16_f32 v97, v108, v109
	v_lshl_add_u64 v[102:103], v[102:103], 0, v[122:123]
	global_store_dwordx4 v[102:103], v[94:97], off sc1
	v_add_u32_e32 v102, 32, v133
	v_pk_mul_f32 v[88:89], v[88:89], s[52:53] op_sel_hi:[1,0]
	v_ashrrev_i32_e32 v94, 9, v102
	v_and_b32_e32 v103, -8, v94
	v_pk_mul_f32 v[94:95], v[98:99], s[52:53] op_sel_hi:[1,0]
	v_pk_mul_f32 v[98:99], v[90:91], s[52:53] op_sel_hi:[1,0]
	v_cvt_pk_bf16_f32 v90, v94, v95
	v_add_u32_e32 v94, v103, v130
	v_pk_mul_f32 v[96:97], v[100:101], s[52:53] op_sel_hi:[1,0]
	v_ashrrev_i32_e32 v95, 31, v94
	v_cvt_pk_bf16_f32 v91, v96, v97
	v_lshlrev_b64 v[94:95], 19, v[94:95]
	v_lshlrev_b32_e32 v96, 7, v102
	v_lshl_add_u64 v[94:95], s[34:35], 0, v[94:95]
	v_and_b32_e32 v158, 0x7ff80, v96
	v_pk_mul_f32 v[100:101], v[92:93], s[52:53] op_sel_hi:[1,0]
	v_lshl_add_u64 v[94:95], v[94:95], 0, v[158:159]
	v_cvt_pk_bf16_f32 v92, v98, v99
	v_cvt_pk_bf16_f32 v93, v100, v101
	v_lshl_add_u64 v[94:95], v[94:95], 0, v[122:123]
	global_store_dwordx4 v[94:95], v[90:93], off sc1
	v_pk_mul_f32 v[70:71], v[70:71], s[52:53] op_sel_hi:[1,0]
	v_pk_mul_f32 v[72:73], v[72:73], s[52:53] op_sel_hi:[1,0]
	v_pk_mul_f32 v[90:91], v[78:79], s[52:53] op_sel_hi:[1,0]
	v_cvt_pk_bf16_f32 v78, v86, v87
	v_add_u32_e32 v86, v103, v120
	v_ashrrev_i32_e32 v87, 31, v86
	v_lshlrev_b64 v[86:87], 19, v[86:87]
	v_lshl_add_u64 v[86:87], s[34:35], 0, v[86:87]
	v_pk_mul_f32 v[92:93], v[80:81], s[52:53] op_sel_hi:[1,0]
	v_lshl_add_u64 v[86:87], v[86:87], 0, v[158:159]
	v_cvt_pk_bf16_f32 v79, v88, v89
	v_cvt_pk_bf16_f32 v80, v90, v91
	v_cvt_pk_bf16_f32 v81, v92, v93
	v_lshl_add_u64 v[86:87], v[86:87], 0, v[122:123]
	global_store_dwordx4 v[86:87], v[78:81], off sc1
	v_add_u32_e32 v86, 48, v133
	v_pk_mul_f32 v[62:63], v[62:63], s[52:53] op_sel_hi:[1,0]
	v_ashrrev_i32_e32 v78, 9, v86
	v_and_b32_e32 v87, -8, v78
	v_pk_mul_f32 v[78:79], v[82:83], s[52:53] op_sel_hi:[1,0]
	v_pk_mul_f32 v[82:83], v[74:75], s[52:53] op_sel_hi:[1,0]
	v_cvt_pk_bf16_f32 v74, v78, v79
	v_add_u32_e32 v78, v87, v130
	v_pk_mul_f32 v[80:81], v[84:85], s[52:53] op_sel_hi:[1,0]
	v_ashrrev_i32_e32 v79, 31, v78
	v_cvt_pk_bf16_f32 v75, v80, v81
	v_lshlrev_b64 v[78:79], 19, v[78:79]
	v_lshlrev_b32_e32 v80, 7, v86
	v_lshl_add_u64 v[78:79], s[34:35], 0, v[78:79]
	v_and_b32_e32 v158, 0x7ff80, v80
	v_pk_mul_f32 v[84:85], v[76:77], s[52:53] op_sel_hi:[1,0]
	v_lshl_add_u64 v[78:79], v[78:79], 0, v[158:159]
	v_cvt_pk_bf16_f32 v76, v82, v83
	v_cvt_pk_bf16_f32 v77, v84, v85
	v_lshl_add_u64 v[78:79], v[78:79], 0, v[122:123]
	global_store_dwordx4 v[78:79], v[74:77], off sc1
	v_pk_mul_f32 v[64:65], v[64:65], s[52:53] op_sel_hi:[1,0]
	v_pk_mul_f32 v[54:55], v[54:55], s[52:53] op_sel_hi:[1,0]
	v_pk_mul_f32 v[74:75], v[66:67], s[52:53] op_sel_hi:[1,0]
	v_cvt_pk_bf16_f32 v66, v70, v71
	v_add_u32_e32 v70, v87, v120
	v_ashrrev_i32_e32 v71, 31, v70
	v_lshlrev_b64 v[70:71], 19, v[70:71]
	v_lshl_add_u64 v[70:71], s[34:35], 0, v[70:71]
	v_pk_mul_f32 v[76:77], v[68:69], s[52:53] op_sel_hi:[1,0]
	v_lshl_add_u64 v[70:71], v[70:71], 0, v[158:159]
	v_cvt_pk_bf16_f32 v67, v72, v73
	v_cvt_pk_bf16_f32 v68, v74, v75
	v_cvt_pk_bf16_f32 v69, v76, v77
	v_lshl_add_u64 v[70:71], v[70:71], 0, v[122:123]
	global_store_dwordx4 v[70:71], v[66:69], off sc1
	v_add_u32_e32 v70, 0x80, v133
	v_pk_mul_f32 v[56:57], v[56:57], s[52:53] op_sel_hi:[1,0]
	v_ashrrev_i32_e32 v66, 9, v70
	v_and_b32_e32 v71, -8, v66
	v_pk_mul_f32 v[66:67], v[58:59], s[52:53] op_sel_hi:[1,0]
	v_cvt_pk_bf16_f32 v58, v62, v63
	v_add_u32_e32 v62, v71, v130
	v_ashrrev_i32_e32 v63, 31, v62
	v_cvt_pk_bf16_f32 v59, v64, v65
	v_lshlrev_b64 v[62:63], 19, v[62:63]
	v_lshlrev_b32_e32 v64, 7, v70
	v_lshl_add_u64 v[62:63], s[34:35], 0, v[62:63]
	v_and_b32_e32 v158, 0x7ff80, v64
	v_pk_mul_f32 v[68:69], v[60:61], s[52:53] op_sel_hi:[1,0]
	v_lshl_add_u64 v[62:63], v[62:63], 0, v[158:159]
	v_cvt_pk_bf16_f32 v60, v66, v67
	v_cvt_pk_bf16_f32 v61, v68, v69
	v_lshl_add_u64 v[62:63], v[62:63], 0, v[122:123]
	global_store_dwordx4 v[62:63], v[58:61], off sc1
	v_pk_mul_f32 v[38:39], v[38:39], s[52:53] op_sel_hi:[1,0]
	v_pk_mul_f32 v[40:41], v[40:41], s[52:53] op_sel_hi:[1,0]
	v_pk_mul_f32 v[58:59], v[46:47], s[52:53] op_sel_hi:[1,0]
	v_cvt_pk_bf16_f32 v46, v54, v55
	v_add_u32_e32 v54, v71, v120
	v_ashrrev_i32_e32 v55, 31, v54
	v_lshlrev_b64 v[54:55], 19, v[54:55]
	v_lshl_add_u64 v[54:55], s[34:35], 0, v[54:55]
	v_pk_mul_f32 v[60:61], v[48:49], s[52:53] op_sel_hi:[1,0]
	v_lshl_add_u64 v[54:55], v[54:55], 0, v[158:159]
	v_cvt_pk_bf16_f32 v47, v56, v57
	v_cvt_pk_bf16_f32 v48, v58, v59
	v_cvt_pk_bf16_f32 v49, v60, v61
	v_lshl_add_u64 v[54:55], v[54:55], 0, v[122:123]
	global_store_dwordx4 v[54:55], v[46:49], off sc1
	v_add_u32_e32 v54, 0x90, v133
	v_pk_mul_f32 v[22:23], v[22:23], s[52:53] op_sel_hi:[1,0]
	v_ashrrev_i32_e32 v46, 9, v54
	v_and_b32_e32 v55, -8, v46
	v_pk_mul_f32 v[46:47], v[50:51], s[52:53] op_sel_hi:[1,0]
	v_pk_mul_f32 v[50:51], v[42:43], s[52:53] op_sel_hi:[1,0]
	v_cvt_pk_bf16_f32 v42, v46, v47
	v_add_u32_e32 v46, v55, v130
	v_pk_mul_f32 v[48:49], v[52:53], s[52:53] op_sel_hi:[1,0]
	v_ashrrev_i32_e32 v47, 31, v46
	v_cvt_pk_bf16_f32 v43, v48, v49
	v_lshlrev_b64 v[46:47], 19, v[46:47]
	v_lshlrev_b32_e32 v48, 7, v54
	v_lshl_add_u64 v[46:47], s[34:35], 0, v[46:47]
	v_and_b32_e32 v158, 0x7ff80, v48
	v_pk_mul_f32 v[52:53], v[44:45], s[52:53] op_sel_hi:[1,0]
	v_lshl_add_u64 v[46:47], v[46:47], 0, v[158:159]
	v_cvt_pk_bf16_f32 v44, v50, v51
	v_cvt_pk_bf16_f32 v45, v52, v53
	v_lshl_add_u64 v[46:47], v[46:47], 0, v[122:123]
	global_store_dwordx4 v[46:47], v[42:45], off sc1
	v_pk_mul_f32 v[24:25], v[24:25], s[52:53] op_sel_hi:[1,0]
	v_pk_mul_f32 v[6:7], v[6:7], s[52:53] op_sel_hi:[1,0]
	v_pk_mul_f32 v[42:43], v[30:31], s[52:53] op_sel_hi:[1,0]
	v_cvt_pk_bf16_f32 v30, v38, v39
	v_add_u32_e32 v38, v55, v120
	v_ashrrev_i32_e32 v39, 31, v38
	v_lshlrev_b64 v[38:39], 19, v[38:39]
	v_lshl_add_u64 v[38:39], s[34:35], 0, v[38:39]
	v_pk_mul_f32 v[44:45], v[32:33], s[52:53] op_sel_hi:[1,0]
	v_lshl_add_u64 v[38:39], v[38:39], 0, v[158:159]
	v_cvt_pk_bf16_f32 v31, v40, v41
	v_cvt_pk_bf16_f32 v32, v42, v43
	v_cvt_pk_bf16_f32 v33, v44, v45
	v_lshl_add_u64 v[38:39], v[38:39], 0, v[122:123]
	global_store_dwordx4 v[38:39], v[30:33], off sc1
	v_add_u32_e32 v38, 0xa0, v133
	v_pk_mul_f32 v[8:9], v[8:9], s[52:53] op_sel_hi:[1,0]
	v_ashrrev_i32_e32 v30, 9, v38
	v_and_b32_e32 v39, -8, v30
	v_pk_mul_f32 v[30:31], v[34:35], s[52:53] op_sel_hi:[1,0]
	v_pk_mul_f32 v[34:35], v[26:27], s[52:53] op_sel_hi:[1,0]
	v_cvt_pk_bf16_f32 v26, v30, v31
	v_add_u32_e32 v30, v39, v130
	v_pk_mul_f32 v[32:33], v[36:37], s[52:53] op_sel_hi:[1,0]
	v_ashrrev_i32_e32 v31, 31, v30
	v_cvt_pk_bf16_f32 v27, v32, v33
	v_lshlrev_b64 v[30:31], 19, v[30:31]
	v_lshlrev_b32_e32 v32, 7, v38
	v_lshl_add_u64 v[30:31], s[34:35], 0, v[30:31]
	v_and_b32_e32 v158, 0x7ff80, v32
	v_pk_mul_f32 v[36:37], v[28:29], s[52:53] op_sel_hi:[1,0]
	v_lshl_add_u64 v[30:31], v[30:31], 0, v[158:159]
	v_cvt_pk_bf16_f32 v28, v34, v35
	v_cvt_pk_bf16_f32 v29, v36, v37
	v_lshl_add_u64 v[30:31], v[30:31], 0, v[122:123]
	global_store_dwordx4 v[30:31], v[26:29], off sc1
	s_nop 1
	v_pk_mul_f32 v[26:27], v[14:15], s[52:53] op_sel_hi:[1,0]
	v_cvt_pk_bf16_f32 v14, v22, v23
	v_add_u32_e32 v22, v39, v120
	v_ashrrev_i32_e32 v23, 31, v22
	v_lshlrev_b64 v[22:23], 19, v[22:23]
	v_lshl_add_u64 v[22:23], s[34:35], 0, v[22:23]
	v_pk_mul_f32 v[28:29], v[16:17], s[52:53] op_sel_hi:[1,0]
	v_lshl_add_u64 v[22:23], v[22:23], 0, v[158:159]
	v_cvt_pk_bf16_f32 v15, v24, v25
	v_cvt_pk_bf16_f32 v16, v26, v27
	v_cvt_pk_bf16_f32 v17, v28, v29
	v_lshl_add_u64 v[22:23], v[22:23], 0, v[122:123]
	global_store_dwordx4 v[22:23], v[14:17], off sc1
	v_add_u32_e32 v22, 0xb0, v133
	s_nop 0
	v_ashrrev_i32_e32 v14, 9, v22
	v_and_b32_e32 v23, -8, v14
	v_pk_mul_f32 v[14:15], v[18:19], s[52:53] op_sel_hi:[1,0]
	v_pk_mul_f32 v[18:19], v[10:11], s[52:53] op_sel_hi:[1,0]
	v_cvt_pk_bf16_f32 v10, v14, v15
	v_add_u32_e32 v14, v23, v130
	v_pk_mul_f32 v[16:17], v[20:21], s[52:53] op_sel_hi:[1,0]
	v_ashrrev_i32_e32 v15, 31, v14
	v_cvt_pk_bf16_f32 v11, v16, v17
	v_lshlrev_b64 v[14:15], 19, v[14:15]
	v_lshlrev_b32_e32 v16, 7, v22
	v_lshl_add_u64 v[14:15], s[34:35], 0, v[14:15]
	v_and_b32_e32 v158, 0x7ff80, v16
	v_pk_mul_f32 v[20:21], v[12:13], s[52:53] op_sel_hi:[1,0]
	v_lshl_add_u64 v[14:15], v[14:15], 0, v[158:159]
	v_cvt_pk_bf16_f32 v12, v18, v19
	v_cvt_pk_bf16_f32 v13, v20, v21
	v_lshl_add_u64 v[14:15], v[14:15], 0, v[122:123]
	global_store_dwordx4 v[14:15], v[10:13], off sc1
	s_nop 1
	v_pk_mul_f32 v[10:11], v[2:3], s[52:53] op_sel_hi:[1,0]
	v_cvt_pk_bf16_f32 v2, v6, v7
	v_add_u32_e32 v6, v23, v120
	v_ashrrev_i32_e32 v7, 31, v6
	v_lshlrev_b64 v[6:7], 19, v[6:7]
	v_lshl_add_u64 v[6:7], s[34:35], 0, v[6:7]
	v_pk_mul_f32 v[12:13], v[4:5], s[52:53] op_sel_hi:[1,0]
	v_lshl_add_u64 v[6:7], v[6:7], 0, v[158:159]
	v_cvt_pk_bf16_f32 v3, v8, v9
	v_cvt_pk_bf16_f32 v4, v10, v11
	v_cvt_pk_bf16_f32 v5, v12, v13
	v_lshl_add_u64 v[6:7], v[6:7], 0, v[122:123]
	global_store_dwordx4 v[6:7], v[2:5], off sc1
	s_branch .LBB0_130

.LBB0_281:
	ds_read_b128 v[130:133], v167
	ds_read_b128 v[134:137], v167 offset:1024
	ds_read_b128 v[138:141], v167 offset:2048
	ds_read_b128 v[142:145], v167 offset:3072
	s_add_u32 s43, s44, 0xfffc0080
	s_addc_u32 s46, s45, -1
	s_cmp_eq_u32 s41, 12
	s_cselect_b32 s49, s9, s46
	s_cselect_b32 s48, s8, s43
	s_cselect_b32 s47, s7, s3
	s_cselect_b32 s46, s6, s2
	v_lshl_add_u64 v[200:201], s[44:45], 0, v[158:159]
	s_add_i32 m0, s53, 0xc000
	ds_read_b128 v[162:165], v169
	ds_read_b128 v[172:175], v169 offset:1024
	ds_read_b128 v[176:179], v169 offset:2048
	ds_read_b128 v[180:183], v169 offset:3072
	ds_read_b128 v[184:187], v169 offset:4096
	ds_read_b128 v[188:191], v169 offset:5120
	ds_read_b128 v[192:195], v169 offset:6144
	ds_read_b128 v[196:199], v169 offset:7168
	global_load_lds_dwordx4 v[200:201], off
	v_lshl_add_u64 v[200:201], s[44:45], 0, v[160:161]
	s_add_i32 m0, s53, 0xe000
	s_nop 0
	global_load_lds_dwordx4 v[200:201], off
	s_waitcnt lgkmcnt(8)
	s_barrier
	s_waitcnt lgkmcnt(0)
	s_setprio 1
	s_waitcnt lgkmcnt(0)
	v_mfma_f32_16x16x32_bf16 v[126:129], v[130:133], v[162:165], v[126:129]
	v_mfma_f32_16x16x32_bf16 v[122:125], v[138:141], v[162:165], v[122:125]
	v_mfma_f32_16x16x32_bf16 v[114:117], v[130:133], v[176:179], v[114:117]
	v_mfma_f32_16x16x32_bf16 v[106:109], v[138:141], v[176:179], v[106:109]
	v_mfma_f32_16x16x32_bf16 v[98:101], v[130:133], v[184:187], v[98:101]
	v_mfma_f32_16x16x32_bf16 v[90:93], v[138:141], v[184:187], v[90:93]
	v_mfma_f32_16x16x32_bf16 v[82:85], v[130:133], v[192:195], v[82:85]
	v_mfma_f32_16x16x32_bf16 v[74:77], v[138:141], v[192:195], v[74:77]
	v_mfma_f32_16x16x32_bf16 v[126:129], v[134:137], v[172:175], v[126:129]
	v_mfma_f32_16x16x32_bf16 v[122:125], v[142:145], v[172:175], v[122:125]
	v_mfma_f32_16x16x32_bf16 v[114:117], v[134:137], v[180:183], v[114:117]
	v_mfma_f32_16x16x32_bf16 v[106:109], v[142:145], v[180:183], v[106:109]
	v_mfma_f32_16x16x32_bf16 v[98:101], v[134:137], v[188:191], v[98:101]
	v_mfma_f32_16x16x32_bf16 v[90:93], v[142:145], v[188:191], v[90:93]
	v_mfma_f32_16x16x32_bf16 v[82:85], v[134:137], v[196:199], v[82:85]
	v_mfma_f32_16x16x32_bf16 v[74:77], v[142:145], v[196:199], v[74:77]
	s_setprio 0
	s_barrier
	s_add_i32 s43, s67, s52
	v_lshl_add_u64 v[216:217], s[46:47], 0, v[150:151]
	s_mov_b32 m0, s43
	ds_read_b128 v[200:203], v170
	ds_read_b128 v[204:207], v170 offset:1024
	ds_read_b128 v[208:211], v170 offset:2048
	ds_read_b128 v[212:215], v170 offset:3072
	global_load_lds_dwordx4 v[216:217], off
	v_lshl_add_u64 v[218:219], s[46:47], 0, v[154:155]
	s_add_i32 m0, s43, 0x2000
	s_nop 0
	global_load_lds_dwordx4 v[218:219], off
	s_barrier
	s_waitcnt lgkmcnt(0)
	s_setprio 1
	s_waitcnt lgkmcnt(0)
	v_mfma_f32_16x16x32_bf16 v[118:121], v[200:203], v[162:165], v[118:121]
	v_mfma_f32_16x16x32_bf16 v[110:113], v[208:211], v[162:165], v[110:113]
	v_mfma_f32_16x16x32_bf16 v[102:105], v[200:203], v[176:179], v[102:105]
	v_mfma_f32_16x16x32_bf16 v[94:97], v[208:211], v[176:179], v[94:97]
	v_mfma_f32_16x16x32_bf16 v[86:89], v[200:203], v[184:187], v[86:89]
	v_mfma_f32_16x16x32_bf16 v[78:81], v[208:211], v[184:187], v[78:81]
	v_mfma_f32_16x16x32_bf16 v[70:73], v[200:203], v[192:195], v[70:73]
	v_mfma_f32_16x16x32_bf16 v[66:69], v[208:211], v[192:195], v[66:69]
	v_mfma_f32_16x16x32_bf16 v[118:121], v[204:207], v[172:175], v[118:121]
	v_mfma_f32_16x16x32_bf16 v[110:113], v[212:215], v[172:175], v[110:113]
	v_mfma_f32_16x16x32_bf16 v[102:105], v[204:207], v[180:183], v[102:105]
	v_mfma_f32_16x16x32_bf16 v[94:97], v[212:215], v[180:183], v[94:97]
	v_mfma_f32_16x16x32_bf16 v[86:89], v[204:207], v[188:191], v[86:89]
	v_mfma_f32_16x16x32_bf16 v[78:81], v[212:215], v[188:191], v[78:81]
	v_mfma_f32_16x16x32_bf16 v[70:73], v[204:207], v[196:199], v[70:73]
	v_mfma_f32_16x16x32_bf16 v[66:69], v[212:215], v[196:199], v[66:69]
	s_setprio 0
	s_mov_b32 m0, s53
	v_lshl_add_u64 v[220:221], s[48:49], 0, v[148:149]
	s_barrier
	ds_read_b128 v[162:165], v169 offset:16384
	ds_read_b128 v[172:175], v169 offset:17408
	ds_read_b128 v[176:179], v169 offset:18432
	ds_read_b128 v[180:183], v169 offset:19456
	ds_read_b128 v[184:187], v169 offset:20480
	ds_read_b128 v[188:191], v169 offset:21504
	ds_read_b128 v[192:195], v169 offset:22528
	ds_read_b128 v[196:199], v169 offset:23552
	global_load_lds_dwordx4 v[220:221], off
	v_lshl_add_u64 v[222:223], s[48:49], 0, v[152:153]
	s_mov_b32 m0, s54
	s_nop 0
	global_load_lds_dwordx4 v[222:223], off
	s_barrier
	s_waitcnt lgkmcnt(0)
	s_setprio 1
	s_waitcnt lgkmcnt(0)
	v_mfma_f32_16x16x32_bf16 v[62:65], v[130:133], v[162:165], v[62:65]
	v_mfma_f32_16x16x32_bf16 v[58:61], v[138:141], v[162:165], v[58:61]
	v_mfma_f32_16x16x32_bf16 v[50:53], v[130:133], v[176:179], v[50:53]
	v_mfma_f32_16x16x32_bf16 v[42:45], v[138:141], v[176:179], v[42:45]
	v_mfma_f32_16x16x32_bf16 v[34:37], v[130:133], v[184:187], v[34:37]
	v_mfma_f32_16x16x32_bf16 v[26:29], v[138:141], v[184:187], v[26:29]
	v_mfma_f32_16x16x32_bf16 v[18:21], v[130:133], v[192:195], v[18:21]
	v_mfma_f32_16x16x32_bf16 v[10:13], v[138:141], v[192:195], v[10:13]
	v_mfma_f32_16x16x32_bf16 v[62:65], v[134:137], v[172:175], v[62:65]
	v_mfma_f32_16x16x32_bf16 v[58:61], v[142:145], v[172:175], v[58:61]
	v_mfma_f32_16x16x32_bf16 v[50:53], v[134:137], v[180:183], v[50:53]
	v_mfma_f32_16x16x32_bf16 v[42:45], v[142:145], v[180:183], v[42:45]
	v_mfma_f32_16x16x32_bf16 v[34:37], v[134:137], v[188:191], v[34:37]
	v_mfma_f32_16x16x32_bf16 v[26:29], v[142:145], v[188:191], v[26:29]
	v_mfma_f32_16x16x32_bf16 v[18:21], v[134:137], v[196:199], v[18:21]
	v_mfma_f32_16x16x32_bf16 v[10:13], v[142:145], v[196:199], v[10:13]
	s_setprio 0
	s_barrier
	s_add_u32 s50, s46, 0x40000
	s_addc_u32 s51, s47, 0
	s_add_i32 s43, s68, s52
	v_lshl_add_u64 v[130:131], s[50:51], 0, v[150:151]
	s_mov_b32 m0, s43
	s_nop 0
	global_load_lds_dwordx4 v[130:131], off
	v_lshl_add_u64 v[130:131], s[50:51], 0, v[154:155]
	s_add_i32 m0, s43, 0x2000
	s_nop 0
	global_load_lds_dwordx4 v[130:131], off
	s_waitcnt vmcnt(6)
	s_barrier
	s_setprio 1
	v_mfma_f32_16x16x32_bf16 v[54:57], v[200:203], v[162:165], v[54:57]
	v_mfma_f32_16x16x32_bf16 v[46:49], v[208:211], v[162:165], v[46:49]
	v_mfma_f32_16x16x32_bf16 v[38:41], v[200:203], v[176:179], v[38:41]
	v_mfma_f32_16x16x32_bf16 v[30:33], v[208:211], v[176:179], v[30:33]
	v_mfma_f32_16x16x32_bf16 v[22:25], v[200:203], v[184:187], v[22:25]
	v_mfma_f32_16x16x32_bf16 v[14:17], v[208:211], v[184:187], v[14:17]
	v_mfma_f32_16x16x32_bf16 v[6:9], v[200:203], v[192:195], v[6:9]
	v_mfma_f32_16x16x32_bf16 v[2:5], v[208:211], v[192:195], v[2:5]
	v_mfma_f32_16x16x32_bf16 v[54:57], v[204:207], v[172:175], v[54:57]
	v_mfma_f32_16x16x32_bf16 v[46:49], v[212:215], v[172:175], v[46:49]
	v_mfma_f32_16x16x32_bf16 v[38:41], v[204:207], v[180:183], v[38:41]
	v_mfma_f32_16x16x32_bf16 v[30:33], v[212:215], v[180:183], v[30:33]
	v_mfma_f32_16x16x32_bf16 v[22:25], v[204:207], v[188:191], v[22:25]
	v_mfma_f32_16x16x32_bf16 v[14:17], v[212:215], v[188:191], v[14:17]
	v_mfma_f32_16x16x32_bf16 v[6:9], v[204:207], v[196:199], v[6:9]
	v_mfma_f32_16x16x32_bf16 v[2:5], v[212:215], v[196:199], v[2:5]
	s_setprio 0
	s_add_i32 s43, 0, 0x18000
	v_add_u32_e32 v142, s43, v166
	s_barrier
	ds_read_b128 v[130:133], v142
	ds_read_b128 v[134:137], v142 offset:1024
	ds_read_b128 v[138:141], v142 offset:2048
	ds_read_b128 v[142:145], v142 offset:3072
	s_add_u32 s48, s48, 0x40000
	s_addc_u32 s49, s49, 0
	s_mov_b32 m0, s55
	v_lshl_add_u64 v[200:201], s[48:49], 0, v[148:149]
	ds_read_b128 v[162:165], v169 offset:32768
	ds_read_b128 v[172:175], v169 offset:33792
	ds_read_b128 v[176:179], v169 offset:34816
	ds_read_b128 v[180:183], v169 offset:35840
	ds_read_b128 v[184:187], v169 offset:36864
	ds_read_b128 v[188:191], v169 offset:37888
	ds_read_b128 v[192:195], v169 offset:38912
	ds_read_b128 v[196:199], v169 offset:39936
	global_load_lds_dwordx4 v[200:201], off
	v_lshl_add_u64 v[200:201], s[48:49], 0, v[152:153]
	s_mov_b32 m0, s56
	s_nop 0
	global_load_lds_dwordx4 v[200:201], off
	s_waitcnt lgkmcnt(8)
	s_barrier
	s_waitcnt lgkmcnt(0)
	s_setprio 1
	s_waitcnt lgkmcnt(0)
	v_mfma_f32_16x16x32_bf16 v[126:129], v[130:133], v[162:165], v[126:129]
	v_mfma_f32_16x16x32_bf16 v[122:125], v[138:141], v[162:165], v[122:125]
	v_mfma_f32_16x16x32_bf16 v[114:117], v[130:133], v[176:179], v[114:117]
	v_mfma_f32_16x16x32_bf16 v[106:109], v[138:141], v[176:179], v[106:109]
	v_mfma_f32_16x16x32_bf16 v[98:101], v[130:133], v[184:187], v[98:101]
	v_mfma_f32_16x16x32_bf16 v[90:93], v[138:141], v[184:187], v[90:93]
	v_mfma_f32_16x16x32_bf16 v[82:85], v[130:133], v[192:195], v[82:85]
	v_mfma_f32_16x16x32_bf16 v[74:77], v[138:141], v[192:195], v[74:77]
	v_mfma_f32_16x16x32_bf16 v[126:129], v[134:137], v[172:175], v[126:129]
	v_mfma_f32_16x16x32_bf16 v[122:125], v[142:145], v[172:175], v[122:125]
	v_mfma_f32_16x16x32_bf16 v[114:117], v[134:137], v[180:183], v[114:117]
	v_mfma_f32_16x16x32_bf16 v[106:109], v[142:145], v[180:183], v[106:109]
	v_mfma_f32_16x16x32_bf16 v[98:101], v[134:137], v[188:191], v[98:101]
	v_mfma_f32_16x16x32_bf16 v[90:93], v[142:145], v[188:191], v[90:93]
	v_mfma_f32_16x16x32_bf16 v[82:85], v[134:137], v[196:199], v[82:85]
	v_mfma_f32_16x16x32_bf16 v[74:77], v[142:145], v[196:199], v[74:77]
	s_setprio 0
	s_barrier
	s_add_i32 s48, 0, 0x1c000
	s_add_i32 s43, s43, s52
	v_add_u32_e32 v156, s48, v166
	v_lshl_add_u64 v[216:217], v[216:217], 0, s[10:11]
	s_mov_b32 m0, s43
	ds_read_b128 v[200:203], v156
	ds_read_b128 v[204:207], v156 offset:1024
	ds_read_b128 v[208:211], v156 offset:2048
	ds_read_b128 v[212:215], v156 offset:3072
	global_load_lds_dwordx4 v[216:217], off
	v_lshl_add_u64 v[216:217], v[218:219], 0, s[10:11]
	s_add_i32 m0, s43, 0x2000
	s_nop 0
	global_load_lds_dwordx4 v[216:217], off
	s_barrier
	s_waitcnt lgkmcnt(0)
	s_setprio 1
	s_waitcnt lgkmcnt(0)
	v_mfma_f32_16x16x32_bf16 v[118:121], v[200:203], v[162:165], v[118:121]
	v_mfma_f32_16x16x32_bf16 v[110:113], v[208:211], v[162:165], v[110:113]
	v_mfma_f32_16x16x32_bf16 v[102:105], v[200:203], v[176:179], v[102:105]
	v_mfma_f32_16x16x32_bf16 v[94:97], v[208:211], v[176:179], v[94:97]
	v_mfma_f32_16x16x32_bf16 v[86:89], v[200:203], v[184:187], v[86:89]
	v_mfma_f32_16x16x32_bf16 v[78:81], v[208:211], v[184:187], v[78:81]
	v_mfma_f32_16x16x32_bf16 v[70:73], v[200:203], v[192:195], v[70:73]
	v_mfma_f32_16x16x32_bf16 v[66:69], v[208:211], v[192:195], v[66:69]
	v_mfma_f32_16x16x32_bf16 v[118:121], v[204:207], v[172:175], v[118:121]
	v_mfma_f32_16x16x32_bf16 v[110:113], v[212:215], v[172:175], v[110:113]
	v_mfma_f32_16x16x32_bf16 v[102:105], v[204:207], v[180:183], v[102:105]
	v_mfma_f32_16x16x32_bf16 v[94:97], v[212:215], v[180:183], v[94:97]
	v_mfma_f32_16x16x32_bf16 v[86:89], v[204:207], v[188:191], v[86:89]
	v_mfma_f32_16x16x32_bf16 v[78:81], v[212:215], v[188:191], v[78:81]
	v_mfma_f32_16x16x32_bf16 v[70:73], v[204:207], v[196:199], v[70:73]
	v_mfma_f32_16x16x32_bf16 v[66:69], v[212:215], v[196:199], v[66:69]
	s_setprio 0
	s_mov_b32 m0, s60
	v_lshl_add_u64 v[216:217], v[220:221], 0, s[10:11]
	s_barrier
	ds_read_b128 v[162:165], v169 offset:49152
	ds_read_b128 v[172:175], v169 offset:50176
	ds_read_b128 v[176:179], v169 offset:51200
	ds_read_b128 v[180:183], v169 offset:52224
	ds_read_b128 v[184:187], v169 offset:53248
	ds_read_b128 v[188:191], v169 offset:54272
	ds_read_b128 v[192:195], v169 offset:55296
	ds_read_b128 v[196:199], v169 offset:56320
	global_load_lds_dwordx4 v[216:217], off
	v_lshl_add_u64 v[216:217], v[222:223], 0, s[10:11]
	s_mov_b32 m0, s61
	s_nop 0
	global_load_lds_dwordx4 v[216:217], off
	s_barrier
	s_waitcnt lgkmcnt(0)
	s_setprio 1
	s_waitcnt lgkmcnt(0)
	v_mfma_f32_16x16x32_bf16 v[62:65], v[130:133], v[162:165], v[62:65]
	v_mfma_f32_16x16x32_bf16 v[58:61], v[138:141], v[162:165], v[58:61]
	v_mfma_f32_16x16x32_bf16 v[50:53], v[130:133], v[176:179], v[50:53]
	v_mfma_f32_16x16x32_bf16 v[42:45], v[138:141], v[176:179], v[42:45]
	v_mfma_f32_16x16x32_bf16 v[34:37], v[130:133], v[184:187], v[34:37]
	v_mfma_f32_16x16x32_bf16 v[26:29], v[138:141], v[184:187], v[26:29]
	v_mfma_f32_16x16x32_bf16 v[18:21], v[130:133], v[192:195], v[18:21]
	v_mfma_f32_16x16x32_bf16 v[10:13], v[138:141], v[192:195], v[10:13]
	v_mfma_f32_16x16x32_bf16 v[62:65], v[134:137], v[172:175], v[62:65]
	v_mfma_f32_16x16x32_bf16 v[58:61], v[142:145], v[172:175], v[58:61]
	v_mfma_f32_16x16x32_bf16 v[50:53], v[134:137], v[180:183], v[50:53]
	v_mfma_f32_16x16x32_bf16 v[42:45], v[142:145], v[180:183], v[42:45]
	v_mfma_f32_16x16x32_bf16 v[34:37], v[134:137], v[188:191], v[34:37]
	v_mfma_f32_16x16x32_bf16 v[26:29], v[142:145], v[188:191], v[26:29]
	v_mfma_f32_16x16x32_bf16 v[18:21], v[134:137], v[196:199], v[18:21]
	v_mfma_f32_16x16x32_bf16 v[10:13], v[142:145], v[196:199], v[10:13]
	s_setprio 0
	s_barrier
	s_add_u32 s46, s46, 0x40080
	s_addc_u32 s47, s47, 0
	s_add_i32 s43, s48, s52
	v_lshl_add_u64 v[130:131], s[46:47], 0, v[150:151]
	s_mov_b32 m0, s43
	s_nop 0
	global_load_lds_dwordx4 v[130:131], off
	v_lshl_add_u64 v[130:131], s[46:47], 0, v[154:155]
	s_add_i32 m0, s43, 0x2000
	s_nop 0
	global_load_lds_dwordx4 v[130:131], off
	s_waitcnt vmcnt(6)
	s_barrier
	s_setprio 1
	v_mfma_f32_16x16x32_bf16 v[54:57], v[200:203], v[162:165], v[54:57]
	v_mfma_f32_16x16x32_bf16 v[46:49], v[208:211], v[162:165], v[46:49]
	v_mfma_f32_16x16x32_bf16 v[38:41], v[200:203], v[176:179], v[38:41]
	v_mfma_f32_16x16x32_bf16 v[30:33], v[208:211], v[176:179], v[30:33]
	v_mfma_f32_16x16x32_bf16 v[22:25], v[200:203], v[184:187], v[22:25]
	v_mfma_f32_16x16x32_bf16 v[14:17], v[208:211], v[184:187], v[14:17]
	v_mfma_f32_16x16x32_bf16 v[6:9], v[200:203], v[192:195], v[6:9]
	v_mfma_f32_16x16x32_bf16 v[2:5], v[208:211], v[192:195], v[2:5]
	v_mfma_f32_16x16x32_bf16 v[54:57], v[204:207], v[172:175], v[54:57]
	v_mfma_f32_16x16x32_bf16 v[46:49], v[212:215], v[172:175], v[46:49]
	v_mfma_f32_16x16x32_bf16 v[38:41], v[204:207], v[180:183], v[38:41]
	v_mfma_f32_16x16x32_bf16 v[30:33], v[212:215], v[180:183], v[30:33]
	v_mfma_f32_16x16x32_bf16 v[22:25], v[204:207], v[188:191], v[22:25]
	v_mfma_f32_16x16x32_bf16 v[14:17], v[212:215], v[188:191], v[14:17]
	v_mfma_f32_16x16x32_bf16 v[6:9], v[204:207], v[196:199], v[6:9]
	v_mfma_f32_16x16x32_bf16 v[2:5], v[212:215], v[196:199], v[2:5]
	s_setprio 0
	s_add_i32 s41, s41, 2
	s_add_u32 s44, s44, 0x100
	s_addc_u32 s45, s45, 0
	s_add_u32 s2, s2, 0x100
	s_addc_u32 s3, s3, 0
	s_cmp_gt_u32 s41, 13
	s_barrier
	s_cbranch_scc0 .LBB0_281
	v_mov_b32_e32 v130, v147
	v_mov_b32_e32 v171, v1
	s_ashr_i32 s41, s66, 1
	s_mov_b64 s[48:49], -1
	v_lshlrev_b32_e32 v173, 3, v130
	s_mov_b64 s[46:47], 0
	s_cmp_lt_i32 s41, 4
	s_mov_b64 s[44:45], 0
	s_cbranch_scc1 .LBB0_297
	s_cmp_gt_i32 s41, 5
	s_cbranch_scc0 .LBB0_291
	s_cmp_gt_i32 s41, 6
	s_cbranch_scc0 .LBB0_288
	s_cmp_eq_u32 s41, 7
	s_mov_b64 s[44:45], -1
	s_cbranch_scc0 .LBB0_287
	s_lshl_b32 s2, s33, 8
	s_or_b32 s2, s2, s59
	v_add_u32_e32 v140, s2, v173
	v_add_u32_e32 v130, 0x8000, v140
	s_lshl_b32 s2, s66, 8
	v_ashrrev_i32_e32 v130, 3, v130
	s_and_b32 s2, s2, 0x100
	v_and_b32_e32 v130, 0xfffffe00, v130
	s_add_i32 s2, s2, s58
	v_add3_u32 v134, s2, v171, v130
	v_ashrrev_i32_e32 v135, 31, v134
	v_lshlrev_b64 v[136:137], 13, v[134:135]
	v_and_b32_e32 v135, 0xff8, v140
	v_lshl_add_u64 v[136:137], s[14:15], 0, v[136:137]
	v_lshlrev_b32_e32 v156, 1, v135
	v_cvt_pk_bf16_f32 v130, v126, v127
	v_cvt_pk_bf16_f32 v131, v128, v129
	v_cvt_pk_bf16_f32 v132, v122, v123
	v_cvt_pk_bf16_f32 v133, v124, v125
	v_lshl_add_u64 v[138:139], v[136:137], 0, v[156:157]
	global_store_dwordx4 v[138:139], v[130:133], off sc1
	v_mov_b32_e32 v139, v157
	s_mov_b64 s[44:45], 0
	v_add_u32_e32 v130, 0x80, v140
	v_and_b32_e32 v135, 0xff8, v130
	v_lshlrev_b32_e32 v138, 1, v135
	v_cvt_pk_bf16_f32 v130, v118, v119
	v_cvt_pk_bf16_f32 v131, v120, v121
	v_cvt_pk_bf16_f32 v132, v110, v111
	v_cvt_pk_bf16_f32 v133, v112, v113
	v_lshl_add_u64 v[136:137], v[136:137], 0, v[138:139]
	global_store_dwordx4 v[136:137], v[130:133], off sc1
	s_nop 1
	v_add_u32_e32 v130, 16, v134
	v_ashrrev_i32_e32 v131, 31, v130
	v_lshlrev_b64 v[136:137], 13, v[130:131]
	v_lshl_add_u64 v[136:137], s[14:15], 0, v[136:137]
	v_cvt_pk_bf16_f32 v130, v114, v115
	v_cvt_pk_bf16_f32 v131, v116, v117
	v_cvt_pk_bf16_f32 v132, v106, v107
	v_cvt_pk_bf16_f32 v133, v108, v109
	v_lshl_add_u64 v[140:141], v[136:137], 0, v[156:157]
	global_store_dwordx4 v[140:141], v[130:133], off sc1
	v_lshl_add_u64 v[136:137], v[136:137], 0, v[138:139]
	s_nop 0
	v_cvt_pk_bf16_f32 v130, v102, v103
	v_cvt_pk_bf16_f32 v131, v104, v105
	v_cvt_pk_bf16_f32 v132, v94, v95
	v_cvt_pk_bf16_f32 v133, v96, v97
	global_store_dwordx4 v[136:137], v[130:133], off sc1
	s_nop 1
	v_add_u32_e32 v130, 32, v134
	v_ashrrev_i32_e32 v131, 31, v130
	v_lshlrev_b64 v[136:137], 13, v[130:131]
	v_lshl_add_u64 v[136:137], s[14:15], 0, v[136:137]
	v_cvt_pk_bf16_f32 v130, v98, v99
	v_cvt_pk_bf16_f32 v131, v100, v101
	v_cvt_pk_bf16_f32 v132, v90, v91
	v_cvt_pk_bf16_f32 v133, v92, v93
	v_lshl_add_u64 v[140:141], v[136:137], 0, v[156:157]
	global_store_dwordx4 v[140:141], v[130:133], off sc1
	v_lshl_add_u64 v[136:137], v[136:137], 0, v[138:139]
	s_nop 0
	v_cvt_pk_bf16_f32 v130, v86, v87
	v_cvt_pk_bf16_f32 v131, v88, v89
	v_cvt_pk_bf16_f32 v132, v78, v79
	v_cvt_pk_bf16_f32 v133, v80, v81
	global_store_dwordx4 v[136:137], v[130:133], off sc1
	s_nop 1
	v_add_u32_e32 v130, 48, v134
	v_ashrrev_i32_e32 v131, 31, v130
	v_lshlrev_b64 v[136:137], 13, v[130:131]
	v_lshl_add_u64 v[136:137], s[14:15], 0, v[136:137]
	v_cvt_pk_bf16_f32 v130, v82, v83
	v_cvt_pk_bf16_f32 v131, v84, v85
	v_cvt_pk_bf16_f32 v132, v74, v75
	v_cvt_pk_bf16_f32 v133, v76, v77
	v_lshl_add_u64 v[140:141], v[136:137], 0, v[156:157]
	global_store_dwordx4 v[140:141], v[130:133], off sc1
	v_lshl_add_u64 v[136:137], v[136:137], 0, v[138:139]
	s_nop 0
	v_cvt_pk_bf16_f32 v130, v70, v71
	v_cvt_pk_bf16_f32 v131, v72, v73
	v_cvt_pk_bf16_f32 v132, v66, v67
	v_cvt_pk_bf16_f32 v133, v68, v69
	global_store_dwordx4 v[136:137], v[130:133], off sc1
	s_nop 1
	v_add_u32_e32 v130, 0x80, v134
	v_ashrrev_i32_e32 v131, 31, v130
	v_lshlrev_b64 v[136:137], 13, v[130:131]
	v_lshl_add_u64 v[136:137], s[14:15], 0, v[136:137]
	v_cvt_pk_bf16_f32 v130, v62, v63
	v_cvt_pk_bf16_f32 v131, v64, v65
	v_cvt_pk_bf16_f32 v132, v58, v59
	v_cvt_pk_bf16_f32 v133, v60, v61
	v_lshl_add_u64 v[140:141], v[136:137], 0, v[156:157]
	global_store_dwordx4 v[140:141], v[130:133], off sc1
	v_lshl_add_u64 v[136:137], v[136:137], 0, v[138:139]
	s_nop 0
	v_cvt_pk_bf16_f32 v130, v54, v55
	v_cvt_pk_bf16_f32 v131, v56, v57
	v_cvt_pk_bf16_f32 v132, v46, v47
	v_cvt_pk_bf16_f32 v133, v48, v49
	global_store_dwordx4 v[136:137], v[130:133], off sc1
	s_nop 1
	v_add_u32_e32 v130, 0x90, v134
	v_ashrrev_i32_e32 v131, 31, v130
	v_lshlrev_b64 v[136:137], 13, v[130:131]
	v_lshl_add_u64 v[136:137], s[14:15], 0, v[136:137]
	v_cvt_pk_bf16_f32 v130, v50, v51
	v_cvt_pk_bf16_f32 v131, v52, v53
	v_cvt_pk_bf16_f32 v132, v42, v43
	v_cvt_pk_bf16_f32 v133, v44, v45
	v_lshl_add_u64 v[140:141], v[136:137], 0, v[156:157]
	global_store_dwordx4 v[140:141], v[130:133], off sc1
	v_lshl_add_u64 v[136:137], v[136:137], 0, v[138:139]
	s_nop 0
	v_cvt_pk_bf16_f32 v130, v38, v39
	v_cvt_pk_bf16_f32 v131, v40, v41
	v_cvt_pk_bf16_f32 v132, v30, v31
	v_cvt_pk_bf16_f32 v133, v32, v33
	global_store_dwordx4 v[136:137], v[130:133], off sc1
	s_nop 1
	v_add_u32_e32 v130, 0xa0, v134
	v_ashrrev_i32_e32 v131, 31, v130
	v_lshlrev_b64 v[136:137], 13, v[130:131]
	v_lshl_add_u64 v[136:137], s[14:15], 0, v[136:137]
	v_cvt_pk_bf16_f32 v130, v34, v35
	v_cvt_pk_bf16_f32 v131, v36, v37
	v_cvt_pk_bf16_f32 v132, v26, v27
	v_cvt_pk_bf16_f32 v133, v28, v29
	v_lshl_add_u64 v[140:141], v[136:137], 0, v[156:157]
	global_store_dwordx4 v[140:141], v[130:133], off sc1
	v_lshl_add_u64 v[136:137], v[136:137], 0, v[138:139]
	s_nop 0
	v_cvt_pk_bf16_f32 v130, v22, v23
	v_cvt_pk_bf16_f32 v131, v24, v25
	v_cvt_pk_bf16_f32 v132, v14, v15
	v_cvt_pk_bf16_f32 v133, v16, v17
	global_store_dwordx4 v[136:137], v[130:133], off sc1
	s_nop 1
	v_add_u32_e32 v130, 0xb0, v134
	v_ashrrev_i32_e32 v131, 31, v130
	v_lshlrev_b64 v[134:135], 13, v[130:131]
	v_lshl_add_u64 v[134:135], s[14:15], 0, v[134:135]
	v_cvt_pk_bf16_f32 v130, v18, v19
	v_cvt_pk_bf16_f32 v131, v20, v21
	v_cvt_pk_bf16_f32 v132, v10, v11
	v_cvt_pk_bf16_f32 v133, v12, v13
	v_lshl_add_u64 v[136:137], v[134:135], 0, v[156:157]
	global_store_dwordx4 v[136:137], v[130:133], off sc1
	v_lshl_add_u64 v[134:135], v[134:135], 0, v[138:139]
	s_nop 0
	v_cvt_pk_bf16_f32 v130, v6, v7
	v_cvt_pk_bf16_f32 v131, v8, v9
	v_cvt_pk_bf16_f32 v132, v2, v3
	v_cvt_pk_bf16_f32 v133, v4, v5
	global_store_dwordx4 v[134:135], v[130:133], off sc1

.LBB0_288:
	s_and_b64 vcc, exec, s[48:49]
	s_cbranch_vccz .LBB0_290
	s_lshl_b32 s2, s66, 8
	s_and_b32 s2, s2, 0x100
	s_or_b32 s2, s2, s59
	v_add_u32_e32 v162, s2, v173
	v_ashrrev_i32_e32 v163, 31, v162
	v_lshl_add_u64 v[142:143], v[162:163], 2, s[18:19]
	global_load_dwordx4 v[130:133], v[142:143], off offset:512
	global_load_dwordx4 v[138:141], v[142:143], off
	global_load_dwordx4 v[134:137], v[142:143], off offset:16
	v_mul_f32_e32 v144, 0xbfb8aa3b, v126
	v_mul_f32_e32 v145, 0xbfb8aa3b, v127
	v_exp_f32_e32 v177, v144
	v_exp_f32_e32 v179, v145
	global_load_dwordx4 v[142:145], v[142:143], off offset:528
	v_mul_f32_e32 v156, 0xbfb8aa3b, v128
	v_mul_f32_e32 v164, 0xbfb8aa3b, v129
	v_mul_f32_e32 v165, 0xbfb8aa3b, v122
	v_mul_f32_e32 v168, 0xbfb8aa3b, v123
	v_exp_f32_e32 v156, v156
	v_exp_f32_e32 v180, v164
	v_exp_f32_e32 v181, v165
	v_exp_f32_e32 v168, v168
	s_lshl_b32 s2, s33, 8
	s_add_i32 s2, s2, s58
	v_mul_f32_e32 v172, 0xbfb8aa3b, v124
	v_mul_f32_e32 v174, 0xbfb8aa3b, v125
	v_add_u32_e32 v183, s2, v171
	v_add_f32_e32 v177, 1.0, v177
	v_add_f32_e32 v179, 1.0, v179
	v_exp_f32_e32 v172, v172
	v_exp_f32_e32 v174, v174
	v_add_u32_e32 v164, 0x8000, v183
	v_add_f32_e32 v156, 1.0, v156
	v_add_f32_e32 v180, 1.0, v180
	v_add_f32_e32 v181, 1.0, v181
	v_add_f32_e32 v168, 1.0, v168
	v_rcp_f32_e32 v186, v177
	v_rcp_f32_e32 v187, v179
	v_ashrrev_i32_e32 v165, 31, v164
	v_rcp_f32_e32 v188, v156
	v_rcp_f32_e32 v189, v180
	v_rcp_f32_e32 v192, v181
	v_rcp_f32_e32 v168, v168
	v_mul_f32_e32 v175, 0xbfb8aa3b, v118
	v_lshlrev_b64 v[164:165], 10, v[164:165]
	v_exp_f32_e32 v175, v175
	v_lshlrev_b64 v[162:163], 1, v[162:163]
	v_lshl_add_u64 v[164:165], s[20:21], 0, v[164:165]
	v_add_f32_e32 v172, 1.0, v172
	v_add_f32_e32 v174, 1.0, v174
	v_lshl_add_u64 v[190:191], v[164:165], 0, v[162:163]
	v_rcp_f32_e32 v172, v172
	v_rcp_f32_e32 v174, v174
	v_add_f32_e32 v175, 1.0, v175
	v_mul_f32_e32 v178, 0xbfb8aa3b, v120
	v_rcp_f32_e32 v193, v175
	v_mul_f32_e32 v176, 0xbfb8aa3b, v119
	v_exp_f32_e32 v176, v176
	s_waitcnt vmcnt(0)
	v_sub_f32_e32 v164, 1.0, v131
	v_sub_f32_e32 v185, 1.0, v138
	v_sub_f32_e32 v184, 1.0, v139
	v_sub_f32_e32 v182, 1.0, v140
	v_sub_f32_e32 v181, 1.0, v141
	v_sub_f32_e32 v180, 1.0, v134
	v_sub_f32_e32 v179, 1.0, v135
	v_fma_f32 v165, v186, v185, v138
	v_fma_f32 v186, v187, v184, v139
	v_fma_f32 v187, v188, v182, v140
	v_fma_f32 v188, v189, v181, v141
	v_fma_f32 v189, v192, v180, v134
	v_fma_f32 v168, v168, v179, v135
	v_log_f32_e32 v165, v165
	v_log_f32_e32 v186, v186
	v_log_f32_e32 v187, v187
	v_log_f32_e32 v188, v188
	v_log_f32_e32 v189, v189
	v_log_f32_e32 v168, v168
	v_sub_f32_e32 v177, 1.0, v136
	v_sub_f32_e32 v175, 1.0, v137
	v_fma_f32 v172, v172, v177, v136
	v_fma_f32 v174, v174, v175, v137
	v_cvt_pk_bf16_f32 v186, v165, v186
	v_exp_f32_e32 v165, v178
	v_log_f32_e32 v172, v172
	v_log_f32_e32 v174, v174
	v_cvt_pk_bf16_f32 v187, v187, v188
	v_cvt_pk_bf16_f32 v188, v189, v168
	v_mul_f32_e32 v168, 0xbfb8aa3b, v121
	v_exp_f32_e32 v168, v168
	v_add_f32_e32 v165, 1.0, v165
	v_cvt_pk_bf16_f32 v189, v172, v174
	v_rcp_f32_e32 v172, v165
	v_add_f32_e32 v168, 1.0, v168
	v_rcp_f32_e32 v168, v168
	v_sub_f32_e32 v165, 1.0, v132
	v_fma_f32 v172, v172, v165, v132
	v_add_f32_e32 v176, 1.0, v176
	global_store_dwordx4 v[190:191], v[186:189], off sc1
	v_mul_f32_e32 v174, 0xbfb8aa3b, v110
	v_rcp_f32_e32 v176, v176
	v_log_f32_e32 v187, v172
	v_sub_f32_e32 v172, 1.0, v133
	v_fma_f32 v168, v168, v172, v133
	v_exp_f32_e32 v174, v174
	v_log_f32_e32 v188, v168
	v_mul_f32_e32 v168, 0xbfb8aa3b, v111
	v_exp_f32_e32 v168, v168
	v_fma_f32 v176, v176, v164, v131
	v_add_f32_e32 v174, 1.0, v174
	v_log_f32_e32 v186, v176
	v_rcp_f32_e32 v176, v174
	v_add_f32_e32 v168, 1.0, v168
	v_rcp_f32_e32 v178, v168
	v_sub_f32_e32 v174, 1.0, v142
	v_fma_f32 v168, v176, v174, v142
	v_log_f32_e32 v189, v168
	v_sub_f32_e32 v168, 1.0, v143
	v_fma_f32 v176, v178, v168, v143
	v_mul_f32_e32 v178, 0xbfb8aa3b, v112
	v_sub_f32_e32 v156, 1.0, v130
	v_exp_f32_e32 v178, v178
	v_fma_f32 v192, v193, v156, v130
	v_log_f32_e32 v193, v176
	v_mul_f32_e32 v176, 0xbfb8aa3b, v113
	v_exp_f32_e32 v194, v176
	v_add_f32_e32 v176, 1.0, v178
	v_rcp_f32_e32 v178, v176
	v_sub_f32_e32 v176, 1.0, v144
	v_add_f32_e32 v194, 1.0, v194
	v_rcp_f32_e32 v194, v194
	v_fma_f32 v178, v178, v176, v144
	v_log_f32_e32 v195, v178
	v_sub_f32_e32 v178, 1.0, v145
	v_fma_f32 v194, v194, v178, v145
	v_log_f32_e32 v192, v192
	v_log_f32_e32 v194, v194
	v_cvt_pk_bf16_f32 v187, v187, v188
	v_cvt_pk_bf16_f32 v188, v189, v193
	v_cvt_pk_bf16_f32 v186, v192, v186
	v_cvt_pk_bf16_f32 v189, v195, v194
	global_store_dwordx4 v[190:191], v[186:189], off offset:256 sc1
	v_mul_f32_e32 v192, 0xbfb8aa3b, v106
	v_mul_f32_e32 v193, 0xbfb8aa3b, v107
	v_mul_f32_e32 v187, 0xbfb8aa3b, v114
	v_exp_f32_e32 v188, v187
	v_mul_f32_e32 v187, 0xbfb8aa3b, v115
	v_exp_f32_e32 v189, v187
	v_add_u32_e32 v186, 0x8010, v183
	v_add_f32_e32 v188, 1.0, v188
	v_rcp_f32_e32 v188, v188
	v_add_f32_e32 v189, 1.0, v189
	v_rcp_f32_e32 v189, v189
	v_ashrrev_i32_e32 v187, 31, v186
	v_lshlrev_b64 v[190:191], 10, v[186:187]
	v_fma_f32 v186, v188, v185, v138
	v_fma_f32 v187, v189, v184, v139
	v_mul_f32_e32 v188, 0xbfb8aa3b, v116
	v_mul_f32_e32 v189, 0xbfb8aa3b, v117
	v_exp_f32_e32 v188, v188
	v_exp_f32_e32 v189, v189
	v_exp_f32_e32 v192, v192
	v_exp_f32_e32 v193, v193
	v_add_f32_e32 v188, 1.0, v188
	v_add_f32_e32 v189, 1.0, v189
	v_add_f32_e32 v192, 1.0, v192
	v_add_f32_e32 v193, 1.0, v193
	v_rcp_f32_e32 v188, v188
	v_rcp_f32_e32 v189, v189
	v_rcp_f32_e32 v192, v192
	v_rcp_f32_e32 v193, v193
	v_mul_f32_e32 v194, 0xbfb8aa3b, v108
	v_mul_f32_e32 v195, 0xbfb8aa3b, v109
	v_fma_f32 v188, v188, v182, v140
	v_fma_f32 v189, v189, v181, v141
	v_fma_f32 v192, v192, v180, v134
	v_exp_f32_e32 v194, v194
	v_exp_f32_e32 v195, v195
	v_fma_f32 v193, v193, v179, v135
	v_log_f32_e32 v186, v186
	v_log_f32_e32 v187, v187
	v_log_f32_e32 v188, v188
	v_log_f32_e32 v189, v189
	v_log_f32_e32 v192, v192
	v_log_f32_e32 v193, v193
	v_add_f32_e32 v194, 1.0, v194
	v_add_f32_e32 v195, 1.0, v195
	v_rcp_f32_e32 v194, v194
	v_rcp_f32_e32 v195, v195
	v_cvt_pk_bf16_f32 v186, v186, v187
	v_cvt_pk_bf16_f32 v187, v188, v189
	v_cvt_pk_bf16_f32 v188, v192, v193
	v_mul_f32_e32 v192, 0xbfb8aa3b, v102
	v_mul_f32_e32 v193, 0xbfb8aa3b, v103
	v_exp_f32_e32 v192, v192
	v_exp_f32_e32 v193, v193
	v_fma_f32 v194, v194, v177, v136
	v_fma_f32 v195, v195, v175, v137
	v_log_f32_e32 v194, v194
	v_log_f32_e32 v195, v195
	v_add_f32_e32 v192, 1.0, v192
	v_add_f32_e32 v193, 1.0, v193
	v_rcp_f32_e32 v192, v192
	v_rcp_f32_e32 v193, v193
	v_lshl_add_u64 v[190:191], s[20:21], 0, v[190:191]
	v_cvt_pk_bf16_f32 v189, v194, v195
	v_lshl_add_u64 v[190:191], v[190:191], 0, v[162:163]
	global_store_dwordx4 v[190:191], v[186:189], off sc1
	v_mul_f32_e32 v194, 0xbfb8aa3b, v96
	v_mul_f32_e32 v195, 0xbfb8aa3b, v97
	v_fma_f32 v186, v192, v156, v130
	v_fma_f32 v187, v193, v164, v131
	v_mul_f32_e32 v188, 0xbfb8aa3b, v104
	v_mul_f32_e32 v189, 0xbfb8aa3b, v105
	v_mul_f32_e32 v192, 0xbfb8aa3b, v94
	v_mul_f32_e32 v193, 0xbfb8aa3b, v95
	v_exp_f32_e32 v188, v188
	v_exp_f32_e32 v189, v189
	v_exp_f32_e32 v192, v192
	v_exp_f32_e32 v193, v193
	v_exp_f32_e32 v194, v194
	v_exp_f32_e32 v195, v195
	v_add_f32_e32 v188, 1.0, v188
	v_add_f32_e32 v189, 1.0, v189
	v_add_f32_e32 v192, 1.0, v192
	v_add_f32_e32 v193, 1.0, v193
	v_add_f32_e32 v194, 1.0, v194
	v_add_f32_e32 v195, 1.0, v195
	v_rcp_f32_e32 v188, v188
	v_rcp_f32_e32 v189, v189
	v_rcp_f32_e32 v192, v192
	v_rcp_f32_e32 v193, v193
	v_rcp_f32_e32 v194, v194
	v_rcp_f32_e32 v195, v195
	v_fma_f32 v188, v188, v165, v132
	v_fma_f32 v189, v189, v172, v133
	v_fma_f32 v192, v192, v174, v142
	v_fma_f32 v193, v193, v168, v143
	v_fma_f32 v194, v194, v176, v144
	v_fma_f32 v195, v195, v178, v145
	v_log_f32_e32 v186, v186
	v_log_f32_e32 v187, v187
	v_log_f32_e32 v188, v188
	v_log_f32_e32 v189, v189
	v_log_f32_e32 v192, v192
	v_log_f32_e32 v193, v193
	v_log_f32_e32 v194, v194
	v_log_f32_e32 v195, v195
	v_cvt_pk_bf16_f32 v186, v186, v187
	v_cvt_pk_bf16_f32 v187, v188, v189
	v_cvt_pk_bf16_f32 v188, v192, v193
	v_cvt_pk_bf16_f32 v189, v194, v195
	global_store_dwordx4 v[190:191], v[186:189], off offset:256 sc1
	v_mul_f32_e32 v192, 0xbfb8aa3b, v90
	v_mul_f32_e32 v193, 0xbfb8aa3b, v91
	v_mul_f32_e32 v187, 0xbfb8aa3b, v98
	v_exp_f32_e32 v188, v187
	v_mul_f32_e32 v187, 0xbfb8aa3b, v99
	v_exp_f32_e32 v189, v187
	v_add_u32_e32 v186, 0x8020, v183
	v_add_f32_e32 v188, 1.0, v188
	v_rcp_f32_e32 v188, v188
	v_add_f32_e32 v189, 1.0, v189
	v_rcp_f32_e32 v189, v189
	v_ashrrev_i32_e32 v187, 31, v186
	v_lshlrev_b64 v[190:191], 10, v[186:187]
	v_fma_f32 v186, v188, v185, v138
	v_fma_f32 v187, v189, v184, v139
	v_mul_f32_e32 v188, 0xbfb8aa3b, v100
	v_mul_f32_e32 v189, 0xbfb8aa3b, v101
	v_exp_f32_e32 v188, v188
	v_exp_f32_e32 v189, v189
	v_exp_f32_e32 v192, v192
	v_exp_f32_e32 v193, v193
	v_add_f32_e32 v188, 1.0, v188
	v_add_f32_e32 v189, 1.0, v189
	v_add_f32_e32 v192, 1.0, v192
	v_add_f32_e32 v193, 1.0, v193
	v_rcp_f32_e32 v188, v188
	v_rcp_f32_e32 v189, v189
	v_rcp_f32_e32 v192, v192
	v_rcp_f32_e32 v193, v193
	v_mul_f32_e32 v194, 0xbfb8aa3b, v92
	v_mul_f32_e32 v195, 0xbfb8aa3b, v93
	v_fma_f32 v188, v188, v182, v140
	v_fma_f32 v189, v189, v181, v141
	v_fma_f32 v192, v192, v180, v134
	v_exp_f32_e32 v194, v194
	v_exp_f32_e32 v195, v195
	v_fma_f32 v193, v193, v179, v135
	v_log_f32_e32 v186, v186
	v_log_f32_e32 v187, v187
	v_log_f32_e32 v188, v188
	v_log_f32_e32 v189, v189
	v_log_f32_e32 v192, v192
	v_log_f32_e32 v193, v193
	v_add_f32_e32 v194, 1.0, v194
	v_add_f32_e32 v195, 1.0, v195
	v_rcp_f32_e32 v194, v194
	v_rcp_f32_e32 v195, v195
	v_cvt_pk_bf16_f32 v186, v186, v187
	v_cvt_pk_bf16_f32 v187, v188, v189
	v_cvt_pk_bf16_f32 v188, v192, v193
	v_mul_f32_e32 v192, 0xbfb8aa3b, v86
	v_mul_f32_e32 v193, 0xbfb8aa3b, v87
	v_exp_f32_e32 v192, v192
	v_exp_f32_e32 v193, v193
	v_fma_f32 v194, v194, v177, v136
	v_fma_f32 v195, v195, v175, v137
	v_log_f32_e32 v194, v194
	v_log_f32_e32 v195, v195
	v_add_f32_e32 v192, 1.0, v192
	v_add_f32_e32 v193, 1.0, v193
	v_rcp_f32_e32 v192, v192
	v_rcp_f32_e32 v193, v193
	v_lshl_add_u64 v[190:191], s[20:21], 0, v[190:191]
	v_cvt_pk_bf16_f32 v189, v194, v195
	v_lshl_add_u64 v[190:191], v[190:191], 0, v[162:163]
	global_store_dwordx4 v[190:191], v[186:189], off sc1
	v_mul_f32_e32 v194, 0xbfb8aa3b, v80
	v_mul_f32_e32 v195, 0xbfb8aa3b, v81
	v_fma_f32 v186, v192, v156, v130
	v_fma_f32 v187, v193, v164, v131
	v_mul_f32_e32 v188, 0xbfb8aa3b, v88
	v_mul_f32_e32 v189, 0xbfb8aa3b, v89
	v_mul_f32_e32 v192, 0xbfb8aa3b, v78
	v_mul_f32_e32 v193, 0xbfb8aa3b, v79
	v_exp_f32_e32 v188, v188
	v_exp_f32_e32 v189, v189
	v_exp_f32_e32 v192, v192
	v_exp_f32_e32 v193, v193
	v_exp_f32_e32 v194, v194
	v_exp_f32_e32 v195, v195
	v_add_f32_e32 v188, 1.0, v188
	v_add_f32_e32 v189, 1.0, v189
	v_add_f32_e32 v192, 1.0, v192
	v_add_f32_e32 v193, 1.0, v193
	v_add_f32_e32 v194, 1.0, v194
	v_add_f32_e32 v195, 1.0, v195
	v_rcp_f32_e32 v188, v188
	v_rcp_f32_e32 v189, v189
	v_rcp_f32_e32 v192, v192
	v_rcp_f32_e32 v193, v193
	v_rcp_f32_e32 v194, v194
	v_rcp_f32_e32 v195, v195
	v_fma_f32 v188, v188, v165, v132
	v_fma_f32 v189, v189, v172, v133
	v_fma_f32 v192, v192, v174, v142
	v_fma_f32 v193, v193, v168, v143
	v_fma_f32 v194, v194, v176, v144
	v_fma_f32 v195, v195, v178, v145
	v_log_f32_e32 v186, v186
	v_log_f32_e32 v187, v187
	v_log_f32_e32 v188, v188
	v_log_f32_e32 v189, v189
	v_log_f32_e32 v192, v192
	v_log_f32_e32 v193, v193
	v_log_f32_e32 v194, v194
	v_log_f32_e32 v195, v195
	v_cvt_pk_bf16_f32 v186, v186, v187
	v_cvt_pk_bf16_f32 v187, v188, v189
	v_cvt_pk_bf16_f32 v188, v192, v193
	v_cvt_pk_bf16_f32 v189, v194, v195
	global_store_dwordx4 v[190:191], v[186:189], off offset:256 sc1
	v_mul_f32_e32 v192, 0xbfb8aa3b, v74
	v_mul_f32_e32 v193, 0xbfb8aa3b, v75
	v_mul_f32_e32 v187, 0xbfb8aa3b, v82
	v_exp_f32_e32 v188, v187
	v_mul_f32_e32 v187, 0xbfb8aa3b, v83
	v_exp_f32_e32 v189, v187
	v_add_u32_e32 v186, 0x8030, v183
	v_add_f32_e32 v188, 1.0, v188
	v_rcp_f32_e32 v188, v188
	v_add_f32_e32 v189, 1.0, v189
	v_rcp_f32_e32 v189, v189
	v_ashrrev_i32_e32 v187, 31, v186
	v_lshlrev_b64 v[190:191], 10, v[186:187]
	v_fma_f32 v186, v188, v185, v138
	v_fma_f32 v187, v189, v184, v139
	v_mul_f32_e32 v188, 0xbfb8aa3b, v84
	v_mul_f32_e32 v189, 0xbfb8aa3b, v85
	v_exp_f32_e32 v188, v188
	v_exp_f32_e32 v189, v189
	v_exp_f32_e32 v192, v192
	v_exp_f32_e32 v193, v193
	v_add_f32_e32 v188, 1.0, v188
	v_add_f32_e32 v189, 1.0, v189
	v_add_f32_e32 v192, 1.0, v192
	v_add_f32_e32 v193, 1.0, v193
	v_rcp_f32_e32 v188, v188
	v_rcp_f32_e32 v189, v189
	v_rcp_f32_e32 v192, v192
	v_rcp_f32_e32 v193, v193
	v_mul_f32_e32 v194, 0xbfb8aa3b, v76
	v_mul_f32_e32 v195, 0xbfb8aa3b, v77
	v_fma_f32 v188, v188, v182, v140
	v_fma_f32 v189, v189, v181, v141
	v_fma_f32 v192, v192, v180, v134
	v_exp_f32_e32 v194, v194
	v_exp_f32_e32 v195, v195
	v_fma_f32 v193, v193, v179, v135
	v_log_f32_e32 v186, v186
	v_log_f32_e32 v187, v187
	v_log_f32_e32 v188, v188
	v_log_f32_e32 v189, v189
	v_log_f32_e32 v192, v192
	v_log_f32_e32 v193, v193
	v_add_f32_e32 v194, 1.0, v194
	v_add_f32_e32 v195, 1.0, v195
	v_rcp_f32_e32 v194, v194
	v_rcp_f32_e32 v195, v195
	v_cvt_pk_bf16_f32 v186, v186, v187
	v_cvt_pk_bf16_f32 v187, v188, v189
	v_cvt_pk_bf16_f32 v188, v192, v193
	v_mul_f32_e32 v192, 0xbfb8aa3b, v70
	v_mul_f32_e32 v193, 0xbfb8aa3b, v71
	v_exp_f32_e32 v192, v192
	v_exp_f32_e32 v193, v193
	v_fma_f32 v194, v194, v177, v136
	v_fma_f32 v195, v195, v175, v137
	v_log_f32_e32 v194, v194
	v_log_f32_e32 v195, v195
	v_add_f32_e32 v192, 1.0, v192
	v_add_f32_e32 v193, 1.0, v193
	v_rcp_f32_e32 v192, v192
	v_rcp_f32_e32 v193, v193
	v_lshl_add_u64 v[190:191], s[20:21], 0, v[190:191]
	v_cvt_pk_bf16_f32 v189, v194, v195
	v_lshl_add_u64 v[190:191], v[190:191], 0, v[162:163]
	global_store_dwordx4 v[190:191], v[186:189], off sc1
	v_mul_f32_e32 v194, 0xbfb8aa3b, v68
	v_mul_f32_e32 v195, 0xbfb8aa3b, v69
	v_fma_f32 v186, v192, v156, v130
	v_fma_f32 v187, v193, v164, v131
	v_mul_f32_e32 v188, 0xbfb8aa3b, v72
	v_mul_f32_e32 v189, 0xbfb8aa3b, v73
	v_mul_f32_e32 v192, 0xbfb8aa3b, v66
	v_mul_f32_e32 v193, 0xbfb8aa3b, v67
	v_exp_f32_e32 v188, v188
	v_exp_f32_e32 v189, v189
	v_exp_f32_e32 v192, v192
	v_exp_f32_e32 v193, v193
	v_exp_f32_e32 v194, v194
	v_exp_f32_e32 v195, v195
	v_add_f32_e32 v188, 1.0, v188
	v_add_f32_e32 v189, 1.0, v189
	v_add_f32_e32 v192, 1.0, v192
	v_add_f32_e32 v193, 1.0, v193
	v_add_f32_e32 v194, 1.0, v194
	v_add_f32_e32 v195, 1.0, v195
	v_rcp_f32_e32 v188, v188
	v_rcp_f32_e32 v189, v189
	v_rcp_f32_e32 v192, v192
	v_rcp_f32_e32 v193, v193
	v_rcp_f32_e32 v194, v194
	v_rcp_f32_e32 v195, v195
	v_fma_f32 v188, v188, v165, v132
	v_fma_f32 v189, v189, v172, v133
	v_fma_f32 v192, v192, v174, v142
	v_fma_f32 v193, v193, v168, v143
	v_fma_f32 v194, v194, v176, v144
	v_fma_f32 v195, v195, v178, v145
	v_log_f32_e32 v186, v186
	v_log_f32_e32 v187, v187
	v_log_f32_e32 v188, v188
	v_log_f32_e32 v189, v189
	v_log_f32_e32 v192, v192
	v_log_f32_e32 v193, v193
	v_log_f32_e32 v194, v194
	v_log_f32_e32 v195, v195
	v_cvt_pk_bf16_f32 v186, v186, v187
	v_cvt_pk_bf16_f32 v187, v188, v189
	v_cvt_pk_bf16_f32 v188, v192, v193
	v_cvt_pk_bf16_f32 v189, v194, v195
	global_store_dwordx4 v[190:191], v[186:189], off offset:256 sc1
	v_mul_f32_e32 v192, 0xbfb8aa3b, v58
	v_mul_f32_e32 v193, 0xbfb8aa3b, v59
	v_mul_f32_e32 v187, 0xbfb8aa3b, v62
	v_exp_f32_e32 v188, v187
	v_mul_f32_e32 v187, 0xbfb8aa3b, v63
	v_exp_f32_e32 v189, v187
	v_add_u32_e32 v186, 0x8080, v183
	v_add_f32_e32 v188, 1.0, v188
	v_rcp_f32_e32 v188, v188
	v_add_f32_e32 v189, 1.0, v189
	v_rcp_f32_e32 v189, v189
	v_ashrrev_i32_e32 v187, 31, v186
	v_lshlrev_b64 v[190:191], 10, v[186:187]
	v_fma_f32 v186, v188, v185, v138
	v_fma_f32 v187, v189, v184, v139
	v_mul_f32_e32 v188, 0xbfb8aa3b, v64
	v_mul_f32_e32 v189, 0xbfb8aa3b, v65
	v_exp_f32_e32 v188, v188
	v_exp_f32_e32 v189, v189
	v_exp_f32_e32 v192, v192
	v_exp_f32_e32 v193, v193
	v_add_f32_e32 v188, 1.0, v188
	v_add_f32_e32 v189, 1.0, v189
	v_add_f32_e32 v192, 1.0, v192
	v_add_f32_e32 v193, 1.0, v193
	v_rcp_f32_e32 v188, v188
	v_rcp_f32_e32 v189, v189
	v_rcp_f32_e32 v192, v192
	v_rcp_f32_e32 v193, v193
	v_mul_f32_e32 v194, 0xbfb8aa3b, v60
	v_mul_f32_e32 v195, 0xbfb8aa3b, v61
	v_fma_f32 v188, v188, v182, v140
	v_fma_f32 v189, v189, v181, v141
	v_fma_f32 v192, v192, v180, v134
	v_exp_f32_e32 v194, v194
	v_exp_f32_e32 v195, v195
	v_fma_f32 v193, v193, v179, v135
	v_log_f32_e32 v186, v186
	v_log_f32_e32 v187, v187
	v_log_f32_e32 v188, v188
	v_log_f32_e32 v189, v189
	v_log_f32_e32 v192, v192
	v_log_f32_e32 v193, v193
	v_add_f32_e32 v194, 1.0, v194
	v_add_f32_e32 v195, 1.0, v195
	v_rcp_f32_e32 v194, v194
	v_rcp_f32_e32 v195, v195
	v_cvt_pk_bf16_f32 v186, v186, v187
	v_cvt_pk_bf16_f32 v187, v188, v189
	v_cvt_pk_bf16_f32 v188, v192, v193
	v_mul_f32_e32 v192, 0xbfb8aa3b, v54
	v_mul_f32_e32 v193, 0xbfb8aa3b, v55
	v_exp_f32_e32 v192, v192
	v_exp_f32_e32 v193, v193
	v_fma_f32 v194, v194, v177, v136
	v_fma_f32 v195, v195, v175, v137
	v_log_f32_e32 v194, v194
	v_log_f32_e32 v195, v195
	v_add_f32_e32 v192, 1.0, v192
	v_add_f32_e32 v193, 1.0, v193
	v_rcp_f32_e32 v192, v192
	v_rcp_f32_e32 v193, v193
	v_lshl_add_u64 v[190:191], s[20:21], 0, v[190:191]
	v_cvt_pk_bf16_f32 v189, v194, v195
	v_lshl_add_u64 v[190:191], v[190:191], 0, v[162:163]
	global_store_dwordx4 v[190:191], v[186:189], off sc1
	v_mul_f32_e32 v194, 0xbfb8aa3b, v48
	v_mul_f32_e32 v195, 0xbfb8aa3b, v49
	v_fma_f32 v186, v192, v156, v130
	v_fma_f32 v187, v193, v164, v131
	v_mul_f32_e32 v188, 0xbfb8aa3b, v56
	v_mul_f32_e32 v189, 0xbfb8aa3b, v57
	v_mul_f32_e32 v192, 0xbfb8aa3b, v46
	v_mul_f32_e32 v193, 0xbfb8aa3b, v47
	v_exp_f32_e32 v188, v188
	v_exp_f32_e32 v189, v189
	v_exp_f32_e32 v192, v192
	v_exp_f32_e32 v193, v193
	v_exp_f32_e32 v194, v194
	v_exp_f32_e32 v195, v195
	v_add_f32_e32 v188, 1.0, v188
	v_add_f32_e32 v189, 1.0, v189
	v_add_f32_e32 v192, 1.0, v192
	v_add_f32_e32 v193, 1.0, v193
	v_add_f32_e32 v194, 1.0, v194
	v_add_f32_e32 v195, 1.0, v195
	v_rcp_f32_e32 v188, v188
	v_rcp_f32_e32 v189, v189
	v_rcp_f32_e32 v192, v192
	v_rcp_f32_e32 v193, v193
	v_rcp_f32_e32 v194, v194
	v_rcp_f32_e32 v195, v195
	v_fma_f32 v188, v188, v165, v132
	v_fma_f32 v189, v189, v172, v133
	v_fma_f32 v192, v192, v174, v142
	v_fma_f32 v193, v193, v168, v143
	v_fma_f32 v194, v194, v176, v144
	v_fma_f32 v195, v195, v178, v145
	v_log_f32_e32 v186, v186
	v_log_f32_e32 v187, v187
	v_log_f32_e32 v188, v188
	v_log_f32_e32 v189, v189
	v_log_f32_e32 v192, v192
	v_log_f32_e32 v193, v193
	v_log_f32_e32 v194, v194
	v_log_f32_e32 v195, v195
	v_cvt_pk_bf16_f32 v186, v186, v187
	v_cvt_pk_bf16_f32 v187, v188, v189
	v_cvt_pk_bf16_f32 v188, v192, v193
	v_cvt_pk_bf16_f32 v189, v194, v195
	global_store_dwordx4 v[190:191], v[186:189], off offset:256 sc1
	v_mul_f32_e32 v192, 0xbfb8aa3b, v42
	v_mul_f32_e32 v193, 0xbfb8aa3b, v43
	v_mul_f32_e32 v187, 0xbfb8aa3b, v50
	v_exp_f32_e32 v188, v187
	v_mul_f32_e32 v187, 0xbfb8aa3b, v51
	v_exp_f32_e32 v189, v187
	v_add_u32_e32 v186, 0x8090, v183
	v_add_f32_e32 v188, 1.0, v188
	v_rcp_f32_e32 v188, v188
	v_add_f32_e32 v189, 1.0, v189
	v_rcp_f32_e32 v189, v189
	v_ashrrev_i32_e32 v187, 31, v186
	v_lshlrev_b64 v[190:191], 10, v[186:187]
	v_fma_f32 v186, v188, v185, v138
	v_fma_f32 v187, v189, v184, v139
	v_mul_f32_e32 v188, 0xbfb8aa3b, v52
	v_mul_f32_e32 v189, 0xbfb8aa3b, v53
	v_exp_f32_e32 v188, v188
	v_exp_f32_e32 v189, v189
	v_exp_f32_e32 v192, v192
	v_exp_f32_e32 v193, v193
	v_add_f32_e32 v188, 1.0, v188
	v_add_f32_e32 v189, 1.0, v189
	v_add_f32_e32 v192, 1.0, v192
	v_add_f32_e32 v193, 1.0, v193
	v_rcp_f32_e32 v188, v188
	v_rcp_f32_e32 v189, v189
	v_rcp_f32_e32 v192, v192
	v_rcp_f32_e32 v193, v193
	v_mul_f32_e32 v194, 0xbfb8aa3b, v44
	v_mul_f32_e32 v195, 0xbfb8aa3b, v45
	v_fma_f32 v188, v188, v182, v140
	v_fma_f32 v189, v189, v181, v141
	v_fma_f32 v192, v192, v180, v134
	v_exp_f32_e32 v194, v194
	v_exp_f32_e32 v195, v195
	v_fma_f32 v193, v193, v179, v135
	v_log_f32_e32 v186, v186
	v_log_f32_e32 v187, v187
	v_log_f32_e32 v188, v188
	v_log_f32_e32 v189, v189
	v_log_f32_e32 v192, v192
	v_log_f32_e32 v193, v193
	v_add_f32_e32 v194, 1.0, v194
	v_add_f32_e32 v195, 1.0, v195
	v_rcp_f32_e32 v194, v194
	v_rcp_f32_e32 v195, v195
	v_cvt_pk_bf16_f32 v186, v186, v187
	v_cvt_pk_bf16_f32 v187, v188, v189
	v_cvt_pk_bf16_f32 v188, v192, v193
	v_mul_f32_e32 v192, 0xbfb8aa3b, v38
	v_mul_f32_e32 v193, 0xbfb8aa3b, v39
	v_exp_f32_e32 v192, v192
	v_exp_f32_e32 v193, v193
	v_fma_f32 v194, v194, v177, v136
	v_fma_f32 v195, v195, v175, v137
	v_log_f32_e32 v194, v194
	v_log_f32_e32 v195, v195
	v_add_f32_e32 v192, 1.0, v192
	v_add_f32_e32 v193, 1.0, v193
	v_rcp_f32_e32 v192, v192
	v_rcp_f32_e32 v193, v193
	v_lshl_add_u64 v[190:191], s[20:21], 0, v[190:191]
	v_cvt_pk_bf16_f32 v189, v194, v195
	v_lshl_add_u64 v[190:191], v[190:191], 0, v[162:163]
	global_store_dwordx4 v[190:191], v[186:189], off sc1
	v_mul_f32_e32 v194, 0xbfb8aa3b, v32
	v_mul_f32_e32 v195, 0xbfb8aa3b, v33
	v_fma_f32 v186, v192, v156, v130
	v_fma_f32 v187, v193, v164, v131
	v_mul_f32_e32 v188, 0xbfb8aa3b, v40
	v_mul_f32_e32 v189, 0xbfb8aa3b, v41
	v_mul_f32_e32 v192, 0xbfb8aa3b, v30
	v_mul_f32_e32 v193, 0xbfb8aa3b, v31
	v_exp_f32_e32 v188, v188
	v_exp_f32_e32 v189, v189
	v_exp_f32_e32 v192, v192
	v_exp_f32_e32 v193, v193
	v_exp_f32_e32 v194, v194
	v_exp_f32_e32 v195, v195
	v_add_f32_e32 v188, 1.0, v188
	v_add_f32_e32 v189, 1.0, v189
	v_add_f32_e32 v192, 1.0, v192
	v_add_f32_e32 v193, 1.0, v193
	v_add_f32_e32 v194, 1.0, v194
	v_add_f32_e32 v195, 1.0, v195
	v_rcp_f32_e32 v188, v188
	v_rcp_f32_e32 v189, v189
	v_rcp_f32_e32 v192, v192
	v_rcp_f32_e32 v193, v193
	v_rcp_f32_e32 v194, v194
	v_rcp_f32_e32 v195, v195
	v_fma_f32 v188, v188, v165, v132
	v_fma_f32 v189, v189, v172, v133
	v_fma_f32 v192, v192, v174, v142
	v_fma_f32 v193, v193, v168, v143
	v_fma_f32 v194, v194, v176, v144
	v_fma_f32 v195, v195, v178, v145
	v_log_f32_e32 v186, v186
	v_log_f32_e32 v187, v187
	v_log_f32_e32 v188, v188
	v_log_f32_e32 v189, v189
	v_log_f32_e32 v192, v192
	v_log_f32_e32 v193, v193
	v_log_f32_e32 v194, v194
	v_log_f32_e32 v195, v195
	v_cvt_pk_bf16_f32 v186, v186, v187
	v_cvt_pk_bf16_f32 v187, v188, v189
	v_cvt_pk_bf16_f32 v188, v192, v193
	v_cvt_pk_bf16_f32 v189, v194, v195
	global_store_dwordx4 v[190:191], v[186:189], off offset:256 sc1
	v_mul_f32_e32 v192, 0xbfb8aa3b, v26
	v_mul_f32_e32 v193, 0xbfb8aa3b, v27
	v_mul_f32_e32 v187, 0xbfb8aa3b, v34
	v_exp_f32_e32 v188, v187
	v_mul_f32_e32 v187, 0xbfb8aa3b, v35
	v_exp_f32_e32 v189, v187
	v_add_u32_e32 v186, 0x80a0, v183
	v_add_f32_e32 v188, 1.0, v188
	v_rcp_f32_e32 v188, v188
	v_add_f32_e32 v189, 1.0, v189
	v_rcp_f32_e32 v189, v189
	v_ashrrev_i32_e32 v187, 31, v186
	v_lshlrev_b64 v[190:191], 10, v[186:187]
	v_fma_f32 v186, v188, v185, v138
	v_fma_f32 v187, v189, v184, v139
	v_mul_f32_e32 v188, 0xbfb8aa3b, v36
	v_mul_f32_e32 v189, 0xbfb8aa3b, v37
	v_exp_f32_e32 v188, v188
	v_exp_f32_e32 v189, v189
	v_exp_f32_e32 v192, v192
	v_exp_f32_e32 v193, v193
	v_add_f32_e32 v188, 1.0, v188
	v_add_f32_e32 v189, 1.0, v189
	v_add_f32_e32 v192, 1.0, v192
	v_add_f32_e32 v193, 1.0, v193
	v_rcp_f32_e32 v188, v188
	v_rcp_f32_e32 v189, v189
	v_rcp_f32_e32 v192, v192
	v_rcp_f32_e32 v193, v193
	v_mul_f32_e32 v194, 0xbfb8aa3b, v28
	v_mul_f32_e32 v195, 0xbfb8aa3b, v29
	v_fma_f32 v188, v188, v182, v140
	v_fma_f32 v189, v189, v181, v141
	v_fma_f32 v192, v192, v180, v134
	v_exp_f32_e32 v194, v194
	v_exp_f32_e32 v195, v195
	v_fma_f32 v193, v193, v179, v135
	v_log_f32_e32 v186, v186
	v_log_f32_e32 v187, v187
	v_log_f32_e32 v188, v188
	v_log_f32_e32 v189, v189
	v_log_f32_e32 v192, v192
	v_log_f32_e32 v193, v193
	v_add_f32_e32 v194, 1.0, v194
	v_add_f32_e32 v195, 1.0, v195
	v_rcp_f32_e32 v194, v194
	v_rcp_f32_e32 v195, v195
	v_cvt_pk_bf16_f32 v186, v186, v187
	v_cvt_pk_bf16_f32 v187, v188, v189
	v_cvt_pk_bf16_f32 v188, v192, v193
	v_mul_f32_e32 v192, 0xbfb8aa3b, v22
	v_mul_f32_e32 v193, 0xbfb8aa3b, v23
	v_exp_f32_e32 v192, v192
	v_exp_f32_e32 v193, v193
	v_fma_f32 v194, v194, v177, v136
	v_fma_f32 v195, v195, v175, v137
	v_log_f32_e32 v194, v194
	v_log_f32_e32 v195, v195
	v_add_f32_e32 v192, 1.0, v192
	v_add_f32_e32 v193, 1.0, v193
	v_rcp_f32_e32 v192, v192
	v_rcp_f32_e32 v193, v193
	v_lshl_add_u64 v[190:191], s[20:21], 0, v[190:191]
	v_cvt_pk_bf16_f32 v189, v194, v195
	v_lshl_add_u64 v[190:191], v[190:191], 0, v[162:163]
	global_store_dwordx4 v[190:191], v[186:189], off sc1
	v_mul_f32_e32 v194, 0xbfb8aa3b, v16
	v_mul_f32_e32 v195, 0xbfb8aa3b, v17
	v_fma_f32 v186, v192, v156, v130
	v_fma_f32 v187, v193, v164, v131
	v_mul_f32_e32 v188, 0xbfb8aa3b, v24
	v_mul_f32_e32 v189, 0xbfb8aa3b, v25
	v_mul_f32_e32 v192, 0xbfb8aa3b, v14
	v_mul_f32_e32 v193, 0xbfb8aa3b, v15
	v_exp_f32_e32 v188, v188
	v_exp_f32_e32 v189, v189
	v_exp_f32_e32 v192, v192
	v_exp_f32_e32 v193, v193
	v_exp_f32_e32 v194, v194
	v_exp_f32_e32 v195, v195
	v_add_f32_e32 v188, 1.0, v188
	v_add_f32_e32 v189, 1.0, v189
	v_add_f32_e32 v192, 1.0, v192
	v_add_f32_e32 v193, 1.0, v193
	v_add_f32_e32 v194, 1.0, v194
	v_add_f32_e32 v195, 1.0, v195
	v_rcp_f32_e32 v188, v188
	v_rcp_f32_e32 v189, v189
	v_rcp_f32_e32 v192, v192
	v_rcp_f32_e32 v193, v193
	v_rcp_f32_e32 v194, v194
	v_rcp_f32_e32 v195, v195
	v_fma_f32 v188, v188, v165, v132
	v_fma_f32 v189, v189, v172, v133
	v_fma_f32 v192, v192, v174, v142
	v_fma_f32 v193, v193, v168, v143
	v_fma_f32 v194, v194, v176, v144
	v_fma_f32 v195, v195, v178, v145
	v_log_f32_e32 v186, v186
	v_log_f32_e32 v187, v187
	v_log_f32_e32 v188, v188
	v_log_f32_e32 v189, v189
	v_log_f32_e32 v192, v192
	v_log_f32_e32 v193, v193
	v_log_f32_e32 v194, v194
	v_log_f32_e32 v195, v195
	v_cvt_pk_bf16_f32 v186, v186, v187
	v_cvt_pk_bf16_f32 v187, v188, v189
	v_cvt_pk_bf16_f32 v188, v192, v193
	v_cvt_pk_bf16_f32 v189, v194, v195
	global_store_dwordx4 v[190:191], v[186:189], off offset:256 sc1
	s_nop 1
	v_mul_f32_e32 v187, 0xbfb8aa3b, v19
	v_add_u32_e32 v186, 0x80b0, v183
	v_mul_f32_e32 v183, 0xbfb8aa3b, v18
	v_exp_f32_e32 v188, v187
	v_exp_f32_e32 v183, v183
	v_ashrrev_i32_e32 v187, 31, v186
	v_lshlrev_b64 v[186:187], 10, v[186:187]
	v_add_f32_e32 v188, 1.0, v188
	v_add_f32_e32 v183, 1.0, v183
	v_rcp_f32_e32 v188, v188
	v_rcp_f32_e32 v183, v183
	v_fma_f32 v139, v188, v184, v139
	v_mul_f32_e32 v184, 0xbfb8aa3b, v21
	v_fma_f32 v138, v183, v185, v138
	v_mul_f32_e32 v183, 0xbfb8aa3b, v20
	v_exp_f32_e32 v184, v184
	v_exp_f32_e32 v183, v183
	v_mul_f32_e32 v185, 0xbfb8aa3b, v10
	v_exp_f32_e32 v185, v185
	v_add_f32_e32 v184, 1.0, v184
	v_add_f32_e32 v183, 1.0, v183
	v_rcp_f32_e32 v184, v184
	v_rcp_f32_e32 v183, v183
	v_log_f32_e32 v138, v138
	v_log_f32_e32 v139, v139
	v_fmac_f32_e32 v141, v184, v181
	v_add_f32_e32 v181, 1.0, v185
	v_fma_f32 v140, v183, v182, v140
	v_rcp_f32_e32 v181, v181
	v_mul_f32_e32 v182, 0xbfb8aa3b, v11
	v_exp_f32_e32 v182, v182
	v_log_f32_e32 v140, v140
	v_fma_f32 v134, v181, v180, v134
	v_log_f32_e32 v180, v134
	v_add_f32_e32 v134, 1.0, v182
	v_mul_f32_e32 v181, 0xbfb8aa3b, v12
	v_mul_f32_e32 v182, 0xbfb8aa3b, v13
	v_rcp_f32_e32 v134, v134
	v_exp_f32_e32 v181, v181
	v_exp_f32_e32 v182, v182
	v_log_f32_e32 v141, v141
	v_fma_f32 v134, v134, v179, v135
	v_add_f32_e32 v135, 1.0, v181
	v_add_f32_e32 v179, 1.0, v182
	v_rcp_f32_e32 v135, v135
	v_rcp_f32_e32 v179, v179
	v_log_f32_e32 v181, v134
	v_fma_f32 v134, v135, v177, v136
	v_fmac_f32_e32 v137, v179, v175
	v_log_f32_e32 v177, v134
	v_log_f32_e32 v137, v137
	v_cvt_pk_bf16_f32 v134, v138, v139
	v_lshl_add_u64 v[138:139], s[20:21], 0, v[186:187]
	v_cvt_pk_bf16_f32 v135, v140, v141
	v_cvt_pk_bf16_f32 v136, v180, v181
	v_cvt_pk_bf16_f32 v137, v177, v137
	v_lshl_add_u64 v[138:139], v[138:139], 0, v[162:163]
	global_store_dwordx4 v[138:139], v[134:137], off sc1
	v_mul_f32_e32 v140, 0xbfb8aa3b, v6
	v_mul_f32_e32 v141, 0xbfb8aa3b, v7
	v_mul_f32_e32 v134, 0xbfb8aa3b, v8
	v_mul_f32_e32 v135, 0xbfb8aa3b, v9
	v_exp_f32_e32 v134, v134
	v_exp_f32_e32 v135, v135
	v_mul_f32_e32 v136, 0xbfb8aa3b, v2
	v_exp_f32_e32 v136, v136
	v_add_f32_e32 v134, 1.0, v134
	v_add_f32_e32 v135, 1.0, v135
	v_rcp_f32_e32 v134, v134
	v_rcp_f32_e32 v135, v135
	v_mul_f32_e32 v137, 0xbfb8aa3b, v5
	v_exp_f32_e32 v140, v140
	v_fma_f32 v132, v134, v165, v132
	v_fmac_f32_e32 v133, v135, v172
	v_add_f32_e32 v134, 1.0, v136
	v_mul_f32_e32 v135, 0xbfb8aa3b, v3
	v_mul_f32_e32 v136, 0xbfb8aa3b, v4
	v_exp_f32_e32 v141, v141
	v_exp_f32_e32 v135, v135
	v_exp_f32_e32 v136, v136
	v_exp_f32_e32 v137, v137
	v_add_f32_e32 v140, 1.0, v140
	v_add_f32_e32 v141, 1.0, v141
	v_add_f32_e32 v135, 1.0, v135
	v_add_f32_e32 v136, 1.0, v136
	v_add_f32_e32 v137, 1.0, v137
	v_rcp_f32_e32 v140, v140
	v_rcp_f32_e32 v141, v141
	v_rcp_f32_e32 v134, v134
	v_rcp_f32_e32 v135, v135
	v_rcp_f32_e32 v136, v136
	v_rcp_f32_e32 v137, v137
	v_fma_f32 v130, v140, v156, v130
	v_fma_f32 v131, v141, v164, v131
	v_fma_f32 v134, v134, v174, v142
	v_fma_f32 v135, v135, v168, v143
	v_fma_f32 v136, v136, v176, v144
	v_fmac_f32_e32 v145, v137, v178
	v_log_f32_e32 v130, v130
	v_log_f32_e32 v131, v131
	v_log_f32_e32 v132, v132
	v_log_f32_e32 v133, v133
	v_log_f32_e32 v134, v134
	v_log_f32_e32 v135, v135
	v_log_f32_e32 v136, v136
	v_log_f32_e32 v137, v145
	v_cvt_pk_bf16_f32 v130, v130, v131
	v_cvt_pk_bf16_f32 v131, v132, v133
	v_cvt_pk_bf16_f32 v132, v134, v135
	v_cvt_pk_bf16_f32 v133, v136, v137
	global_store_dwordx4 v[138:139], v[130:133], off offset:256 sc1

.LBB0_291:
	s_and_b64 vcc, exec, s[48:49]
	s_cbranch_vccz .LBB0_296
	v_mul_f32_e32 v130, 0xbfb8aa3b, v126
	v_mul_f32_e32 v131, 0xbfb8aa3b, v127
	v_mul_f32_e32 v132, 0xbfb8aa3b, v128
	v_mul_f32_e32 v133, 0xbfb8aa3b, v129
	v_mul_f32_e32 v134, 0xbfb8aa3b, v122
	v_mul_f32_e32 v135, 0xbfb8aa3b, v123
	v_mul_f32_e32 v136, 0xbfb8aa3b, v124
	v_mul_f32_e32 v137, 0xbfb8aa3b, v125
	v_mul_f32_e32 v138, 0xbfb8aa3b, v118
	v_mul_f32_e32 v139, 0xbfb8aa3b, v119
	v_mul_f32_e32 v140, 0xbfb8aa3b, v120
	v_mul_f32_e32 v141, 0xbfb8aa3b, v121
	v_mul_f32_e32 v142, 0xbfb8aa3b, v110
	v_mul_f32_e32 v143, 0xbfb8aa3b, v111
	v_mul_f32_e32 v144, 0xbfb8aa3b, v112
	v_mul_f32_e32 v145, 0xbfb8aa3b, v113
	v_mul_f32_e32 v156, 0xbfb8aa3b, v114
	v_mul_f32_e32 v162, 0xbfb8aa3b, v115
	v_mul_f32_e32 v163, 0xbfb8aa3b, v116
	v_mul_f32_e32 v164, 0xbfb8aa3b, v117
	v_mul_f32_e32 v165, 0xbfb8aa3b, v106
	v_mul_f32_e32 v168, 0xbfb8aa3b, v107
	v_mul_f32_e32 v172, 0xbfb8aa3b, v108
	v_mul_f32_e32 v174, 0xbfb8aa3b, v109
	v_mul_f32_e32 v175, 0xbfb8aa3b, v102
	v_mul_f32_e32 v176, 0xbfb8aa3b, v103
	v_mul_f32_e32 v177, 0xbfb8aa3b, v104
	v_mul_f32_e32 v178, 0xbfb8aa3b, v105
	v_mul_f32_e32 v179, 0xbfb8aa3b, v94
	v_mul_f32_e32 v180, 0xbfb8aa3b, v95
	v_mul_f32_e32 v181, 0xbfb8aa3b, v96
	v_mul_f32_e32 v182, 0xbfb8aa3b, v97
	v_mul_f32_e32 v183, 0xbfb8aa3b, v98
	v_mul_f32_e32 v184, 0xbfb8aa3b, v99
	v_mul_f32_e32 v185, 0xbfb8aa3b, v100
	v_mul_f32_e32 v186, 0xbfb8aa3b, v101
	v_mul_f32_e32 v187, 0xbfb8aa3b, v90
	v_mul_f32_e32 v188, 0xbfb8aa3b, v91
	v_mul_f32_e32 v189, 0xbfb8aa3b, v92
	v_mul_f32_e32 v190, 0xbfb8aa3b, v93
	v_mul_f32_e32 v191, 0xbfb8aa3b, v86
	v_mul_f32_e32 v192, 0xbfb8aa3b, v87
	v_mul_f32_e32 v193, 0xbfb8aa3b, v88
	v_mul_f32_e32 v194, 0xbfb8aa3b, v89
	v_mul_f32_e32 v195, 0xbfb8aa3b, v78
	v_mul_f32_e32 v196, 0xbfb8aa3b, v79
	v_mul_f32_e32 v197, 0xbfb8aa3b, v80
	v_mul_f32_e32 v198, 0xbfb8aa3b, v81
	v_mul_f32_e32 v246, 0xbfb8aa3b, v82
	v_mul_f32_e32 v247, 0xbfb8aa3b, v83
	v_mul_f32_e32 v248, 0xbfb8aa3b, v84
	v_mul_f32_e32 v249, 0xbfb8aa3b, v85
	v_exp_f32_e32 v245, v130
	v_exp_f32_e32 v244, v131
	v_exp_f32_e32 v243, v132
	v_exp_f32_e32 v242, v133
	v_exp_f32_e32 v241, v134
	v_exp_f32_e32 v240, v135
	v_exp_f32_e32 v239, v136
	v_exp_f32_e32 v238, v137
	v_exp_f32_e32 v237, v138
	v_exp_f32_e32 v236, v139
	v_exp_f32_e32 v235, v140
	v_exp_f32_e32 v234, v141
	v_exp_f32_e32 v233, v142
	v_exp_f32_e32 v232, v143
	v_exp_f32_e32 v231, v144
	v_exp_f32_e32 v230, v145
	v_exp_f32_e32 v229, v156
	v_exp_f32_e32 v228, v162
	v_exp_f32_e32 v227, v163
	v_exp_f32_e32 v226, v164
	v_exp_f32_e32 v225, v165
	v_exp_f32_e32 v224, v168
	v_exp_f32_e32 v223, v172
	v_exp_f32_e32 v222, v174
	v_exp_f32_e32 v221, v175
	v_exp_f32_e32 v220, v176
	v_exp_f32_e32 v219, v177
	v_exp_f32_e32 v218, v178
	v_exp_f32_e32 v217, v179
	v_exp_f32_e32 v216, v180
	v_exp_f32_e32 v215, v181
	v_exp_f32_e32 v214, v182
	v_exp_f32_e32 v213, v183
	v_exp_f32_e32 v212, v184
	v_exp_f32_e32 v211, v185
	v_exp_f32_e32 v210, v186
	v_exp_f32_e32 v209, v187
	v_exp_f32_e32 v208, v188
	v_exp_f32_e32 v207, v189
	v_exp_f32_e32 v206, v190
	v_exp_f32_e32 v205, v191
	v_exp_f32_e32 v204, v192
	v_exp_f32_e32 v203, v193
	v_exp_f32_e32 v202, v194
	v_exp_f32_e32 v201, v195
	v_exp_f32_e32 v200, v196
	v_exp_f32_e32 v199, v197
	v_exp_f32_e32 v198, v198
	v_exp_f32_e32 v197, v246
	v_exp_f32_e32 v196, v247
	v_exp_f32_e32 v195, v248
	v_exp_f32_e32 v193, v249
	s_mov_b64 s[48:49], -1
	s_cmp_gt_i32 s41, 4
	v_mul_f32_e32 v194, 0xbfb8aa3b, v74
	v_mul_f32_e32 v192, 0xbfb8aa3b, v75
	v_mul_f32_e32 v191, 0xbfb8aa3b, v76
	v_mul_f32_e32 v190, 0xbfb8aa3b, v77
	v_mul_f32_e32 v189, 0xbfb8aa3b, v70
	v_mul_f32_e32 v188, 0xbfb8aa3b, v71
	v_mul_f32_e32 v187, 0xbfb8aa3b, v72
	s_cbranch_scc0 .LBB0_294
	s_lshl_b32 s2, s66, 8
	s_and_b32 s2, s2, 0x100
	s_or_b32 s2, s2, s59
	v_add_u32_e32 v162, s2, v173
	v_ashrrev_i32_e32 v163, 31, v162
	v_lshl_add_u64 v[134:135], v[162:163], 2, s[12:13]
	global_load_dwordx4 v[138:141], v[134:135], off offset:16
	global_load_dwordx4 v[142:145], v[134:135], off
	global_load_dwordx4 v[130:133], v[134:135], off offset:528
	s_nop 0
	global_load_dwordx4 v[134:137], v[134:135], off offset:512
	v_add_f32_e32 v156, 1.0, v245
	v_rcp_f32_e32 v156, v156
	v_add_f32_e32 v168, 1.0, v242
	v_rcp_f32_e32 v168, v168
	v_add_f32_e32 v178, 1.0, v240
	v_rcp_f32_e32 v178, v178
	s_lshl_b32 s2, s33, 8
	s_add_i32 s2, s2, s58
	v_add_u32_e32 v175, s2, v171
	v_add_u32_e32 v164, 0x8000, v175
	v_ashrrev_i32_e32 v165, 31, v164
	v_lshlrev_b64 v[164:165], 10, v[164:165]
	v_lshl_add_u64 v[164:165], s[22:23], 0, v[164:165]
	v_lshlrev_b64 v[162:163], 1, v[162:163]
	v_lshl_add_u64 v[164:165], v[164:165], 0, v[162:163]
	v_add_f32_e32 v186, 1.0, v230
	v_rcp_f32_e32 v186, v186
	s_mov_b64 s[48:49], 0
	s_waitcnt vmcnt(0)
	v_sub_f32_e32 v252, 1.0, v138
	v_sub_f32_e32 v254, 1.0, v142
	v_fma_f32 v156, v156, v254, v142
	v_log_f32_e32 v172, v156
	v_add_f32_e32 v156, 1.0, v244
	v_rcp_f32_e32 v156, v156
	v_sub_f32_e32 v174, 1.0, v143
	v_sub_f32_e32 v176, 1.0, v144
	v_sub_f32_e32 v253, 1.0, v140
	v_fma_f32 v156, v156, v174, v143
	v_log_f32_e32 v177, v156
	v_add_f32_e32 v156, 1.0, v243
	v_rcp_f32_e32 v156, v156
	v_sub_f32_e32 v248, 1.0, v141
	v_sub_f32_e32 v246, 1.0, v134
	v_sub_f32_e32 v251, 1.0, v135
	v_fma_f32 v156, v156, v176, v144
	v_log_f32_e32 v179, v156
	v_sub_f32_e32 v156, 1.0, v145
	v_fma_f32 v168, v168, v156, v145
	v_log_f32_e32 v180, v168
	v_add_f32_e32 v168, 1.0, v241
	v_rcp_f32_e32 v168, v168
	v_sub_f32_e32 v250, 1.0, v137
	v_cvt_pk_bf16_f32 v179, v179, v180
	v_sub_f32_e32 v249, 1.0, v130
	v_fma_f32 v168, v168, v252, v138
	v_log_f32_e32 v181, v168
	v_sub_f32_e32 v168, 1.0, v139
	v_fma_f32 v178, v178, v168, v139
	v_log_f32_e32 v182, v178
	v_add_f32_e32 v178, 1.0, v239
	v_rcp_f32_e32 v178, v178
	v_cvt_pk_bf16_f32 v180, v181, v182
	v_fma_f32 v178, v178, v253, v140
	v_log_f32_e32 v183, v178
	v_add_f32_e32 v178, 1.0, v238
	v_rcp_f32_e32 v178, v178
	s_nop 0
	v_fma_f32 v178, v178, v248, v141
	v_log_f32_e32 v247, v178
	v_cvt_pk_bf16_f32 v178, v172, v177
	v_add_f32_e32 v172, 1.0, v237
	v_rcp_f32_e32 v172, v172
	v_cvt_pk_bf16_f32 v181, v183, v247
	global_store_dwordx4 v[164:165], v[178:181], off sc1
	v_add_f32_e32 v177, 1.0, v235
	v_fma_f32 v172, v172, v246, v134
	v_log_f32_e32 v179, v172
	v_add_f32_e32 v172, 1.0, v236
	v_rcp_f32_e32 v172, v172
	v_rcp_f32_e32 v177, v177
	v_sub_f32_e32 v247, 1.0, v131
	v_sub_f32_e32 v178, 1.0, v132
	v_fma_f32 v172, v172, v251, v135
	v_log_f32_e32 v180, v172
	v_sub_f32_e32 v172, 1.0, v136
	v_fma_f32 v177, v177, v172, v136
	v_log_f32_e32 v181, v177
	v_add_f32_e32 v177, 1.0, v234
	v_rcp_f32_e32 v177, v177
	v_cvt_pk_bf16_f32 v180, v179, v180
	v_add_f32_e32 v179, 1.0, v229
	v_rcp_f32_e32 v179, v179
	v_fma_f32 v177, v177, v250, v137
	v_log_f32_e32 v182, v177
	v_add_f32_e32 v177, 1.0, v233
	v_rcp_f32_e32 v177, v177
	v_fma_f32 v179, v179, v254, v142
	v_cvt_pk_bf16_f32 v181, v181, v182
	v_log_f32_e32 v179, v179
	v_fma_f32 v177, v177, v249, v130
	v_log_f32_e32 v183, v177
	v_add_f32_e32 v177, 1.0, v232
	v_rcp_f32_e32 v177, v177
	s_nop 0
	v_fma_f32 v177, v177, v247, v131
	v_log_f32_e32 v184, v177
	v_add_f32_e32 v177, 1.0, v231
	v_rcp_f32_e32 v177, v177
	v_cvt_pk_bf16_f32 v182, v183, v184
	v_add_f32_e32 v184, 1.0, v224
	v_fma_f32 v177, v177, v178, v132
	v_log_f32_e32 v185, v177
	v_sub_f32_e32 v177, 1.0, v133
	v_fma_f32 v186, v186, v177, v133
	v_log_f32_e32 v186, v186
	v_rcp_f32_e32 v184, v184
	v_cvt_pk_bf16_f32 v183, v185, v186
	global_store_dwordx4 v[164:165], v[180:183], off offset:256 sc1
	v_add_f32_e32 v185, 1.0, v223
	v_add_f32_e32 v186, 1.0, v222
	v_add_f32_e32 v180, 1.0, v228
	v_add_f32_e32 v181, 1.0, v227
	v_add_f32_e32 v182, 1.0, v226
	v_add_f32_e32 v183, 1.0, v225
	v_rcp_f32_e32 v180, v180
	v_rcp_f32_e32 v181, v181
	v_rcp_f32_e32 v182, v182
	v_rcp_f32_e32 v183, v183
	v_rcp_f32_e32 v185, v185
	v_rcp_f32_e32 v186, v186
	v_fma_f32 v180, v180, v174, v143
	v_fma_f32 v181, v181, v176, v144
	v_fma_f32 v182, v182, v156, v145
	v_fma_f32 v183, v183, v252, v138
	v_fma_f32 v184, v184, v168, v139
	v_fma_f32 v185, v185, v253, v140
	v_fma_f32 v186, v186, v248, v141
	v_add_u32_e32 v164, 0x8010, v175
	v_log_f32_e32 v180, v180
	v_log_f32_e32 v181, v181
	v_log_f32_e32 v182, v182
	v_log_f32_e32 v183, v183
	v_log_f32_e32 v184, v184
	v_log_f32_e32 v185, v185
	v_log_f32_e32 v186, v186
	v_ashrrev_i32_e32 v165, 31, v164
	v_lshlrev_b64 v[164:165], 10, v[164:165]
	v_lshl_add_u64 v[164:165], s[22:23], 0, v[164:165]
	v_cvt_pk_bf16_f32 v180, v179, v180
	v_cvt_pk_bf16_f32 v181, v181, v182
	v_cvt_pk_bf16_f32 v182, v183, v184
	v_cvt_pk_bf16_f32 v183, v185, v186
	v_lshl_add_u64 v[164:165], v[164:165], 0, v[162:163]
	global_store_dwordx4 v[164:165], v[180:183], off sc1
	v_add_f32_e32 v179, 1.0, v221
	v_add_f32_e32 v184, 1.0, v216
	v_add_f32_e32 v180, 1.0, v220
	v_add_f32_e32 v181, 1.0, v219
	v_add_f32_e32 v182, 1.0, v218
	v_add_f32_e32 v183, 1.0, v217
	v_add_f32_e32 v185, 1.0, v215
	v_add_f32_e32 v186, 1.0, v214
	v_rcp_f32_e32 v179, v179
	v_rcp_f32_e32 v180, v180
	v_rcp_f32_e32 v181, v181
	v_rcp_f32_e32 v182, v182
	v_rcp_f32_e32 v183, v183
	v_rcp_f32_e32 v184, v184
	v_rcp_f32_e32 v185, v185
	v_rcp_f32_e32 v186, v186
	v_fma_f32 v179, v179, v246, v134
	v_fma_f32 v180, v180, v251, v135
	v_fma_f32 v181, v181, v172, v136
	v_fma_f32 v182, v182, v250, v137
	v_fma_f32 v183, v183, v249, v130
	v_fma_f32 v184, v184, v247, v131
	v_fma_f32 v185, v185, v178, v132
	v_fma_f32 v186, v186, v177, v133
	v_log_f32_e32 v179, v179
	v_log_f32_e32 v180, v180
	v_log_f32_e32 v181, v181
	v_log_f32_e32 v182, v182
	v_log_f32_e32 v183, v183
	v_log_f32_e32 v184, v184
	v_log_f32_e32 v185, v185
	v_log_f32_e32 v186, v186
	v_cvt_pk_bf16_f32 v180, v179, v180
	v_cvt_pk_bf16_f32 v181, v181, v182
	v_cvt_pk_bf16_f32 v182, v183, v184
	v_cvt_pk_bf16_f32 v183, v185, v186
	global_store_dwordx4 v[164:165], v[180:183], off offset:256 sc1
	v_add_f32_e32 v179, 1.0, v213
	v_add_f32_e32 v184, 1.0, v208
	v_add_f32_e32 v180, 1.0, v212
	v_add_f32_e32 v181, 1.0, v211
	v_add_f32_e32 v182, 1.0, v210
	v_add_f32_e32 v183, 1.0, v209
	v_add_f32_e32 v185, 1.0, v207
	v_add_f32_e32 v186, 1.0, v206
	v_rcp_f32_e32 v179, v179
	v_rcp_f32_e32 v180, v180
	v_rcp_f32_e32 v181, v181
	v_rcp_f32_e32 v182, v182
	v_rcp_f32_e32 v183, v183
	v_rcp_f32_e32 v184, v184
	v_rcp_f32_e32 v185, v185
	v_rcp_f32_e32 v186, v186
	v_fma_f32 v179, v179, v254, v142
	v_fma_f32 v180, v180, v174, v143
	v_fma_f32 v181, v181, v176, v144
	v_fma_f32 v182, v182, v156, v145
	v_fma_f32 v183, v183, v252, v138
	v_fma_f32 v184, v184, v168, v139
	v_fma_f32 v185, v185, v253, v140
	v_fma_f32 v186, v186, v248, v141
	v_add_u32_e32 v164, 0x8020, v175
	v_log_f32_e32 v179, v179
	v_log_f32_e32 v180, v180
	v_log_f32_e32 v181, v181
	v_log_f32_e32 v182, v182
	v_log_f32_e32 v183, v183
	v_log_f32_e32 v184, v184
	v_log_f32_e32 v185, v185
	v_log_f32_e32 v186, v186
	v_ashrrev_i32_e32 v165, 31, v164
	v_lshlrev_b64 v[164:165], 10, v[164:165]
	v_lshl_add_u64 v[164:165], s[22:23], 0, v[164:165]
	v_cvt_pk_bf16_f32 v180, v179, v180
	v_cvt_pk_bf16_f32 v181, v181, v182
	v_cvt_pk_bf16_f32 v182, v183, v184
	v_cvt_pk_bf16_f32 v183, v185, v186
	v_lshl_add_u64 v[164:165], v[164:165], 0, v[162:163]
	global_store_dwordx4 v[164:165], v[180:183], off sc1
	v_add_f32_e32 v179, 1.0, v205
	v_add_f32_e32 v184, 1.0, v200
	v_add_f32_e32 v180, 1.0, v204
	v_add_f32_e32 v181, 1.0, v203
	v_add_f32_e32 v182, 1.0, v202
	v_add_f32_e32 v183, 1.0, v201
	v_add_f32_e32 v185, 1.0, v199
	v_add_f32_e32 v186, 1.0, v198
	v_rcp_f32_e32 v179, v179
	v_rcp_f32_e32 v180, v180
	v_rcp_f32_e32 v181, v181
	v_rcp_f32_e32 v182, v182
	v_rcp_f32_e32 v183, v183
	v_rcp_f32_e32 v184, v184
	v_rcp_f32_e32 v185, v185
	v_rcp_f32_e32 v186, v186
	v_fma_f32 v179, v179, v246, v134
	v_fma_f32 v180, v180, v251, v135
	v_fma_f32 v181, v181, v172, v136
	v_fma_f32 v182, v182, v250, v137
	v_fma_f32 v183, v183, v249, v130
	v_fma_f32 v184, v184, v247, v131
	v_fma_f32 v185, v185, v178, v132
	v_fma_f32 v186, v186, v177, v133
	v_log_f32_e32 v179, v179
	v_log_f32_e32 v180, v180
	v_log_f32_e32 v181, v181
	v_log_f32_e32 v182, v182
	v_log_f32_e32 v183, v183
	v_log_f32_e32 v184, v184
	v_log_f32_e32 v185, v185
	v_log_f32_e32 v186, v186
	v_cvt_pk_bf16_f32 v180, v179, v180
	v_cvt_pk_bf16_f32 v181, v181, v182
	v_cvt_pk_bf16_f32 v182, v183, v184
	v_cvt_pk_bf16_f32 v183, v185, v186
	global_store_dwordx4 v[164:165], v[180:183], off offset:256 sc1
	v_exp_f32_e32 v184, v192
	v_exp_f32_e32 v185, v191
	v_exp_f32_e32 v183, v194
	v_exp_f32_e32 v186, v190
	v_add_f32_e32 v179, 1.0, v197
	v_add_f32_e32 v180, 1.0, v196
	v_add_f32_e32 v181, 1.0, v195
	v_add_f32_e32 v182, 1.0, v193
	v_add_f32_e32 v183, 1.0, v183
	v_add_f32_e32 v184, 1.0, v184
	v_add_f32_e32 v185, 1.0, v185
	v_add_f32_e32 v186, 1.0, v186
	v_rcp_f32_e32 v179, v179
	v_rcp_f32_e32 v180, v180
	v_rcp_f32_e32 v181, v181
	v_rcp_f32_e32 v182, v182
	v_rcp_f32_e32 v183, v183
	v_rcp_f32_e32 v184, v184
	v_rcp_f32_e32 v185, v185
	v_rcp_f32_e32 v186, v186
	v_fma_f32 v179, v179, v254, v142
	v_fma_f32 v180, v180, v174, v143
	v_fma_f32 v181, v181, v176, v144
	v_fma_f32 v182, v182, v156, v145
	v_fma_f32 v183, v183, v252, v138
	v_fma_f32 v184, v184, v168, v139
	v_fma_f32 v185, v185, v253, v140
	v_fma_f32 v186, v186, v248, v141
	v_add_u32_e32 v164, 0x8030, v175
	v_log_f32_e32 v179, v179
	v_log_f32_e32 v180, v180
	v_log_f32_e32 v181, v181
	v_log_f32_e32 v182, v182
	v_log_f32_e32 v183, v183
	v_log_f32_e32 v184, v184
	v_log_f32_e32 v185, v185
	v_log_f32_e32 v186, v186
	v_ashrrev_i32_e32 v165, 31, v164
	v_lshlrev_b64 v[164:165], 10, v[164:165]
	v_lshl_add_u64 v[164:165], s[22:23], 0, v[164:165]
	v_cvt_pk_bf16_f32 v180, v179, v180
	v_cvt_pk_bf16_f32 v181, v181, v182
	v_cvt_pk_bf16_f32 v182, v183, v184
	v_cvt_pk_bf16_f32 v183, v185, v186
	v_lshl_add_u64 v[164:165], v[164:165], 0, v[162:163]
	global_store_dwordx4 v[164:165], v[180:183], off sc1
	v_mul_f32_e32 v184, 0xbfb8aa3b, v67
	v_mul_f32_e32 v185, 0xbfb8aa3b, v68
	v_mul_f32_e32 v182, 0xbfb8aa3b, v73
	v_mul_f32_e32 v183, 0xbfb8aa3b, v66
	v_mul_f32_e32 v186, 0xbfb8aa3b, v69
	v_exp_f32_e32 v179, v189
	v_exp_f32_e32 v180, v188
	v_exp_f32_e32 v181, v187
	v_exp_f32_e32 v182, v182
	v_exp_f32_e32 v183, v183
	v_exp_f32_e32 v184, v184
	v_exp_f32_e32 v185, v185
	v_exp_f32_e32 v186, v186
	v_add_f32_e32 v179, 1.0, v179
	v_add_f32_e32 v180, 1.0, v180
	v_add_f32_e32 v181, 1.0, v181
	v_add_f32_e32 v182, 1.0, v182
	v_add_f32_e32 v183, 1.0, v183
	v_add_f32_e32 v184, 1.0, v184
	v_add_f32_e32 v185, 1.0, v185
	v_add_f32_e32 v186, 1.0, v186
	v_rcp_f32_e32 v179, v179
	v_rcp_f32_e32 v180, v180
	v_rcp_f32_e32 v181, v181
	v_rcp_f32_e32 v182, v182
	v_rcp_f32_e32 v183, v183
	v_rcp_f32_e32 v184, v184
	v_rcp_f32_e32 v185, v185
	v_rcp_f32_e32 v186, v186
	v_fma_f32 v179, v179, v246, v134
	v_fma_f32 v180, v180, v251, v135
	v_fma_f32 v181, v181, v172, v136
	v_fma_f32 v182, v182, v250, v137
	v_fma_f32 v183, v183, v249, v130
	v_fma_f32 v184, v184, v247, v131
	v_fma_f32 v185, v185, v178, v132
	v_fma_f32 v186, v186, v177, v133
	v_log_f32_e32 v179, v179
	v_log_f32_e32 v180, v180
	v_log_f32_e32 v181, v181
	v_log_f32_e32 v182, v182
	v_log_f32_e32 v183, v183
	v_log_f32_e32 v184, v184
	v_log_f32_e32 v185, v185
	v_log_f32_e32 v186, v186
	v_cvt_pk_bf16_f32 v180, v179, v180
	v_cvt_pk_bf16_f32 v181, v181, v182
	v_cvt_pk_bf16_f32 v182, v183, v184
	v_cvt_pk_bf16_f32 v183, v185, v186
	global_store_dwordx4 v[164:165], v[180:183], off offset:256 sc1
	v_mul_f32_e32 v179, 0xbfb8aa3b, v62
	v_mul_f32_e32 v184, 0xbfb8aa3b, v59
	v_mul_f32_e32 v180, 0xbfb8aa3b, v63
	v_mul_f32_e32 v181, 0xbfb8aa3b, v64
	v_mul_f32_e32 v182, 0xbfb8aa3b, v65
	v_mul_f32_e32 v183, 0xbfb8aa3b, v58
	v_mul_f32_e32 v185, 0xbfb8aa3b, v60
	v_mul_f32_e32 v186, 0xbfb8aa3b, v61
	v_exp_f32_e32 v179, v179
	v_exp_f32_e32 v180, v180
	v_exp_f32_e32 v181, v181
	v_exp_f32_e32 v182, v182
	v_exp_f32_e32 v183, v183
	v_exp_f32_e32 v184, v184
	v_exp_f32_e32 v185, v185
	v_exp_f32_e32 v186, v186
	v_add_f32_e32 v179, 1.0, v179
	v_add_f32_e32 v180, 1.0, v180
	v_add_f32_e32 v181, 1.0, v181
	v_add_f32_e32 v182, 1.0, v182
	v_add_f32_e32 v183, 1.0, v183
	v_add_f32_e32 v184, 1.0, v184
	v_add_f32_e32 v185, 1.0, v185
	v_add_f32_e32 v186, 1.0, v186
	v_rcp_f32_e32 v179, v179
	v_rcp_f32_e32 v180, v180
	v_rcp_f32_e32 v181, v181
	v_rcp_f32_e32 v182, v182
	v_rcp_f32_e32 v183, v183
	v_rcp_f32_e32 v184, v184
	v_rcp_f32_e32 v185, v185
	v_rcp_f32_e32 v186, v186
	v_fma_f32 v179, v179, v254, v142
	v_fma_f32 v180, v180, v174, v143
	v_fma_f32 v181, v181, v176, v144
	v_fma_f32 v182, v182, v156, v145
	v_fma_f32 v183, v183, v252, v138
	v_fma_f32 v184, v184, v168, v139
	v_fma_f32 v185, v185, v253, v140
	v_fma_f32 v186, v186, v248, v141
	v_add_u32_e32 v164, 0x8080, v175
	v_log_f32_e32 v179, v179
	v_log_f32_e32 v180, v180
	v_log_f32_e32 v181, v181
	v_log_f32_e32 v182, v182
	v_log_f32_e32 v183, v183
	v_log_f32_e32 v184, v184
	v_log_f32_e32 v185, v185
	v_log_f32_e32 v186, v186
	v_ashrrev_i32_e32 v165, 31, v164
	v_lshlrev_b64 v[164:165], 10, v[164:165]
	v_lshl_add_u64 v[164:165], s[22:23], 0, v[164:165]
	v_cvt_pk_bf16_f32 v180, v179, v180
	v_cvt_pk_bf16_f32 v181, v181, v182
	v_cvt_pk_bf16_f32 v182, v183, v184
	v_cvt_pk_bf16_f32 v183, v185, v186
	v_lshl_add_u64 v[164:165], v[164:165], 0, v[162:163]
	global_store_dwordx4 v[164:165], v[180:183], off sc1
	v_mul_f32_e32 v179, 0xbfb8aa3b, v54
	v_mul_f32_e32 v184, 0xbfb8aa3b, v47
	v_mul_f32_e32 v180, 0xbfb8aa3b, v55
	v_mul_f32_e32 v181, 0xbfb8aa3b, v56
	v_mul_f32_e32 v182, 0xbfb8aa3b, v57
	v_mul_f32_e32 v183, 0xbfb8aa3b, v46
	v_mul_f32_e32 v185, 0xbfb8aa3b, v48
	v_mul_f32_e32 v186, 0xbfb8aa3b, v49
	v_exp_f32_e32 v179, v179
	v_exp_f32_e32 v180, v180
	v_exp_f32_e32 v181, v181
	v_exp_f32_e32 v182, v182
	v_exp_f32_e32 v183, v183
	v_exp_f32_e32 v184, v184
	v_exp_f32_e32 v185, v185
	v_exp_f32_e32 v186, v186
	v_add_f32_e32 v179, 1.0, v179
	v_add_f32_e32 v180, 1.0, v180
	v_add_f32_e32 v181, 1.0, v181
	v_add_f32_e32 v182, 1.0, v182
	v_add_f32_e32 v183, 1.0, v183
	v_add_f32_e32 v184, 1.0, v184
	v_add_f32_e32 v185, 1.0, v185
	v_add_f32_e32 v186, 1.0, v186
	v_rcp_f32_e32 v179, v179
	v_rcp_f32_e32 v180, v180
	v_rcp_f32_e32 v181, v181
	v_rcp_f32_e32 v182, v182
	v_rcp_f32_e32 v183, v183
	v_rcp_f32_e32 v184, v184
	v_rcp_f32_e32 v185, v185
	v_rcp_f32_e32 v186, v186
	v_fma_f32 v179, v179, v246, v134
	v_fma_f32 v180, v180, v251, v135
	v_fma_f32 v181, v181, v172, v136
	v_fma_f32 v182, v182, v250, v137
	v_fma_f32 v183, v183, v249, v130
	v_fma_f32 v184, v184, v247, v131
	v_fma_f32 v185, v185, v178, v132
	v_fma_f32 v186, v186, v177, v133
	v_log_f32_e32 v179, v179
	v_log_f32_e32 v180, v180
	v_log_f32_e32 v181, v181
	v_log_f32_e32 v182, v182
	v_log_f32_e32 v183, v183
	v_log_f32_e32 v184, v184
	v_log_f32_e32 v185, v185
	v_log_f32_e32 v186, v186
	v_cvt_pk_bf16_f32 v180, v179, v180
	v_cvt_pk_bf16_f32 v181, v181, v182
	v_cvt_pk_bf16_f32 v182, v183, v184
	v_cvt_pk_bf16_f32 v183, v185, v186
	global_store_dwordx4 v[164:165], v[180:183], off offset:256 sc1
	v_mul_f32_e32 v179, 0xbfb8aa3b, v50
	v_mul_f32_e32 v184, 0xbfb8aa3b, v43
	v_mul_f32_e32 v180, 0xbfb8aa3b, v51
	v_mul_f32_e32 v181, 0xbfb8aa3b, v52
	v_mul_f32_e32 v182, 0xbfb8aa3b, v53
	v_mul_f32_e32 v183, 0xbfb8aa3b, v42
	v_mul_f32_e32 v185, 0xbfb8aa3b, v44
	v_mul_f32_e32 v186, 0xbfb8aa3b, v45
	v_exp_f32_e32 v179, v179
	v_exp_f32_e32 v180, v180
	v_exp_f32_e32 v181, v181
	v_exp_f32_e32 v182, v182
	v_exp_f32_e32 v183, v183
	v_exp_f32_e32 v184, v184
	v_exp_f32_e32 v185, v185
	v_exp_f32_e32 v186, v186
	v_add_f32_e32 v179, 1.0, v179
	v_add_f32_e32 v180, 1.0, v180
	v_add_f32_e32 v181, 1.0, v181
	v_add_f32_e32 v182, 1.0, v182
	v_add_f32_e32 v183, 1.0, v183
	v_add_f32_e32 v184, 1.0, v184
	v_add_f32_e32 v185, 1.0, v185
	v_add_f32_e32 v186, 1.0, v186
	v_rcp_f32_e32 v179, v179
	v_rcp_f32_e32 v180, v180
	v_rcp_f32_e32 v181, v181
	v_rcp_f32_e32 v182, v182
	v_rcp_f32_e32 v183, v183
	v_rcp_f32_e32 v184, v184
	v_rcp_f32_e32 v185, v185
	v_rcp_f32_e32 v186, v186
	v_fma_f32 v179, v179, v254, v142
	v_fma_f32 v180, v180, v174, v143
	v_fma_f32 v181, v181, v176, v144
	v_fma_f32 v182, v182, v156, v145
	v_fma_f32 v183, v183, v252, v138
	v_fma_f32 v184, v184, v168, v139
	v_fma_f32 v185, v185, v253, v140
	v_fma_f32 v186, v186, v248, v141
	v_add_u32_e32 v164, 0x8090, v175
	v_log_f32_e32 v179, v179
	v_log_f32_e32 v180, v180
	v_log_f32_e32 v181, v181
	v_log_f32_e32 v182, v182
	v_log_f32_e32 v183, v183
	v_log_f32_e32 v184, v184
	v_log_f32_e32 v185, v185
	v_log_f32_e32 v186, v186
	v_ashrrev_i32_e32 v165, 31, v164
	v_lshlrev_b64 v[164:165], 10, v[164:165]
	v_lshl_add_u64 v[164:165], s[22:23], 0, v[164:165]
	v_cvt_pk_bf16_f32 v180, v179, v180
	v_cvt_pk_bf16_f32 v181, v181, v182
	v_cvt_pk_bf16_f32 v182, v183, v184
	v_cvt_pk_bf16_f32 v183, v185, v186
	v_lshl_add_u64 v[164:165], v[164:165], 0, v[162:163]
	global_store_dwordx4 v[164:165], v[180:183], off sc1
	v_mul_f32_e32 v179, 0xbfb8aa3b, v38
	v_mul_f32_e32 v184, 0xbfb8aa3b, v31
	v_mul_f32_e32 v180, 0xbfb8aa3b, v39
	v_mul_f32_e32 v181, 0xbfb8aa3b, v40
	v_mul_f32_e32 v182, 0xbfb8aa3b, v41
	v_mul_f32_e32 v183, 0xbfb8aa3b, v30
	v_mul_f32_e32 v185, 0xbfb8aa3b, v32
	v_mul_f32_e32 v186, 0xbfb8aa3b, v33
	v_exp_f32_e32 v179, v179
	v_exp_f32_e32 v180, v180
	v_exp_f32_e32 v181, v181
	v_exp_f32_e32 v182, v182
	v_exp_f32_e32 v183, v183
	v_exp_f32_e32 v184, v184
	v_exp_f32_e32 v185, v185
	v_exp_f32_e32 v186, v186
	v_add_f32_e32 v179, 1.0, v179
	v_add_f32_e32 v180, 1.0, v180
	v_add_f32_e32 v181, 1.0, v181
	v_add_f32_e32 v182, 1.0, v182
	v_add_f32_e32 v183, 1.0, v183
	v_add_f32_e32 v184, 1.0, v184
	v_add_f32_e32 v185, 1.0, v185
	v_add_f32_e32 v186, 1.0, v186
	v_rcp_f32_e32 v179, v179
	v_rcp_f32_e32 v180, v180
	v_rcp_f32_e32 v181, v181
	v_rcp_f32_e32 v182, v182
	v_rcp_f32_e32 v183, v183
	v_rcp_f32_e32 v184, v184
	v_rcp_f32_e32 v185, v185
	v_rcp_f32_e32 v186, v186
	v_fma_f32 v179, v179, v246, v134
	v_fma_f32 v180, v180, v251, v135
	v_fma_f32 v181, v181, v172, v136
	v_fma_f32 v182, v182, v250, v137
	v_fma_f32 v183, v183, v249, v130
	v_fma_f32 v184, v184, v247, v131
	v_fma_f32 v185, v185, v178, v132
	v_fma_f32 v186, v186, v177, v133
	v_log_f32_e32 v179, v179
	v_log_f32_e32 v180, v180
	v_log_f32_e32 v181, v181
	v_log_f32_e32 v182, v182
	v_log_f32_e32 v183, v183
	v_log_f32_e32 v184, v184
	v_log_f32_e32 v185, v185
	v_log_f32_e32 v186, v186
	v_cvt_pk_bf16_f32 v180, v179, v180
	v_cvt_pk_bf16_f32 v181, v181, v182
	v_cvt_pk_bf16_f32 v182, v183, v184
	v_cvt_pk_bf16_f32 v183, v185, v186
	global_store_dwordx4 v[164:165], v[180:183], off offset:256 sc1
	v_mul_f32_e32 v179, 0xbfb8aa3b, v34
	v_mul_f32_e32 v184, 0xbfb8aa3b, v27
	v_mul_f32_e32 v180, 0xbfb8aa3b, v35
	v_mul_f32_e32 v181, 0xbfb8aa3b, v36
	v_mul_f32_e32 v182, 0xbfb8aa3b, v37
	v_mul_f32_e32 v183, 0xbfb8aa3b, v26
	v_mul_f32_e32 v185, 0xbfb8aa3b, v28
	v_mul_f32_e32 v186, 0xbfb8aa3b, v29
	v_exp_f32_e32 v179, v179
	v_exp_f32_e32 v180, v180
	v_exp_f32_e32 v181, v181
	v_exp_f32_e32 v182, v182
	v_exp_f32_e32 v183, v183
	v_exp_f32_e32 v184, v184
	v_exp_f32_e32 v185, v185
	v_exp_f32_e32 v186, v186
	v_add_f32_e32 v179, 1.0, v179
	v_add_f32_e32 v180, 1.0, v180
	v_add_f32_e32 v181, 1.0, v181
	v_add_f32_e32 v182, 1.0, v182
	v_add_f32_e32 v183, 1.0, v183
	v_add_f32_e32 v184, 1.0, v184
	v_add_f32_e32 v185, 1.0, v185
	v_add_f32_e32 v186, 1.0, v186
	v_rcp_f32_e32 v179, v179
	v_rcp_f32_e32 v180, v180
	v_rcp_f32_e32 v181, v181
	v_rcp_f32_e32 v182, v182
	v_rcp_f32_e32 v183, v183
	v_rcp_f32_e32 v184, v184
	v_rcp_f32_e32 v185, v185
	v_rcp_f32_e32 v186, v186
	v_fma_f32 v179, v179, v254, v142
	v_fma_f32 v180, v180, v174, v143
	v_fma_f32 v181, v181, v176, v144
	v_fma_f32 v182, v182, v156, v145
	v_fma_f32 v183, v183, v252, v138
	v_fma_f32 v184, v184, v168, v139
	v_fma_f32 v185, v185, v253, v140
	v_fma_f32 v186, v186, v248, v141
	v_add_u32_e32 v164, 0x80a0, v175
	v_log_f32_e32 v179, v179
	v_log_f32_e32 v180, v180
	v_log_f32_e32 v181, v181
	v_log_f32_e32 v182, v182
	v_log_f32_e32 v183, v183
	v_log_f32_e32 v184, v184
	v_log_f32_e32 v185, v185
	v_log_f32_e32 v186, v186
	v_ashrrev_i32_e32 v165, 31, v164
	v_lshlrev_b64 v[164:165], 10, v[164:165]
	v_lshl_add_u64 v[164:165], s[22:23], 0, v[164:165]
	v_cvt_pk_bf16_f32 v180, v179, v180
	v_cvt_pk_bf16_f32 v181, v181, v182
	v_cvt_pk_bf16_f32 v182, v183, v184
	v_cvt_pk_bf16_f32 v183, v185, v186
	v_lshl_add_u64 v[164:165], v[164:165], 0, v[162:163]
	global_store_dwordx4 v[164:165], v[180:183], off sc1
	v_mul_f32_e32 v179, 0xbfb8aa3b, v22
	v_mul_f32_e32 v184, 0xbfb8aa3b, v15
	v_mul_f32_e32 v180, 0xbfb8aa3b, v23
	v_mul_f32_e32 v181, 0xbfb8aa3b, v24
	v_mul_f32_e32 v182, 0xbfb8aa3b, v25
	v_mul_f32_e32 v183, 0xbfb8aa3b, v14
	v_mul_f32_e32 v185, 0xbfb8aa3b, v16
	v_mul_f32_e32 v186, 0xbfb8aa3b, v17
	v_exp_f32_e32 v179, v179
	v_exp_f32_e32 v180, v180
	v_exp_f32_e32 v181, v181
	v_exp_f32_e32 v182, v182
	v_exp_f32_e32 v183, v183
	v_exp_f32_e32 v184, v184
	v_exp_f32_e32 v185, v185
	v_exp_f32_e32 v186, v186
	v_add_f32_e32 v179, 1.0, v179
	v_add_f32_e32 v180, 1.0, v180
	v_add_f32_e32 v181, 1.0, v181
	v_add_f32_e32 v182, 1.0, v182
	v_add_f32_e32 v183, 1.0, v183
	v_add_f32_e32 v184, 1.0, v184
	v_add_f32_e32 v185, 1.0, v185
	v_add_f32_e32 v186, 1.0, v186
	v_rcp_f32_e32 v179, v179
	v_rcp_f32_e32 v180, v180
	v_rcp_f32_e32 v181, v181
	v_rcp_f32_e32 v182, v182
	v_rcp_f32_e32 v183, v183
	v_rcp_f32_e32 v184, v184
	v_rcp_f32_e32 v185, v185
	v_rcp_f32_e32 v186, v186
	v_fma_f32 v179, v179, v246, v134
	v_fma_f32 v180, v180, v251, v135
	v_fma_f32 v181, v181, v172, v136
	v_fma_f32 v182, v182, v250, v137
	v_fma_f32 v183, v183, v249, v130
	v_fma_f32 v184, v184, v247, v131
	v_fma_f32 v185, v185, v178, v132
	v_fma_f32 v186, v186, v177, v133
	v_log_f32_e32 v179, v179
	v_log_f32_e32 v180, v180
	v_log_f32_e32 v181, v181
	v_log_f32_e32 v182, v182
	v_log_f32_e32 v183, v183
	v_log_f32_e32 v184, v184
	v_log_f32_e32 v185, v185
	v_log_f32_e32 v186, v186
	v_cvt_pk_bf16_f32 v180, v179, v180
	v_cvt_pk_bf16_f32 v181, v181, v182
	v_cvt_pk_bf16_f32 v182, v183, v184
	v_cvt_pk_bf16_f32 v183, v185, v186
	global_store_dwordx4 v[164:165], v[180:183], off offset:256 sc1
	v_add_u32_e32 v164, 0x80b0, v175
	v_mul_f32_e32 v175, 0xbfb8aa3b, v18
	v_exp_f32_e32 v175, v175
	v_ashrrev_i32_e32 v165, 31, v164
	v_lshlrev_b64 v[164:165], 10, v[164:165]
	v_add_f32_e32 v175, 1.0, v175
	v_rcp_f32_e32 v175, v175
	s_nop 0
	v_fma_f32 v142, v175, v254, v142
	v_mul_f32_e32 v175, 0xbfb8aa3b, v19
	v_exp_f32_e32 v175, v175
	v_log_f32_e32 v142, v142
	v_add_f32_e32 v175, 1.0, v175
	v_rcp_f32_e32 v175, v175
	s_nop 0
	v_fma_f32 v143, v175, v174, v143
	v_mul_f32_e32 v174, 0xbfb8aa3b, v20
	v_exp_f32_e32 v174, v174
	v_log_f32_e32 v143, v143
	v_add_f32_e32 v174, 1.0, v174
	v_rcp_f32_e32 v174, v174
	s_nop 0
	v_fma_f32 v144, v174, v176, v144
	v_mul_f32_e32 v174, 0xbfb8aa3b, v21
	v_exp_f32_e32 v174, v174
	v_log_f32_e32 v144, v144
	v_add_f32_e32 v174, 1.0, v174
	v_rcp_f32_e32 v174, v174
	s_nop 0
	v_fmac_f32_e32 v145, v174, v156
	v_mul_f32_e32 v156, 0xbfb8aa3b, v10
	v_exp_f32_e32 v156, v156
	v_log_f32_e32 v145, v145
	v_add_f32_e32 v156, 1.0, v156
	v_rcp_f32_e32 v156, v156
	s_nop 0
	v_fma_f32 v138, v156, v252, v138
	v_log_f32_e32 v156, v138
	v_mul_f32_e32 v138, 0xbfb8aa3b, v11
	v_exp_f32_e32 v138, v138
	s_nop 0
	v_add_f32_e32 v138, 1.0, v138
	v_rcp_f32_e32 v138, v138
	s_nop 0
	v_fma_f32 v138, v138, v168, v139
	v_log_f32_e32 v168, v138
	v_mul_f32_e32 v138, 0xbfb8aa3b, v12
	v_exp_f32_e32 v138, v138
	v_cvt_pk_bf16_f32 v139, v144, v145
	v_add_f32_e32 v138, 1.0, v138
	v_rcp_f32_e32 v138, v138
	s_nop 0
	v_fma_f32 v138, v138, v253, v140
	v_log_f32_e32 v174, v138
	v_mul_f32_e32 v138, 0xbfb8aa3b, v13
	v_exp_f32_e32 v138, v138
	v_cvt_pk_bf16_f32 v140, v156, v168
	v_add_f32_e32 v138, 1.0, v138
	v_rcp_f32_e32 v138, v138
	s_nop 0
	v_fmac_f32_e32 v141, v138, v248
	v_log_f32_e32 v141, v141
	v_cvt_pk_bf16_f32 v138, v142, v143
	v_lshl_add_u64 v[142:143], s[22:23], 0, v[164:165]
	v_lshl_add_u64 v[142:143], v[142:143], 0, v[162:163]
	v_cvt_pk_bf16_f32 v141, v174, v141
	global_store_dwordx4 v[142:143], v[138:141], off sc1
	s_nop 1
	v_mul_f32_e32 v138, 0xbfb8aa3b, v6
	v_exp_f32_e32 v138, v138
	s_nop 0
	v_add_f32_e32 v138, 1.0, v138
	v_rcp_f32_e32 v138, v138
	s_nop 0
	v_fma_f32 v134, v138, v246, v134
	v_mul_f32_e32 v138, 0xbfb8aa3b, v7
	v_exp_f32_e32 v138, v138
	v_log_f32_e32 v134, v134
	v_add_f32_e32 v138, 1.0, v138
	v_rcp_f32_e32 v138, v138
	s_nop 0
	v_fma_f32 v135, v138, v251, v135
	v_mul_f32_e32 v138, 0xbfb8aa3b, v8
	v_exp_f32_e32 v138, v138
	v_log_f32_e32 v135, v135
	v_add_f32_e32 v138, 1.0, v138
	v_rcp_f32_e32 v138, v138
	s_nop 0
	v_fma_f32 v136, v138, v172, v136
	v_mul_f32_e32 v138, 0xbfb8aa3b, v9
	v_exp_f32_e32 v138, v138
	v_log_f32_e32 v136, v136
	v_add_f32_e32 v138, 1.0, v138
	v_rcp_f32_e32 v138, v138
	s_nop 0
	v_fmac_f32_e32 v137, v138, v250
	v_mul_f32_e32 v138, 0xbfb8aa3b, v2
	v_exp_f32_e32 v138, v138
	v_log_f32_e32 v137, v137
	v_add_f32_e32 v138, 1.0, v138
	v_rcp_f32_e32 v138, v138
	s_nop 0
	v_fma_f32 v130, v138, v249, v130
	v_log_f32_e32 v138, v130
	v_mul_f32_e32 v130, 0xbfb8aa3b, v3
	v_exp_f32_e32 v130, v130
	s_nop 0
	v_add_f32_e32 v130, 1.0, v130
	v_rcp_f32_e32 v130, v130
	s_nop 0
	v_fma_f32 v130, v130, v247, v131
	v_log_f32_e32 v139, v130
	v_mul_f32_e32 v130, 0xbfb8aa3b, v4
	v_exp_f32_e32 v130, v130
	v_cvt_pk_bf16_f32 v131, v136, v137
	v_add_f32_e32 v130, 1.0, v130
	v_rcp_f32_e32 v130, v130
	s_nop 0
	v_fma_f32 v130, v130, v178, v132
	v_log_f32_e32 v140, v130
	v_mul_f32_e32 v130, 0xbfb8aa3b, v5
	v_exp_f32_e32 v130, v130
	v_cvt_pk_bf16_f32 v132, v138, v139
	v_add_f32_e32 v130, 1.0, v130
	v_rcp_f32_e32 v130, v130
	s_nop 0
	v_fmac_f32_e32 v133, v130, v177
	v_log_f32_e32 v133, v133
	v_cvt_pk_bf16_f32 v130, v134, v135
	v_cvt_pk_bf16_f32 v133, v140, v133
	global_store_dwordx4 v[142:143], v[130:133], off offset:256 sc1
.LBB0_294:
	s_andn2_b64 vcc, exec, s[48:49]
	s_cbranch_vccnz .LBB0_296
	s_lshl_b32 s2, s66, 8
	s_and_b32 s2, s2, 0x100
	s_or_b32 s2, s2, s59
	v_add_u32_e32 v130, s2, v173
	s_lshl_b32 s2, s33, 8
	s_add_i32 s2, s2, s58
	v_add_u32_e32 v132, s2, v171
	v_add_u32_e32 v134, 0x8000, v132
	v_ashrrev_i32_e32 v135, 31, v134
	v_add_f32_e32 v131, 1.0, v245
	v_lshlrev_b64 v[138:139], 10, v[134:135]
	v_rcp_f32_e32 v134, v131
	v_add_f32_e32 v131, 1.0, v244
	v_rcp_f32_e32 v135, v131
	v_add_f32_e32 v131, 1.0, v243
	v_rcp_f32_e32 v136, v131
	v_add_f32_e32 v131, 1.0, v242
	v_rcp_f32_e32 v137, v131
	v_add_f32_e32 v131, 1.0, v241
	v_rcp_f32_e32 v140, v131
	v_add_f32_e32 v131, 1.0, v240
	v_rcp_f32_e32 v141, v131
	v_add_f32_e32 v131, 1.0, v239
	v_rcp_f32_e32 v142, v131
	v_add_f32_e32 v131, 1.0, v238
	v_rcp_f32_e32 v143, v131
	v_ashrrev_i32_e32 v131, 31, v130
	v_pk_mul_f32 v[134:135], v[126:127], v[134:135]
	v_pk_mul_f32 v[136:137], v[128:129], v[136:137]
	v_pk_mul_f32 v[140:141], v[122:123], v[140:141]
	v_pk_mul_f32 v[142:143], v[124:125], v[142:143]
	v_lshl_add_u64 v[138:139], s[24:25], 0, v[138:139]
	v_lshlrev_b64 v[130:131], 1, v[130:131]
	v_cvt_pk_bf16_f32 v134, v134, v135
	v_cvt_pk_bf16_f32 v135, v136, v137
	v_cvt_pk_bf16_f32 v136, v140, v141
	v_cvt_pk_bf16_f32 v137, v142, v143
	v_lshl_add_u64 v[138:139], v[138:139], 0, v[130:131]
	v_add_f32_e32 v133, 1.0, v237
	global_store_dwordx4 v[138:139], v[134:137], off sc1
	s_nop 1
	v_rcp_f32_e32 v134, v133
	v_add_f32_e32 v133, 1.0, v236
	v_rcp_f32_e32 v135, v133
	v_add_f32_e32 v133, 1.0, v235
	v_rcp_f32_e32 v136, v133
	v_add_f32_e32 v133, 1.0, v234
	v_rcp_f32_e32 v137, v133
	v_add_f32_e32 v133, 1.0, v233
	v_rcp_f32_e32 v140, v133
	v_add_f32_e32 v133, 1.0, v232
	v_rcp_f32_e32 v141, v133
	v_add_f32_e32 v133, 1.0, v231
	v_rcp_f32_e32 v142, v133
	v_add_f32_e32 v133, 1.0, v230
	v_rcp_f32_e32 v143, v133
	v_pk_mul_f32 v[134:135], v[118:119], v[134:135]
	v_pk_mul_f32 v[136:137], v[120:121], v[136:137]
	v_pk_mul_f32 v[140:141], v[110:111], v[140:141]
	v_pk_mul_f32 v[142:143], v[112:113], v[142:143]
	v_cvt_pk_bf16_f32 v134, v134, v135
	v_cvt_pk_bf16_f32 v135, v136, v137
	v_cvt_pk_bf16_f32 v136, v140, v141
	v_cvt_pk_bf16_f32 v137, v142, v143
	global_store_dwordx4 v[138:139], v[134:137], off offset:256 sc1
	v_add_f32_e32 v133, 1.0, v229
	s_nop 0
	v_add_u32_e32 v134, 0x8010, v132
	v_ashrrev_i32_e32 v135, 31, v134
	v_lshlrev_b64 v[138:139], 10, v[134:135]
	v_rcp_f32_e32 v134, v133
	v_add_f32_e32 v133, 1.0, v228
	v_rcp_f32_e32 v135, v133
	v_add_f32_e32 v133, 1.0, v227
	v_rcp_f32_e32 v136, v133
	v_add_f32_e32 v133, 1.0, v226
	v_rcp_f32_e32 v137, v133
	v_add_f32_e32 v133, 1.0, v225
	v_rcp_f32_e32 v140, v133
	v_add_f32_e32 v133, 1.0, v224
	v_rcp_f32_e32 v141, v133
	v_add_f32_e32 v133, 1.0, v223
	v_rcp_f32_e32 v142, v133
	v_add_f32_e32 v133, 1.0, v222
	v_rcp_f32_e32 v143, v133
	v_pk_mul_f32 v[134:135], v[114:115], v[134:135]
	v_pk_mul_f32 v[136:137], v[116:117], v[136:137]
	v_pk_mul_f32 v[140:141], v[106:107], v[140:141]
	v_pk_mul_f32 v[142:143], v[108:109], v[142:143]
	v_lshl_add_u64 v[138:139], s[24:25], 0, v[138:139]
	v_cvt_pk_bf16_f32 v134, v134, v135
	v_cvt_pk_bf16_f32 v135, v136, v137
	v_cvt_pk_bf16_f32 v136, v140, v141
	v_cvt_pk_bf16_f32 v137, v142, v143
	v_lshl_add_u64 v[138:139], v[138:139], 0, v[130:131]
	v_add_f32_e32 v133, 1.0, v221
	global_store_dwordx4 v[138:139], v[134:137], off sc1
	s_nop 1
	v_rcp_f32_e32 v134, v133
	v_add_f32_e32 v133, 1.0, v220
	v_rcp_f32_e32 v135, v133
	v_add_f32_e32 v133, 1.0, v219
	v_rcp_f32_e32 v136, v133
	v_add_f32_e32 v133, 1.0, v218
	v_rcp_f32_e32 v137, v133
	v_add_f32_e32 v133, 1.0, v217
	v_rcp_f32_e32 v140, v133
	v_add_f32_e32 v133, 1.0, v216
	v_rcp_f32_e32 v141, v133
	v_add_f32_e32 v133, 1.0, v215
	v_rcp_f32_e32 v142, v133
	v_add_f32_e32 v133, 1.0, v214
	v_rcp_f32_e32 v143, v133
	v_pk_mul_f32 v[134:135], v[102:103], v[134:135]
	v_pk_mul_f32 v[136:137], v[104:105], v[136:137]
	v_pk_mul_f32 v[140:141], v[94:95], v[140:141]
	v_pk_mul_f32 v[142:143], v[96:97], v[142:143]
	v_cvt_pk_bf16_f32 v134, v134, v135
	v_cvt_pk_bf16_f32 v135, v136, v137
	v_cvt_pk_bf16_f32 v136, v140, v141
	v_cvt_pk_bf16_f32 v137, v142, v143
	global_store_dwordx4 v[138:139], v[134:137], off offset:256 sc1
	v_add_f32_e32 v133, 1.0, v213
	s_nop 0
	v_add_u32_e32 v134, 0x8020, v132
	v_ashrrev_i32_e32 v135, 31, v134
	v_lshlrev_b64 v[138:139], 10, v[134:135]
	v_rcp_f32_e32 v134, v133
	v_add_f32_e32 v133, 1.0, v212
	v_rcp_f32_e32 v135, v133
	v_add_f32_e32 v133, 1.0, v211
	v_rcp_f32_e32 v136, v133
	v_add_f32_e32 v133, 1.0, v210
	v_rcp_f32_e32 v137, v133
	v_add_f32_e32 v133, 1.0, v209
	v_rcp_f32_e32 v140, v133
	v_add_f32_e32 v133, 1.0, v208
	v_rcp_f32_e32 v141, v133
	v_add_f32_e32 v133, 1.0, v207
	v_rcp_f32_e32 v142, v133
	v_add_f32_e32 v133, 1.0, v206
	v_rcp_f32_e32 v143, v133
	v_pk_mul_f32 v[134:135], v[98:99], v[134:135]
	v_pk_mul_f32 v[136:137], v[100:101], v[136:137]
	v_pk_mul_f32 v[140:141], v[90:91], v[140:141]
	v_pk_mul_f32 v[142:143], v[92:93], v[142:143]
	v_lshl_add_u64 v[138:139], s[24:25], 0, v[138:139]
	v_cvt_pk_bf16_f32 v134, v134, v135
	v_cvt_pk_bf16_f32 v135, v136, v137
	v_cvt_pk_bf16_f32 v136, v140, v141
	v_cvt_pk_bf16_f32 v137, v142, v143
	v_lshl_add_u64 v[138:139], v[138:139], 0, v[130:131]
	v_add_f32_e32 v133, 1.0, v205
	global_store_dwordx4 v[138:139], v[134:137], off sc1
	s_nop 1
	v_rcp_f32_e32 v134, v133
	v_add_f32_e32 v133, 1.0, v204
	v_rcp_f32_e32 v135, v133
	v_add_f32_e32 v133, 1.0, v203
	v_rcp_f32_e32 v136, v133
	v_add_f32_e32 v133, 1.0, v202
	v_rcp_f32_e32 v137, v133
	v_add_f32_e32 v133, 1.0, v201
	v_rcp_f32_e32 v140, v133
	v_add_f32_e32 v133, 1.0, v200
	v_rcp_f32_e32 v141, v133
	v_add_f32_e32 v133, 1.0, v199
	v_rcp_f32_e32 v142, v133
	v_add_f32_e32 v133, 1.0, v198
	v_rcp_f32_e32 v143, v133
	v_pk_mul_f32 v[134:135], v[86:87], v[134:135]
	v_pk_mul_f32 v[136:137], v[88:89], v[136:137]
	v_pk_mul_f32 v[140:141], v[78:79], v[140:141]
	v_pk_mul_f32 v[142:143], v[80:81], v[142:143]
	v_cvt_pk_bf16_f32 v134, v134, v135
	v_cvt_pk_bf16_f32 v135, v136, v137
	v_cvt_pk_bf16_f32 v136, v140, v141
	v_cvt_pk_bf16_f32 v137, v142, v143
	global_store_dwordx4 v[138:139], v[134:137], off offset:256 sc1
	v_add_f32_e32 v133, 1.0, v197
	v_exp_f32_e32 v141, v192
	v_add_u32_e32 v134, 0x8030, v132
	v_ashrrev_i32_e32 v135, 31, v134
	v_lshlrev_b64 v[138:139], 10, v[134:135]
	v_rcp_f32_e32 v134, v133
	v_add_f32_e32 v133, 1.0, v196
	v_rcp_f32_e32 v135, v133
	v_add_f32_e32 v133, 1.0, v195
	v_rcp_f32_e32 v136, v133
	v_exp_f32_e32 v133, v194
	v_exp_f32_e32 v143, v190
	v_add_f32_e32 v137, 1.0, v193
	v_add_f32_e32 v141, 1.0, v141
	v_add_f32_e32 v133, 1.0, v133
	v_rcp_f32_e32 v140, v133
	v_exp_f32_e32 v133, v191
	v_rcp_f32_e32 v137, v137
	v_rcp_f32_e32 v141, v141
	v_pk_mul_f32 v[134:135], v[82:83], v[134:135]
	v_add_f32_e32 v133, 1.0, v133
	v_rcp_f32_e32 v142, v133
	v_add_f32_e32 v133, 1.0, v143
	v_rcp_f32_e32 v143, v133
	v_exp_f32_e32 v133, v189
	v_pk_mul_f32 v[136:137], v[84:85], v[136:137]
	v_pk_mul_f32 v[140:141], v[74:75], v[140:141]
	v_pk_mul_f32 v[142:143], v[76:77], v[142:143]
	v_lshl_add_u64 v[138:139], s[24:25], 0, v[138:139]
	v_cvt_pk_bf16_f32 v134, v134, v135
	v_cvt_pk_bf16_f32 v135, v136, v137
	v_cvt_pk_bf16_f32 v136, v140, v141
	v_cvt_pk_bf16_f32 v137, v142, v143
	v_lshl_add_u64 v[138:139], v[138:139], 0, v[130:131]
	v_add_f32_e32 v133, 1.0, v133
	global_store_dwordx4 v[138:139], v[134:137], off sc1
	v_mul_f32_e32 v140, 0xbfb8aa3b, v67
	v_exp_f32_e32 v141, v140
	v_rcp_f32_e32 v134, v133
	v_exp_f32_e32 v133, v187
	v_mul_f32_e32 v136, 0xbfb8aa3b, v73
	v_exp_f32_e32 v137, v136
	v_mul_f32_e32 v142, 0xbfb8aa3b, v69
	v_add_f32_e32 v133, 1.0, v133
	v_rcp_f32_e32 v136, v133
	v_mul_f32_e32 v133, 0xbfb8aa3b, v66
	v_exp_f32_e32 v133, v133
	v_exp_f32_e32 v135, v188
	v_exp_f32_e32 v143, v142
	v_add_f32_e32 v137, 1.0, v137
	v_add_f32_e32 v133, 1.0, v133
	v_rcp_f32_e32 v140, v133
	v_mul_f32_e32 v133, 0xbfb8aa3b, v68
	v_exp_f32_e32 v133, v133
	v_add_f32_e32 v135, 1.0, v135
	v_add_f32_e32 v141, 1.0, v141
	v_rcp_f32_e32 v135, v135
	v_add_f32_e32 v133, 1.0, v133
	v_rcp_f32_e32 v142, v133
	v_add_f32_e32 v133, 1.0, v143
	v_rcp_f32_e32 v137, v137
	v_rcp_f32_e32 v141, v141
	v_rcp_f32_e32 v143, v133
	v_mul_f32_e32 v133, 0xbfb8aa3b, v62
	v_pk_mul_f32 v[134:135], v[70:71], v[134:135]
	v_pk_mul_f32 v[136:137], v[72:73], v[136:137]
	v_pk_mul_f32 v[140:141], v[66:67], v[140:141]
	v_pk_mul_f32 v[142:143], v[68:69], v[142:143]
	v_exp_f32_e32 v133, v133
	v_cvt_pk_bf16_f32 v134, v134, v135
	v_cvt_pk_bf16_f32 v135, v136, v137
	v_cvt_pk_bf16_f32 v136, v140, v141
	v_cvt_pk_bf16_f32 v137, v142, v143
	global_store_dwordx4 v[138:139], v[134:137], off offset:256 sc1
	v_add_f32_e32 v133, 1.0, v133
	v_mul_f32_e32 v140, 0xbfb8aa3b, v59
	v_add_u32_e32 v134, 0x8080, v132
	v_ashrrev_i32_e32 v135, 31, v134
	v_lshlrev_b64 v[138:139], 10, v[134:135]
	v_mul_f32_e32 v134, 0xbfb8aa3b, v63
	v_exp_f32_e32 v135, v134
	v_rcp_f32_e32 v134, v133
	v_mul_f32_e32 v133, 0xbfb8aa3b, v64
	v_exp_f32_e32 v133, v133
	v_mul_f32_e32 v136, 0xbfb8aa3b, v65
	v_exp_f32_e32 v137, v136
	v_exp_f32_e32 v141, v140
	v_add_f32_e32 v133, 1.0, v133
	v_rcp_f32_e32 v136, v133
	v_mul_f32_e32 v133, 0xbfb8aa3b, v58
	v_exp_f32_e32 v133, v133
	v_mul_f32_e32 v142, 0xbfb8aa3b, v61
	v_exp_f32_e32 v143, v142
	v_add_f32_e32 v135, 1.0, v135
	v_add_f32_e32 v133, 1.0, v133
	v_rcp_f32_e32 v140, v133
	v_mul_f32_e32 v133, 0xbfb8aa3b, v60
	v_exp_f32_e32 v133, v133
	v_add_f32_e32 v137, 1.0, v137
	v_add_f32_e32 v141, 1.0, v141
	v_rcp_f32_e32 v135, v135
	v_add_f32_e32 v133, 1.0, v133
	v_rcp_f32_e32 v142, v133
	v_add_f32_e32 v133, 1.0, v143
	v_rcp_f32_e32 v137, v137
	v_rcp_f32_e32 v141, v141
	v_rcp_f32_e32 v143, v133
	v_pk_mul_f32 v[134:135], v[62:63], v[134:135]
	v_pk_mul_f32 v[136:137], v[64:65], v[136:137]
	v_pk_mul_f32 v[140:141], v[58:59], v[140:141]
	v_pk_mul_f32 v[142:143], v[60:61], v[142:143]
	v_lshl_add_u64 v[138:139], s[24:25], 0, v[138:139]
	v_mul_f32_e32 v133, 0xbfb8aa3b, v54
	v_cvt_pk_bf16_f32 v134, v134, v135
	v_cvt_pk_bf16_f32 v135, v136, v137
	v_cvt_pk_bf16_f32 v136, v140, v141
	v_cvt_pk_bf16_f32 v137, v142, v143
	v_lshl_add_u64 v[138:139], v[138:139], 0, v[130:131]
	v_exp_f32_e32 v133, v133
	v_mul_f32_e32 v140, 0xbfb8aa3b, v55
	v_exp_f32_e32 v140, v140
	global_store_dwordx4 v[138:139], v[134:137], off sc1
	v_add_f32_e32 v133, 1.0, v133
	s_nop 0
	v_mul_f32_e32 v135, 0xbfb8aa3b, v56
	v_exp_f32_e32 v136, v135
	v_mul_f32_e32 v135, 0xbfb8aa3b, v57
	v_exp_f32_e32 v137, v135
	v_rcp_f32_e32 v134, v133
	v_add_f32_e32 v133, 1.0, v140
	v_rcp_f32_e32 v135, v133
	v_add_f32_e32 v133, 1.0, v136
	v_rcp_f32_e32 v136, v133
	v_add_f32_e32 v133, 1.0, v137
	v_mul_f32_e32 v137, 0xbfb8aa3b, v46
	v_exp_f32_e32 v140, v137
	v_mul_f32_e32 v137, 0xbfb8aa3b, v47
	v_exp_f32_e32 v141, v137
	v_rcp_f32_e32 v137, v133
	v_add_f32_e32 v133, 1.0, v140
	v_rcp_f32_e32 v140, v133
	v_add_f32_e32 v133, 1.0, v141
	v_mul_f32_e32 v141, 0xbfb8aa3b, v48
	v_exp_f32_e32 v142, v141
	v_mul_f32_e32 v141, 0xbfb8aa3b, v49
	v_exp_f32_e32 v143, v141
	v_rcp_f32_e32 v141, v133
	v_add_f32_e32 v133, 1.0, v142
	v_rcp_f32_e32 v142, v133
	v_add_f32_e32 v133, 1.0, v143
	v_rcp_f32_e32 v143, v133
	v_pk_mul_f32 v[134:135], v[54:55], v[134:135]
	v_pk_mul_f32 v[136:137], v[56:57], v[136:137]
	v_pk_mul_f32 v[140:141], v[46:47], v[140:141]
	v_pk_mul_f32 v[142:143], v[48:49], v[142:143]
	v_cvt_pk_bf16_f32 v134, v134, v135
	v_cvt_pk_bf16_f32 v135, v136, v137
	v_cvt_pk_bf16_f32 v136, v140, v141
	v_cvt_pk_bf16_f32 v137, v142, v143
	v_mul_f32_e32 v133, 0xbfb8aa3b, v50
	global_store_dwordx4 v[138:139], v[134:137], off offset:256 sc1
	v_exp_f32_e32 v133, v133
	s_nop 0
	v_mul_f32_e32 v136, 0xbfb8aa3b, v51
	v_exp_f32_e32 v136, v136
	v_add_u32_e32 v134, 0x8090, v132
	v_ashrrev_i32_e32 v135, 31, v134
	v_lshlrev_b64 v[138:139], 10, v[134:135]
	v_add_f32_e32 v133, 1.0, v133
	v_mul_f32_e32 v135, 0xbfb8aa3b, v52
	v_rcp_f32_e32 v134, v133
	v_add_f32_e32 v133, 1.0, v136
	v_exp_f32_e32 v136, v135
	v_mul_f32_e32 v135, 0xbfb8aa3b, v53
	v_exp_f32_e32 v137, v135
	v_rcp_f32_e32 v135, v133
	v_add_f32_e32 v133, 1.0, v136
	v_rcp_f32_e32 v136, v133
	v_add_f32_e32 v133, 1.0, v137
	v_mul_f32_e32 v137, 0xbfb8aa3b, v42
	v_exp_f32_e32 v140, v137
	v_mul_f32_e32 v137, 0xbfb8aa3b, v43
	v_exp_f32_e32 v141, v137
	v_rcp_f32_e32 v137, v133
	v_add_f32_e32 v133, 1.0, v140
	v_rcp_f32_e32 v140, v133
	v_add_f32_e32 v133, 1.0, v141
	v_mul_f32_e32 v141, 0xbfb8aa3b, v44
	v_exp_f32_e32 v142, v141
	v_mul_f32_e32 v141, 0xbfb8aa3b, v45
	v_exp_f32_e32 v143, v141
	v_rcp_f32_e32 v141, v133
	v_add_f32_e32 v133, 1.0, v142
	v_rcp_f32_e32 v142, v133
	v_add_f32_e32 v133, 1.0, v143
	v_rcp_f32_e32 v143, v133
	v_pk_mul_f32 v[134:135], v[50:51], v[134:135]
	v_pk_mul_f32 v[136:137], v[52:53], v[136:137]
	v_pk_mul_f32 v[140:141], v[42:43], v[140:141]
	v_pk_mul_f32 v[142:143], v[44:45], v[142:143]
	v_lshl_add_u64 v[138:139], s[24:25], 0, v[138:139]
	v_mul_f32_e32 v133, 0xbfb8aa3b, v38
	v_cvt_pk_bf16_f32 v134, v134, v135
	v_cvt_pk_bf16_f32 v135, v136, v137
	v_cvt_pk_bf16_f32 v136, v140, v141
	v_cvt_pk_bf16_f32 v137, v142, v143
	v_lshl_add_u64 v[138:139], v[138:139], 0, v[130:131]
	v_exp_f32_e32 v133, v133
	v_mul_f32_e32 v140, 0xbfb8aa3b, v39
	v_exp_f32_e32 v140, v140
	global_store_dwordx4 v[138:139], v[134:137], off sc1
	v_add_f32_e32 v133, 1.0, v133
	s_nop 0
	v_mul_f32_e32 v135, 0xbfb8aa3b, v40
	v_exp_f32_e32 v136, v135
	v_mul_f32_e32 v135, 0xbfb8aa3b, v41
	v_exp_f32_e32 v137, v135
	v_rcp_f32_e32 v134, v133
	v_add_f32_e32 v133, 1.0, v140
	v_rcp_f32_e32 v135, v133
	v_add_f32_e32 v133, 1.0, v136
	v_rcp_f32_e32 v136, v133
	v_add_f32_e32 v133, 1.0, v137
	v_mul_f32_e32 v137, 0xbfb8aa3b, v30
	v_exp_f32_e32 v140, v137
	v_mul_f32_e32 v137, 0xbfb8aa3b, v31
	v_exp_f32_e32 v141, v137
	v_rcp_f32_e32 v137, v133
	v_add_f32_e32 v133, 1.0, v140
	v_rcp_f32_e32 v140, v133
	v_add_f32_e32 v133, 1.0, v141
	v_mul_f32_e32 v141, 0xbfb8aa3b, v32
	v_exp_f32_e32 v142, v141
	v_mul_f32_e32 v141, 0xbfb8aa3b, v33
	v_exp_f32_e32 v143, v141
	v_rcp_f32_e32 v141, v133
	v_add_f32_e32 v133, 1.0, v142
	v_rcp_f32_e32 v142, v133
	v_add_f32_e32 v133, 1.0, v143
	v_rcp_f32_e32 v143, v133
	v_pk_mul_f32 v[134:135], v[38:39], v[134:135]
	v_pk_mul_f32 v[136:137], v[40:41], v[136:137]
	v_pk_mul_f32 v[140:141], v[30:31], v[140:141]
	v_pk_mul_f32 v[142:143], v[32:33], v[142:143]
	v_cvt_pk_bf16_f32 v134, v134, v135
	v_cvt_pk_bf16_f32 v135, v136, v137
	v_cvt_pk_bf16_f32 v136, v140, v141
	v_cvt_pk_bf16_f32 v137, v142, v143
	v_mul_f32_e32 v133, 0xbfb8aa3b, v34
	global_store_dwordx4 v[138:139], v[134:137], off offset:256 sc1
	v_exp_f32_e32 v133, v133
	s_nop 0
	v_mul_f32_e32 v136, 0xbfb8aa3b, v35
	v_exp_f32_e32 v136, v136
	v_add_u32_e32 v134, 0x80a0, v132
	v_ashrrev_i32_e32 v135, 31, v134
	v_lshlrev_b64 v[138:139], 10, v[134:135]
	v_add_f32_e32 v133, 1.0, v133
	v_mul_f32_e32 v135, 0xbfb8aa3b, v36
	v_rcp_f32_e32 v134, v133
	v_add_f32_e32 v133, 1.0, v136
	v_exp_f32_e32 v136, v135
	v_mul_f32_e32 v135, 0xbfb8aa3b, v37
	v_exp_f32_e32 v137, v135
	v_rcp_f32_e32 v135, v133
	v_add_f32_e32 v133, 1.0, v136
	v_rcp_f32_e32 v136, v133
	v_add_f32_e32 v133, 1.0, v137
	v_mul_f32_e32 v137, 0xbfb8aa3b, v26
	v_exp_f32_e32 v140, v137
	v_mul_f32_e32 v137, 0xbfb8aa3b, v27
	v_exp_f32_e32 v141, v137
	v_rcp_f32_e32 v137, v133
	v_add_f32_e32 v133, 1.0, v140
	v_rcp_f32_e32 v140, v133
	v_add_f32_e32 v133, 1.0, v141
	v_mul_f32_e32 v141, 0xbfb8aa3b, v28
	v_exp_f32_e32 v142, v141
	v_mul_f32_e32 v141, 0xbfb8aa3b, v29
	v_exp_f32_e32 v143, v141
	v_rcp_f32_e32 v141, v133
	v_add_f32_e32 v133, 1.0, v142
	v_rcp_f32_e32 v142, v133
	v_add_f32_e32 v133, 1.0, v143
	v_rcp_f32_e32 v143, v133
	v_pk_mul_f32 v[134:135], v[34:35], v[134:135]
	v_pk_mul_f32 v[136:137], v[36:37], v[136:137]
	v_pk_mul_f32 v[140:141], v[26:27], v[140:141]
	v_pk_mul_f32 v[142:143], v[28:29], v[142:143]
	v_lshl_add_u64 v[138:139], s[24:25], 0, v[138:139]
	v_mul_f32_e32 v133, 0xbfb8aa3b, v22
	v_cvt_pk_bf16_f32 v134, v134, v135
	v_cvt_pk_bf16_f32 v135, v136, v137
	v_cvt_pk_bf16_f32 v136, v140, v141
	v_cvt_pk_bf16_f32 v137, v142, v143
	v_lshl_add_u64 v[138:139], v[138:139], 0, v[130:131]
	v_exp_f32_e32 v133, v133
	v_mul_f32_e32 v140, 0xbfb8aa3b, v23
	v_exp_f32_e32 v140, v140
	global_store_dwordx4 v[138:139], v[134:137], off sc1
	v_add_f32_e32 v133, 1.0, v133
	v_add_u32_e32 v132, 0x80b0, v132
	v_mul_f32_e32 v135, 0xbfb8aa3b, v24
	v_exp_f32_e32 v136, v135
	v_mul_f32_e32 v135, 0xbfb8aa3b, v25
	v_exp_f32_e32 v137, v135
	v_rcp_f32_e32 v134, v133
	v_add_f32_e32 v133, 1.0, v140
	v_rcp_f32_e32 v135, v133
	v_add_f32_e32 v133, 1.0, v136
	v_rcp_f32_e32 v136, v133
	v_add_f32_e32 v133, 1.0, v137
	v_mul_f32_e32 v137, 0xbfb8aa3b, v14
	v_exp_f32_e32 v140, v137
	v_mul_f32_e32 v137, 0xbfb8aa3b, v15
	v_exp_f32_e32 v141, v137
	v_rcp_f32_e32 v137, v133
	v_add_f32_e32 v133, 1.0, v140
	v_rcp_f32_e32 v140, v133
	v_add_f32_e32 v133, 1.0, v141
	v_mul_f32_e32 v141, 0xbfb8aa3b, v16
	v_exp_f32_e32 v142, v141
	v_mul_f32_e32 v141, 0xbfb8aa3b, v17
	v_exp_f32_e32 v143, v141
	v_rcp_f32_e32 v141, v133
	v_add_f32_e32 v133, 1.0, v142
	v_rcp_f32_e32 v142, v133
	v_add_f32_e32 v133, 1.0, v143
	v_rcp_f32_e32 v143, v133
	v_pk_mul_f32 v[134:135], v[22:23], v[134:135]
	v_pk_mul_f32 v[136:137], v[24:25], v[136:137]
	v_pk_mul_f32 v[140:141], v[14:15], v[140:141]
	v_pk_mul_f32 v[142:143], v[16:17], v[142:143]
	v_cvt_pk_bf16_f32 v134, v134, v135
	v_cvt_pk_bf16_f32 v135, v136, v137
	v_cvt_pk_bf16_f32 v136, v140, v141
	v_cvt_pk_bf16_f32 v137, v142, v143
	global_store_dwordx4 v[138:139], v[134:137], off offset:256 sc1
	v_ashrrev_i32_e32 v133, 31, v132
	v_mul_f32_e32 v138, 0xbfb8aa3b, v10
	v_mul_f32_e32 v134, 0xbfb8aa3b, v18
	v_mul_f32_e32 v135, 0xbfb8aa3b, v19
	v_exp_f32_e32 v134, v134
	v_exp_f32_e32 v135, v135
	v_lshlrev_b64 v[136:137], 10, v[132:133]
	v_mul_f32_e32 v139, 0xbfb8aa3b, v11
	v_add_f32_e32 v132, 1.0, v134
	v_add_f32_e32 v133, 1.0, v135
	v_mul_f32_e32 v134, 0xbfb8aa3b, v20
	v_mul_f32_e32 v135, 0xbfb8aa3b, v21
	v_mul_f32_e32 v140, 0xbfb8aa3b, v12
	v_mul_f32_e32 v141, 0xbfb8aa3b, v13
	v_exp_f32_e32 v134, v134
	v_exp_f32_e32 v135, v135
	v_exp_f32_e32 v138, v138
	v_exp_f32_e32 v139, v139
	v_exp_f32_e32 v140, v140
	v_exp_f32_e32 v141, v141
	v_add_f32_e32 v134, 1.0, v134
	v_add_f32_e32 v135, 1.0, v135
	v_add_f32_e32 v138, 1.0, v138
	v_add_f32_e32 v139, 1.0, v139
	v_add_f32_e32 v140, 1.0, v140
	v_add_f32_e32 v141, 1.0, v141
	v_rcp_f32_e32 v132, v132
	v_rcp_f32_e32 v133, v133
	v_rcp_f32_e32 v134, v134
	v_rcp_f32_e32 v135, v135
	v_rcp_f32_e32 v138, v138
	v_rcp_f32_e32 v139, v139
	v_rcp_f32_e32 v140, v140
	v_rcp_f32_e32 v141, v141
	v_pk_mul_f32 v[132:133], v[18:19], v[132:133]
	v_pk_mul_f32 v[134:135], v[20:21], v[134:135]
	v_pk_mul_f32 v[138:139], v[10:11], v[138:139]
	v_pk_mul_f32 v[140:141], v[12:13], v[140:141]
	v_lshl_add_u64 v[136:137], s[24:25], 0, v[136:137]
	v_cvt_pk_bf16_f32 v132, v132, v133
	v_cvt_pk_bf16_f32 v133, v134, v135
	v_cvt_pk_bf16_f32 v134, v138, v139
	v_cvt_pk_bf16_f32 v135, v140, v141
	v_lshl_add_u64 v[136:137], v[136:137], 0, v[130:131]
	v_mul_f32_e32 v130, 0xbfb8aa3b, v6
	v_mul_f32_e32 v131, 0xbfb8aa3b, v7
	global_store_dwordx4 v[136:137], v[132:135], off sc1
	v_mul_f32_e32 v138, 0xbfb8aa3b, v4
	v_mul_f32_e32 v139, 0xbfb8aa3b, v5
	v_mul_f32_e32 v132, 0xbfb8aa3b, v8
	v_mul_f32_e32 v133, 0xbfb8aa3b, v9
	v_mul_f32_e32 v134, 0xbfb8aa3b, v2
	v_mul_f32_e32 v135, 0xbfb8aa3b, v3
	v_exp_f32_e32 v130, v130
	v_exp_f32_e32 v131, v131
	v_exp_f32_e32 v132, v132
	v_exp_f32_e32 v133, v133
	v_exp_f32_e32 v134, v134
	v_exp_f32_e32 v135, v135
	v_exp_f32_e32 v138, v138
	v_exp_f32_e32 v139, v139
	v_add_f32_e32 v130, 1.0, v130
	v_add_f32_e32 v131, 1.0, v131
	v_add_f32_e32 v132, 1.0, v132
	v_add_f32_e32 v133, 1.0, v133
	v_add_f32_e32 v134, 1.0, v134
	v_add_f32_e32 v135, 1.0, v135
	v_add_f32_e32 v138, 1.0, v138
	v_add_f32_e32 v139, 1.0, v139
	v_rcp_f32_e32 v130, v130
	v_rcp_f32_e32 v131, v131
	v_rcp_f32_e32 v132, v132
	v_rcp_f32_e32 v133, v133
	v_rcp_f32_e32 v134, v134
	v_rcp_f32_e32 v135, v135
	v_rcp_f32_e32 v138, v138
	v_rcp_f32_e32 v139, v139
	v_pk_mul_f32 v[130:131], v[6:7], v[130:131]
	v_pk_mul_f32 v[132:133], v[8:9], v[132:133]
	v_pk_mul_f32 v[134:135], v[2:3], v[134:135]
	v_pk_mul_f32 v[138:139], v[4:5], v[138:139]
	v_cvt_pk_bf16_f32 v130, v130, v131
	v_cvt_pk_bf16_f32 v131, v132, v133
	v_cvt_pk_bf16_f32 v132, v134, v135
	v_cvt_pk_bf16_f32 v133, v138, v139
	global_store_dwordx4 v[136:137], v[130:133], off offset:256 sc1

.LBB0_297:
	s_and_b64 vcc, exec, s[48:49]
	s_cbranch_vccz .LBB0_309
	s_cmp_gt_i32 s41, 1
	s_mov_b64 s[46:47], -1
	s_cbranch_scc0 .LBB0_304
	s_cmp_gt_i32 s41, 2
	s_cbranch_scc0 .LBB0_301
	s_lshl_b32 s2, s66, 8
	s_and_b32 s2, s2, 0x100
	s_or_b32 s2, s2, s59
	v_add_u32_e32 v134, s2, v173
	s_lshl_b32 s2, s33, 8
	s_add_i32 s2, s2, s58
	v_add_u32_e32 v138, s2, v171
	v_add_u32_e32 v130, 0x8000, v138
	v_ashrrev_i32_e32 v131, 31, v130
	v_lshlrev_b64 v[136:137], 10, v[130:131]
	v_ashrrev_i32_e32 v135, 31, v134
	v_lshl_add_u64 v[136:137], s[26:27], 0, v[136:137]
	v_lshlrev_b64 v[134:135], 1, v[134:135]
	v_cvt_pk_bf16_f32 v130, v126, v127
	v_cvt_pk_bf16_f32 v131, v128, v129
	v_cvt_pk_bf16_f32 v132, v122, v123
	v_cvt_pk_bf16_f32 v133, v124, v125
	v_lshl_add_u64 v[136:137], v[136:137], 0, v[134:135]
	global_store_dwordx4 v[136:137], v[130:133], off sc1
	s_mov_b64 s[46:47], 0
	s_nop 0
	v_cvt_pk_bf16_f32 v130, v118, v119
	v_cvt_pk_bf16_f32 v131, v120, v121
	v_cvt_pk_bf16_f32 v132, v110, v111
	v_cvt_pk_bf16_f32 v133, v112, v113
	global_store_dwordx4 v[136:137], v[130:133], off offset:256 sc1
	s_nop 1
	v_add_u32_e32 v130, 0x8010, v138
	v_ashrrev_i32_e32 v131, 31, v130
	v_lshlrev_b64 v[136:137], 10, v[130:131]
	v_lshl_add_u64 v[136:137], s[26:27], 0, v[136:137]
	v_cvt_pk_bf16_f32 v130, v114, v115
	v_cvt_pk_bf16_f32 v131, v116, v117
	v_cvt_pk_bf16_f32 v132, v106, v107
	v_cvt_pk_bf16_f32 v133, v108, v109
	v_lshl_add_u64 v[136:137], v[136:137], 0, v[134:135]
	global_store_dwordx4 v[136:137], v[130:133], off sc1
	s_nop 1
	v_cvt_pk_bf16_f32 v130, v102, v103
	v_cvt_pk_bf16_f32 v131, v104, v105
	v_cvt_pk_bf16_f32 v132, v94, v95
	v_cvt_pk_bf16_f32 v133, v96, v97
	global_store_dwordx4 v[136:137], v[130:133], off offset:256 sc1
	s_nop 1
	v_add_u32_e32 v130, 0x8020, v138
	v_ashrrev_i32_e32 v131, 31, v130
	v_lshlrev_b64 v[136:137], 10, v[130:131]
	v_lshl_add_u64 v[136:137], s[26:27], 0, v[136:137]
	v_cvt_pk_bf16_f32 v130, v98, v99
	v_cvt_pk_bf16_f32 v131, v100, v101
	v_cvt_pk_bf16_f32 v132, v90, v91
	v_cvt_pk_bf16_f32 v133, v92, v93
	v_lshl_add_u64 v[136:137], v[136:137], 0, v[134:135]
	global_store_dwordx4 v[136:137], v[130:133], off sc1
	s_nop 1
	v_cvt_pk_bf16_f32 v130, v86, v87
	v_cvt_pk_bf16_f32 v131, v88, v89
	v_cvt_pk_bf16_f32 v132, v78, v79
	v_cvt_pk_bf16_f32 v133, v80, v81
	global_store_dwordx4 v[136:137], v[130:133], off offset:256 sc1
	s_nop 1
	v_add_u32_e32 v130, 0x8030, v138
	v_ashrrev_i32_e32 v131, 31, v130
	v_lshlrev_b64 v[136:137], 10, v[130:131]
	v_lshl_add_u64 v[136:137], s[26:27], 0, v[136:137]
	v_cvt_pk_bf16_f32 v130, v82, v83
	v_cvt_pk_bf16_f32 v131, v84, v85
	v_cvt_pk_bf16_f32 v132, v74, v75
	v_cvt_pk_bf16_f32 v133, v76, v77
	v_lshl_add_u64 v[136:137], v[136:137], 0, v[134:135]
	global_store_dwordx4 v[136:137], v[130:133], off sc1
	s_nop 1
	v_cvt_pk_bf16_f32 v130, v70, v71
	v_cvt_pk_bf16_f32 v131, v72, v73
	v_cvt_pk_bf16_f32 v132, v66, v67
	v_cvt_pk_bf16_f32 v133, v68, v69
	global_store_dwordx4 v[136:137], v[130:133], off offset:256 sc1
	s_nop 1
	v_add_u32_e32 v130, 0x8080, v138
	v_ashrrev_i32_e32 v131, 31, v130
	v_lshlrev_b64 v[136:137], 10, v[130:131]
	v_lshl_add_u64 v[136:137], s[26:27], 0, v[136:137]
	v_cvt_pk_bf16_f32 v130, v62, v63
	v_cvt_pk_bf16_f32 v131, v64, v65
	v_cvt_pk_bf16_f32 v132, v58, v59
	v_cvt_pk_bf16_f32 v133, v60, v61
	v_lshl_add_u64 v[136:137], v[136:137], 0, v[134:135]
	global_store_dwordx4 v[136:137], v[130:133], off sc1
	s_nop 1
	v_cvt_pk_bf16_f32 v130, v54, v55
	v_cvt_pk_bf16_f32 v131, v56, v57
	v_cvt_pk_bf16_f32 v132, v46, v47
	v_cvt_pk_bf16_f32 v133, v48, v49
	global_store_dwordx4 v[136:137], v[130:133], off offset:256 sc1
	s_nop 1
	v_add_u32_e32 v130, 0x8090, v138
	v_ashrrev_i32_e32 v131, 31, v130
	v_lshlrev_b64 v[136:137], 10, v[130:131]
	v_lshl_add_u64 v[136:137], s[26:27], 0, v[136:137]
	v_cvt_pk_bf16_f32 v130, v50, v51
	v_cvt_pk_bf16_f32 v131, v52, v53
	v_cvt_pk_bf16_f32 v132, v42, v43
	v_cvt_pk_bf16_f32 v133, v44, v45
	v_lshl_add_u64 v[136:137], v[136:137], 0, v[134:135]
	global_store_dwordx4 v[136:137], v[130:133], off sc1
	s_nop 1
	v_cvt_pk_bf16_f32 v130, v38, v39
	v_cvt_pk_bf16_f32 v131, v40, v41
	v_cvt_pk_bf16_f32 v132, v30, v31
	v_cvt_pk_bf16_f32 v133, v32, v33
	global_store_dwordx4 v[136:137], v[130:133], off offset:256 sc1
	s_nop 1
	v_add_u32_e32 v130, 0x80a0, v138
	v_ashrrev_i32_e32 v131, 31, v130
	v_lshlrev_b64 v[136:137], 10, v[130:131]
	v_lshl_add_u64 v[136:137], s[26:27], 0, v[136:137]
	v_cvt_pk_bf16_f32 v130, v34, v35
	v_cvt_pk_bf16_f32 v131, v36, v37
	v_cvt_pk_bf16_f32 v132, v26, v27
	v_cvt_pk_bf16_f32 v133, v28, v29
	v_lshl_add_u64 v[136:137], v[136:137], 0, v[134:135]
	global_store_dwordx4 v[136:137], v[130:133], off sc1
	s_nop 1
	v_cvt_pk_bf16_f32 v130, v22, v23
	v_cvt_pk_bf16_f32 v131, v24, v25
	v_cvt_pk_bf16_f32 v132, v14, v15
	v_cvt_pk_bf16_f32 v133, v16, v17
	global_store_dwordx4 v[136:137], v[130:133], off offset:256 sc1
	s_nop 1
	v_add_u32_e32 v130, 0x80b0, v138
	v_ashrrev_i32_e32 v131, 31, v130
	v_lshlrev_b64 v[136:137], 10, v[130:131]
	v_lshl_add_u64 v[136:137], s[26:27], 0, v[136:137]
	v_cvt_pk_bf16_f32 v130, v18, v19
	v_cvt_pk_bf16_f32 v131, v20, v21
	v_cvt_pk_bf16_f32 v132, v10, v11
	v_cvt_pk_bf16_f32 v133, v12, v13
	v_lshl_add_u64 v[134:135], v[136:137], 0, v[134:135]
	global_store_dwordx4 v[134:135], v[130:133], off sc1
	s_nop 1
	v_cvt_pk_bf16_f32 v130, v6, v7
	v_cvt_pk_bf16_f32 v131, v8, v9
	v_cvt_pk_bf16_f32 v132, v2, v3
	v_cvt_pk_bf16_f32 v133, v4, v5
	global_store_dwordx4 v[134:135], v[130:133], off offset:256 sc1
.LBB0_301:
	s_andn2_b64 vcc, exec, s[46:47]
	s_cbranch_vccnz .LBB0_303
	s_lshl_b32 s2, s33, 8
	v_add_u32_e32 v130, s59, v173
	s_add_i32 s2, s2, 0x8000
	v_add_u32_e32 v138, s2, v130
	v_ashrrev_i32_e32 v131, 3, v138
	s_lshl_b32 s2, s66, 8
	v_and_b32_e32 v131, 0xfffffe00, v131
	s_and_b32 s2, s2, 0x100
	v_add_u32_e32 v140, s58, v171
	v_or_b32_e32 v141, s2, v131
	v_add_u32_e32 v142, v141, v140
	v_lshrrev_b32_e32 v144, 6, v138
	v_and_b32_e32 v139, 56, v130
	v_bfi_b32 v130, s69, v142, v144
	v_ashrrev_i32_e32 v131, 31, v130
	v_lshlrev_b64 v[130:131], 13, v[130:131]
	v_lshlrev_b32_e32 v136, 7, v171
	v_lshl_add_u64 v[130:131], s[28:29], 0, v[130:131]
	v_and_b32_e32 v156, 0x1f80, v136
	v_lshl_add_u64 v[136:137], v[130:131], 0, v[156:157]
	v_lshlrev_b32_e32 v130, 1, v139
	v_mov_b32_e32 v131, v157
	v_cvt_pk_bf16_f32 v132, v126, v127
	v_cvt_pk_bf16_f32 v133, v128, v129
	v_cvt_pk_bf16_f32 v134, v122, v123
	v_cvt_pk_bf16_f32 v135, v124, v125
	v_lshl_add_u64 v[136:137], v[136:137], 0, v[130:131]
	global_store_dwordx4 v[136:137], v[132:135], off sc1
	v_add_u32_e32 v136, 0x80, v138
	v_lshrrev_b32_e32 v162, 6, v136
	v_bfe_u32 v163, v136, 6, 6
	v_bfi_b32 v136, s69, v142, v162
	v_ashrrev_i32_e32 v137, 31, v136
	v_lshlrev_b64 v[136:137], 13, v[136:137]
	v_lshl_add_u64 v[136:137], s[28:29], 0, v[136:137]
	v_bfe_u32 v145, v138, 6, 6
	v_lshl_add_u64 v[136:137], v[136:137], 0, v[156:157]
	v_add_u32_e32 v138, 16, v140
	v_and_b32_e32 v143, 0xffffffc0, v142
	v_cvt_pk_bf16_f32 v132, v118, v119
	v_cvt_pk_bf16_f32 v133, v120, v121
	v_cvt_pk_bf16_f32 v134, v110, v111
	v_cvt_pk_bf16_f32 v135, v112, v113
	v_lshl_add_u64 v[136:137], v[136:137], 0, v[130:131]
	v_add_u32_e32 v142, v141, v138
	global_store_dwordx4 v[136:137], v[132:135], off sc1
	v_bfi_b32 v136, s69, v142, v144
	v_ashrrev_i32_e32 v137, 31, v136
	v_lshlrev_b64 v[136:137], 13, v[136:137]
	v_lshlrev_b32_e32 v138, 7, v138
	v_lshl_add_u64 v[136:137], s[28:29], 0, v[136:137]
	v_and_b32_e32 v138, 0x1f80, v138
	v_mov_b32_e32 v139, v157
	v_lshl_add_u64 v[136:137], v[136:137], 0, v[138:139]
	v_cvt_pk_bf16_f32 v132, v114, v115
	v_cvt_pk_bf16_f32 v133, v116, v117
	v_cvt_pk_bf16_f32 v134, v106, v107
	v_cvt_pk_bf16_f32 v135, v108, v109
	v_lshl_add_u64 v[136:137], v[136:137], 0, v[130:131]
	global_store_dwordx4 v[136:137], v[132:135], off sc1
	v_bfi_b32 v136, s69, v142, v162
	v_ashrrev_i32_e32 v137, 31, v136
	v_lshlrev_b64 v[136:137], 13, v[136:137]
	v_lshl_add_u64 v[136:137], s[28:29], 0, v[136:137]
	v_lshl_add_u64 v[136:137], v[136:137], 0, v[138:139]
	v_add_u32_e32 v138, 32, v140
	v_cvt_pk_bf16_f32 v132, v102, v103
	v_cvt_pk_bf16_f32 v133, v104, v105
	v_cvt_pk_bf16_f32 v134, v94, v95
	v_cvt_pk_bf16_f32 v135, v96, v97
	v_lshl_add_u64 v[136:137], v[136:137], 0, v[130:131]
	v_add_u32_e32 v142, v141, v138
	global_store_dwordx4 v[136:137], v[132:135], off sc1
	v_bfi_b32 v136, s69, v142, v144
	v_ashrrev_i32_e32 v137, 31, v136
	v_lshlrev_b64 v[136:137], 13, v[136:137]
	v_lshlrev_b32_e32 v138, 7, v138
	v_lshl_add_u64 v[136:137], s[28:29], 0, v[136:137]
	v_and_b32_e32 v138, 0x1f80, v138
	v_lshl_add_u64 v[136:137], v[136:137], 0, v[138:139]
	v_cvt_pk_bf16_f32 v132, v98, v99
	v_cvt_pk_bf16_f32 v133, v100, v101
	v_cvt_pk_bf16_f32 v134, v90, v91
	v_cvt_pk_bf16_f32 v135, v92, v93
	v_lshl_add_u64 v[136:137], v[136:137], 0, v[130:131]
	global_store_dwordx4 v[136:137], v[132:135], off sc1
	v_bfi_b32 v136, s69, v142, v162
	v_ashrrev_i32_e32 v137, 31, v136
	v_lshlrev_b64 v[136:137], 13, v[136:137]
	v_lshl_add_u64 v[136:137], s[28:29], 0, v[136:137]
	v_lshl_add_u64 v[136:137], v[136:137], 0, v[138:139]
	v_add_u32_e32 v138, 48, v140
	v_cvt_pk_bf16_f32 v132, v86, v87
	v_cvt_pk_bf16_f32 v133, v88, v89
	v_cvt_pk_bf16_f32 v134, v78, v79
	v_cvt_pk_bf16_f32 v135, v80, v81
	v_lshl_add_u64 v[136:137], v[136:137], 0, v[130:131]
	v_add_u32_e32 v142, v141, v138
	global_store_dwordx4 v[136:137], v[132:135], off sc1
	v_bfi_b32 v136, s69, v142, v144
	v_ashrrev_i32_e32 v137, 31, v136
	v_lshlrev_b64 v[136:137], 13, v[136:137]
	v_lshlrev_b32_e32 v138, 7, v138
	v_lshl_add_u64 v[136:137], s[28:29], 0, v[136:137]
	v_and_b32_e32 v138, 0x1f80, v138
	v_lshl_add_u64 v[136:137], v[136:137], 0, v[138:139]
	v_cvt_pk_bf16_f32 v132, v82, v83
	v_cvt_pk_bf16_f32 v133, v84, v85
	v_cvt_pk_bf16_f32 v134, v74, v75
	v_cvt_pk_bf16_f32 v135, v76, v77
	v_lshl_add_u64 v[136:137], v[136:137], 0, v[130:131]
	global_store_dwordx4 v[136:137], v[132:135], off sc1
	v_bfi_b32 v136, s69, v142, v162
	v_ashrrev_i32_e32 v137, 31, v136
	v_lshlrev_b64 v[136:137], 13, v[136:137]
	v_lshl_add_u64 v[136:137], s[28:29], 0, v[136:137]
	v_lshl_add_u64 v[136:137], v[136:137], 0, v[138:139]
	v_cvt_pk_bf16_f32 v132, v70, v71
	v_cvt_pk_bf16_f32 v133, v72, v73
	v_cvt_pk_bf16_f32 v134, v66, v67
	v_cvt_pk_bf16_f32 v135, v68, v69
	v_lshl_add_u64 v[136:137], v[136:137], 0, v[130:131]
	v_add_u32_e32 v138, 0x80, v143
	global_store_dwordx4 v[136:137], v[132:135], off sc1
	v_or_b32_e32 v136, v145, v138
	v_ashrrev_i32_e32 v137, 31, v136
	v_lshlrev_b64 v[136:137], 13, v[136:137]
	v_lshl_add_u64 v[136:137], s[28:29], 0, v[136:137]
	v_lshl_add_u64 v[136:137], v[136:137], 0, v[156:157]
	v_cvt_pk_bf16_f32 v132, v62, v63
	v_cvt_pk_bf16_f32 v133, v64, v65
	v_cvt_pk_bf16_f32 v134, v58, v59
	v_cvt_pk_bf16_f32 v135, v60, v61
	v_lshl_add_u64 v[136:137], v[136:137], 0, v[130:131]
	global_store_dwordx4 v[136:137], v[132:135], off sc1
	v_or_b32_e32 v136, v163, v138
	v_ashrrev_i32_e32 v137, 31, v136
	v_lshlrev_b64 v[136:137], 13, v[136:137]
	v_lshl_add_u64 v[136:137], s[28:29], 0, v[136:137]
	v_lshl_add_u64 v[136:137], v[136:137], 0, v[156:157]
	v_add_u32_e32 v138, 0x90, v140
	v_cvt_pk_bf16_f32 v132, v54, v55
	v_cvt_pk_bf16_f32 v133, v56, v57
	v_cvt_pk_bf16_f32 v134, v46, v47
	v_cvt_pk_bf16_f32 v135, v48, v49
	v_lshl_add_u64 v[136:137], v[136:137], 0, v[130:131]
	v_add_u32_e32 v139, v141, v138
	global_store_dwordx4 v[136:137], v[132:135], off sc1
	v_bfi_b32 v136, s69, v139, v144
	v_ashrrev_i32_e32 v137, 31, v136
	v_lshlrev_b64 v[136:137], 13, v[136:137]
	v_lshlrev_b32_e32 v138, 7, v138
	v_lshl_add_u64 v[136:137], s[28:29], 0, v[136:137]
	v_and_b32_e32 v156, 0x1f80, v138
	v_lshl_add_u64 v[136:137], v[136:137], 0, v[156:157]
	v_cvt_pk_bf16_f32 v132, v50, v51
	v_cvt_pk_bf16_f32 v133, v52, v53
	v_cvt_pk_bf16_f32 v134, v42, v43
	v_cvt_pk_bf16_f32 v135, v44, v45
	v_lshl_add_u64 v[136:137], v[136:137], 0, v[130:131]
	global_store_dwordx4 v[136:137], v[132:135], off sc1
	v_bfi_b32 v136, s69, v139, v162
	v_ashrrev_i32_e32 v137, 31, v136
	v_lshlrev_b64 v[136:137], 13, v[136:137]
	v_lshl_add_u64 v[136:137], s[28:29], 0, v[136:137]
	v_lshl_add_u64 v[136:137], v[136:137], 0, v[156:157]
	v_add_u32_e32 v138, 0xa0, v140
	v_cvt_pk_bf16_f32 v132, v38, v39
	v_cvt_pk_bf16_f32 v133, v40, v41
	v_cvt_pk_bf16_f32 v134, v30, v31
	v_cvt_pk_bf16_f32 v135, v32, v33
	v_lshl_add_u64 v[136:137], v[136:137], 0, v[130:131]
	v_add_u32_e32 v139, v141, v138
	global_store_dwordx4 v[136:137], v[132:135], off sc1
	v_bfi_b32 v136, s69, v139, v144
	v_ashrrev_i32_e32 v137, 31, v136
	v_lshlrev_b64 v[136:137], 13, v[136:137]
	v_lshlrev_b32_e32 v138, 7, v138
	v_lshl_add_u64 v[136:137], s[28:29], 0, v[136:137]
	v_and_b32_e32 v156, 0x1f80, v138
	v_lshl_add_u64 v[136:137], v[136:137], 0, v[156:157]
	v_cvt_pk_bf16_f32 v132, v34, v35
	v_cvt_pk_bf16_f32 v133, v36, v37
	v_cvt_pk_bf16_f32 v134, v26, v27
	v_cvt_pk_bf16_f32 v135, v28, v29
	v_lshl_add_u64 v[136:137], v[136:137], 0, v[130:131]
	global_store_dwordx4 v[136:137], v[132:135], off sc1
	v_bfi_b32 v136, s69, v139, v162
	v_ashrrev_i32_e32 v137, 31, v136
	v_lshlrev_b64 v[136:137], 13, v[136:137]
	v_lshl_add_u64 v[136:137], s[28:29], 0, v[136:137]
	v_lshl_add_u64 v[136:137], v[136:137], 0, v[156:157]
	v_add_u32_e32 v138, 0xb0, v140
	v_cvt_pk_bf16_f32 v132, v22, v23
	v_cvt_pk_bf16_f32 v133, v24, v25
	v_cvt_pk_bf16_f32 v134, v14, v15
	v_cvt_pk_bf16_f32 v135, v16, v17
	v_lshl_add_u64 v[136:137], v[136:137], 0, v[130:131]
	v_add_u32_e32 v139, v141, v138
	global_store_dwordx4 v[136:137], v[132:135], off sc1
	v_bfi_b32 v136, s69, v139, v144
	v_ashrrev_i32_e32 v137, 31, v136
	v_lshlrev_b64 v[136:137], 13, v[136:137]
	v_lshlrev_b32_e32 v138, 7, v138
	v_lshl_add_u64 v[136:137], s[28:29], 0, v[136:137]
	v_and_b32_e32 v156, 0x1f80, v138
	v_lshl_add_u64 v[136:137], v[136:137], 0, v[156:157]
	v_cvt_pk_bf16_f32 v132, v18, v19
	v_cvt_pk_bf16_f32 v133, v20, v21
	v_cvt_pk_bf16_f32 v134, v10, v11
	v_cvt_pk_bf16_f32 v135, v12, v13
	v_lshl_add_u64 v[136:137], v[136:137], 0, v[130:131]
	global_store_dwordx4 v[136:137], v[132:135], off sc1
	v_bfi_b32 v136, s69, v139, v162
	v_ashrrev_i32_e32 v137, 31, v136
	v_lshlrev_b64 v[136:137], 13, v[136:137]
	v_lshl_add_u64 v[136:137], s[28:29], 0, v[136:137]
	v_lshl_add_u64 v[136:137], v[136:137], 0, v[156:157]
	v_cvt_pk_bf16_f32 v132, v6, v7
	v_cvt_pk_bf16_f32 v133, v8, v9
	v_cvt_pk_bf16_f32 v134, v2, v3
	v_cvt_pk_bf16_f32 v135, v4, v5
	v_lshl_add_u64 v[130:131], v[136:137], 0, v[130:131]
	global_store_dwordx4 v[130:131], v[132:135], off sc1

.LBB0_304:
	s_andn2_b64 vcc, exec, s[46:47]
	s_mov_b64 s[46:47], 0
	s_cbranch_vccnz .LBB0_309
	s_cmp_gt_i32 s41, 0
	s_mov_b64 s[46:47], -1
	s_cbranch_scc0 .LBB0_307
	s_lshl_b32 s2, s66, 8
	s_and_b32 s2, s2, 0x100
	s_or_b32 s2, s2, s59
	v_add_u32_e32 v138, s2, v173
	s_lshl_b32 s2, s33, 8
	s_add_i32 s2, s2, s58
	v_add_u32_e32 v139, s2, v171
	v_add_u32_e32 v130, 0x8000, v139
	v_ashrrev_i32_e32 v130, 9, v130
	v_and_b32_e32 v141, -8, v130
	v_ashrrev_i32_e32 v142, 6, v138
	v_add_u32_e32 v130, v141, v142
	v_ashrrev_i32_e32 v131, 31, v130
	v_lshlrev_b64 v[130:131], 19, v[130:131]
	v_lshlrev_b32_e32 v136, 7, v139
	v_and_b32_e32 v140, 56, v138
	v_lshl_add_u64 v[130:131], s[30:31], 0, v[130:131]
	v_and_b32_e32 v156, 0x7ff80, v136
	v_lshl_add_u64 v[136:137], v[130:131], 0, v[156:157]
	v_lshlrev_b32_e32 v130, 1, v140
	v_mov_b32_e32 v131, v157
	v_cvt_pk_bf16_f32 v132, v126, v127
	v_cvt_pk_bf16_f32 v133, v128, v129
	v_cvt_pk_bf16_f32 v134, v122, v123
	v_cvt_pk_bf16_f32 v135, v124, v125
	v_lshl_add_u64 v[136:137], v[136:137], 0, v[130:131]
	global_store_dwordx4 v[136:137], v[132:135], off sc1
	v_add_u32_e32 v136, 0x80, v138
	v_ashrrev_i32_e32 v138, 6, v136
	v_add_u32_e32 v136, v141, v138
	v_ashrrev_i32_e32 v137, 31, v136
	v_lshlrev_b64 v[136:137], 19, v[136:137]
	v_lshl_add_u64 v[136:137], s[30:31], 0, v[136:137]
	v_lshl_add_u64 v[136:137], v[136:137], 0, v[156:157]
	v_cvt_pk_bf16_f32 v132, v118, v119
	v_cvt_pk_bf16_f32 v133, v120, v121
	v_cvt_pk_bf16_f32 v134, v110, v111
	v_cvt_pk_bf16_f32 v135, v112, v113
	v_lshl_add_u64 v[136:137], v[136:137], 0, v[130:131]
	v_add_u32_e32 v140, 0x8010, v139
	global_store_dwordx4 v[136:137], v[132:135], off sc1
	s_mov_b64 s[46:47], 0
	s_nop 0
	v_ashrrev_i32_e32 v132, 9, v140
	v_and_b32_e32 v141, -8, v132
	v_add_u32_e32 v136, v141, v142
	v_ashrrev_i32_e32 v137, 31, v136
	v_lshlrev_b64 v[136:137], 19, v[136:137]
	v_lshlrev_b32_e32 v140, 7, v140
	v_lshl_add_u64 v[136:137], s[30:31], 0, v[136:137]
	v_and_b32_e32 v156, 0x7ff80, v140
	v_lshl_add_u64 v[136:137], v[136:137], 0, v[156:157]
	v_cvt_pk_bf16_f32 v132, v114, v115
	v_cvt_pk_bf16_f32 v133, v116, v117
	v_cvt_pk_bf16_f32 v134, v106, v107
	v_cvt_pk_bf16_f32 v135, v108, v109
	v_lshl_add_u64 v[136:137], v[136:137], 0, v[130:131]
	global_store_dwordx4 v[136:137], v[132:135], off sc1
	v_add_u32_e32 v136, v141, v138
	v_ashrrev_i32_e32 v137, 31, v136
	v_lshlrev_b64 v[136:137], 19, v[136:137]
	v_lshl_add_u64 v[136:137], s[30:31], 0, v[136:137]
	v_lshl_add_u64 v[136:137], v[136:137], 0, v[156:157]
	v_cvt_pk_bf16_f32 v132, v102, v103
	v_cvt_pk_bf16_f32 v133, v104, v105
	v_cvt_pk_bf16_f32 v134, v94, v95
	v_cvt_pk_bf16_f32 v135, v96, v97
	v_lshl_add_u64 v[136:137], v[136:137], 0, v[130:131]
	v_add_u32_e32 v140, 0x8020, v139
	global_store_dwordx4 v[136:137], v[132:135], off sc1
	s_nop 1
	v_ashrrev_i32_e32 v132, 9, v140
	v_and_b32_e32 v141, -8, v132
	v_add_u32_e32 v136, v141, v142
	v_ashrrev_i32_e32 v137, 31, v136
	v_lshlrev_b64 v[136:137], 19, v[136:137]
	v_lshlrev_b32_e32 v140, 7, v140
	v_lshl_add_u64 v[136:137], s[30:31], 0, v[136:137]
	v_and_b32_e32 v156, 0x7ff80, v140
	v_lshl_add_u64 v[136:137], v[136:137], 0, v[156:157]
	v_cvt_pk_bf16_f32 v132, v98, v99
	v_cvt_pk_bf16_f32 v133, v100, v101
	v_cvt_pk_bf16_f32 v134, v90, v91
	v_cvt_pk_bf16_f32 v135, v92, v93
	v_lshl_add_u64 v[136:137], v[136:137], 0, v[130:131]
	global_store_dwordx4 v[136:137], v[132:135], off sc1
	v_add_u32_e32 v136, v141, v138
	v_ashrrev_i32_e32 v137, 31, v136
	v_lshlrev_b64 v[136:137], 19, v[136:137]
	v_lshl_add_u64 v[136:137], s[30:31], 0, v[136:137]
	v_lshl_add_u64 v[136:137], v[136:137], 0, v[156:157]
	v_cvt_pk_bf16_f32 v132, v86, v87
	v_cvt_pk_bf16_f32 v133, v88, v89
	v_cvt_pk_bf16_f32 v134, v78, v79
	v_cvt_pk_bf16_f32 v135, v80, v81
	v_lshl_add_u64 v[136:137], v[136:137], 0, v[130:131]
	v_add_u32_e32 v140, 0x8030, v139
	global_store_dwordx4 v[136:137], v[132:135], off sc1
	s_nop 1
	v_ashrrev_i32_e32 v132, 9, v140
	v_and_b32_e32 v141, -8, v132
	v_add_u32_e32 v136, v141, v142
	v_ashrrev_i32_e32 v137, 31, v136
	v_lshlrev_b64 v[136:137], 19, v[136:137]
	v_lshlrev_b32_e32 v140, 7, v140
	v_lshl_add_u64 v[136:137], s[30:31], 0, v[136:137]
	v_and_b32_e32 v156, 0x7ff80, v140
	v_lshl_add_u64 v[136:137], v[136:137], 0, v[156:157]
	v_cvt_pk_bf16_f32 v132, v82, v83
	v_cvt_pk_bf16_f32 v133, v84, v85
	v_cvt_pk_bf16_f32 v134, v74, v75
	v_cvt_pk_bf16_f32 v135, v76, v77
	v_lshl_add_u64 v[136:137], v[136:137], 0, v[130:131]
	global_store_dwordx4 v[136:137], v[132:135], off sc1
	v_add_u32_e32 v136, v141, v138
	v_ashrrev_i32_e32 v137, 31, v136
	v_lshlrev_b64 v[136:137], 19, v[136:137]
	v_lshl_add_u64 v[136:137], s[30:31], 0, v[136:137]
	v_lshl_add_u64 v[136:137], v[136:137], 0, v[156:157]
	v_cvt_pk_bf16_f32 v132, v70, v71
	v_cvt_pk_bf16_f32 v133, v72, v73
	v_cvt_pk_bf16_f32 v134, v66, v67
	v_cvt_pk_bf16_f32 v135, v68, v69
	v_lshl_add_u64 v[136:137], v[136:137], 0, v[130:131]
	v_add_u32_e32 v140, 0x8080, v139
	global_store_dwordx4 v[136:137], v[132:135], off sc1
	s_nop 1
	v_ashrrev_i32_e32 v132, 9, v140
	v_and_b32_e32 v141, -8, v132
	v_add_u32_e32 v136, v141, v142
	v_ashrrev_i32_e32 v137, 31, v136
	v_lshlrev_b64 v[136:137], 19, v[136:137]
	v_lshlrev_b32_e32 v140, 7, v140
	v_lshl_add_u64 v[136:137], s[30:31], 0, v[136:137]
	v_and_b32_e32 v156, 0x7ff80, v140
	v_lshl_add_u64 v[136:137], v[136:137], 0, v[156:157]
	v_cvt_pk_bf16_f32 v132, v62, v63
	v_cvt_pk_bf16_f32 v133, v64, v65
	v_cvt_pk_bf16_f32 v134, v58, v59
	v_cvt_pk_bf16_f32 v135, v60, v61
	v_lshl_add_u64 v[136:137], v[136:137], 0, v[130:131]
	global_store_dwordx4 v[136:137], v[132:135], off sc1
	v_add_u32_e32 v136, v141, v138
	v_ashrrev_i32_e32 v137, 31, v136
	v_lshlrev_b64 v[136:137], 19, v[136:137]
	v_lshl_add_u64 v[136:137], s[30:31], 0, v[136:137]
	v_lshl_add_u64 v[136:137], v[136:137], 0, v[156:157]
	v_cvt_pk_bf16_f32 v132, v54, v55
	v_cvt_pk_bf16_f32 v133, v56, v57
	v_cvt_pk_bf16_f32 v134, v46, v47
	v_cvt_pk_bf16_f32 v135, v48, v49
	v_lshl_add_u64 v[136:137], v[136:137], 0, v[130:131]
	v_add_u32_e32 v140, 0x8090, v139
	global_store_dwordx4 v[136:137], v[132:135], off sc1
	s_nop 1
	v_ashrrev_i32_e32 v132, 9, v140
	v_and_b32_e32 v141, -8, v132
	v_add_u32_e32 v136, v141, v142
	v_ashrrev_i32_e32 v137, 31, v136
	v_lshlrev_b64 v[136:137], 19, v[136:137]
	v_lshlrev_b32_e32 v140, 7, v140
	v_lshl_add_u64 v[136:137], s[30:31], 0, v[136:137]
	v_and_b32_e32 v156, 0x7ff80, v140
	v_lshl_add_u64 v[136:137], v[136:137], 0, v[156:157]
	v_cvt_pk_bf16_f32 v132, v50, v51
	v_cvt_pk_bf16_f32 v133, v52, v53
	v_cvt_pk_bf16_f32 v134, v42, v43
	v_cvt_pk_bf16_f32 v135, v44, v45
	v_lshl_add_u64 v[136:137], v[136:137], 0, v[130:131]
	global_store_dwordx4 v[136:137], v[132:135], off sc1
	v_add_u32_e32 v136, v141, v138
	v_ashrrev_i32_e32 v137, 31, v136
	v_lshlrev_b64 v[136:137], 19, v[136:137]
	v_lshl_add_u64 v[136:137], s[30:31], 0, v[136:137]
	v_lshl_add_u64 v[136:137], v[136:137], 0, v[156:157]
	v_cvt_pk_bf16_f32 v132, v38, v39
	v_cvt_pk_bf16_f32 v133, v40, v41
	v_cvt_pk_bf16_f32 v134, v30, v31
	v_cvt_pk_bf16_f32 v135, v32, v33
	v_lshl_add_u64 v[136:137], v[136:137], 0, v[130:131]
	v_add_u32_e32 v140, 0x80a0, v139
	global_store_dwordx4 v[136:137], v[132:135], off sc1
	v_add_u32_e32 v139, 0x80b0, v139
	s_nop 0
	v_ashrrev_i32_e32 v132, 9, v140
	v_and_b32_e32 v141, -8, v132
	v_add_u32_e32 v136, v141, v142
	v_ashrrev_i32_e32 v137, 31, v136
	v_lshlrev_b64 v[136:137], 19, v[136:137]
	v_lshlrev_b32_e32 v140, 7, v140
	v_lshl_add_u64 v[136:137], s[30:31], 0, v[136:137]
	v_and_b32_e32 v156, 0x7ff80, v140
	v_lshl_add_u64 v[136:137], v[136:137], 0, v[156:157]
	v_cvt_pk_bf16_f32 v132, v34, v35
	v_cvt_pk_bf16_f32 v133, v36, v37
	v_cvt_pk_bf16_f32 v134, v26, v27
	v_cvt_pk_bf16_f32 v135, v28, v29
	v_lshl_add_u64 v[136:137], v[136:137], 0, v[130:131]
	global_store_dwordx4 v[136:137], v[132:135], off sc1
	v_add_u32_e32 v136, v141, v138
	v_ashrrev_i32_e32 v137, 31, v136
	v_lshlrev_b64 v[136:137], 19, v[136:137]
	v_lshl_add_u64 v[136:137], s[30:31], 0, v[136:137]
	v_lshl_add_u64 v[136:137], v[136:137], 0, v[156:157]
	v_cvt_pk_bf16_f32 v132, v22, v23
	v_cvt_pk_bf16_f32 v133, v24, v25
	v_cvt_pk_bf16_f32 v134, v14, v15
	v_cvt_pk_bf16_f32 v135, v16, v17
	v_lshl_add_u64 v[136:137], v[136:137], 0, v[130:131]
	global_store_dwordx4 v[136:137], v[132:135], off sc1
	s_nop 1
	v_ashrrev_i32_e32 v132, 9, v139
	v_and_b32_e32 v140, -8, v132
	v_add_u32_e32 v136, v140, v142
	v_ashrrev_i32_e32 v137, 31, v136
	v_lshlrev_b64 v[136:137], 19, v[136:137]
	v_lshlrev_b32_e32 v139, 7, v139
	v_lshl_add_u64 v[136:137], s[30:31], 0, v[136:137]
	v_and_b32_e32 v156, 0x7ff80, v139
	v_lshl_add_u64 v[136:137], v[136:137], 0, v[156:157]
	v_cvt_pk_bf16_f32 v132, v18, v19
	v_cvt_pk_bf16_f32 v133, v20, v21
	v_cvt_pk_bf16_f32 v134, v10, v11
	v_cvt_pk_bf16_f32 v135, v12, v13
	v_lshl_add_u64 v[136:137], v[136:137], 0, v[130:131]
	global_store_dwordx4 v[136:137], v[132:135], off sc1
	v_add_u32_e32 v136, v140, v138
	v_ashrrev_i32_e32 v137, 31, v136
	v_lshlrev_b64 v[136:137], 19, v[136:137]
	v_lshl_add_u64 v[136:137], s[30:31], 0, v[136:137]
	v_lshl_add_u64 v[136:137], v[136:137], 0, v[156:157]
	v_cvt_pk_bf16_f32 v132, v6, v7
	v_cvt_pk_bf16_f32 v133, v8, v9
	v_cvt_pk_bf16_f32 v134, v2, v3
	v_cvt_pk_bf16_f32 v135, v4, v5
	v_lshl_add_u64 v[130:131], v[136:137], 0, v[130:131]
	global_store_dwordx4 v[130:131], v[132:135], off sc1

.LBB0_309:
	s_and_b64 vcc, exec, s[44:45]
	s_cbranch_vccz .LBB0_311
	s_lshl_b32 s2, s66, 8
	s_and_b32 s2, s2, 0x100
	s_or_b32 s2, s2, s59
	v_add_u32_e32 v134, s2, v173
	s_lshl_b32 s2, s33, 8
	s_add_i32 s2, s2, s58
	v_add_u32_e32 v138, s2, v171
	v_add_u32_e32 v130, 0x8000, v138
	v_ashrrev_i32_e32 v131, 31, v130
	v_lshlrev_b64 v[136:137], 10, v[130:131]
	v_ashrrev_i32_e32 v135, 31, v134
	v_lshl_add_u64 v[136:137], s[36:37], 0, v[136:137]
	v_lshlrev_b64 v[134:135], 1, v[134:135]
	v_cvt_pk_bf16_f32 v130, v126, v127
	v_cvt_pk_bf16_f32 v131, v128, v129
	v_cvt_pk_bf16_f32 v132, v122, v123
	v_cvt_pk_bf16_f32 v133, v124, v125
	v_lshl_add_u64 v[136:137], v[136:137], 0, v[134:135]
	global_store_dwordx4 v[136:137], v[130:133], off sc1
	s_mov_b64 s[46:47], 0
	s_nop 0
	v_cvt_pk_bf16_f32 v130, v118, v119
	v_cvt_pk_bf16_f32 v131, v120, v121
	v_cvt_pk_bf16_f32 v132, v110, v111
	v_cvt_pk_bf16_f32 v133, v112, v113
	global_store_dwordx4 v[136:137], v[130:133], off offset:256 sc1
	s_nop 1
	v_add_u32_e32 v130, 0x8010, v138
	v_ashrrev_i32_e32 v131, 31, v130
	v_lshlrev_b64 v[136:137], 10, v[130:131]
	v_lshl_add_u64 v[136:137], s[36:37], 0, v[136:137]
	v_cvt_pk_bf16_f32 v130, v114, v115
	v_cvt_pk_bf16_f32 v131, v116, v117
	v_cvt_pk_bf16_f32 v132, v106, v107
	v_cvt_pk_bf16_f32 v133, v108, v109
	v_lshl_add_u64 v[136:137], v[136:137], 0, v[134:135]
	global_store_dwordx4 v[136:137], v[130:133], off sc1
	s_nop 1
	v_cvt_pk_bf16_f32 v130, v102, v103
	v_cvt_pk_bf16_f32 v131, v104, v105
	v_cvt_pk_bf16_f32 v132, v94, v95
	v_cvt_pk_bf16_f32 v133, v96, v97
	global_store_dwordx4 v[136:137], v[130:133], off offset:256 sc1
	s_nop 1
	v_add_u32_e32 v130, 0x8020, v138
	v_ashrrev_i32_e32 v131, 31, v130
	v_lshlrev_b64 v[136:137], 10, v[130:131]
	v_lshl_add_u64 v[136:137], s[36:37], 0, v[136:137]
	v_cvt_pk_bf16_f32 v130, v98, v99
	v_cvt_pk_bf16_f32 v131, v100, v101
	v_cvt_pk_bf16_f32 v132, v90, v91
	v_cvt_pk_bf16_f32 v133, v92, v93
	v_lshl_add_u64 v[136:137], v[136:137], 0, v[134:135]
	global_store_dwordx4 v[136:137], v[130:133], off sc1
	s_nop 1
	v_cvt_pk_bf16_f32 v130, v86, v87
	v_cvt_pk_bf16_f32 v131, v88, v89
	v_cvt_pk_bf16_f32 v132, v78, v79
	v_cvt_pk_bf16_f32 v133, v80, v81
	global_store_dwordx4 v[136:137], v[130:133], off offset:256 sc1
	s_nop 1
	v_add_u32_e32 v130, 0x8030, v138
	v_ashrrev_i32_e32 v131, 31, v130
	v_lshlrev_b64 v[136:137], 10, v[130:131]
	v_lshl_add_u64 v[136:137], s[36:37], 0, v[136:137]
	v_cvt_pk_bf16_f32 v130, v82, v83
	v_cvt_pk_bf16_f32 v131, v84, v85
	v_cvt_pk_bf16_f32 v132, v74, v75
	v_cvt_pk_bf16_f32 v133, v76, v77
	v_lshl_add_u64 v[136:137], v[136:137], 0, v[134:135]
	global_store_dwordx4 v[136:137], v[130:133], off sc1
	s_nop 1
	v_cvt_pk_bf16_f32 v130, v70, v71
	v_cvt_pk_bf16_f32 v131, v72, v73
	v_cvt_pk_bf16_f32 v132, v66, v67
	v_cvt_pk_bf16_f32 v133, v68, v69
	global_store_dwordx4 v[136:137], v[130:133], off offset:256 sc1
	s_nop 1
	v_add_u32_e32 v130, 0x8080, v138
	v_ashrrev_i32_e32 v131, 31, v130
	v_lshlrev_b64 v[136:137], 10, v[130:131]
	v_lshl_add_u64 v[136:137], s[36:37], 0, v[136:137]
	v_cvt_pk_bf16_f32 v130, v62, v63
	v_cvt_pk_bf16_f32 v131, v64, v65
	v_cvt_pk_bf16_f32 v132, v58, v59
	v_cvt_pk_bf16_f32 v133, v60, v61
	v_lshl_add_u64 v[136:137], v[136:137], 0, v[134:135]
	global_store_dwordx4 v[136:137], v[130:133], off sc1
	s_nop 1
	v_cvt_pk_bf16_f32 v130, v54, v55
	v_cvt_pk_bf16_f32 v131, v56, v57
	v_cvt_pk_bf16_f32 v132, v46, v47
	v_cvt_pk_bf16_f32 v133, v48, v49
	global_store_dwordx4 v[136:137], v[130:133], off offset:256 sc1
	s_nop 1
	v_add_u32_e32 v130, 0x8090, v138
	v_ashrrev_i32_e32 v131, 31, v130
	v_lshlrev_b64 v[136:137], 10, v[130:131]
	v_lshl_add_u64 v[136:137], s[36:37], 0, v[136:137]
	v_cvt_pk_bf16_f32 v130, v50, v51
	v_cvt_pk_bf16_f32 v131, v52, v53
	v_cvt_pk_bf16_f32 v132, v42, v43
	v_cvt_pk_bf16_f32 v133, v44, v45
	v_lshl_add_u64 v[136:137], v[136:137], 0, v[134:135]
	global_store_dwordx4 v[136:137], v[130:133], off sc1
	s_nop 1
	v_cvt_pk_bf16_f32 v130, v38, v39
	v_cvt_pk_bf16_f32 v131, v40, v41
	v_cvt_pk_bf16_f32 v132, v30, v31
	v_cvt_pk_bf16_f32 v133, v32, v33
	global_store_dwordx4 v[136:137], v[130:133], off offset:256 sc1
	s_nop 1
	v_add_u32_e32 v130, 0x80a0, v138
	v_ashrrev_i32_e32 v131, 31, v130
	v_lshlrev_b64 v[136:137], 10, v[130:131]
	v_lshl_add_u64 v[136:137], s[36:37], 0, v[136:137]
	v_cvt_pk_bf16_f32 v130, v34, v35
	v_cvt_pk_bf16_f32 v131, v36, v37
	v_cvt_pk_bf16_f32 v132, v26, v27
	v_cvt_pk_bf16_f32 v133, v28, v29
	v_lshl_add_u64 v[136:137], v[136:137], 0, v[134:135]
	global_store_dwordx4 v[136:137], v[130:133], off sc1
	s_nop 1
	v_cvt_pk_bf16_f32 v130, v22, v23
	v_cvt_pk_bf16_f32 v131, v24, v25
	v_cvt_pk_bf16_f32 v132, v14, v15
	v_cvt_pk_bf16_f32 v133, v16, v17
	global_store_dwordx4 v[136:137], v[130:133], off offset:256 sc1
	s_nop 1
	v_add_u32_e32 v130, 0x80b0, v138
	v_ashrrev_i32_e32 v131, 31, v130
	v_lshlrev_b64 v[136:137], 10, v[130:131]
	v_lshl_add_u64 v[136:137], s[36:37], 0, v[136:137]
	v_cvt_pk_bf16_f32 v130, v18, v19
	v_cvt_pk_bf16_f32 v131, v20, v21
	v_cvt_pk_bf16_f32 v132, v10, v11
	v_cvt_pk_bf16_f32 v133, v12, v13
	v_lshl_add_u64 v[134:135], v[136:137], 0, v[134:135]
	global_store_dwordx4 v[134:135], v[130:133], off sc1
	s_nop 1
	v_cvt_pk_bf16_f32 v130, v6, v7
	v_cvt_pk_bf16_f32 v131, v8, v9
	v_cvt_pk_bf16_f32 v132, v2, v3
	v_cvt_pk_bf16_f32 v133, v4, v5
	global_store_dwordx4 v[134:135], v[130:133], off offset:256 sc1
.LBB0_311:
	s_andn2_b64 vcc, exec, s[46:47]
	s_cbranch_vccnz .LBB0_260
	s_lshl_b32 s2, s66, 8
	s_and_b32 s2, s2, 0x100
	s_or_b32 s2, s2, s59
	v_add_u32_e32 v132, s2, v173
	s_lshl_b32 s2, s33, 8
	s_add_i32 s2, s2, s58
	v_add_u32_e32 v133, s2, v171
	v_add_u32_e32 v130, 0x8000, v133
	v_ashrrev_i32_e32 v130, 9, v130
	v_and_b32_e32 v135, -8, v130
	v_pk_mul_f32 v[126:127], v[126:127], s[38:39] op_sel_hi:[1,0]
	v_pk_mul_f32 v[130:131], v[124:125], s[38:39] op_sel_hi:[1,0]
	v_pk_mul_f32 v[122:123], v[122:123], s[38:39] op_sel_hi:[1,0]
	v_cvt_pk_bf16_f32 v124, v126, v127
	v_cvt_pk_bf16_f32 v127, v130, v131
	v_ashrrev_i32_e32 v130, 6, v132
	v_cvt_pk_bf16_f32 v126, v122, v123
	v_add_u32_e32 v122, v135, v130
	v_pk_mul_f32 v[128:129], v[128:129], s[38:39] op_sel_hi:[1,0]
	v_ashrrev_i32_e32 v123, 31, v122
	v_cvt_pk_bf16_f32 v125, v128, v129
	v_lshlrev_b64 v[122:123], 19, v[122:123]
	v_lshlrev_b32_e32 v128, 7, v133
	v_and_b32_e32 v134, 56, v132
	v_lshl_add_u64 v[122:123], s[34:35], 0, v[122:123]
	v_and_b32_e32 v156, 0x7ff80, v128
	v_lshl_add_u64 v[128:129], v[122:123], 0, v[156:157]
	v_lshlrev_b32_e32 v122, 1, v134
	v_mov_b32_e32 v123, v157
	v_lshl_add_u64 v[128:129], v[128:129], 0, v[122:123]
	global_store_dwordx4 v[128:129], v[124:127], off sc1
	v_pk_mul_f32 v[120:121], v[120:121], s[38:39] op_sel_hi:[1,0]
	v_add_u32_e32 v128, 0x80, v132
	v_pk_mul_f32 v[118:119], v[118:119], s[38:39] op_sel_hi:[1,0]
	v_pk_mul_f32 v[124:125], v[110:111], s[38:39] op_sel_hi:[1,0]
	v_cvt_pk_bf16_f32 v111, v120, v121
	v_ashrrev_i32_e32 v120, 6, v128
	v_cvt_pk_bf16_f32 v110, v118, v119
	v_add_u32_e32 v118, v135, v120
	v_ashrrev_i32_e32 v119, 31, v118
	v_lshlrev_b64 v[118:119], 19, v[118:119]
	v_lshl_add_u64 v[118:119], s[34:35], 0, v[118:119]
	v_pk_mul_f32 v[126:127], v[112:113], s[38:39] op_sel_hi:[1,0]
	v_lshl_add_u64 v[118:119], v[118:119], 0, v[156:157]
	v_cvt_pk_bf16_f32 v112, v124, v125
	v_cvt_pk_bf16_f32 v113, v126, v127
	v_lshl_add_u64 v[118:119], v[118:119], 0, v[122:123]
	global_store_dwordx4 v[118:119], v[110:113], off sc1
	v_add_u32_e32 v118, 0x8010, v133
	v_pk_mul_f32 v[102:103], v[102:103], s[38:39] op_sel_hi:[1,0]
	v_ashrrev_i32_e32 v110, 9, v118
	v_and_b32_e32 v119, -8, v110
	v_pk_mul_f32 v[110:111], v[114:115], s[38:39] op_sel_hi:[1,0]
	v_pk_mul_f32 v[114:115], v[106:107], s[38:39] op_sel_hi:[1,0]
	v_cvt_pk_bf16_f32 v106, v110, v111
	v_add_u32_e32 v110, v119, v130
	v_pk_mul_f32 v[112:113], v[116:117], s[38:39] op_sel_hi:[1,0]
	v_ashrrev_i32_e32 v111, 31, v110
	v_cvt_pk_bf16_f32 v107, v112, v113
	v_lshlrev_b64 v[110:111], 19, v[110:111]
	v_lshlrev_b32_e32 v112, 7, v118
	v_lshl_add_u64 v[110:111], s[34:35], 0, v[110:111]
	v_and_b32_e32 v156, 0x7ff80, v112
	v_pk_mul_f32 v[116:117], v[108:109], s[38:39] op_sel_hi:[1,0]
	v_lshl_add_u64 v[110:111], v[110:111], 0, v[156:157]
	v_cvt_pk_bf16_f32 v108, v114, v115
	v_cvt_pk_bf16_f32 v109, v116, v117
	v_lshl_add_u64 v[110:111], v[110:111], 0, v[122:123]
	global_store_dwordx4 v[110:111], v[106:109], off sc1
	v_pk_mul_f32 v[104:105], v[104:105], s[38:39] op_sel_hi:[1,0]
	v_pk_mul_f32 v[86:87], v[86:87], s[38:39] op_sel_hi:[1,0]
	v_pk_mul_f32 v[106:107], v[94:95], s[38:39] op_sel_hi:[1,0]
	v_cvt_pk_bf16_f32 v94, v102, v103
	v_add_u32_e32 v102, v119, v120
	v_ashrrev_i32_e32 v103, 31, v102
	v_lshlrev_b64 v[102:103], 19, v[102:103]
	v_lshl_add_u64 v[102:103], s[34:35], 0, v[102:103]
	v_pk_mul_f32 v[108:109], v[96:97], s[38:39] op_sel_hi:[1,0]
	v_lshl_add_u64 v[102:103], v[102:103], 0, v[156:157]
	v_cvt_pk_bf16_f32 v95, v104, v105
	v_cvt_pk_bf16_f32 v96, v106, v107
	v_cvt_pk_bf16_f32 v97, v108, v109
	v_lshl_add_u64 v[102:103], v[102:103], 0, v[122:123]
	global_store_dwordx4 v[102:103], v[94:97], off sc1
	v_add_u32_e32 v102, 0x8020, v133
	v_pk_mul_f32 v[88:89], v[88:89], s[38:39] op_sel_hi:[1,0]
	v_ashrrev_i32_e32 v94, 9, v102
	v_and_b32_e32 v103, -8, v94
	v_pk_mul_f32 v[94:95], v[98:99], s[38:39] op_sel_hi:[1,0]
	v_pk_mul_f32 v[98:99], v[90:91], s[38:39] op_sel_hi:[1,0]
	v_cvt_pk_bf16_f32 v90, v94, v95
	v_add_u32_e32 v94, v103, v130
	v_pk_mul_f32 v[96:97], v[100:101], s[38:39] op_sel_hi:[1,0]
	v_ashrrev_i32_e32 v95, 31, v94
	v_cvt_pk_bf16_f32 v91, v96, v97
	v_lshlrev_b64 v[94:95], 19, v[94:95]
	v_lshlrev_b32_e32 v96, 7, v102
	v_lshl_add_u64 v[94:95], s[34:35], 0, v[94:95]
	v_and_b32_e32 v156, 0x7ff80, v96
	v_pk_mul_f32 v[100:101], v[92:93], s[38:39] op_sel_hi:[1,0]
	v_lshl_add_u64 v[94:95], v[94:95], 0, v[156:157]
	v_cvt_pk_bf16_f32 v92, v98, v99
	v_cvt_pk_bf16_f32 v93, v100, v101
	v_lshl_add_u64 v[94:95], v[94:95], 0, v[122:123]
	global_store_dwordx4 v[94:95], v[90:93], off sc1
	v_pk_mul_f32 v[70:71], v[70:71], s[38:39] op_sel_hi:[1,0]
	v_pk_mul_f32 v[72:73], v[72:73], s[38:39] op_sel_hi:[1,0]
	v_pk_mul_f32 v[90:91], v[78:79], s[38:39] op_sel_hi:[1,0]
	v_cvt_pk_bf16_f32 v78, v86, v87
	v_add_u32_e32 v86, v103, v120
	v_ashrrev_i32_e32 v87, 31, v86
	v_lshlrev_b64 v[86:87], 19, v[86:87]
	v_lshl_add_u64 v[86:87], s[34:35], 0, v[86:87]
	v_pk_mul_f32 v[92:93], v[80:81], s[38:39] op_sel_hi:[1,0]
	v_lshl_add_u64 v[86:87], v[86:87], 0, v[156:157]
	v_cvt_pk_bf16_f32 v79, v88, v89
	v_cvt_pk_bf16_f32 v80, v90, v91
	v_cvt_pk_bf16_f32 v81, v92, v93
	v_lshl_add_u64 v[86:87], v[86:87], 0, v[122:123]
	global_store_dwordx4 v[86:87], v[78:81], off sc1
	v_add_u32_e32 v86, 0x8030, v133
	v_pk_mul_f32 v[62:63], v[62:63], s[38:39] op_sel_hi:[1,0]
	v_ashrrev_i32_e32 v78, 9, v86
	v_and_b32_e32 v87, -8, v78
	v_pk_mul_f32 v[78:79], v[82:83], s[38:39] op_sel_hi:[1,0]
	v_pk_mul_f32 v[82:83], v[74:75], s[38:39] op_sel_hi:[1,0]
	v_cvt_pk_bf16_f32 v74, v78, v79
	v_add_u32_e32 v78, v87, v130
	v_pk_mul_f32 v[80:81], v[84:85], s[38:39] op_sel_hi:[1,0]
	v_ashrrev_i32_e32 v79, 31, v78
	v_cvt_pk_bf16_f32 v75, v80, v81
	v_lshlrev_b64 v[78:79], 19, v[78:79]
	v_lshlrev_b32_e32 v80, 7, v86
	v_lshl_add_u64 v[78:79], s[34:35], 0, v[78:79]
	v_and_b32_e32 v156, 0x7ff80, v80
	v_pk_mul_f32 v[84:85], v[76:77], s[38:39] op_sel_hi:[1,0]
	v_lshl_add_u64 v[78:79], v[78:79], 0, v[156:157]
	v_cvt_pk_bf16_f32 v76, v82, v83
	v_cvt_pk_bf16_f32 v77, v84, v85
	v_lshl_add_u64 v[78:79], v[78:79], 0, v[122:123]
	global_store_dwordx4 v[78:79], v[74:77], off sc1
	v_pk_mul_f32 v[64:65], v[64:65], s[38:39] op_sel_hi:[1,0]
	v_pk_mul_f32 v[54:55], v[54:55], s[38:39] op_sel_hi:[1,0]
	v_pk_mul_f32 v[74:75], v[66:67], s[38:39] op_sel_hi:[1,0]
	v_cvt_pk_bf16_f32 v66, v70, v71
	v_add_u32_e32 v70, v87, v120
	v_ashrrev_i32_e32 v71, 31, v70
	v_lshlrev_b64 v[70:71], 19, v[70:71]
	v_lshl_add_u64 v[70:71], s[34:35], 0, v[70:71]
	v_pk_mul_f32 v[76:77], v[68:69], s[38:39] op_sel_hi:[1,0]
	v_lshl_add_u64 v[70:71], v[70:71], 0, v[156:157]
	v_cvt_pk_bf16_f32 v67, v72, v73
	v_cvt_pk_bf16_f32 v68, v74, v75
	v_cvt_pk_bf16_f32 v69, v76, v77
	v_lshl_add_u64 v[70:71], v[70:71], 0, v[122:123]
	global_store_dwordx4 v[70:71], v[66:69], off sc1
	v_add_u32_e32 v70, 0x8080, v133
	v_pk_mul_f32 v[56:57], v[56:57], s[38:39] op_sel_hi:[1,0]
	v_ashrrev_i32_e32 v66, 9, v70
	v_and_b32_e32 v71, -8, v66
	v_pk_mul_f32 v[66:67], v[58:59], s[38:39] op_sel_hi:[1,0]
	v_cvt_pk_bf16_f32 v58, v62, v63
	v_add_u32_e32 v62, v71, v130
	v_ashrrev_i32_e32 v63, 31, v62
	v_cvt_pk_bf16_f32 v59, v64, v65
	v_lshlrev_b64 v[62:63], 19, v[62:63]
	v_lshlrev_b32_e32 v64, 7, v70
	v_lshl_add_u64 v[62:63], s[34:35], 0, v[62:63]
	v_and_b32_e32 v156, 0x7ff80, v64
	v_pk_mul_f32 v[68:69], v[60:61], s[38:39] op_sel_hi:[1,0]
	v_lshl_add_u64 v[62:63], v[62:63], 0, v[156:157]
	v_cvt_pk_bf16_f32 v60, v66, v67
	v_cvt_pk_bf16_f32 v61, v68, v69
	v_lshl_add_u64 v[62:63], v[62:63], 0, v[122:123]
	global_store_dwordx4 v[62:63], v[58:61], off sc1
	v_pk_mul_f32 v[38:39], v[38:39], s[38:39] op_sel_hi:[1,0]
	v_pk_mul_f32 v[40:41], v[40:41], s[38:39] op_sel_hi:[1,0]
	v_pk_mul_f32 v[58:59], v[46:47], s[38:39] op_sel_hi:[1,0]
	v_cvt_pk_bf16_f32 v46, v54, v55
	v_add_u32_e32 v54, v71, v120
	v_ashrrev_i32_e32 v55, 31, v54
	v_lshlrev_b64 v[54:55], 19, v[54:55]
	v_lshl_add_u64 v[54:55], s[34:35], 0, v[54:55]
	v_pk_mul_f32 v[60:61], v[48:49], s[38:39] op_sel_hi:[1,0]
	v_lshl_add_u64 v[54:55], v[54:55], 0, v[156:157]
	v_cvt_pk_bf16_f32 v47, v56, v57
	v_cvt_pk_bf16_f32 v48, v58, v59
	v_cvt_pk_bf16_f32 v49, v60, v61
	v_lshl_add_u64 v[54:55], v[54:55], 0, v[122:123]
	global_store_dwordx4 v[54:55], v[46:49], off sc1
	v_add_u32_e32 v54, 0x8090, v133
	v_pk_mul_f32 v[22:23], v[22:23], s[38:39] op_sel_hi:[1,0]
	v_ashrrev_i32_e32 v46, 9, v54
	v_and_b32_e32 v55, -8, v46
	v_pk_mul_f32 v[46:47], v[50:51], s[38:39] op_sel_hi:[1,0]
	v_pk_mul_f32 v[50:51], v[42:43], s[38:39] op_sel_hi:[1,0]
	v_cvt_pk_bf16_f32 v42, v46, v47
	v_add_u32_e32 v46, v55, v130
	v_pk_mul_f32 v[48:49], v[52:53], s[38:39] op_sel_hi:[1,0]
	v_ashrrev_i32_e32 v47, 31, v46
	v_cvt_pk_bf16_f32 v43, v48, v49
	v_lshlrev_b64 v[46:47], 19, v[46:47]
	v_lshlrev_b32_e32 v48, 7, v54
	v_lshl_add_u64 v[46:47], s[34:35], 0, v[46:47]
	v_and_b32_e32 v156, 0x7ff80, v48
	v_pk_mul_f32 v[52:53], v[44:45], s[38:39] op_sel_hi:[1,0]
	v_lshl_add_u64 v[46:47], v[46:47], 0, v[156:157]
	v_cvt_pk_bf16_f32 v44, v50, v51
	v_cvt_pk_bf16_f32 v45, v52, v53
	v_lshl_add_u64 v[46:47], v[46:47], 0, v[122:123]
	global_store_dwordx4 v[46:47], v[42:45], off sc1
	v_pk_mul_f32 v[24:25], v[24:25], s[38:39] op_sel_hi:[1,0]
	v_pk_mul_f32 v[6:7], v[6:7], s[38:39] op_sel_hi:[1,0]
	v_pk_mul_f32 v[42:43], v[30:31], s[38:39] op_sel_hi:[1,0]
	v_cvt_pk_bf16_f32 v30, v38, v39
	v_add_u32_e32 v38, v55, v120
	v_ashrrev_i32_e32 v39, 31, v38
	v_lshlrev_b64 v[38:39], 19, v[38:39]
	v_lshl_add_u64 v[38:39], s[34:35], 0, v[38:39]
	v_pk_mul_f32 v[44:45], v[32:33], s[38:39] op_sel_hi:[1,0]
	v_lshl_add_u64 v[38:39], v[38:39], 0, v[156:157]
	v_cvt_pk_bf16_f32 v31, v40, v41
	v_cvt_pk_bf16_f32 v32, v42, v43
	v_cvt_pk_bf16_f32 v33, v44, v45
	v_lshl_add_u64 v[38:39], v[38:39], 0, v[122:123]
	global_store_dwordx4 v[38:39], v[30:33], off sc1
	v_add_u32_e32 v38, 0x80a0, v133
	v_pk_mul_f32 v[8:9], v[8:9], s[38:39] op_sel_hi:[1,0]
	v_ashrrev_i32_e32 v30, 9, v38
	v_and_b32_e32 v39, -8, v30
	v_pk_mul_f32 v[30:31], v[34:35], s[38:39] op_sel_hi:[1,0]
	v_pk_mul_f32 v[34:35], v[26:27], s[38:39] op_sel_hi:[1,0]
	v_cvt_pk_bf16_f32 v26, v30, v31
	v_add_u32_e32 v30, v39, v130
	v_pk_mul_f32 v[32:33], v[36:37], s[38:39] op_sel_hi:[1,0]
	v_ashrrev_i32_e32 v31, 31, v30
	v_cvt_pk_bf16_f32 v27, v32, v33
	v_lshlrev_b64 v[30:31], 19, v[30:31]
	v_lshlrev_b32_e32 v32, 7, v38
	v_lshl_add_u64 v[30:31], s[34:35], 0, v[30:31]
	v_and_b32_e32 v156, 0x7ff80, v32
	v_pk_mul_f32 v[36:37], v[28:29], s[38:39] op_sel_hi:[1,0]
	v_lshl_add_u64 v[30:31], v[30:31], 0, v[156:157]
	v_cvt_pk_bf16_f32 v28, v34, v35
	v_cvt_pk_bf16_f32 v29, v36, v37
	v_lshl_add_u64 v[30:31], v[30:31], 0, v[122:123]
	global_store_dwordx4 v[30:31], v[26:29], off sc1
	s_nop 1
	v_pk_mul_f32 v[26:27], v[14:15], s[38:39] op_sel_hi:[1,0]
	v_cvt_pk_bf16_f32 v14, v22, v23
	v_add_u32_e32 v22, v39, v120
	v_ashrrev_i32_e32 v23, 31, v22
	v_lshlrev_b64 v[22:23], 19, v[22:23]
	v_lshl_add_u64 v[22:23], s[34:35], 0, v[22:23]
	v_pk_mul_f32 v[28:29], v[16:17], s[38:39] op_sel_hi:[1,0]
	v_lshl_add_u64 v[22:23], v[22:23], 0, v[156:157]
	v_cvt_pk_bf16_f32 v15, v24, v25
	v_cvt_pk_bf16_f32 v16, v26, v27
	v_cvt_pk_bf16_f32 v17, v28, v29
	v_lshl_add_u64 v[22:23], v[22:23], 0, v[122:123]
	global_store_dwordx4 v[22:23], v[14:17], off sc1
	v_add_u32_e32 v22, 0x80b0, v133
	s_nop 0
	v_ashrrev_i32_e32 v14, 9, v22
	v_and_b32_e32 v23, -8, v14
	v_pk_mul_f32 v[14:15], v[18:19], s[38:39] op_sel_hi:[1,0]
	v_pk_mul_f32 v[18:19], v[10:11], s[38:39] op_sel_hi:[1,0]
	v_cvt_pk_bf16_f32 v10, v14, v15
	v_add_u32_e32 v14, v23, v130
	v_pk_mul_f32 v[16:17], v[20:21], s[38:39] op_sel_hi:[1,0]
	v_ashrrev_i32_e32 v15, 31, v14
	v_cvt_pk_bf16_f32 v11, v16, v17
	v_lshlrev_b64 v[14:15], 19, v[14:15]
	v_lshlrev_b32_e32 v16, 7, v22
	v_lshl_add_u64 v[14:15], s[34:35], 0, v[14:15]
	v_and_b32_e32 v156, 0x7ff80, v16
	v_pk_mul_f32 v[20:21], v[12:13], s[38:39] op_sel_hi:[1,0]
	v_lshl_add_u64 v[14:15], v[14:15], 0, v[156:157]
	v_cvt_pk_bf16_f32 v12, v18, v19
	v_cvt_pk_bf16_f32 v13, v20, v21
	v_lshl_add_u64 v[14:15], v[14:15], 0, v[122:123]
	global_store_dwordx4 v[14:15], v[10:13], off sc1
	s_nop 1
	v_pk_mul_f32 v[10:11], v[2:3], s[38:39] op_sel_hi:[1,0]
	v_cvt_pk_bf16_f32 v2, v6, v7
	v_add_u32_e32 v6, v23, v120
	v_ashrrev_i32_e32 v7, 31, v6
	v_lshlrev_b64 v[6:7], 19, v[6:7]
	v_lshl_add_u64 v[6:7], s[34:35], 0, v[6:7]
	v_pk_mul_f32 v[12:13], v[4:5], s[38:39] op_sel_hi:[1,0]
	v_lshl_add_u64 v[6:7], v[6:7], 0, v[156:157]
	v_cvt_pk_bf16_f32 v3, v8, v9
	v_cvt_pk_bf16_f32 v4, v10, v11
	v_cvt_pk_bf16_f32 v5, v12, v13
	v_lshl_add_u64 v[6:7], v[6:7], 0, v[122:123]
	global_store_dwordx4 v[6:7], v[2:5], off sc1
	s_branch .LBB0_260
